# v009 + m0 write moved ahead of the DMA address add (100 s_nop 0 removed from K-loop load segments)
# baseline (speedup 1.0000x reference)
; #define PG8_STAGE(bufoff, gbase, voff) do { _Pragma("unroll") for (int _i = 0; _i < 2; ++_i) \
;         __builtin_amdgcn_global_load_lds((const unsigned*)((const char*)(gbase) + (voff)[_i]), (PG8_LAS unsigned*)(lds + (bufoff) + ldsw + _i * 8192), 16, 0, PG8_LOAD_AUX); } while (0)
; #define PG8_LDA(dst, b, h) do { _Pragma("unroll") for (int m = 0; m < 4; ++m) _Pragma("unroll") for (int k = 0; k < 2; ++k) dst[m][k] = *(const PG8_LAS bf16x8*)(lds + PG8_SA(b, h) + aoff + m * 2048 + k * 1024); } while (0)
; #define PG8_LDB(dst, b, h) do { _Pragma("unroll") for (int n = 0; n < 2; ++n) _Pragma("unroll") for (int k = 0; k < 2; ++k) dst[n][k] = *(const PG8_LAS bf16x8*)(lds + PG8_SB(b, h) + boff + n * 2048 + k * 1024); } while (0)
; #define PG8_WAIT_V(n) asm volatile("s_waitcnt vmcnt(" #n ")" ::: "memory")
; #define PG8_WAIT_L(n) asm volatile("s_waitcnt lgkmcnt(" #n ")" ::: "memory")
; #define PG8_BAR __builtin_amdgcn_s_barrier()
; #define PG8_SCHED __builtin_amdgcn_sched_barrier(0)
; template <class Epi, class Sched, bool ALIGN_EPI = false, bool SP2 = false>
; __device__ __forceinline__ void gemm_phase(PG8_LAS unsigned char* lds, const Gemm g, const Sched& S, const Epi& E) {
;     ...
;         const bool has_next = S.next(ui + 1, nxt);
;         const char* nA = has_next ? (const char*)g.A + (size_t)nxt.pm * tstepA + (size_t)nxt.pn * apn : cA; const char* nB = has_next ? (const char*)g.Bt + (size_t)nxt.pn * tstepB : cB;
;         for (int t = 0; t < nt; t += 2) {
;             const bool last = (t == nt - 2);
;             const char* a1 = cA + (size_t)(t + 1) * kstep;
;             const char* a2 = last ? nA : cA + (size_t)(t + 2) * kstep; const char* b2 = last ? nB : cB + (size_t)(t + 2) * kstep;
;             const char* a3 = a2 + kstep; const char* b3 = b2 + kstep;
;             if (last && has_next) S.a_ready(nxt);
;             if constexpr (SP2) {
;             PG8_LDB(B0, 0, 0); PG8_LDB(B1, 0, 1); PG8_SCHED; PG8_LDA(At, 0, 0); PG8_STAGE(PG8_SA(1, 1), a1 + hstepA, voffA);
;             PG8_WAIT_V(8); PG8_WAIT_L(0); PG8_BAR; PG8_MMA(0, 0, At, B0); PG8_MMA(0, 1, At, B1); PG8_BAR; PG8_SCHED;
;             PG8_LDA(At, 0, 1); PG8_STAGE(PG8_SB(0, 0), b2, voffB); PG8_STAGE(PG8_SB(0, 1), b2 + hstepB, voffB); PG8_STAGE(PG8_SA(0, 0), a2, voffA);
;             PG8_WAIT_V(8); PG8_WAIT_L(0); PG8_BAR; PG8_MMA(1, 0, At, B0); PG8_MMA(1, 1, At, B1); PG8_BAR; PG8_SCHED;
.LBB0_212:
	s_add_u32 s20, s20, 0x40080
	s_addc_u32 s21, s21, 0
	s_add_u32 s26, s22, 0x100
	s_addc_u32 s27, s23, 0
	s_mov_b32 s28, -2
	ds_read_b128 v[162:165], v158
	ds_read_b128 v[166:169], v158 offset:1024
	ds_read_b128 v[170:173], v158 offset:2048
	ds_read_b128 v[174:177], v158 offset:3072
	ds_read_b128 v[178:181], v159
	ds_read_b128 v[182:185], v159 offset:1024
	ds_read_b128 v[186:189], v159 offset:2048
	ds_read_b128 v[190:193], v159 offset:3072
	s_add_u32 s22, s20, 0xfffc0080
	s_addc_u32 s23, s21, -1
	s_cmp_eq_u32 s28, 12
	s_cselect_b32 s35, s17, s23
	s_cselect_b32 s34, s24, s22
	s_cselect_b32 s23, s15, s27
	s_cselect_b32 s22, s25, s26
	v_lshl_add_u64 v[226:227], s[20:21], 0, v[138:139]
	s_add_i32 m0, s42, 0xc000
	ds_read_b128 v[194:197], v160
	ds_read_b128 v[198:201], v160 offset:1024
	ds_read_b128 v[202:205], v160 offset:2048
	ds_read_b128 v[206:209], v160 offset:3072
	ds_read_b128 v[210:213], v160 offset:4096
	ds_read_b128 v[214:217], v160 offset:5120
	ds_read_b128 v[218:221], v160 offset:6144
	ds_read_b128 v[222:225], v160 offset:7168
	global_load_lds_dwordx4 v[226:227], off
	s_add_i32 m0, s42, 0xe000
	v_lshl_add_u64 v[226:227], s[20:21], 0, v[140:141]
	global_load_lds_dwordx4 v[226:227], off
	s_waitcnt vmcnt(8)
	s_waitcnt lgkmcnt(0)
	s_barrier
	s_waitcnt lgkmcnt(0)
	v_mfma_f32_16x16x32_bf16 v[124:127], v[162:165], v[194:197], 0
	s_add_i32 s46, s46, 1
	s_mul_i32 s4, s46, s47
	v_mfma_f32_16x16x32_bf16 v[120:123], v[170:173], v[194:197], 0
	s_mul_hi_u32 s5, s46, s50
	s_add_i32 s5, s5, s4
	v_mfma_f32_16x16x32_bf16 v[108:111], v[162:165], v[202:205], 0
	s_mul_i32 s4, s46, s50
	v_readlane_b32 s15, v239, 0
	v_mfma_f32_16x16x32_bf16 v[104:107], v[170:173], v[202:205], 0
	s_add_u32 s18, s4, s15
	s_addc_u32 s19, s5, s36
	v_mfma_f32_16x16x32_bf16 v[92:95], v[162:165], v[210:213], 0
	s_cmp_lt_u32 s18, 0x900
	s_cselect_b64 s[4:5], -1, 0
	v_mfma_f32_16x16x32_bf16 v[88:91], v[170:173], v[210:213], 0
	s_ashr_i32 s14, s18, 31
	s_lshr_b32 s14, s14, 29
	v_mfma_f32_16x16x32_bf16 v[76:79], v[162:165], v[218:221], 0
	s_add_i32 s14, s18, s14
	s_ashr_i32 s15, s14, 3
	v_mfma_f32_16x16x32_bf16 v[72:75], v[170:173], v[218:221], 0
	s_and_b32 s14, s14, -8
	s_sub_i32 s14, s18, s14
	v_mfma_f32_16x16x32_bf16 v[124:127], v[166:169], v[198:201], v[124:127]
	s_cmp_lt_i32 s14, 0
	s_cselect_b32 s16, s37, 0x120
	v_mfma_f32_16x16x32_bf16 v[120:123], v[174:177], v[198:201], v[120:123]
	s_mul_i32 s14, s14, s16
	s_add_i32 s14, s14, s15
	v_mfma_f32_16x16x32_bf16 v[108:111], v[166:169], v[206:209], v[108:111]
	s_mul_hi_i32 s15, s14, 0x38e38e39
	s_lshr_b32 s16, s15, 31
	v_mfma_f32_16x16x32_bf16 v[104:107], v[174:177], v[206:209], v[104:107]
	s_ashr_i32 s15, s15, 5
	s_add_i32 s15, s15, s16
	v_mfma_f32_16x16x32_bf16 v[92:95], v[166:169], v[214:217], v[92:95]
	s_lshl_b32 s16, s15, 2
	s_sub_i32 s17, 64, s16
	v_mfma_f32_16x16x32_bf16 v[88:91], v[174:177], v[214:217], v[88:91]
	s_min_i32 s17, s17, 4
	s_mulk_i32 s15, 0x90
	v_mfma_f32_16x16x32_bf16 v[76:79], v[166:169], v[222:225], v[76:79]
	s_sub_i32 s15, s14, s15
	s_lshr_b32 s14, s15, 2
	v_mfma_f32_16x16x32_bf16 v[72:75], v[174:177], v[222:225], v[72:75]
	s_and_b32 s15, s15, 3
	s_add_i32 s16, s16, s15
	v_mfma_f32_16x16x32_bf16 v[116:119], v[178:181], v[194:197], 0
	s_ashr_i32 s17, s16, 31
	s_lshl_b64 s[18:19], s[16:17], 19
	v_mfma_f32_16x16x32_bf16 v[112:115], v[186:189], v[194:197], 0
	v_readlane_b32 s24, v239, 47
	v_readlane_b32 s25, v239, 48
	v_mfma_f32_16x16x32_bf16 v[100:103], v[178:181], v[202:205], 0
	s_add_u32 s18, s24, s18
	s_addc_u32 s19, s25, s19
	v_mfma_f32_16x16x32_bf16 v[96:99], v[186:189], v[202:205], 0
	s_sub_u32 s98, s20, 0x40080
	s_subb_u32 s99, s21, 0
	v_mfma_f32_16x16x32_bf16 v[84:87], v[178:181], v[210:213], 0
	s_cmp_lg_u64 s[4:5], 0
	s_cselect_b32 s17, s19, s99
	v_mfma_f32_16x16x32_bf16 v[80:83], v[186:189], v[210:213], 0
	s_cselect_b32 s24, s18, s98
	s_ashr_i32 s15, s14, 31
	v_mfma_f32_16x16x32_bf16 v[68:71], v[178:181], v[218:221], 0
	s_lshl_b64 s[98:99], s[14:15], 19
	s_add_u32 s40, s64, s98
	v_mfma_f32_16x16x32_bf16 v[64:67], v[186:189], v[218:221], 0
	s_addc_u32 s41, s65, s99
	s_sub_u32 s98, s26, 0x100
	v_mfma_f32_16x16x32_bf16 v[116:119], v[182:185], v[198:201], v[116:119]
	s_subb_u32 s99, s27, 0
	s_cmp_lg_u64 s[4:5], 0
	v_mfma_f32_16x16x32_bf16 v[112:115], v[190:193], v[198:201], v[112:115]
	s_cselect_b32 s15, s41, s99
	s_cselect_b32 s25, s40, s98
	v_mfma_f32_16x16x32_bf16 v[100:103], v[182:185], v[206:209], v[100:103]
	v_mfma_f32_16x16x32_bf16 v[96:99], v[190:193], v[206:209], v[96:99]
	v_mfma_f32_16x16x32_bf16 v[84:87], v[182:185], v[214:217], v[84:87]
	v_mfma_f32_16x16x32_bf16 v[80:83], v[190:193], v[214:217], v[80:83]
	v_mfma_f32_16x16x32_bf16 v[68:71], v[182:185], v[222:225], v[68:71]
	v_mfma_f32_16x16x32_bf16 v[64:67], v[190:193], v[222:225], v[64:67]
	s_barrier
	s_add_i32 s29, s51, s33
	v_lshl_add_u64 v[226:227], s[22:23], 0, v[130:131]
	s_mov_b32 m0, s29
	ds_read_b128 v[194:197], v160 offset:16384
	ds_read_b128 v[198:201], v160 offset:17408
	ds_read_b128 v[202:205], v160 offset:18432
	ds_read_b128 v[206:209], v160 offset:19456
	ds_read_b128 v[210:213], v160 offset:20480
	ds_read_b128 v[214:217], v160 offset:21504
	ds_read_b128 v[218:221], v160 offset:22528
	ds_read_b128 v[222:225], v160 offset:23552
	global_load_lds_dwordx4 v[226:227], off
	s_add_i32 m0, s29, 0x2000
	s_add_u32 s30, s22, 0x10000
	v_lshl_add_u64 v[228:229], s[22:23], 0, v[134:135]
	s_addc_u32 s31, s23, 0
	s_add_i32 s29, s52, s33
	global_load_lds_dwordx4 v[228:229], off
	v_lshl_add_u64 v[230:231], s[30:31], 0, v[130:131]
	s_mov_b32 m0, s29
	v_lshl_add_u64 v[232:233], s[34:35], 0, v[132:133]
	global_load_lds_dwordx4 v[230:231], off
	s_add_i32 m0, s29, 0x2000
	v_lshl_add_u64 v[230:231], s[30:31], 0, v[134:135]
	global_load_lds_dwordx4 v[230:231], off
	s_mov_b32 m0, s42
	v_lshl_add_u64 v[230:231], s[34:35], 0, v[128:129]
	global_load_lds_dwordx4 v[230:231], off
	s_mov_b32 m0, s43
	s_nop 0
	global_load_lds_dwordx4 v[232:233], off
	s_waitcnt vmcnt(8)
	s_waitcnt lgkmcnt(0)
	s_barrier
; #define PG8_STAGE(bufoff, gbase, voff) do { _Pragma("unroll") for (int _i = 0; _i < 2; ++_i) \
;         __builtin_amdgcn_global_load_lds((const unsigned*)((const char*)(gbase) + (voff)[_i]), (PG8_LAS unsigned*)(lds + (bufoff) + ldsw + _i * 8192), 16, 0, PG8_LOAD_AUX); } while (0)
; #define PG8_LDA(dst, b, h) do { _Pragma("unroll") for (int m = 0; m < 4; ++m) _Pragma("unroll") for (int k = 0; k < 2; ++k) dst[m][k] = *(const PG8_LAS bf16x8*)(lds + PG8_SA(b, h) + aoff + m * 2048 + k * 1024); } while (0)
; #define PG8_LDB(dst, b, h) do { _Pragma("unroll") for (int n = 0; n < 2; ++n) _Pragma("unroll") for (int k = 0; k < 2; ++k) dst[n][k] = *(const PG8_LAS bf16x8*)(lds + PG8_SB(b, h) + boff + n * 2048 + k * 1024); } while (0)
; #define PG8_MMA(ai, bj, At, Bt) do { __builtin_amdgcn_s_setprio(1); _Pragma("unroll") for (int m = 0; m < 4; ++m) _Pragma("unroll") for (int n = 0; n < 2; ++n) _Pragma("unroll") for (int k = 0; k < 2; ++k) \
;         acc[ai][bj][m][n] = __builtin_amdgcn_mfma_f32_16x16x32_bf16(Bt[n][k], At[m][k], acc[ai][bj][m][n], 0, 0, 0); __builtin_amdgcn_s_setprio(0); } while (0)
; #define PG8_WAIT_V(n) asm volatile("s_waitcnt vmcnt(" #n ")" ::: "memory")
; #define PG8_WAIT_L(n) asm volatile("s_waitcnt lgkmcnt(" #n ")" ::: "memory")
; #define PG8_BAR __builtin_amdgcn_s_barrier()
; #define PG8_SCHED __builtin_amdgcn_sched_barrier(0)
; template <class Epi, class Sched, bool ALIGN_EPI = false, bool SP2 = false>
; __device__ __forceinline__ void gemm_phase(PG8_LAS unsigned char* lds, const Gemm g, const Sched& S, const Epi& E) {
;     ...
;             PG8_LDB(B0, 0, 0); PG8_LDB(B1, 0, 1); PG8_SCHED; PG8_LDA(At, 0, 0); PG8_STAGE(PG8_SA(1, 1), a1 + hstepA, voffA);
;             PG8_WAIT_V(8); PG8_WAIT_L(0); PG8_BAR; PG8_MMA(0, 0, At, B0); PG8_MMA(0, 1, At, B1); PG8_BAR; PG8_SCHED;
;             PG8_LDA(At, 0, 1); PG8_STAGE(PG8_SB(0, 0), b2, voffB); PG8_STAGE(PG8_SB(0, 1), b2 + hstepB, voffB); PG8_STAGE(PG8_SA(0, 0), a2, voffA);
;             PG8_WAIT_V(8); PG8_WAIT_L(0); PG8_BAR; PG8_MMA(1, 0, At, B0); PG8_MMA(1, 1, At, B1); PG8_BAR; PG8_SCHED;
	s_waitcnt lgkmcnt(0)
	v_mfma_f32_16x16x32_bf16 v[60:63], v[162:165], v[194:197], 0
	v_mfma_f32_16x16x32_bf16 v[56:59], v[170:173], v[194:197], 0
	v_mfma_f32_16x16x32_bf16 v[44:47], v[162:165], v[202:205], 0
	v_mfma_f32_16x16x32_bf16 v[40:43], v[170:173], v[202:205], 0
	v_mfma_f32_16x16x32_bf16 v[28:31], v[162:165], v[210:213], 0
	v_mfma_f32_16x16x32_bf16 v[24:27], v[170:173], v[210:213], 0
	v_mfma_f32_16x16x32_bf16 v[12:15], v[162:165], v[218:221], 0
	v_mfma_f32_16x16x32_bf16 v[8:11], v[170:173], v[218:221], 0
	v_mfma_f32_16x16x32_bf16 v[60:63], v[166:169], v[198:201], v[60:63]
	v_mfma_f32_16x16x32_bf16 v[56:59], v[174:177], v[198:201], v[56:59]
	v_mfma_f32_16x16x32_bf16 v[44:47], v[166:169], v[206:209], v[44:47]
	v_mfma_f32_16x16x32_bf16 v[40:43], v[174:177], v[206:209], v[40:43]
	v_mfma_f32_16x16x32_bf16 v[28:31], v[166:169], v[214:217], v[28:31]
	v_mfma_f32_16x16x32_bf16 v[24:27], v[174:177], v[214:217], v[24:27]
	v_mfma_f32_16x16x32_bf16 v[12:15], v[166:169], v[222:225], v[12:15]
	v_mfma_f32_16x16x32_bf16 v[8:11], v[174:177], v[222:225], v[8:11]
	v_mfma_f32_16x16x32_bf16 v[52:55], v[178:181], v[194:197], 0
	v_mfma_f32_16x16x32_bf16 v[48:51], v[186:189], v[194:197], 0
	v_mfma_f32_16x16x32_bf16 v[36:39], v[178:181], v[202:205], 0
	v_mfma_f32_16x16x32_bf16 v[32:35], v[186:189], v[202:205], 0
	v_mfma_f32_16x16x32_bf16 v[20:23], v[178:181], v[210:213], 0
	v_mfma_f32_16x16x32_bf16 v[16:19], v[186:189], v[210:213], 0
	v_mfma_f32_16x16x32_bf16 v[4:7], v[178:181], v[218:221], 0
	v_mfma_f32_16x16x32_bf16 v[0:3], v[186:189], v[218:221], 0
	v_mfma_f32_16x16x32_bf16 v[52:55], v[182:185], v[198:201], v[52:55]
	v_mfma_f32_16x16x32_bf16 v[48:51], v[190:193], v[198:201], v[48:51]
	v_mfma_f32_16x16x32_bf16 v[36:39], v[182:185], v[206:209], v[36:39]
	v_mfma_f32_16x16x32_bf16 v[32:35], v[190:193], v[206:209], v[32:35]
	v_mfma_f32_16x16x32_bf16 v[20:23], v[182:185], v[214:217], v[20:23]
	v_mfma_f32_16x16x32_bf16 v[16:19], v[190:193], v[214:217], v[16:19]
	v_mfma_f32_16x16x32_bf16 v[4:7], v[182:185], v[222:225], v[4:7]
	v_mfma_f32_16x16x32_bf16 v[0:3], v[190:193], v[222:225], v[0:3]
	s_barrier
	s_branch .Lkmid_P1
.LBB0_215:
	ds_read_b128 v[162:165], v158
	ds_read_b128 v[166:169], v158 offset:1024
	ds_read_b128 v[170:173], v158 offset:2048
	ds_read_b128 v[174:177], v158 offset:3072
	ds_read_b128 v[178:181], v159
	ds_read_b128 v[182:185], v159 offset:1024
	ds_read_b128 v[186:189], v159 offset:2048
	ds_read_b128 v[190:193], v159 offset:3072
	s_add_u32 s22, s20, 0xfffc0080
	s_addc_u32 s23, s21, -1
	s_cmp_eq_u32 s28, 12
	s_cselect_b32 s35, s17, s23
	s_cselect_b32 s34, s24, s22
	s_cselect_b32 s23, s15, s27
	s_cselect_b32 s22, s25, s26
	v_lshl_add_u64 v[226:227], s[20:21], 0, v[138:139]
	s_add_i32 m0, s42, 0xc000
	ds_read_b128 v[194:197], v160
	ds_read_b128 v[198:201], v160 offset:1024
	ds_read_b128 v[202:205], v160 offset:2048
	ds_read_b128 v[206:209], v160 offset:3072
	ds_read_b128 v[210:213], v160 offset:4096
	ds_read_b128 v[214:217], v160 offset:5120
	ds_read_b128 v[218:221], v160 offset:6144
	ds_read_b128 v[222:225], v160 offset:7168
	global_load_lds_dwordx4 v[226:227], off
	s_add_i32 m0, s42, 0xe000
	v_lshl_add_u64 v[226:227], s[20:21], 0, v[140:141]
	global_load_lds_dwordx4 v[226:227], off
	s_waitcnt vmcnt(8)
	s_waitcnt lgkmcnt(0)
	s_barrier
	s_waitcnt lgkmcnt(0)
	v_mfma_f32_16x16x32_bf16 v[124:127], v[162:165], v[194:197], v[124:127]
	v_mfma_f32_16x16x32_bf16 v[120:123], v[170:173], v[194:197], v[120:123]
	v_mfma_f32_16x16x32_bf16 v[108:111], v[162:165], v[202:205], v[108:111]
	v_mfma_f32_16x16x32_bf16 v[104:107], v[170:173], v[202:205], v[104:107]
	v_mfma_f32_16x16x32_bf16 v[92:95], v[162:165], v[210:213], v[92:95]
	v_mfma_f32_16x16x32_bf16 v[88:91], v[170:173], v[210:213], v[88:91]
	v_mfma_f32_16x16x32_bf16 v[76:79], v[162:165], v[218:221], v[76:79]
	v_mfma_f32_16x16x32_bf16 v[72:75], v[170:173], v[218:221], v[72:75]
	v_mfma_f32_16x16x32_bf16 v[124:127], v[166:169], v[198:201], v[124:127]
	v_mfma_f32_16x16x32_bf16 v[120:123], v[174:177], v[198:201], v[120:123]
	v_mfma_f32_16x16x32_bf16 v[108:111], v[166:169], v[206:209], v[108:111]
	v_mfma_f32_16x16x32_bf16 v[104:107], v[174:177], v[206:209], v[104:107]
	v_mfma_f32_16x16x32_bf16 v[92:95], v[166:169], v[214:217], v[92:95]
	v_mfma_f32_16x16x32_bf16 v[88:91], v[174:177], v[214:217], v[88:91]
	v_mfma_f32_16x16x32_bf16 v[76:79], v[166:169], v[222:225], v[76:79]
	v_mfma_f32_16x16x32_bf16 v[72:75], v[174:177], v[222:225], v[72:75]
	v_mfma_f32_16x16x32_bf16 v[116:119], v[178:181], v[194:197], v[116:119]
	v_mfma_f32_16x16x32_bf16 v[112:115], v[186:189], v[194:197], v[112:115]
	v_mfma_f32_16x16x32_bf16 v[100:103], v[178:181], v[202:205], v[100:103]
	v_mfma_f32_16x16x32_bf16 v[96:99], v[186:189], v[202:205], v[96:99]
	v_mfma_f32_16x16x32_bf16 v[84:87], v[178:181], v[210:213], v[84:87]
	v_mfma_f32_16x16x32_bf16 v[80:83], v[186:189], v[210:213], v[80:83]
	v_mfma_f32_16x16x32_bf16 v[68:71], v[178:181], v[218:221], v[68:71]
	v_mfma_f32_16x16x32_bf16 v[64:67], v[186:189], v[218:221], v[64:67]
	v_mfma_f32_16x16x32_bf16 v[116:119], v[182:185], v[198:201], v[116:119]
	v_mfma_f32_16x16x32_bf16 v[112:115], v[190:193], v[198:201], v[112:115]
	v_mfma_f32_16x16x32_bf16 v[100:103], v[182:185], v[206:209], v[100:103]
	v_mfma_f32_16x16x32_bf16 v[96:99], v[190:193], v[206:209], v[96:99]
	v_mfma_f32_16x16x32_bf16 v[84:87], v[182:185], v[214:217], v[84:87]
	v_mfma_f32_16x16x32_bf16 v[80:83], v[190:193], v[214:217], v[80:83]
	v_mfma_f32_16x16x32_bf16 v[68:71], v[182:185], v[222:225], v[68:71]
	v_mfma_f32_16x16x32_bf16 v[64:67], v[190:193], v[222:225], v[64:67]
	s_barrier
; #define PG8_STAGE(bufoff, gbase, voff) do { _Pragma("unroll") for (int _i = 0; _i < 2; ++_i) \
;         __builtin_amdgcn_global_load_lds((const unsigned*)((const char*)(gbase) + (voff)[_i]), (PG8_LAS unsigned*)(lds + (bufoff) + ldsw + _i * 8192), 16, 0, PG8_LOAD_AUX); } while (0)
; #define PG8_LDA(dst, b, h) do { _Pragma("unroll") for (int m = 0; m < 4; ++m) _Pragma("unroll") for (int k = 0; k < 2; ++k) dst[m][k] = *(const PG8_LAS bf16x8*)(lds + PG8_SA(b, h) + aoff + m * 2048 + k * 1024); } while (0)
; #define PG8_LDB(dst, b, h) do { _Pragma("unroll") for (int n = 0; n < 2; ++n) _Pragma("unroll") for (int k = 0; k < 2; ++k) dst[n][k] = *(const PG8_LAS bf16x8*)(lds + PG8_SB(b, h) + boff + n * 2048 + k * 1024); } while (0)
; #define PG8_MMA(ai, bj, At, Bt) do { __builtin_amdgcn_s_setprio(1); _Pragma("unroll") for (int m = 0; m < 4; ++m) _Pragma("unroll") for (int n = 0; n < 2; ++n) _Pragma("unroll") for (int k = 0; k < 2; ++k) \
;         acc[ai][bj][m][n] = __builtin_amdgcn_mfma_f32_16x16x32_bf16(Bt[n][k], At[m][k], acc[ai][bj][m][n], 0, 0, 0); __builtin_amdgcn_s_setprio(0); } while (0)
; #define PG8_WAIT_V(n) asm volatile("s_waitcnt vmcnt(" #n ")" ::: "memory")
; #define PG8_WAIT_L(n) asm volatile("s_waitcnt lgkmcnt(" #n ")" ::: "memory")
; #define PG8_BAR __builtin_amdgcn_s_barrier()
; #define PG8_SCHED __builtin_amdgcn_sched_barrier(0)
; template <class Epi, class Sched, bool ALIGN_EPI = false, bool SP2 = false>
; __device__ __forceinline__ void gemm_phase(PG8_LAS unsigned char* lds, const Gemm g, const Sched& S, const Epi& E) {
;     ...
;             PG8_LDA(At, 0, 1); PG8_STAGE(PG8_SB(0, 0), b2, voffB); PG8_STAGE(PG8_SB(0, 1), b2 + hstepB, voffB); PG8_STAGE(PG8_SA(0, 0), a2, voffA);
;             PG8_WAIT_V(8); PG8_WAIT_L(0); PG8_BAR; PG8_MMA(1, 0, At, B0); PG8_MMA(1, 1, At, B1); PG8_BAR; PG8_SCHED;
;             PG8_LDB(B0, 1, 0); PG8_LDB(B1, 1, 1); PG8_SCHED; PG8_LDA(At, 1, 0); PG8_STAGE(PG8_SA(0, 1), a2 + hstepA, voffA);
;             PG8_WAIT_V(8); PG8_WAIT_L(0); PG8_BAR; PG8_MMA(0, 0, At, B0); PG8_MMA(0, 1, At, B1); PG8_BAR; PG8_SCHED;
	s_add_i32 s29, s51, s33
	v_lshl_add_u64 v[226:227], s[22:23], 0, v[130:131]
	s_mov_b32 m0, s29
	ds_read_b128 v[194:197], v160 offset:16384
	ds_read_b128 v[198:201], v160 offset:17408
	ds_read_b128 v[202:205], v160 offset:18432
	ds_read_b128 v[206:209], v160 offset:19456
	ds_read_b128 v[210:213], v160 offset:20480
	ds_read_b128 v[214:217], v160 offset:21504
	ds_read_b128 v[218:221], v160 offset:22528
	ds_read_b128 v[222:225], v160 offset:23552
	global_load_lds_dwordx4 v[226:227], off
	s_add_i32 m0, s29, 0x2000
	s_add_u32 s30, s22, 0x10000
	v_lshl_add_u64 v[228:229], s[22:23], 0, v[134:135]
	s_addc_u32 s31, s23, 0
	s_add_i32 s29, s52, s33
	global_load_lds_dwordx4 v[228:229], off
	v_lshl_add_u64 v[230:231], s[30:31], 0, v[130:131]
	s_mov_b32 m0, s29
	v_lshl_add_u64 v[232:233], s[34:35], 0, v[132:133]
	global_load_lds_dwordx4 v[230:231], off
	s_add_i32 m0, s29, 0x2000
	v_lshl_add_u64 v[230:231], s[30:31], 0, v[134:135]
	global_load_lds_dwordx4 v[230:231], off
	s_mov_b32 m0, s42
	v_lshl_add_u64 v[230:231], s[34:35], 0, v[128:129]
	global_load_lds_dwordx4 v[230:231], off
	s_mov_b32 m0, s43
	s_nop 0
	global_load_lds_dwordx4 v[232:233], off
	s_waitcnt vmcnt(8)
	s_waitcnt lgkmcnt(0)
	s_barrier
	s_waitcnt lgkmcnt(0)
	v_mfma_f32_16x16x32_bf16 v[60:63], v[162:165], v[194:197], v[60:63]
	v_mfma_f32_16x16x32_bf16 v[56:59], v[170:173], v[194:197], v[56:59]
	v_mfma_f32_16x16x32_bf16 v[44:47], v[162:165], v[202:205], v[44:47]
	v_mfma_f32_16x16x32_bf16 v[40:43], v[170:173], v[202:205], v[40:43]
	v_mfma_f32_16x16x32_bf16 v[28:31], v[162:165], v[210:213], v[28:31]
	v_mfma_f32_16x16x32_bf16 v[24:27], v[170:173], v[210:213], v[24:27]
	v_mfma_f32_16x16x32_bf16 v[12:15], v[162:165], v[218:221], v[12:15]
	v_mfma_f32_16x16x32_bf16 v[8:11], v[170:173], v[218:221], v[8:11]
	v_mfma_f32_16x16x32_bf16 v[60:63], v[166:169], v[198:201], v[60:63]
	v_mfma_f32_16x16x32_bf16 v[56:59], v[174:177], v[198:201], v[56:59]
	v_mfma_f32_16x16x32_bf16 v[44:47], v[166:169], v[206:209], v[44:47]
	v_mfma_f32_16x16x32_bf16 v[40:43], v[174:177], v[206:209], v[40:43]
	v_mfma_f32_16x16x32_bf16 v[28:31], v[166:169], v[214:217], v[28:31]
	v_mfma_f32_16x16x32_bf16 v[24:27], v[174:177], v[214:217], v[24:27]
	v_mfma_f32_16x16x32_bf16 v[12:15], v[166:169], v[222:225], v[12:15]
	v_mfma_f32_16x16x32_bf16 v[8:11], v[174:177], v[222:225], v[8:11]
	v_mfma_f32_16x16x32_bf16 v[52:55], v[178:181], v[194:197], v[52:55]
	v_mfma_f32_16x16x32_bf16 v[48:51], v[186:189], v[194:197], v[48:51]
	v_mfma_f32_16x16x32_bf16 v[36:39], v[178:181], v[202:205], v[36:39]
	v_mfma_f32_16x16x32_bf16 v[32:35], v[186:189], v[202:205], v[32:35]
	v_mfma_f32_16x16x32_bf16 v[20:23], v[178:181], v[210:213], v[20:23]
	v_mfma_f32_16x16x32_bf16 v[16:19], v[186:189], v[210:213], v[16:19]
	v_mfma_f32_16x16x32_bf16 v[4:7], v[178:181], v[218:221], v[4:7]
	v_mfma_f32_16x16x32_bf16 v[0:3], v[186:189], v[218:221], v[0:3]
	v_mfma_f32_16x16x32_bf16 v[52:55], v[182:185], v[198:201], v[52:55]
	v_mfma_f32_16x16x32_bf16 v[48:51], v[190:193], v[198:201], v[48:51]
	v_mfma_f32_16x16x32_bf16 v[36:39], v[182:185], v[206:209], v[36:39]
	v_mfma_f32_16x16x32_bf16 v[32:35], v[190:193], v[206:209], v[32:35]
	v_mfma_f32_16x16x32_bf16 v[20:23], v[182:185], v[214:217], v[20:23]
	v_mfma_f32_16x16x32_bf16 v[16:19], v[190:193], v[214:217], v[16:19]
	v_mfma_f32_16x16x32_bf16 v[4:7], v[182:185], v[222:225], v[4:7]
	v_mfma_f32_16x16x32_bf16 v[0:3], v[190:193], v[222:225], v[0:3]
	s_barrier
.Lkmid_P1:
	s_add_i32 s29, 0, 0x18000
	v_add_u32_e32 v161, s29, v146
	s_add_i32 s38, 0, 0x1c000
	ds_read_b128 v[162:165], v161
	ds_read_b128 v[166:169], v161 offset:1024
	ds_read_b128 v[170:173], v161 offset:2048
	ds_read_b128 v[174:177], v161 offset:3072
	v_add_u32_e32 v161, s38, v146
	ds_read_b128 v[178:181], v161
	ds_read_b128 v[182:185], v161 offset:1024
	ds_read_b128 v[186:189], v161 offset:2048
	ds_read_b128 v[190:193], v161 offset:3072
	s_add_u32 s30, s34, 0x40000
	s_addc_u32 s31, s35, 0
	s_mov_b32 m0, s44
	v_lshl_add_u64 v[234:235], s[30:31], 0, v[128:129]
	ds_read_b128 v[194:197], v160 offset:32768
	ds_read_b128 v[198:201], v160 offset:33792
	ds_read_b128 v[202:205], v160 offset:34816
	ds_read_b128 v[206:209], v160 offset:35840
	ds_read_b128 v[210:213], v160 offset:36864
	ds_read_b128 v[214:217], v160 offset:37888
	ds_read_b128 v[218:221], v160 offset:38912
	ds_read_b128 v[222:225], v160 offset:39936
	global_load_lds_dwordx4 v[234:235], off
	s_mov_b32 m0, s45
	v_lshl_add_u64 v[234:235], s[30:31], 0, v[132:133]
	global_load_lds_dwordx4 v[234:235], off
	s_waitcnt vmcnt(8)
	s_waitcnt lgkmcnt(0)
	s_barrier
; #define PG8_STAGE(bufoff, gbase, voff) do { _Pragma("unroll") for (int _i = 0; _i < 2; ++_i) \
;         __builtin_amdgcn_global_load_lds((const unsigned*)((const char*)(gbase) + (voff)[_i]), (PG8_LAS unsigned*)(lds + (bufoff) + ldsw + _i * 8192), 16, 0, PG8_LOAD_AUX); } while (0)
; #define PG8_LDA(dst, b, h) do { _Pragma("unroll") for (int m = 0; m < 4; ++m) _Pragma("unroll") for (int k = 0; k < 2; ++k) dst[m][k] = *(const PG8_LAS bf16x8*)(lds + PG8_SA(b, h) + aoff + m * 2048 + k * 1024); } while (0)
; #define PG8_LDB(dst, b, h) do { _Pragma("unroll") for (int n = 0; n < 2; ++n) _Pragma("unroll") for (int k = 0; k < 2; ++k) dst[n][k] = *(const PG8_LAS bf16x8*)(lds + PG8_SB(b, h) + boff + n * 2048 + k * 1024); } while (0)
; #define PG8_MMA(ai, bj, At, Bt) do { __builtin_amdgcn_s_setprio(1); _Pragma("unroll") for (int m = 0; m < 4; ++m) _Pragma("unroll") for (int n = 0; n < 2; ++n) _Pragma("unroll") for (int k = 0; k < 2; ++k) \
;         acc[ai][bj][m][n] = __builtin_amdgcn_mfma_f32_16x16x32_bf16(Bt[n][k], At[m][k], acc[ai][bj][m][n], 0, 0, 0); __builtin_amdgcn_s_setprio(0); } while (0)
; #define PG8_WAIT_V(n) asm volatile("s_waitcnt vmcnt(" #n ")" ::: "memory")
; #define PG8_WAIT_L(n) asm volatile("s_waitcnt lgkmcnt(" #n ")" ::: "memory")
; #define PG8_BAR __builtin_amdgcn_s_barrier()
; #define PG8_SCHED __builtin_amdgcn_sched_barrier(0)
; template <class Epi, class Sched, bool ALIGN_EPI = false, bool SP2 = false>
; __device__ __forceinline__ void gemm_phase(PG8_LAS unsigned char* lds, const Gemm g, const Sched& S, const Epi& E) {
;     ...
;             PG8_LDB(B0, 1, 0); PG8_LDB(B1, 1, 1); PG8_SCHED; PG8_LDA(At, 1, 0); PG8_STAGE(PG8_SA(0, 1), a2 + hstepA, voffA);
;             PG8_WAIT_V(8); PG8_WAIT_L(0); PG8_BAR; PG8_MMA(0, 0, At, B0); PG8_MMA(0, 1, At, B1); PG8_BAR; PG8_SCHED;
;             PG8_LDA(At, 1, 1); PG8_STAGE(PG8_SB(1, 0), b3, voffB); PG8_STAGE(PG8_SB(1, 1), b3 + hstepB, voffB); PG8_STAGE(PG8_SA(1, 0), a3, voffA);
;             PG8_WAIT_V(8); PG8_WAIT_L(0); PG8_BAR; PG8_MMA(1, 0, At, B0); PG8_MMA(1, 1, At, B1); PG8_BAR; PG8_SCHED;
;     ...
;         if constexpr (ALIGN_EPI) { if (wr == 0) PG8_BAR; }
	s_waitcnt lgkmcnt(0)
	v_mfma_f32_16x16x32_bf16 v[124:127], v[162:165], v[194:197], v[124:127]
	v_mfma_f32_16x16x32_bf16 v[120:123], v[170:173], v[194:197], v[120:123]
	v_mfma_f32_16x16x32_bf16 v[108:111], v[162:165], v[202:205], v[108:111]
	v_mfma_f32_16x16x32_bf16 v[104:107], v[170:173], v[202:205], v[104:107]
	v_mfma_f32_16x16x32_bf16 v[92:95], v[162:165], v[210:213], v[92:95]
	v_mfma_f32_16x16x32_bf16 v[88:91], v[170:173], v[210:213], v[88:91]
	v_mfma_f32_16x16x32_bf16 v[76:79], v[162:165], v[218:221], v[76:79]
	v_mfma_f32_16x16x32_bf16 v[72:75], v[170:173], v[218:221], v[72:75]
	v_mfma_f32_16x16x32_bf16 v[124:127], v[166:169], v[198:201], v[124:127]
	v_mfma_f32_16x16x32_bf16 v[120:123], v[174:177], v[198:201], v[120:123]
	v_mfma_f32_16x16x32_bf16 v[108:111], v[166:169], v[206:209], v[108:111]
	v_mfma_f32_16x16x32_bf16 v[104:107], v[174:177], v[206:209], v[104:107]
	v_mfma_f32_16x16x32_bf16 v[92:95], v[166:169], v[214:217], v[92:95]
	v_mfma_f32_16x16x32_bf16 v[88:91], v[174:177], v[214:217], v[88:91]
	v_mfma_f32_16x16x32_bf16 v[76:79], v[166:169], v[222:225], v[76:79]
	v_mfma_f32_16x16x32_bf16 v[72:75], v[174:177], v[222:225], v[72:75]
	v_mfma_f32_16x16x32_bf16 v[116:119], v[178:181], v[194:197], v[116:119]
	v_mfma_f32_16x16x32_bf16 v[112:115], v[186:189], v[194:197], v[112:115]
	v_mfma_f32_16x16x32_bf16 v[100:103], v[178:181], v[202:205], v[100:103]
	v_mfma_f32_16x16x32_bf16 v[96:99], v[186:189], v[202:205], v[96:99]
	v_mfma_f32_16x16x32_bf16 v[84:87], v[178:181], v[210:213], v[84:87]
	v_mfma_f32_16x16x32_bf16 v[80:83], v[186:189], v[210:213], v[80:83]
	v_mfma_f32_16x16x32_bf16 v[68:71], v[178:181], v[218:221], v[68:71]
	v_mfma_f32_16x16x32_bf16 v[64:67], v[186:189], v[218:221], v[64:67]
	v_mfma_f32_16x16x32_bf16 v[116:119], v[182:185], v[198:201], v[116:119]
	v_mfma_f32_16x16x32_bf16 v[112:115], v[190:193], v[198:201], v[112:115]
	v_mfma_f32_16x16x32_bf16 v[100:103], v[182:185], v[206:209], v[100:103]
	v_mfma_f32_16x16x32_bf16 v[96:99], v[190:193], v[206:209], v[96:99]
	v_mfma_f32_16x16x32_bf16 v[84:87], v[182:185], v[214:217], v[84:87]
	v_mfma_f32_16x16x32_bf16 v[80:83], v[190:193], v[214:217], v[80:83]
	v_mfma_f32_16x16x32_bf16 v[68:71], v[182:185], v[222:225], v[68:71]
	v_mfma_f32_16x16x32_bf16 v[64:67], v[190:193], v[222:225], v[64:67]
	s_barrier
	s_add_i32 s29, s29, s33
	v_lshl_add_u64 v[226:227], v[226:227], 0, s[10:11]
	s_mov_b32 m0, s29
	ds_read_b128 v[194:197], v160 offset:49152
	ds_read_b128 v[198:201], v160 offset:50176
	ds_read_b128 v[202:205], v160 offset:51200
	ds_read_b128 v[206:209], v160 offset:52224
	ds_read_b128 v[210:213], v160 offset:53248
	ds_read_b128 v[214:217], v160 offset:54272
	ds_read_b128 v[218:221], v160 offset:55296
	ds_read_b128 v[222:225], v160 offset:56320
	global_load_lds_dwordx4 v[226:227], off
	s_add_i32 m0, s29, 0x2000
	s_add_u32 s22, s22, 0x10080
	v_lshl_add_u64 v[226:227], v[228:229], 0, s[10:11]
	s_addc_u32 s23, s23, 0
	s_add_i32 s29, s38, s33
	global_load_lds_dwordx4 v[226:227], off
	s_mov_b32 m0, s29
	v_lshl_add_u64 v[226:227], s[22:23], 0, v[130:131]
	global_load_lds_dwordx4 v[226:227], off
	s_add_i32 m0, s29, 0x2000
	v_lshl_add_u64 v[226:227], s[22:23], 0, v[134:135]
	global_load_lds_dwordx4 v[226:227], off
	s_mov_b32 m0, s48
	v_lshl_add_u64 v[226:227], v[230:231], 0, s[10:11]
	global_load_lds_dwordx4 v[226:227], off
	s_mov_b32 m0, s49
	v_lshl_add_u64 v[226:227], v[232:233], 0, s[10:11]
	global_load_lds_dwordx4 v[226:227], off
	s_waitcnt vmcnt(8)
	s_waitcnt lgkmcnt(0)
	s_barrier
	s_waitcnt lgkmcnt(0)
	v_mfma_f32_16x16x32_bf16 v[60:63], v[162:165], v[194:197], v[60:63]
	v_mfma_f32_16x16x32_bf16 v[56:59], v[170:173], v[194:197], v[56:59]
	v_mfma_f32_16x16x32_bf16 v[44:47], v[162:165], v[202:205], v[44:47]
	v_mfma_f32_16x16x32_bf16 v[40:43], v[170:173], v[202:205], v[40:43]
	v_mfma_f32_16x16x32_bf16 v[28:31], v[162:165], v[210:213], v[28:31]
	v_mfma_f32_16x16x32_bf16 v[24:27], v[170:173], v[210:213], v[24:27]
	v_mfma_f32_16x16x32_bf16 v[12:15], v[162:165], v[218:221], v[12:15]
	v_mfma_f32_16x16x32_bf16 v[8:11], v[170:173], v[218:221], v[8:11]
	v_mfma_f32_16x16x32_bf16 v[60:63], v[166:169], v[198:201], v[60:63]
	v_mfma_f32_16x16x32_bf16 v[56:59], v[174:177], v[198:201], v[56:59]
	v_mfma_f32_16x16x32_bf16 v[44:47], v[166:169], v[206:209], v[44:47]
	v_mfma_f32_16x16x32_bf16 v[40:43], v[174:177], v[206:209], v[40:43]
	v_mfma_f32_16x16x32_bf16 v[28:31], v[166:169], v[214:217], v[28:31]
	v_mfma_f32_16x16x32_bf16 v[24:27], v[174:177], v[214:217], v[24:27]
	v_mfma_f32_16x16x32_bf16 v[12:15], v[166:169], v[222:225], v[12:15]
	v_mfma_f32_16x16x32_bf16 v[8:11], v[174:177], v[222:225], v[8:11]
	v_mfma_f32_16x16x32_bf16 v[52:55], v[178:181], v[194:197], v[52:55]
	v_mfma_f32_16x16x32_bf16 v[48:51], v[186:189], v[194:197], v[48:51]
	v_mfma_f32_16x16x32_bf16 v[36:39], v[178:181], v[202:205], v[36:39]
	v_mfma_f32_16x16x32_bf16 v[32:35], v[186:189], v[202:205], v[32:35]
	v_mfma_f32_16x16x32_bf16 v[20:23], v[178:181], v[210:213], v[20:23]
	v_mfma_f32_16x16x32_bf16 v[16:19], v[186:189], v[210:213], v[16:19]
	v_mfma_f32_16x16x32_bf16 v[4:7], v[178:181], v[218:221], v[4:7]
	v_mfma_f32_16x16x32_bf16 v[0:3], v[186:189], v[218:221], v[0:3]
	v_mfma_f32_16x16x32_bf16 v[52:55], v[182:185], v[198:201], v[52:55]
	v_mfma_f32_16x16x32_bf16 v[48:51], v[190:193], v[198:201], v[48:51]
	v_mfma_f32_16x16x32_bf16 v[36:39], v[182:185], v[206:209], v[36:39]
	v_mfma_f32_16x16x32_bf16 v[32:35], v[190:193], v[206:209], v[32:35]
	v_mfma_f32_16x16x32_bf16 v[20:23], v[182:185], v[214:217], v[20:23]
	v_mfma_f32_16x16x32_bf16 v[16:19], v[190:193], v[214:217], v[16:19]
	v_mfma_f32_16x16x32_bf16 v[4:7], v[182:185], v[222:225], v[4:7]
	v_mfma_f32_16x16x32_bf16 v[0:3], v[190:193], v[222:225], v[0:3]
	s_barrier
	s_add_i32 s28, s28, 2
	s_add_u32 s20, s20, 0x100
	s_addc_u32 s21, s21, 0
	s_add_u32 s26, s26, 0x100
	s_addc_u32 s27, s27, 0
	s_cmp_gt_u32 s28, 13
	s_cbranch_scc0 .LBB0_215
	s_and_b64 vcc, exec, s[12:13]
	s_cbranch_vccz .LBB0_218
	s_barrier

; #define PG8_STAGE(bufoff, gbase, voff) do { _Pragma("unroll") for (int _i = 0; _i < 2; ++_i) \
;         __builtin_amdgcn_global_load_lds((const unsigned*)((const char*)(gbase) + (voff)[_i]), (PG8_LAS unsigned*)(lds + (bufoff) + ldsw + _i * 8192), 16, 0, PG8_LOAD_AUX); } while (0)
; #define PG8_LDA(dst, b, h) do { _Pragma("unroll") for (int m = 0; m < 4; ++m) _Pragma("unroll") for (int k = 0; k < 2; ++k) dst[m][k] = *(const PG8_LAS bf16x8*)(lds + PG8_SA(b, h) + aoff + m * 2048 + k * 1024); } while (0)
; #define PG8_LDB(dst, b, h) do { _Pragma("unroll") for (int n = 0; n < 2; ++n) _Pragma("unroll") for (int k = 0; k < 2; ++k) dst[n][k] = *(const PG8_LAS bf16x8*)(lds + PG8_SB(b, h) + boff + n * 2048 + k * 1024); } while (0)
; #define PG8_WAIT_V(n) asm volatile("s_waitcnt vmcnt(" #n ")" ::: "memory")
; #define PG8_WAIT_L(n) asm volatile("s_waitcnt lgkmcnt(" #n ")" ::: "memory")
; #define PG8_BAR __builtin_amdgcn_s_barrier()
; #define PG8_SCHED __builtin_amdgcn_sched_barrier(0)
; template <class Epi, class Sched, bool ALIGN_EPI = false, bool SP2 = false>
; __device__ __forceinline__ void gemm_phase(PG8_LAS unsigned char* lds, const Gemm g, const Sched& S, const Epi& E) {
;     ...
;         const bool has_next = S.next(ui + 1, nxt);
;         const char* nA = has_next ? (const char*)g.A + (size_t)nxt.pm * tstepA + (size_t)nxt.pn * apn : cA; const char* nB = has_next ? (const char*)g.Bt + (size_t)nxt.pn * tstepB : cB;
;         for (int t = 0; t < nt; t += 2) {
;             const bool last = (t == nt - 2);
;             const char* a1 = cA + (size_t)(t + 1) * kstep;
;             const char* a2 = last ? nA : cA + (size_t)(t + 2) * kstep; const char* b2 = last ? nB : cB + (size_t)(t + 2) * kstep;
;             const char* a3 = a2 + kstep; const char* b3 = b2 + kstep;
;             if (last && has_next) S.a_ready(nxt);
;             if constexpr (SP2) {
;             PG8_LDB(B0, 0, 0); PG8_LDB(B1, 0, 1); PG8_SCHED; PG8_LDA(At, 0, 0); PG8_STAGE(PG8_SA(1, 1), a1 + hstepA, voffA);
;             PG8_WAIT_V(8); PG8_WAIT_L(0); PG8_BAR; PG8_MMA(0, 0, At, B0); PG8_MMA(0, 1, At, B1); PG8_BAR; PG8_SCHED;
;             PG8_LDA(At, 0, 1); PG8_STAGE(PG8_SB(0, 0), b2, voffB); PG8_STAGE(PG8_SB(0, 1), b2 + hstepB, voffB); PG8_STAGE(PG8_SA(0, 0), a2, voffA);
;             PG8_WAIT_V(8); PG8_WAIT_L(0); PG8_BAR; PG8_MMA(1, 0, At, B0); PG8_MMA(1, 1, At, B1); PG8_BAR; PG8_SCHED;
.LBB0_366:
	s_add_u32 s20, s20, 0x40080
	s_addc_u32 s21, s21, 0
	s_add_u32 s26, s22, 0x100
	s_addc_u32 s27, s23, 0
	s_mov_b32 s28, -2
	ds_read_b128 v[162:165], v159
	ds_read_b128 v[166:169], v159 offset:1024
	ds_read_b128 v[170:173], v159 offset:2048
	ds_read_b128 v[174:177], v159 offset:3072
	ds_read_b128 v[178:181], v160
	ds_read_b128 v[182:185], v160 offset:1024
	ds_read_b128 v[186:189], v160 offset:2048
	ds_read_b128 v[190:193], v160 offset:3072
	s_add_u32 s22, s20, 0xfffc0080
	s_addc_u32 s23, s21, -1
	s_cmp_eq_u32 s28, 12
	s_cselect_b32 s35, s17, s23
	s_cselect_b32 s34, s24, s22
	s_cselect_b32 s23, s15, s27
	s_cselect_b32 s22, s25, s26
	v_lshl_add_u64 v[226:227], s[20:21], 0, v[138:139]
	s_add_i32 m0, s44, 0xc000
	ds_read_b128 v[194:197], v161
	ds_read_b128 v[198:201], v161 offset:1024
	ds_read_b128 v[202:205], v161 offset:2048
	ds_read_b128 v[206:209], v161 offset:3072
	ds_read_b128 v[210:213], v161 offset:4096
	ds_read_b128 v[214:217], v161 offset:5120
	ds_read_b128 v[218:221], v161 offset:6144
	ds_read_b128 v[222:225], v161 offset:7168
	global_load_lds_dwordx4 v[226:227], off
	s_add_i32 m0, s44, 0xe000
	v_lshl_add_u64 v[226:227], s[20:21], 0, v[140:141]
	global_load_lds_dwordx4 v[226:227], off
	s_waitcnt vmcnt(8)
	s_waitcnt lgkmcnt(0)
	s_barrier
	s_waitcnt lgkmcnt(0)
	v_mfma_f32_16x16x32_bf16 v[124:127], v[162:165], v[194:197], 0
	s_add_i32 s48, s48, 1
	s_mul_i32 s4, s48, s51
	v_mfma_f32_16x16x32_bf16 v[120:123], v[170:173], v[194:197], 0
	s_mul_hi_u32 s5, s48, s52
	s_add_i32 s5, s5, s4
	v_mfma_f32_16x16x32_bf16 v[108:111], v[162:165], v[202:205], 0
	s_mul_i32 s4, s48, s52
	v_readlane_b32 s15, v239, 0
	v_mfma_f32_16x16x32_bf16 v[104:107], v[170:173], v[202:205], 0
	s_add_u32 s18, s4, s15
	s_addc_u32 s19, s5, s42
	v_mfma_f32_16x16x32_bf16 v[92:95], v[162:165], v[210:213], 0
	s_cmp_lt_u32 s18, 0x900
	s_cselect_b64 s[4:5], -1, 0
	v_mfma_f32_16x16x32_bf16 v[88:91], v[170:173], v[210:213], 0
	s_ashr_i32 s14, s18, 31
	s_lshr_b32 s14, s14, 29
	v_mfma_f32_16x16x32_bf16 v[76:79], v[162:165], v[218:221], 0
	s_add_i32 s14, s18, s14
	s_ashr_i32 s15, s14, 3
	v_mfma_f32_16x16x32_bf16 v[72:75], v[170:173], v[218:221], 0
	s_and_b32 s14, s14, -8
	s_sub_i32 s14, s18, s14
	v_mfma_f32_16x16x32_bf16 v[124:127], v[166:169], v[198:201], v[124:127]
	s_cmp_lt_i32 s14, 0
	s_cselect_b32 s16, s43, 0x120
	v_mfma_f32_16x16x32_bf16 v[120:123], v[174:177], v[198:201], v[120:123]
	s_mul_i32 s14, s14, s16
	s_add_i32 s14, s14, s15
	v_mfma_f32_16x16x32_bf16 v[108:111], v[166:169], v[206:209], v[108:111]
	s_mul_hi_i32 s15, s14, 0x38e38e39
	s_lshr_b32 s16, s15, 31
	v_mfma_f32_16x16x32_bf16 v[104:107], v[174:177], v[206:209], v[104:107]
	s_ashr_i32 s15, s15, 5
	s_add_i32 s15, s15, s16
	v_mfma_f32_16x16x32_bf16 v[92:95], v[166:169], v[214:217], v[92:95]
	s_lshl_b32 s16, s15, 2
	s_sub_i32 s17, 64, s16
	v_mfma_f32_16x16x32_bf16 v[88:91], v[174:177], v[214:217], v[88:91]
	s_min_i32 s17, s17, 4
	s_mulk_i32 s15, 0x90
	v_mfma_f32_16x16x32_bf16 v[76:79], v[166:169], v[222:225], v[76:79]
	s_sub_i32 s15, s14, s15
	s_lshr_b32 s14, s15, 2
	v_mfma_f32_16x16x32_bf16 v[72:75], v[174:177], v[222:225], v[72:75]
	s_and_b32 s15, s15, 3
	s_add_i32 s16, s16, s15
	v_mfma_f32_16x16x32_bf16 v[116:119], v[178:181], v[194:197], 0
	s_ashr_i32 s17, s16, 31
	s_lshl_b64 s[18:19], s[16:17], 19
	v_mfma_f32_16x16x32_bf16 v[112:115], v[186:189], v[194:197], 0
	s_add_u32 s18, s33, s18
	s_addc_u32 s19, s36, s19
	v_mfma_f32_16x16x32_bf16 v[100:103], v[178:181], v[202:205], 0
	s_sub_u32 s98, s20, 0x40080
	s_subb_u32 s99, s21, 0
	v_mfma_f32_16x16x32_bf16 v[96:99], v[186:189], v[202:205], 0
	s_cmp_lg_u64 s[4:5], 0
	s_cselect_b32 s17, s19, s99
	v_mfma_f32_16x16x32_bf16 v[84:87], v[178:181], v[210:213], 0
	s_cselect_b32 s24, s18, s98
	s_ashr_i32 s15, s14, 31
	v_mfma_f32_16x16x32_bf16 v[80:83], v[186:189], v[210:213], 0
	s_lshl_b64 s[98:99], s[14:15], 19
	s_add_u32 s40, s64, s98
	v_mfma_f32_16x16x32_bf16 v[68:71], v[178:181], v[218:221], 0
	s_addc_u32 s41, s65, s99
	s_sub_u32 s98, s26, 0x100
	v_mfma_f32_16x16x32_bf16 v[64:67], v[186:189], v[218:221], 0
	s_subb_u32 s99, s27, 0
	s_cmp_lg_u64 s[4:5], 0
	v_mfma_f32_16x16x32_bf16 v[116:119], v[182:185], v[198:201], v[116:119]
	s_cselect_b32 s15, s41, s99
	s_cselect_b32 s25, s40, s98
	v_mfma_f32_16x16x32_bf16 v[112:115], v[190:193], v[198:201], v[112:115]
	v_mfma_f32_16x16x32_bf16 v[100:103], v[182:185], v[206:209], v[100:103]
	v_mfma_f32_16x16x32_bf16 v[96:99], v[190:193], v[206:209], v[96:99]
	v_mfma_f32_16x16x32_bf16 v[84:87], v[182:185], v[214:217], v[84:87]
	v_mfma_f32_16x16x32_bf16 v[80:83], v[190:193], v[214:217], v[80:83]
	v_mfma_f32_16x16x32_bf16 v[68:71], v[182:185], v[222:225], v[68:71]
	v_mfma_f32_16x16x32_bf16 v[64:67], v[190:193], v[222:225], v[64:67]
	s_barrier
	s_add_i32 s29, s53, s37
	v_lshl_add_u64 v[226:227], s[22:23], 0, v[132:133]
	s_mov_b32 m0, s29
	ds_read_b128 v[194:197], v161 offset:16384
	ds_read_b128 v[198:201], v161 offset:17408
	ds_read_b128 v[202:205], v161 offset:18432
	ds_read_b128 v[206:209], v161 offset:19456
	ds_read_b128 v[210:213], v161 offset:20480
	ds_read_b128 v[214:217], v161 offset:21504
	ds_read_b128 v[218:221], v161 offset:22528
	ds_read_b128 v[222:225], v161 offset:23552
	global_load_lds_dwordx4 v[226:227], off
	s_add_i32 m0, s29, 0x2000
	s_add_u32 s30, s22, 0x10000
	v_lshl_add_u64 v[228:229], s[22:23], 0, v[128:129]
	s_addc_u32 s31, s23, 0
	s_add_i32 s29, s54, s37
	global_load_lds_dwordx4 v[228:229], off
	v_lshl_add_u64 v[230:231], s[30:31], 0, v[132:133]
	s_mov_b32 m0, s29
	v_lshl_add_u64 v[232:233], s[34:35], 0, v[130:131]
	global_load_lds_dwordx4 v[230:231], off
	s_add_i32 m0, s29, 0x2000
	v_lshl_add_u64 v[230:231], s[30:31], 0, v[128:129]
	global_load_lds_dwordx4 v[230:231], off
	s_mov_b32 m0, s44
	v_lshl_add_u64 v[230:231], s[34:35], 0, v[134:135]
	global_load_lds_dwordx4 v[230:231], off
	s_mov_b32 m0, s45
	s_nop 0
	global_load_lds_dwordx4 v[232:233], off
	s_waitcnt vmcnt(8)
	s_waitcnt lgkmcnt(0)
	s_barrier
; #define PG8_STAGE(bufoff, gbase, voff) do { _Pragma("unroll") for (int _i = 0; _i < 2; ++_i) \
;         __builtin_amdgcn_global_load_lds((const unsigned*)((const char*)(gbase) + (voff)[_i]), (PG8_LAS unsigned*)(lds + (bufoff) + ldsw + _i * 8192), 16, 0, PG8_LOAD_AUX); } while (0)
; #define PG8_LDA(dst, b, h) do { _Pragma("unroll") for (int m = 0; m < 4; ++m) _Pragma("unroll") for (int k = 0; k < 2; ++k) dst[m][k] = *(const PG8_LAS bf16x8*)(lds + PG8_SA(b, h) + aoff + m * 2048 + k * 1024); } while (0)
; #define PG8_LDB(dst, b, h) do { _Pragma("unroll") for (int n = 0; n < 2; ++n) _Pragma("unroll") for (int k = 0; k < 2; ++k) dst[n][k] = *(const PG8_LAS bf16x8*)(lds + PG8_SB(b, h) + boff + n * 2048 + k * 1024); } while (0)
; #define PG8_MMA(ai, bj, At, Bt) do { __builtin_amdgcn_s_setprio(1); _Pragma("unroll") for (int m = 0; m < 4; ++m) _Pragma("unroll") for (int n = 0; n < 2; ++n) _Pragma("unroll") for (int k = 0; k < 2; ++k) \
;         acc[ai][bj][m][n] = __builtin_amdgcn_mfma_f32_16x16x32_bf16(Bt[n][k], At[m][k], acc[ai][bj][m][n], 0, 0, 0); __builtin_amdgcn_s_setprio(0); } while (0)
; #define PG8_WAIT_V(n) asm volatile("s_waitcnt vmcnt(" #n ")" ::: "memory")
; #define PG8_WAIT_L(n) asm volatile("s_waitcnt lgkmcnt(" #n ")" ::: "memory")
; #define PG8_BAR __builtin_amdgcn_s_barrier()
; #define PG8_SCHED __builtin_amdgcn_sched_barrier(0)
; template <class Epi, class Sched, bool ALIGN_EPI = false, bool SP2 = false>
; __device__ __forceinline__ void gemm_phase(PG8_LAS unsigned char* lds, const Gemm g, const Sched& S, const Epi& E) {
;     ...
;             PG8_LDB(B0, 0, 0); PG8_LDB(B1, 0, 1); PG8_SCHED; PG8_LDA(At, 0, 0); PG8_STAGE(PG8_SA(1, 1), a1 + hstepA, voffA);
;             PG8_WAIT_V(8); PG8_WAIT_L(0); PG8_BAR; PG8_MMA(0, 0, At, B0); PG8_MMA(0, 1, At, B1); PG8_BAR; PG8_SCHED;
;             PG8_LDA(At, 0, 1); PG8_STAGE(PG8_SB(0, 0), b2, voffB); PG8_STAGE(PG8_SB(0, 1), b2 + hstepB, voffB); PG8_STAGE(PG8_SA(0, 0), a2, voffA);
;             PG8_WAIT_V(8); PG8_WAIT_L(0); PG8_BAR; PG8_MMA(1, 0, At, B0); PG8_MMA(1, 1, At, B1); PG8_BAR; PG8_SCHED;
	s_waitcnt lgkmcnt(0)
	v_mfma_f32_16x16x32_bf16 v[60:63], v[162:165], v[194:197], 0
	v_mfma_f32_16x16x32_bf16 v[56:59], v[170:173], v[194:197], 0
	v_mfma_f32_16x16x32_bf16 v[44:47], v[162:165], v[202:205], 0
	v_mfma_f32_16x16x32_bf16 v[40:43], v[170:173], v[202:205], 0
	v_mfma_f32_16x16x32_bf16 v[28:31], v[162:165], v[210:213], 0
	v_mfma_f32_16x16x32_bf16 v[24:27], v[170:173], v[210:213], 0
	v_mfma_f32_16x16x32_bf16 v[12:15], v[162:165], v[218:221], 0
	v_mfma_f32_16x16x32_bf16 v[8:11], v[170:173], v[218:221], 0
	v_mfma_f32_16x16x32_bf16 v[60:63], v[166:169], v[198:201], v[60:63]
	v_mfma_f32_16x16x32_bf16 v[56:59], v[174:177], v[198:201], v[56:59]
	v_mfma_f32_16x16x32_bf16 v[44:47], v[166:169], v[206:209], v[44:47]
	v_mfma_f32_16x16x32_bf16 v[40:43], v[174:177], v[206:209], v[40:43]
	v_mfma_f32_16x16x32_bf16 v[28:31], v[166:169], v[214:217], v[28:31]
	v_mfma_f32_16x16x32_bf16 v[24:27], v[174:177], v[214:217], v[24:27]
	v_mfma_f32_16x16x32_bf16 v[12:15], v[166:169], v[222:225], v[12:15]
	v_mfma_f32_16x16x32_bf16 v[8:11], v[174:177], v[222:225], v[8:11]
	v_mfma_f32_16x16x32_bf16 v[52:55], v[178:181], v[194:197], 0
	v_mfma_f32_16x16x32_bf16 v[48:51], v[186:189], v[194:197], 0
	v_mfma_f32_16x16x32_bf16 v[36:39], v[178:181], v[202:205], 0
	v_mfma_f32_16x16x32_bf16 v[32:35], v[186:189], v[202:205], 0
	v_mfma_f32_16x16x32_bf16 v[20:23], v[178:181], v[210:213], 0
	v_mfma_f32_16x16x32_bf16 v[16:19], v[186:189], v[210:213], 0
	v_mfma_f32_16x16x32_bf16 v[4:7], v[178:181], v[218:221], 0
	v_mfma_f32_16x16x32_bf16 v[0:3], v[186:189], v[218:221], 0
	v_mfma_f32_16x16x32_bf16 v[52:55], v[182:185], v[198:201], v[52:55]
	v_mfma_f32_16x16x32_bf16 v[48:51], v[190:193], v[198:201], v[48:51]
	v_mfma_f32_16x16x32_bf16 v[36:39], v[182:185], v[206:209], v[36:39]
	v_mfma_f32_16x16x32_bf16 v[32:35], v[190:193], v[206:209], v[32:35]
	v_mfma_f32_16x16x32_bf16 v[20:23], v[182:185], v[214:217], v[20:23]
	v_mfma_f32_16x16x32_bf16 v[16:19], v[190:193], v[214:217], v[16:19]
	v_mfma_f32_16x16x32_bf16 v[4:7], v[182:185], v[222:225], v[4:7]
	v_mfma_f32_16x16x32_bf16 v[0:3], v[190:193], v[222:225], v[0:3]
	s_barrier
	s_branch .Lkmid_P3
.LBB0_369:
	ds_read_b128 v[162:165], v159
	ds_read_b128 v[166:169], v159 offset:1024
	ds_read_b128 v[170:173], v159 offset:2048
	ds_read_b128 v[174:177], v159 offset:3072
	ds_read_b128 v[178:181], v160
	ds_read_b128 v[182:185], v160 offset:1024
	ds_read_b128 v[186:189], v160 offset:2048
	ds_read_b128 v[190:193], v160 offset:3072
	s_add_u32 s22, s20, 0xfffc0080
	s_addc_u32 s23, s21, -1
	s_cmp_eq_u32 s28, 12
	s_cselect_b32 s35, s17, s23
	s_cselect_b32 s34, s24, s22
	s_cselect_b32 s23, s15, s27
	s_cselect_b32 s22, s25, s26
	v_lshl_add_u64 v[226:227], s[20:21], 0, v[138:139]
	s_add_i32 m0, s44, 0xc000
	ds_read_b128 v[194:197], v161
	ds_read_b128 v[198:201], v161 offset:1024
	ds_read_b128 v[202:205], v161 offset:2048
	ds_read_b128 v[206:209], v161 offset:3072
	ds_read_b128 v[210:213], v161 offset:4096
	ds_read_b128 v[214:217], v161 offset:5120
	ds_read_b128 v[218:221], v161 offset:6144
	ds_read_b128 v[222:225], v161 offset:7168
	global_load_lds_dwordx4 v[226:227], off
	s_add_i32 m0, s44, 0xe000
	v_lshl_add_u64 v[226:227], s[20:21], 0, v[140:141]
	global_load_lds_dwordx4 v[226:227], off
	s_waitcnt vmcnt(8)
	s_waitcnt lgkmcnt(0)
	s_barrier
	s_waitcnt lgkmcnt(0)
	v_mfma_f32_16x16x32_bf16 v[124:127], v[162:165], v[194:197], v[124:127]
	v_mfma_f32_16x16x32_bf16 v[120:123], v[170:173], v[194:197], v[120:123]
	v_mfma_f32_16x16x32_bf16 v[108:111], v[162:165], v[202:205], v[108:111]
	v_mfma_f32_16x16x32_bf16 v[104:107], v[170:173], v[202:205], v[104:107]
	v_mfma_f32_16x16x32_bf16 v[92:95], v[162:165], v[210:213], v[92:95]
	v_mfma_f32_16x16x32_bf16 v[88:91], v[170:173], v[210:213], v[88:91]
	v_mfma_f32_16x16x32_bf16 v[76:79], v[162:165], v[218:221], v[76:79]
	v_mfma_f32_16x16x32_bf16 v[72:75], v[170:173], v[218:221], v[72:75]
	v_mfma_f32_16x16x32_bf16 v[124:127], v[166:169], v[198:201], v[124:127]
	v_mfma_f32_16x16x32_bf16 v[120:123], v[174:177], v[198:201], v[120:123]
	v_mfma_f32_16x16x32_bf16 v[108:111], v[166:169], v[206:209], v[108:111]
	v_mfma_f32_16x16x32_bf16 v[104:107], v[174:177], v[206:209], v[104:107]
	v_mfma_f32_16x16x32_bf16 v[92:95], v[166:169], v[214:217], v[92:95]
	v_mfma_f32_16x16x32_bf16 v[88:91], v[174:177], v[214:217], v[88:91]
	v_mfma_f32_16x16x32_bf16 v[76:79], v[166:169], v[222:225], v[76:79]
	v_mfma_f32_16x16x32_bf16 v[72:75], v[174:177], v[222:225], v[72:75]
	v_mfma_f32_16x16x32_bf16 v[116:119], v[178:181], v[194:197], v[116:119]
	v_mfma_f32_16x16x32_bf16 v[112:115], v[186:189], v[194:197], v[112:115]
	v_mfma_f32_16x16x32_bf16 v[100:103], v[178:181], v[202:205], v[100:103]
	v_mfma_f32_16x16x32_bf16 v[96:99], v[186:189], v[202:205], v[96:99]
	v_mfma_f32_16x16x32_bf16 v[84:87], v[178:181], v[210:213], v[84:87]
	v_mfma_f32_16x16x32_bf16 v[80:83], v[186:189], v[210:213], v[80:83]
	v_mfma_f32_16x16x32_bf16 v[68:71], v[178:181], v[218:221], v[68:71]
	v_mfma_f32_16x16x32_bf16 v[64:67], v[186:189], v[218:221], v[64:67]
	v_mfma_f32_16x16x32_bf16 v[116:119], v[182:185], v[198:201], v[116:119]
	v_mfma_f32_16x16x32_bf16 v[112:115], v[190:193], v[198:201], v[112:115]
	v_mfma_f32_16x16x32_bf16 v[100:103], v[182:185], v[206:209], v[100:103]
	v_mfma_f32_16x16x32_bf16 v[96:99], v[190:193], v[206:209], v[96:99]
	v_mfma_f32_16x16x32_bf16 v[84:87], v[182:185], v[214:217], v[84:87]
	v_mfma_f32_16x16x32_bf16 v[80:83], v[190:193], v[214:217], v[80:83]
	v_mfma_f32_16x16x32_bf16 v[68:71], v[182:185], v[222:225], v[68:71]
	v_mfma_f32_16x16x32_bf16 v[64:67], v[190:193], v[222:225], v[64:67]
	s_barrier
; #define PG8_STAGE(bufoff, gbase, voff) do { _Pragma("unroll") for (int _i = 0; _i < 2; ++_i) \
;         __builtin_amdgcn_global_load_lds((const unsigned*)((const char*)(gbase) + (voff)[_i]), (PG8_LAS unsigned*)(lds + (bufoff) + ldsw + _i * 8192), 16, 0, PG8_LOAD_AUX); } while (0)
; #define PG8_LDA(dst, b, h) do { _Pragma("unroll") for (int m = 0; m < 4; ++m) _Pragma("unroll") for (int k = 0; k < 2; ++k) dst[m][k] = *(const PG8_LAS bf16x8*)(lds + PG8_SA(b, h) + aoff + m * 2048 + k * 1024); } while (0)
; #define PG8_LDB(dst, b, h) do { _Pragma("unroll") for (int n = 0; n < 2; ++n) _Pragma("unroll") for (int k = 0; k < 2; ++k) dst[n][k] = *(const PG8_LAS bf16x8*)(lds + PG8_SB(b, h) + boff + n * 2048 + k * 1024); } while (0)
; #define PG8_MMA(ai, bj, At, Bt) do { __builtin_amdgcn_s_setprio(1); _Pragma("unroll") for (int m = 0; m < 4; ++m) _Pragma("unroll") for (int n = 0; n < 2; ++n) _Pragma("unroll") for (int k = 0; k < 2; ++k) \
;         acc[ai][bj][m][n] = __builtin_amdgcn_mfma_f32_16x16x32_bf16(Bt[n][k], At[m][k], acc[ai][bj][m][n], 0, 0, 0); __builtin_amdgcn_s_setprio(0); } while (0)
; #define PG8_WAIT_V(n) asm volatile("s_waitcnt vmcnt(" #n ")" ::: "memory")
; #define PG8_WAIT_L(n) asm volatile("s_waitcnt lgkmcnt(" #n ")" ::: "memory")
; #define PG8_BAR __builtin_amdgcn_s_barrier()
; #define PG8_SCHED __builtin_amdgcn_sched_barrier(0)
; template <class Epi, class Sched, bool ALIGN_EPI = false, bool SP2 = false>
; __device__ __forceinline__ void gemm_phase(PG8_LAS unsigned char* lds, const Gemm g, const Sched& S, const Epi& E) {
;     ...
;             PG8_LDA(At, 0, 1); PG8_STAGE(PG8_SB(0, 0), b2, voffB); PG8_STAGE(PG8_SB(0, 1), b2 + hstepB, voffB); PG8_STAGE(PG8_SA(0, 0), a2, voffA);
;             PG8_WAIT_V(8); PG8_WAIT_L(0); PG8_BAR; PG8_MMA(1, 0, At, B0); PG8_MMA(1, 1, At, B1); PG8_BAR; PG8_SCHED;
;             PG8_LDB(B0, 1, 0); PG8_LDB(B1, 1, 1); PG8_SCHED; PG8_LDA(At, 1, 0); PG8_STAGE(PG8_SA(0, 1), a2 + hstepA, voffA);
;             PG8_WAIT_V(8); PG8_WAIT_L(0); PG8_BAR; PG8_MMA(0, 0, At, B0); PG8_MMA(0, 1, At, B1); PG8_BAR; PG8_SCHED;
	s_add_i32 s29, s53, s37
	v_lshl_add_u64 v[226:227], s[22:23], 0, v[132:133]
	s_mov_b32 m0, s29
	ds_read_b128 v[194:197], v161 offset:16384
	ds_read_b128 v[198:201], v161 offset:17408
	ds_read_b128 v[202:205], v161 offset:18432
	ds_read_b128 v[206:209], v161 offset:19456
	ds_read_b128 v[210:213], v161 offset:20480
	ds_read_b128 v[214:217], v161 offset:21504
	ds_read_b128 v[218:221], v161 offset:22528
	ds_read_b128 v[222:225], v161 offset:23552
	global_load_lds_dwordx4 v[226:227], off
	s_add_i32 m0, s29, 0x2000
	s_add_u32 s30, s22, 0x10000
	v_lshl_add_u64 v[228:229], s[22:23], 0, v[128:129]
	s_addc_u32 s31, s23, 0
	s_add_i32 s29, s54, s37
	global_load_lds_dwordx4 v[228:229], off
	v_lshl_add_u64 v[230:231], s[30:31], 0, v[132:133]
	s_mov_b32 m0, s29
	v_lshl_add_u64 v[232:233], s[34:35], 0, v[130:131]
	global_load_lds_dwordx4 v[230:231], off
	s_add_i32 m0, s29, 0x2000
	v_lshl_add_u64 v[230:231], s[30:31], 0, v[128:129]
	global_load_lds_dwordx4 v[230:231], off
	s_mov_b32 m0, s44
	v_lshl_add_u64 v[230:231], s[34:35], 0, v[134:135]
	global_load_lds_dwordx4 v[230:231], off
	s_mov_b32 m0, s45
	s_nop 0
	global_load_lds_dwordx4 v[232:233], off
	s_waitcnt vmcnt(8)
	s_waitcnt lgkmcnt(0)
	s_barrier
	s_waitcnt lgkmcnt(0)
	v_mfma_f32_16x16x32_bf16 v[60:63], v[162:165], v[194:197], v[60:63]
	v_mfma_f32_16x16x32_bf16 v[56:59], v[170:173], v[194:197], v[56:59]
	v_mfma_f32_16x16x32_bf16 v[44:47], v[162:165], v[202:205], v[44:47]
	v_mfma_f32_16x16x32_bf16 v[40:43], v[170:173], v[202:205], v[40:43]
	v_mfma_f32_16x16x32_bf16 v[28:31], v[162:165], v[210:213], v[28:31]
	v_mfma_f32_16x16x32_bf16 v[24:27], v[170:173], v[210:213], v[24:27]
	v_mfma_f32_16x16x32_bf16 v[12:15], v[162:165], v[218:221], v[12:15]
	v_mfma_f32_16x16x32_bf16 v[8:11], v[170:173], v[218:221], v[8:11]
	v_mfma_f32_16x16x32_bf16 v[60:63], v[166:169], v[198:201], v[60:63]
	v_mfma_f32_16x16x32_bf16 v[56:59], v[174:177], v[198:201], v[56:59]
	v_mfma_f32_16x16x32_bf16 v[44:47], v[166:169], v[206:209], v[44:47]
	v_mfma_f32_16x16x32_bf16 v[40:43], v[174:177], v[206:209], v[40:43]
	v_mfma_f32_16x16x32_bf16 v[28:31], v[166:169], v[214:217], v[28:31]
	v_mfma_f32_16x16x32_bf16 v[24:27], v[174:177], v[214:217], v[24:27]
	v_mfma_f32_16x16x32_bf16 v[12:15], v[166:169], v[222:225], v[12:15]
	v_mfma_f32_16x16x32_bf16 v[8:11], v[174:177], v[222:225], v[8:11]
	v_mfma_f32_16x16x32_bf16 v[52:55], v[178:181], v[194:197], v[52:55]
	v_mfma_f32_16x16x32_bf16 v[48:51], v[186:189], v[194:197], v[48:51]
	v_mfma_f32_16x16x32_bf16 v[36:39], v[178:181], v[202:205], v[36:39]
	v_mfma_f32_16x16x32_bf16 v[32:35], v[186:189], v[202:205], v[32:35]
	v_mfma_f32_16x16x32_bf16 v[20:23], v[178:181], v[210:213], v[20:23]
	v_mfma_f32_16x16x32_bf16 v[16:19], v[186:189], v[210:213], v[16:19]
	v_mfma_f32_16x16x32_bf16 v[4:7], v[178:181], v[218:221], v[4:7]
	v_mfma_f32_16x16x32_bf16 v[0:3], v[186:189], v[218:221], v[0:3]
	v_mfma_f32_16x16x32_bf16 v[52:55], v[182:185], v[198:201], v[52:55]
	v_mfma_f32_16x16x32_bf16 v[48:51], v[190:193], v[198:201], v[48:51]
	v_mfma_f32_16x16x32_bf16 v[36:39], v[182:185], v[206:209], v[36:39]
	v_mfma_f32_16x16x32_bf16 v[32:35], v[190:193], v[206:209], v[32:35]
	v_mfma_f32_16x16x32_bf16 v[20:23], v[182:185], v[214:217], v[20:23]
	v_mfma_f32_16x16x32_bf16 v[16:19], v[190:193], v[214:217], v[16:19]
	v_mfma_f32_16x16x32_bf16 v[4:7], v[182:185], v[222:225], v[4:7]
	v_mfma_f32_16x16x32_bf16 v[0:3], v[190:193], v[222:225], v[0:3]
	s_barrier
.Lkmid_P3:
	s_add_i32 s29, 0, 0x18000
	s_add_i32 s38, 0, 0x1c000
	v_add_u32_e32 v174, s29, v146
	v_add_u32_e32 v190, s38, v146
	ds_read_b128 v[162:165], v174
	ds_read_b128 v[166:169], v174 offset:1024
	ds_read_b128 v[170:173], v174 offset:2048
	ds_read_b128 v[174:177], v174 offset:3072
	ds_read_b128 v[178:181], v190
	ds_read_b128 v[182:185], v190 offset:1024
	ds_read_b128 v[186:189], v190 offset:2048
	ds_read_b128 v[190:193], v190 offset:3072
	s_add_u32 s30, s34, 0x40000
	s_addc_u32 s31, s35, 0
	s_mov_b32 m0, s46
	v_lshl_add_u64 v[234:235], s[30:31], 0, v[134:135]
	ds_read_b128 v[194:197], v161 offset:32768
	ds_read_b128 v[198:201], v161 offset:33792
	ds_read_b128 v[202:205], v161 offset:34816
	ds_read_b128 v[206:209], v161 offset:35840
	ds_read_b128 v[210:213], v161 offset:36864
	ds_read_b128 v[214:217], v161 offset:37888
	ds_read_b128 v[218:221], v161 offset:38912
	ds_read_b128 v[222:225], v161 offset:39936
	global_load_lds_dwordx4 v[234:235], off
	s_mov_b32 m0, s47
	v_lshl_add_u64 v[234:235], s[30:31], 0, v[130:131]
	global_load_lds_dwordx4 v[234:235], off
	s_waitcnt vmcnt(8)
	s_waitcnt lgkmcnt(0)
	s_barrier
; #define PG8_STAGE(bufoff, gbase, voff) do { _Pragma("unroll") for (int _i = 0; _i < 2; ++_i) \
;         __builtin_amdgcn_global_load_lds((const unsigned*)((const char*)(gbase) + (voff)[_i]), (PG8_LAS unsigned*)(lds + (bufoff) + ldsw + _i * 8192), 16, 0, PG8_LOAD_AUX); } while (0)
; #define PG8_LDA(dst, b, h) do { _Pragma("unroll") for (int m = 0; m < 4; ++m) _Pragma("unroll") for (int k = 0; k < 2; ++k) dst[m][k] = *(const PG8_LAS bf16x8*)(lds + PG8_SA(b, h) + aoff + m * 2048 + k * 1024); } while (0)
; #define PG8_LDB(dst, b, h) do { _Pragma("unroll") for (int n = 0; n < 2; ++n) _Pragma("unroll") for (int k = 0; k < 2; ++k) dst[n][k] = *(const PG8_LAS bf16x8*)(lds + PG8_SB(b, h) + boff + n * 2048 + k * 1024); } while (0)
; #define PG8_MMA(ai, bj, At, Bt) do { __builtin_amdgcn_s_setprio(1); _Pragma("unroll") for (int m = 0; m < 4; ++m) _Pragma("unroll") for (int n = 0; n < 2; ++n) _Pragma("unroll") for (int k = 0; k < 2; ++k) \
;         acc[ai][bj][m][n] = __builtin_amdgcn_mfma_f32_16x16x32_bf16(Bt[n][k], At[m][k], acc[ai][bj][m][n], 0, 0, 0); __builtin_amdgcn_s_setprio(0); } while (0)
; #define PG8_WAIT_V(n) asm volatile("s_waitcnt vmcnt(" #n ")" ::: "memory")
; #define PG8_WAIT_L(n) asm volatile("s_waitcnt lgkmcnt(" #n ")" ::: "memory")
; #define PG8_BAR __builtin_amdgcn_s_barrier()
; #define PG8_SCHED __builtin_amdgcn_sched_barrier(0)
; template <class Epi, class Sched, bool ALIGN_EPI = false, bool SP2 = false>
; __device__ __forceinline__ void gemm_phase(PG8_LAS unsigned char* lds, const Gemm g, const Sched& S, const Epi& E) {
;     ...
;             PG8_LDB(B0, 1, 0); PG8_LDB(B1, 1, 1); PG8_SCHED; PG8_LDA(At, 1, 0); PG8_STAGE(PG8_SA(0, 1), a2 + hstepA, voffA);
;             PG8_WAIT_V(8); PG8_WAIT_L(0); PG8_BAR; PG8_MMA(0, 0, At, B0); PG8_MMA(0, 1, At, B1); PG8_BAR; PG8_SCHED;
;             PG8_LDA(At, 1, 1); PG8_STAGE(PG8_SB(1, 0), b3, voffB); PG8_STAGE(PG8_SB(1, 1), b3 + hstepB, voffB); PG8_STAGE(PG8_SA(1, 0), a3, voffA);
;             PG8_WAIT_V(8); PG8_WAIT_L(0); PG8_BAR; PG8_MMA(1, 0, At, B0); PG8_MMA(1, 1, At, B1); PG8_BAR; PG8_SCHED;
;     ...
;         if constexpr (ALIGN_EPI) { if (wr == 0) PG8_BAR; }
	s_waitcnt lgkmcnt(0)
	v_mfma_f32_16x16x32_bf16 v[124:127], v[162:165], v[194:197], v[124:127]
	v_mfma_f32_16x16x32_bf16 v[120:123], v[170:173], v[194:197], v[120:123]
	v_mfma_f32_16x16x32_bf16 v[108:111], v[162:165], v[202:205], v[108:111]
	v_mfma_f32_16x16x32_bf16 v[104:107], v[170:173], v[202:205], v[104:107]
	v_mfma_f32_16x16x32_bf16 v[92:95], v[162:165], v[210:213], v[92:95]
	v_mfma_f32_16x16x32_bf16 v[88:91], v[170:173], v[210:213], v[88:91]
	v_mfma_f32_16x16x32_bf16 v[76:79], v[162:165], v[218:221], v[76:79]
	v_mfma_f32_16x16x32_bf16 v[72:75], v[170:173], v[218:221], v[72:75]
	v_mfma_f32_16x16x32_bf16 v[124:127], v[166:169], v[198:201], v[124:127]
	v_mfma_f32_16x16x32_bf16 v[120:123], v[174:177], v[198:201], v[120:123]
	v_mfma_f32_16x16x32_bf16 v[108:111], v[166:169], v[206:209], v[108:111]
	v_mfma_f32_16x16x32_bf16 v[104:107], v[174:177], v[206:209], v[104:107]
	v_mfma_f32_16x16x32_bf16 v[92:95], v[166:169], v[214:217], v[92:95]
	v_mfma_f32_16x16x32_bf16 v[88:91], v[174:177], v[214:217], v[88:91]
	v_mfma_f32_16x16x32_bf16 v[76:79], v[166:169], v[222:225], v[76:79]
	v_mfma_f32_16x16x32_bf16 v[72:75], v[174:177], v[222:225], v[72:75]
	v_mfma_f32_16x16x32_bf16 v[116:119], v[178:181], v[194:197], v[116:119]
	v_mfma_f32_16x16x32_bf16 v[112:115], v[186:189], v[194:197], v[112:115]
	v_mfma_f32_16x16x32_bf16 v[100:103], v[178:181], v[202:205], v[100:103]
	v_mfma_f32_16x16x32_bf16 v[96:99], v[186:189], v[202:205], v[96:99]
	v_mfma_f32_16x16x32_bf16 v[84:87], v[178:181], v[210:213], v[84:87]
	v_mfma_f32_16x16x32_bf16 v[80:83], v[186:189], v[210:213], v[80:83]
	v_mfma_f32_16x16x32_bf16 v[68:71], v[178:181], v[218:221], v[68:71]
	v_mfma_f32_16x16x32_bf16 v[64:67], v[186:189], v[218:221], v[64:67]
	v_mfma_f32_16x16x32_bf16 v[116:119], v[182:185], v[198:201], v[116:119]
	v_mfma_f32_16x16x32_bf16 v[112:115], v[190:193], v[198:201], v[112:115]
	v_mfma_f32_16x16x32_bf16 v[100:103], v[182:185], v[206:209], v[100:103]
	v_mfma_f32_16x16x32_bf16 v[96:99], v[190:193], v[206:209], v[96:99]
	v_mfma_f32_16x16x32_bf16 v[84:87], v[182:185], v[214:217], v[84:87]
	v_mfma_f32_16x16x32_bf16 v[80:83], v[190:193], v[214:217], v[80:83]
	v_mfma_f32_16x16x32_bf16 v[68:71], v[182:185], v[222:225], v[68:71]
	v_mfma_f32_16x16x32_bf16 v[64:67], v[190:193], v[222:225], v[64:67]
	s_barrier
	s_add_i32 s29, s29, s37
	v_lshl_add_u64 v[226:227], v[226:227], 0, s[10:11]
	s_mov_b32 m0, s29
	ds_read_b128 v[194:197], v161 offset:49152
	ds_read_b128 v[198:201], v161 offset:50176
	ds_read_b128 v[202:205], v161 offset:51200
	ds_read_b128 v[206:209], v161 offset:52224
	ds_read_b128 v[210:213], v161 offset:53248
	ds_read_b128 v[214:217], v161 offset:54272
	ds_read_b128 v[218:221], v161 offset:55296
	ds_read_b128 v[222:225], v161 offset:56320
	global_load_lds_dwordx4 v[226:227], off
	s_add_i32 m0, s29, 0x2000
	s_add_u32 s22, s22, 0x10080
	v_lshl_add_u64 v[226:227], v[228:229], 0, s[10:11]
	s_addc_u32 s23, s23, 0
	s_add_i32 s29, s38, s37
	global_load_lds_dwordx4 v[226:227], off
	s_mov_b32 m0, s29
	v_lshl_add_u64 v[226:227], s[22:23], 0, v[132:133]
	global_load_lds_dwordx4 v[226:227], off
	s_add_i32 m0, s29, 0x2000
	v_lshl_add_u64 v[226:227], s[22:23], 0, v[128:129]
	global_load_lds_dwordx4 v[226:227], off
	s_mov_b32 m0, s49
	v_lshl_add_u64 v[226:227], v[230:231], 0, s[10:11]
	global_load_lds_dwordx4 v[226:227], off
	s_mov_b32 m0, s50
	v_lshl_add_u64 v[226:227], v[232:233], 0, s[10:11]
	global_load_lds_dwordx4 v[226:227], off
	s_waitcnt vmcnt(8)
	s_waitcnt lgkmcnt(0)
	s_barrier
	s_waitcnt lgkmcnt(0)
	v_mfma_f32_16x16x32_bf16 v[60:63], v[162:165], v[194:197], v[60:63]
	v_mfma_f32_16x16x32_bf16 v[56:59], v[170:173], v[194:197], v[56:59]
	v_mfma_f32_16x16x32_bf16 v[44:47], v[162:165], v[202:205], v[44:47]
	v_mfma_f32_16x16x32_bf16 v[40:43], v[170:173], v[202:205], v[40:43]
	v_mfma_f32_16x16x32_bf16 v[28:31], v[162:165], v[210:213], v[28:31]
	v_mfma_f32_16x16x32_bf16 v[24:27], v[170:173], v[210:213], v[24:27]
	v_mfma_f32_16x16x32_bf16 v[12:15], v[162:165], v[218:221], v[12:15]
	v_mfma_f32_16x16x32_bf16 v[8:11], v[170:173], v[218:221], v[8:11]
	v_mfma_f32_16x16x32_bf16 v[60:63], v[166:169], v[198:201], v[60:63]
	v_mfma_f32_16x16x32_bf16 v[56:59], v[174:177], v[198:201], v[56:59]
	v_mfma_f32_16x16x32_bf16 v[44:47], v[166:169], v[206:209], v[44:47]
	v_mfma_f32_16x16x32_bf16 v[40:43], v[174:177], v[206:209], v[40:43]
	v_mfma_f32_16x16x32_bf16 v[28:31], v[166:169], v[214:217], v[28:31]
	v_mfma_f32_16x16x32_bf16 v[24:27], v[174:177], v[214:217], v[24:27]
	v_mfma_f32_16x16x32_bf16 v[12:15], v[166:169], v[222:225], v[12:15]
	v_mfma_f32_16x16x32_bf16 v[8:11], v[174:177], v[222:225], v[8:11]
	v_mfma_f32_16x16x32_bf16 v[52:55], v[178:181], v[194:197], v[52:55]
	v_mfma_f32_16x16x32_bf16 v[48:51], v[186:189], v[194:197], v[48:51]
	v_mfma_f32_16x16x32_bf16 v[36:39], v[178:181], v[202:205], v[36:39]
	v_mfma_f32_16x16x32_bf16 v[32:35], v[186:189], v[202:205], v[32:35]
	v_mfma_f32_16x16x32_bf16 v[20:23], v[178:181], v[210:213], v[20:23]
	v_mfma_f32_16x16x32_bf16 v[16:19], v[186:189], v[210:213], v[16:19]
	v_mfma_f32_16x16x32_bf16 v[4:7], v[178:181], v[218:221], v[4:7]
	v_mfma_f32_16x16x32_bf16 v[0:3], v[186:189], v[218:221], v[0:3]
	v_mfma_f32_16x16x32_bf16 v[52:55], v[182:185], v[198:201], v[52:55]
	v_mfma_f32_16x16x32_bf16 v[48:51], v[190:193], v[198:201], v[48:51]
	v_mfma_f32_16x16x32_bf16 v[36:39], v[182:185], v[206:209], v[36:39]
	v_mfma_f32_16x16x32_bf16 v[32:35], v[190:193], v[206:209], v[32:35]
	v_mfma_f32_16x16x32_bf16 v[20:23], v[182:185], v[214:217], v[20:23]
	v_mfma_f32_16x16x32_bf16 v[16:19], v[190:193], v[214:217], v[16:19]
	v_mfma_f32_16x16x32_bf16 v[4:7], v[182:185], v[222:225], v[4:7]
	v_mfma_f32_16x16x32_bf16 v[0:3], v[190:193], v[222:225], v[0:3]
	s_barrier
	s_add_i32 s28, s28, 2
	s_add_u32 s20, s20, 0x100
	s_addc_u32 s21, s21, 0
	s_add_u32 s26, s26, 0x100
	s_addc_u32 s27, s27, 0
	s_cmp_gt_u32 s28, 13
	s_cbranch_scc0 .LBB0_369
	s_and_b64 vcc, exec, s[12:13]
	s_cbranch_vccz .LBB0_372
	s_barrier

; #define PG8_STAGE(bufoff, gbase, voff) do { _Pragma("unroll") for (int _i = 0; _i < 2; ++_i) \
;         __builtin_amdgcn_global_load_lds((const unsigned*)((const char*)(gbase) + (voff)[_i]), (PG8_LAS unsigned*)(lds + (bufoff) + ldsw + _i * 8192), 16, 0, PG8_LOAD_AUX); } while (0)
; #define PG8_LDA(dst, b, h) do { _Pragma("unroll") for (int m = 0; m < 4; ++m) _Pragma("unroll") for (int k = 0; k < 2; ++k) dst[m][k] = *(const PG8_LAS bf16x8*)(lds + PG8_SA(b, h) + aoff + m * 2048 + k * 1024); } while (0)
; #define PG8_WAIT_V(n) asm volatile("s_waitcnt vmcnt(" #n ")" ::: "memory")
; template <class Epi, class Sched, bool ALIGN_EPI = false, bool SP2 = false>
; __device__ __forceinline__ void gemm_phase(PG8_LAS unsigned char* lds, const Gemm g, const Sched& S, const Epi& E) {
;     ...
;         const bool has_next = S.next(ui + 1, nxt);
;         const char* nA = has_next ? (const char*)g.A + (size_t)nxt.pm * tstepA + (size_t)nxt.pn * apn : cA; const char* nB = has_next ? (const char*)g.Bt + (size_t)nxt.pn * tstepB : cB;
;         for (int t = 0; t < nt; t += 2) {
;             const bool last = (t == nt - 2);
;             const char* a1 = cA + (size_t)(t + 1) * kstep;
;             const char* a2 = last ? nA : cA + (size_t)(t + 2) * kstep; const char* b2 = last ? nB : cB + (size_t)(t + 2) * kstep;
;             const char* a3 = a2 + kstep; const char* b3 = b2 + kstep;
;             if (last && has_next) S.a_ready(nxt);
;             if constexpr (SP2) {
;             PG8_LDB(B0, 0, 0); PG8_LDB(B1, 0, 1); PG8_SCHED; PG8_LDA(At, 0, 0); PG8_STAGE(PG8_SA(1, 1), a1 + hstepA, voffA);
;             PG8_WAIT_V(8); PG8_WAIT_L(0); PG8_BAR; PG8_MMA(0, 0, At, B0); PG8_MMA(0, 1, At, B1); PG8_BAR; PG8_SCHED;
;             PG8_LDA(At, 0, 1); PG8_STAGE(PG8_SB(0, 0), b2, voffB); PG8_STAGE(PG8_SB(0, 1), b2 + hstepB, voffB); PG8_STAGE(PG8_SA(0, 0), a2, voffA);
;             PG8_WAIT_V(8); PG8_WAIT_L(0); PG8_BAR; PG8_MMA(1, 0, At, B0); PG8_MMA(1, 1, At, B1); PG8_BAR; PG8_SCHED;
;             PG8_LDB(B0, 1, 0); PG8_LDB(B1, 1, 1); PG8_SCHED; PG8_LDA(At, 1, 0); PG8_STAGE(PG8_SA(0, 1), a2 + hstepA, voffA);
;             PG8_WAIT_V(8); PG8_WAIT_L(0); PG8_BAR; PG8_MMA(0, 0, At, B0); PG8_MMA(0, 1, At, B1); PG8_BAR; PG8_SCHED;
;             PG8_LDA(At, 1, 1); PG8_STAGE(PG8_SB(1, 0), b3, voffB); PG8_STAGE(PG8_SB(1, 1), b3 + hstepB, voffB); PG8_STAGE(PG8_SA(1, 0), a3, voffA);
.LBB0_584:
	s_ashr_i32 s41, s40, 31
	s_lshl_b64 s[22:23], s[40:41], 19
	v_readlane_b32 s24, v239, 47
	v_readlane_b32 s25, v239, 48
	s_add_u32 s42, s24, s22
	s_addc_u32 s43, s25, s23
	s_and_b64 s[22:23], s[6:7], exec
	s_cselect_b32 s24, s43, s1
	s_cselect_b32 s25, s42, s0
	s_ashr_i32 s19, s18, 31
	s_lshl_b64 s[22:23], s[18:19], 19
	v_readlane_b32 s26, v239, 34
	v_readlane_b32 s27, v239, 35
	s_add_u32 s46, s26, s22
	s_addc_u32 s47, s27, s23
	s_and_b64 s[22:23], s[6:7], exec
	s_cselect_b32 s19, s47, s21
	s_cselect_b32 s26, s46, s20
	s_add_u32 s0, s0, 0x40080
	s_addc_u32 s1, s1, 0
	s_add_u32 s27, s20, 0x100
	s_addc_u32 s28, s21, 0
	s_mov_b32 s29, -2
	s_waitcnt lgkmcnt(0)
	ds_read_b128 v[146:149], v157
	ds_read_b128 v[162:165], v157 offset:1024
	ds_read_b128 v[166:169], v157 offset:2048
	ds_read_b128 v[170:173], v157 offset:3072
	ds_read_b128 v[174:177], v158
	ds_read_b128 v[178:181], v158 offset:1024
	ds_read_b128 v[182:185], v158 offset:2048
	ds_read_b128 v[186:189], v158 offset:3072
	s_add_u32 s20, s0, 0xfffc0080
	s_addc_u32 s21, s1, -1
	s_cmp_eq_u32 s29, 12
	s_cselect_b32 s23, s24, s21
	s_cselect_b32 s22, s25, s20
	s_cselect_b32 s21, s19, s28
	s_cselect_b32 s20, s26, s27
	v_lshl_add_u64 v[222:223], s[0:1], 0, v[138:139]
	s_add_i32 m0, s35, 0xc000
	ds_read_b128 v[190:193], v159
	ds_read_b128 v[194:197], v159 offset:1024
	ds_read_b128 v[198:201], v159 offset:2048
	ds_read_b128 v[202:205], v159 offset:3072
	ds_read_b128 v[206:209], v159 offset:4096
	ds_read_b128 v[210:213], v159 offset:5120
	ds_read_b128 v[214:217], v159 offset:6144
	ds_read_b128 v[218:221], v159 offset:7168
	global_load_lds_dwordx4 v[222:223], off
	s_add_i32 m0, s35, 0xe000
	v_lshl_add_u64 v[222:223], s[0:1], 0, v[140:141]
	global_load_lds_dwordx4 v[222:223], off
	s_waitcnt vmcnt(8)
	s_waitcnt lgkmcnt(0)
	s_barrier
	s_waitcnt lgkmcnt(0)
	v_mfma_f32_16x16x32_bf16 v[124:127], v[146:149], v[190:193], 0
	v_mfma_f32_16x16x32_bf16 v[120:123], v[166:169], v[190:193], 0
	v_mfma_f32_16x16x32_bf16 v[108:111], v[146:149], v[198:201], 0
	v_mfma_f32_16x16x32_bf16 v[104:107], v[166:169], v[198:201], 0
	v_mfma_f32_16x16x32_bf16 v[92:95], v[146:149], v[206:209], 0
	v_mfma_f32_16x16x32_bf16 v[88:91], v[166:169], v[206:209], 0
	v_mfma_f32_16x16x32_bf16 v[76:79], v[146:149], v[214:217], 0
	v_mfma_f32_16x16x32_bf16 v[72:75], v[166:169], v[214:217], 0
	v_mfma_f32_16x16x32_bf16 v[124:127], v[162:165], v[194:197], v[124:127]
	v_mfma_f32_16x16x32_bf16 v[120:123], v[170:173], v[194:197], v[120:123]
	v_mfma_f32_16x16x32_bf16 v[108:111], v[162:165], v[202:205], v[108:111]
	v_mfma_f32_16x16x32_bf16 v[104:107], v[170:173], v[202:205], v[104:107]
	v_mfma_f32_16x16x32_bf16 v[92:95], v[162:165], v[210:213], v[92:95]
	v_mfma_f32_16x16x32_bf16 v[88:91], v[170:173], v[210:213], v[88:91]
	v_mfma_f32_16x16x32_bf16 v[76:79], v[162:165], v[218:221], v[76:79]
	v_mfma_f32_16x16x32_bf16 v[72:75], v[170:173], v[218:221], v[72:75]
	v_mfma_f32_16x16x32_bf16 v[116:119], v[174:177], v[190:193], 0
	v_mfma_f32_16x16x32_bf16 v[112:115], v[182:185], v[190:193], 0
	v_mfma_f32_16x16x32_bf16 v[100:103], v[174:177], v[198:201], 0
	v_mfma_f32_16x16x32_bf16 v[96:99], v[182:185], v[198:201], 0
	v_mfma_f32_16x16x32_bf16 v[84:87], v[174:177], v[206:209], 0
	v_mfma_f32_16x16x32_bf16 v[80:83], v[182:185], v[206:209], 0
	v_mfma_f32_16x16x32_bf16 v[68:71], v[174:177], v[214:217], 0
	v_mfma_f32_16x16x32_bf16 v[64:67], v[182:185], v[214:217], 0
	v_mfma_f32_16x16x32_bf16 v[116:119], v[178:181], v[194:197], v[116:119]
	v_mfma_f32_16x16x32_bf16 v[112:115], v[186:189], v[194:197], v[112:115]
	v_mfma_f32_16x16x32_bf16 v[100:103], v[178:181], v[202:205], v[100:103]
	v_mfma_f32_16x16x32_bf16 v[96:99], v[186:189], v[202:205], v[96:99]
	v_mfma_f32_16x16x32_bf16 v[84:87], v[178:181], v[210:213], v[84:87]
	v_mfma_f32_16x16x32_bf16 v[80:83], v[186:189], v[210:213], v[80:83]
	v_mfma_f32_16x16x32_bf16 v[68:71], v[178:181], v[218:221], v[68:71]
	v_mfma_f32_16x16x32_bf16 v[64:67], v[186:189], v[218:221], v[64:67]
	s_barrier
	s_add_i32 s30, s60, s34
	v_lshl_add_u64 v[222:223], s[20:21], 0, v[130:131]
	s_mov_b32 m0, s30
	ds_read_b128 v[190:193], v159 offset:16384
	ds_read_b128 v[194:197], v159 offset:17408
	ds_read_b128 v[198:201], v159 offset:18432
	ds_read_b128 v[202:205], v159 offset:19456
	ds_read_b128 v[206:209], v159 offset:20480
	ds_read_b128 v[210:213], v159 offset:21504
	ds_read_b128 v[214:217], v159 offset:22528
	ds_read_b128 v[218:221], v159 offset:23552
	global_load_lds_dwordx4 v[222:223], off
	s_add_i32 m0, s30, 0x2000
	s_add_u32 s30, s20, 0x10000
	v_lshl_add_u64 v[224:225], s[20:21], 0, v[134:135]
	s_addc_u32 s31, s21, 0
	s_add_i32 s33, s61, s34
	global_load_lds_dwordx4 v[224:225], off
	v_lshl_add_u64 v[226:227], s[30:31], 0, v[130:131]
	s_mov_b32 m0, s33
	v_lshl_add_u64 v[228:229], s[22:23], 0, v[132:133]
	global_load_lds_dwordx4 v[226:227], off
	s_add_i32 m0, s33, 0x2000
	v_lshl_add_u64 v[226:227], s[30:31], 0, v[134:135]
	global_load_lds_dwordx4 v[226:227], off
	s_mov_b32 m0, s35
	v_lshl_add_u64 v[226:227], s[22:23], 0, v[128:129]
	global_load_lds_dwordx4 v[226:227], off
	s_mov_b32 m0, s49
	s_nop 0
	global_load_lds_dwordx4 v[228:229], off
	s_waitcnt vmcnt(8)
	s_waitcnt lgkmcnt(0)
	s_barrier
; #define PG8_STAGE(bufoff, gbase, voff) do { _Pragma("unroll") for (int _i = 0; _i < 2; ++_i) \
;         __builtin_amdgcn_global_load_lds((const unsigned*)((const char*)(gbase) + (voff)[_i]), (PG8_LAS unsigned*)(lds + (bufoff) + ldsw + _i * 8192), 16, 0, PG8_LOAD_AUX); } while (0)
; #define PG8_LDA(dst, b, h) do { _Pragma("unroll") for (int m = 0; m < 4; ++m) _Pragma("unroll") for (int k = 0; k < 2; ++k) dst[m][k] = *(const PG8_LAS bf16x8*)(lds + PG8_SA(b, h) + aoff + m * 2048 + k * 1024); } while (0)
; #define PG8_LDB(dst, b, h) do { _Pragma("unroll") for (int n = 0; n < 2; ++n) _Pragma("unroll") for (int k = 0; k < 2; ++k) dst[n][k] = *(const PG8_LAS bf16x8*)(lds + PG8_SB(b, h) + boff + n * 2048 + k * 1024); } while (0)
; #define PG8_MMA(ai, bj, At, Bt) do { __builtin_amdgcn_s_setprio(1); _Pragma("unroll") for (int m = 0; m < 4; ++m) _Pragma("unroll") for (int n = 0; n < 2; ++n) _Pragma("unroll") for (int k = 0; k < 2; ++k) \
;         acc[ai][bj][m][n] = __builtin_amdgcn_mfma_f32_16x16x32_bf16(Bt[n][k], At[m][k], acc[ai][bj][m][n], 0, 0, 0); __builtin_amdgcn_s_setprio(0); } while (0)
; #define PG8_WAIT_V(n) asm volatile("s_waitcnt vmcnt(" #n ")" ::: "memory")
; #define PG8_WAIT_L(n) asm volatile("s_waitcnt lgkmcnt(" #n ")" ::: "memory")
; #define PG8_BAR __builtin_amdgcn_s_barrier()
; #define PG8_SCHED __builtin_amdgcn_sched_barrier(0)
; template <class Epi, class Sched, bool ALIGN_EPI = false, bool SP2 = false>
; __device__ __forceinline__ void gemm_phase(PG8_LAS unsigned char* lds, const Gemm g, const Sched& S, const Epi& E) {
;     ...
;             PG8_LDB(B0, 0, 0); PG8_LDB(B1, 0, 1); PG8_SCHED; PG8_LDA(At, 0, 0); PG8_STAGE(PG8_SA(1, 1), a1 + hstepA, voffA);
;             PG8_WAIT_V(8); PG8_WAIT_L(0); PG8_BAR; PG8_MMA(0, 0, At, B0); PG8_MMA(0, 1, At, B1); PG8_BAR; PG8_SCHED;
;             PG8_LDA(At, 0, 1); PG8_STAGE(PG8_SB(0, 0), b2, voffB); PG8_STAGE(PG8_SB(0, 1), b2 + hstepB, voffB); PG8_STAGE(PG8_SA(0, 0), a2, voffA);
;             PG8_WAIT_V(8); PG8_WAIT_L(0); PG8_BAR; PG8_MMA(1, 0, At, B0); PG8_MMA(1, 1, At, B1); PG8_BAR; PG8_SCHED;
	s_waitcnt lgkmcnt(0)
	v_mfma_f32_16x16x32_bf16 v[60:63], v[146:149], v[190:193], 0
	v_mfma_f32_16x16x32_bf16 v[56:59], v[166:169], v[190:193], 0
	v_mfma_f32_16x16x32_bf16 v[44:47], v[146:149], v[198:201], 0
	v_mfma_f32_16x16x32_bf16 v[40:43], v[166:169], v[198:201], 0
	v_mfma_f32_16x16x32_bf16 v[28:31], v[146:149], v[206:209], 0
	v_mfma_f32_16x16x32_bf16 v[24:27], v[166:169], v[206:209], 0
	v_mfma_f32_16x16x32_bf16 v[12:15], v[146:149], v[214:217], 0
	v_mfma_f32_16x16x32_bf16 v[8:11], v[166:169], v[214:217], 0
	v_mfma_f32_16x16x32_bf16 v[60:63], v[162:165], v[194:197], v[60:63]
	v_mfma_f32_16x16x32_bf16 v[56:59], v[170:173], v[194:197], v[56:59]
	v_mfma_f32_16x16x32_bf16 v[44:47], v[162:165], v[202:205], v[44:47]
	v_mfma_f32_16x16x32_bf16 v[40:43], v[170:173], v[202:205], v[40:43]
	v_mfma_f32_16x16x32_bf16 v[28:31], v[162:165], v[210:213], v[28:31]
	v_mfma_f32_16x16x32_bf16 v[24:27], v[170:173], v[210:213], v[24:27]
	v_mfma_f32_16x16x32_bf16 v[12:15], v[162:165], v[218:221], v[12:15]
	v_mfma_f32_16x16x32_bf16 v[8:11], v[170:173], v[218:221], v[8:11]
	v_mfma_f32_16x16x32_bf16 v[52:55], v[174:177], v[190:193], 0
	v_mfma_f32_16x16x32_bf16 v[48:51], v[182:185], v[190:193], 0
	v_mfma_f32_16x16x32_bf16 v[36:39], v[174:177], v[198:201], 0
	v_mfma_f32_16x16x32_bf16 v[32:35], v[182:185], v[198:201], 0
	v_mfma_f32_16x16x32_bf16 v[20:23], v[174:177], v[206:209], 0
	v_mfma_f32_16x16x32_bf16 v[16:19], v[182:185], v[206:209], 0
	v_mfma_f32_16x16x32_bf16 v[4:7], v[174:177], v[214:217], 0
	v_mfma_f32_16x16x32_bf16 v[0:3], v[182:185], v[214:217], 0
	v_mfma_f32_16x16x32_bf16 v[52:55], v[178:181], v[194:197], v[52:55]
	v_mfma_f32_16x16x32_bf16 v[48:51], v[186:189], v[194:197], v[48:51]
	v_mfma_f32_16x16x32_bf16 v[36:39], v[178:181], v[202:205], v[36:39]
	v_mfma_f32_16x16x32_bf16 v[32:35], v[186:189], v[202:205], v[32:35]
	v_mfma_f32_16x16x32_bf16 v[20:23], v[178:181], v[210:213], v[20:23]
	v_mfma_f32_16x16x32_bf16 v[16:19], v[186:189], v[210:213], v[16:19]
	v_mfma_f32_16x16x32_bf16 v[4:7], v[178:181], v[218:221], v[4:7]
	v_mfma_f32_16x16x32_bf16 v[0:3], v[186:189], v[218:221], v[0:3]
	s_barrier
	s_branch .Lkmid_P6
.LBB0_585:
	ds_read_b128 v[146:149], v157
	ds_read_b128 v[162:165], v157 offset:1024
	ds_read_b128 v[166:169], v157 offset:2048
	ds_read_b128 v[170:173], v157 offset:3072
	ds_read_b128 v[174:177], v158
	ds_read_b128 v[178:181], v158 offset:1024
	ds_read_b128 v[182:185], v158 offset:2048
	ds_read_b128 v[186:189], v158 offset:3072
	s_add_u32 s20, s0, 0xfffc0080
	s_addc_u32 s21, s1, -1
	s_cmp_eq_u32 s29, 12
	s_cselect_b32 s23, s24, s21
	s_cselect_b32 s22, s25, s20
	s_cselect_b32 s21, s19, s28
	s_cselect_b32 s20, s26, s27
	v_lshl_add_u64 v[222:223], s[0:1], 0, v[138:139]
	s_add_i32 m0, s35, 0xc000
	ds_read_b128 v[190:193], v159
	ds_read_b128 v[194:197], v159 offset:1024
	ds_read_b128 v[198:201], v159 offset:2048
	ds_read_b128 v[202:205], v159 offset:3072
	ds_read_b128 v[206:209], v159 offset:4096
	ds_read_b128 v[210:213], v159 offset:5120
	ds_read_b128 v[214:217], v159 offset:6144
	ds_read_b128 v[218:221], v159 offset:7168
	global_load_lds_dwordx4 v[222:223], off
	s_add_i32 m0, s35, 0xe000
	v_lshl_add_u64 v[222:223], s[0:1], 0, v[140:141]
	global_load_lds_dwordx4 v[222:223], off
	s_waitcnt vmcnt(8)
	s_waitcnt lgkmcnt(0)
	s_barrier
	s_waitcnt lgkmcnt(0)
	v_mfma_f32_16x16x32_bf16 v[124:127], v[146:149], v[190:193], v[124:127]
	v_mfma_f32_16x16x32_bf16 v[120:123], v[166:169], v[190:193], v[120:123]
	v_mfma_f32_16x16x32_bf16 v[108:111], v[146:149], v[198:201], v[108:111]
	v_mfma_f32_16x16x32_bf16 v[104:107], v[166:169], v[198:201], v[104:107]
	v_mfma_f32_16x16x32_bf16 v[92:95], v[146:149], v[206:209], v[92:95]
	v_mfma_f32_16x16x32_bf16 v[88:91], v[166:169], v[206:209], v[88:91]
	v_mfma_f32_16x16x32_bf16 v[76:79], v[146:149], v[214:217], v[76:79]
	v_mfma_f32_16x16x32_bf16 v[72:75], v[166:169], v[214:217], v[72:75]
	v_mfma_f32_16x16x32_bf16 v[124:127], v[162:165], v[194:197], v[124:127]
	v_mfma_f32_16x16x32_bf16 v[120:123], v[170:173], v[194:197], v[120:123]
	v_mfma_f32_16x16x32_bf16 v[108:111], v[162:165], v[202:205], v[108:111]
	v_mfma_f32_16x16x32_bf16 v[104:107], v[170:173], v[202:205], v[104:107]
	v_mfma_f32_16x16x32_bf16 v[92:95], v[162:165], v[210:213], v[92:95]
	v_mfma_f32_16x16x32_bf16 v[88:91], v[170:173], v[210:213], v[88:91]
	v_mfma_f32_16x16x32_bf16 v[76:79], v[162:165], v[218:221], v[76:79]
	v_mfma_f32_16x16x32_bf16 v[72:75], v[170:173], v[218:221], v[72:75]
	v_mfma_f32_16x16x32_bf16 v[116:119], v[174:177], v[190:193], v[116:119]
	v_mfma_f32_16x16x32_bf16 v[112:115], v[182:185], v[190:193], v[112:115]
	v_mfma_f32_16x16x32_bf16 v[100:103], v[174:177], v[198:201], v[100:103]
	v_mfma_f32_16x16x32_bf16 v[96:99], v[182:185], v[198:201], v[96:99]
	v_mfma_f32_16x16x32_bf16 v[84:87], v[174:177], v[206:209], v[84:87]
	v_mfma_f32_16x16x32_bf16 v[80:83], v[182:185], v[206:209], v[80:83]
	v_mfma_f32_16x16x32_bf16 v[68:71], v[174:177], v[214:217], v[68:71]
	v_mfma_f32_16x16x32_bf16 v[64:67], v[182:185], v[214:217], v[64:67]
	v_mfma_f32_16x16x32_bf16 v[116:119], v[178:181], v[194:197], v[116:119]
	v_mfma_f32_16x16x32_bf16 v[112:115], v[186:189], v[194:197], v[112:115]
	v_mfma_f32_16x16x32_bf16 v[100:103], v[178:181], v[202:205], v[100:103]
	v_mfma_f32_16x16x32_bf16 v[96:99], v[186:189], v[202:205], v[96:99]
	v_mfma_f32_16x16x32_bf16 v[84:87], v[178:181], v[210:213], v[84:87]
	v_mfma_f32_16x16x32_bf16 v[80:83], v[186:189], v[210:213], v[80:83]
	v_mfma_f32_16x16x32_bf16 v[68:71], v[178:181], v[218:221], v[68:71]
	v_mfma_f32_16x16x32_bf16 v[64:67], v[186:189], v[218:221], v[64:67]
	s_barrier
; #define PG8_STAGE(bufoff, gbase, voff) do { _Pragma("unroll") for (int _i = 0; _i < 2; ++_i) \
;         __builtin_amdgcn_global_load_lds((const unsigned*)((const char*)(gbase) + (voff)[_i]), (PG8_LAS unsigned*)(lds + (bufoff) + ldsw + _i * 8192), 16, 0, PG8_LOAD_AUX); } while (0)
; #define PG8_LDA(dst, b, h) do { _Pragma("unroll") for (int m = 0; m < 4; ++m) _Pragma("unroll") for (int k = 0; k < 2; ++k) dst[m][k] = *(const PG8_LAS bf16x8*)(lds + PG8_SA(b, h) + aoff + m * 2048 + k * 1024); } while (0)
; #define PG8_LDB(dst, b, h) do { _Pragma("unroll") for (int n = 0; n < 2; ++n) _Pragma("unroll") for (int k = 0; k < 2; ++k) dst[n][k] = *(const PG8_LAS bf16x8*)(lds + PG8_SB(b, h) + boff + n * 2048 + k * 1024); } while (0)
; #define PG8_MMA(ai, bj, At, Bt) do { __builtin_amdgcn_s_setprio(1); _Pragma("unroll") for (int m = 0; m < 4; ++m) _Pragma("unroll") for (int n = 0; n < 2; ++n) _Pragma("unroll") for (int k = 0; k < 2; ++k) \
;         acc[ai][bj][m][n] = __builtin_amdgcn_mfma_f32_16x16x32_bf16(Bt[n][k], At[m][k], acc[ai][bj][m][n], 0, 0, 0); __builtin_amdgcn_s_setprio(0); } while (0)
; #define PG8_WAIT_V(n) asm volatile("s_waitcnt vmcnt(" #n ")" ::: "memory")
; #define PG8_WAIT_L(n) asm volatile("s_waitcnt lgkmcnt(" #n ")" ::: "memory")
; #define PG8_BAR __builtin_amdgcn_s_barrier()
; #define PG8_SCHED __builtin_amdgcn_sched_barrier(0)
; template <class Epi, class Sched, bool ALIGN_EPI = false, bool SP2 = false>
; __device__ __forceinline__ void gemm_phase(PG8_LAS unsigned char* lds, const Gemm g, const Sched& S, const Epi& E) {
;     ...
;             PG8_WAIT_V(8); PG8_WAIT_L(0); PG8_BAR; PG8_MMA(1, 0, At, B0); PG8_MMA(1, 1, At, B1); PG8_BAR; PG8_SCHED;
;             PG8_LDB(B0, 1, 0); PG8_LDB(B1, 1, 1); PG8_SCHED; PG8_LDA(At, 1, 0); PG8_STAGE(PG8_SA(0, 1), a2 + hstepA, voffA);
;             PG8_WAIT_V(8); PG8_WAIT_L(0); PG8_BAR; PG8_MMA(0, 0, At, B0); PG8_MMA(0, 1, At, B1); PG8_BAR; PG8_SCHED;
;             PG8_LDA(At, 1, 1); PG8_STAGE(PG8_SB(1, 0), b3, voffB); PG8_STAGE(PG8_SB(1, 1), b3 + hstepB, voffB); PG8_STAGE(PG8_SA(1, 0), a3, voffA);
	s_add_i32 s30, s60, s34
	v_lshl_add_u64 v[222:223], s[20:21], 0, v[130:131]
	s_mov_b32 m0, s30
	ds_read_b128 v[190:193], v159 offset:16384
	ds_read_b128 v[194:197], v159 offset:17408
	ds_read_b128 v[198:201], v159 offset:18432
	ds_read_b128 v[202:205], v159 offset:19456
	ds_read_b128 v[206:209], v159 offset:20480
	ds_read_b128 v[210:213], v159 offset:21504
	ds_read_b128 v[214:217], v159 offset:22528
	ds_read_b128 v[218:221], v159 offset:23552
	global_load_lds_dwordx4 v[222:223], off
	s_add_i32 m0, s30, 0x2000
	s_add_u32 s30, s20, 0x10000
	v_lshl_add_u64 v[224:225], s[20:21], 0, v[134:135]
	s_addc_u32 s31, s21, 0
	s_add_i32 s33, s61, s34
	global_load_lds_dwordx4 v[224:225], off
	v_lshl_add_u64 v[226:227], s[30:31], 0, v[130:131]
	s_mov_b32 m0, s33
	v_lshl_add_u64 v[228:229], s[22:23], 0, v[132:133]
	global_load_lds_dwordx4 v[226:227], off
	s_add_i32 m0, s33, 0x2000
	v_lshl_add_u64 v[226:227], s[30:31], 0, v[134:135]
	global_load_lds_dwordx4 v[226:227], off
	s_mov_b32 m0, s35
	v_lshl_add_u64 v[226:227], s[22:23], 0, v[128:129]
	global_load_lds_dwordx4 v[226:227], off
	s_mov_b32 m0, s49
	s_nop 0
	global_load_lds_dwordx4 v[228:229], off
	s_waitcnt vmcnt(8)
	s_waitcnt lgkmcnt(0)
	s_barrier
	s_waitcnt lgkmcnt(0)
	v_mfma_f32_16x16x32_bf16 v[60:63], v[146:149], v[190:193], v[60:63]
	v_mfma_f32_16x16x32_bf16 v[56:59], v[166:169], v[190:193], v[56:59]
	v_mfma_f32_16x16x32_bf16 v[44:47], v[146:149], v[198:201], v[44:47]
	v_mfma_f32_16x16x32_bf16 v[40:43], v[166:169], v[198:201], v[40:43]
	v_mfma_f32_16x16x32_bf16 v[28:31], v[146:149], v[206:209], v[28:31]
	v_mfma_f32_16x16x32_bf16 v[24:27], v[166:169], v[206:209], v[24:27]
	v_mfma_f32_16x16x32_bf16 v[12:15], v[146:149], v[214:217], v[12:15]
	v_mfma_f32_16x16x32_bf16 v[8:11], v[166:169], v[214:217], v[8:11]
	v_mfma_f32_16x16x32_bf16 v[60:63], v[162:165], v[194:197], v[60:63]
	v_mfma_f32_16x16x32_bf16 v[56:59], v[170:173], v[194:197], v[56:59]
	v_mfma_f32_16x16x32_bf16 v[44:47], v[162:165], v[202:205], v[44:47]
	v_mfma_f32_16x16x32_bf16 v[40:43], v[170:173], v[202:205], v[40:43]
	v_mfma_f32_16x16x32_bf16 v[28:31], v[162:165], v[210:213], v[28:31]
	v_mfma_f32_16x16x32_bf16 v[24:27], v[170:173], v[210:213], v[24:27]
	v_mfma_f32_16x16x32_bf16 v[12:15], v[162:165], v[218:221], v[12:15]
	v_mfma_f32_16x16x32_bf16 v[8:11], v[170:173], v[218:221], v[8:11]
	v_mfma_f32_16x16x32_bf16 v[52:55], v[174:177], v[190:193], v[52:55]
	v_mfma_f32_16x16x32_bf16 v[48:51], v[182:185], v[190:193], v[48:51]
	v_mfma_f32_16x16x32_bf16 v[36:39], v[174:177], v[198:201], v[36:39]
	v_mfma_f32_16x16x32_bf16 v[32:35], v[182:185], v[198:201], v[32:35]
	v_mfma_f32_16x16x32_bf16 v[20:23], v[174:177], v[206:209], v[20:23]
	v_mfma_f32_16x16x32_bf16 v[16:19], v[182:185], v[206:209], v[16:19]
	v_mfma_f32_16x16x32_bf16 v[4:7], v[174:177], v[214:217], v[4:7]
	v_mfma_f32_16x16x32_bf16 v[0:3], v[182:185], v[214:217], v[0:3]
	v_mfma_f32_16x16x32_bf16 v[52:55], v[178:181], v[194:197], v[52:55]
	v_mfma_f32_16x16x32_bf16 v[48:51], v[186:189], v[194:197], v[48:51]
	v_mfma_f32_16x16x32_bf16 v[36:39], v[178:181], v[202:205], v[36:39]
	v_mfma_f32_16x16x32_bf16 v[32:35], v[186:189], v[202:205], v[32:35]
	v_mfma_f32_16x16x32_bf16 v[20:23], v[178:181], v[210:213], v[20:23]
	v_mfma_f32_16x16x32_bf16 v[16:19], v[186:189], v[210:213], v[16:19]
	v_mfma_f32_16x16x32_bf16 v[4:7], v[178:181], v[218:221], v[4:7]
	v_mfma_f32_16x16x32_bf16 v[0:3], v[186:189], v[218:221], v[0:3]
	s_barrier
.Lkmid_P6:
	s_add_i32 s30, 0, 0x18000
	v_add_u32_e32 v161, s30, v152
	s_add_i32 s31, 0, 0x1c000
	ds_read_b128 v[146:149], v161
	ds_read_b128 v[162:165], v161 offset:1024
	ds_read_b128 v[166:169], v161 offset:2048
	ds_read_b128 v[170:173], v161 offset:3072
	v_add_u32_e32 v161, s31, v152
	ds_read_b128 v[174:177], v161
	ds_read_b128 v[178:181], v161 offset:1024
	ds_read_b128 v[182:185], v161 offset:2048
	ds_read_b128 v[186:189], v161 offset:3072
	s_add_u32 s22, s22, 0x40000
	s_addc_u32 s23, s23, 0
	s_mov_b32 m0, s50
	v_lshl_add_u64 v[230:231], s[22:23], 0, v[128:129]
	ds_read_b128 v[190:193], v159 offset:32768
	ds_read_b128 v[194:197], v159 offset:33792
	ds_read_b128 v[198:201], v159 offset:34816
	ds_read_b128 v[202:205], v159 offset:35840
	ds_read_b128 v[206:209], v159 offset:36864
	ds_read_b128 v[210:213], v159 offset:37888
	ds_read_b128 v[214:217], v159 offset:38912
	ds_read_b128 v[218:221], v159 offset:39936
	global_load_lds_dwordx4 v[230:231], off
	s_mov_b32 m0, s51
	v_lshl_add_u64 v[230:231], s[22:23], 0, v[132:133]
	global_load_lds_dwordx4 v[230:231], off
	s_waitcnt vmcnt(8)
	s_waitcnt lgkmcnt(0)
	s_barrier
; #define PG8_STAGE(bufoff, gbase, voff) do { _Pragma("unroll") for (int _i = 0; _i < 2; ++_i) \
;         __builtin_amdgcn_global_load_lds((const unsigned*)((const char*)(gbase) + (voff)[_i]), (PG8_LAS unsigned*)(lds + (bufoff) + ldsw + _i * 8192), 16, 0, PG8_LOAD_AUX); } while (0)
; #define PG8_LDA(dst, b, h) do { _Pragma("unroll") for (int m = 0; m < 4; ++m) _Pragma("unroll") for (int k = 0; k < 2; ++k) dst[m][k] = *(const PG8_LAS bf16x8*)(lds + PG8_SA(b, h) + aoff + m * 2048 + k * 1024); } while (0)
; #define PG8_MMA(ai, bj, At, Bt) do { __builtin_amdgcn_s_setprio(1); _Pragma("unroll") for (int m = 0; m < 4; ++m) _Pragma("unroll") for (int n = 0; n < 2; ++n) _Pragma("unroll") for (int k = 0; k < 2; ++k) \
;         acc[ai][bj][m][n] = __builtin_amdgcn_mfma_f32_16x16x32_bf16(Bt[n][k], At[m][k], acc[ai][bj][m][n], 0, 0, 0); __builtin_amdgcn_s_setprio(0); } while (0)
; #define PG8_WAIT_V(n) asm volatile("s_waitcnt vmcnt(" #n ")" ::: "memory")
; #define PG8_WAIT_L(n) asm volatile("s_waitcnt lgkmcnt(" #n ")" ::: "memory")
; #define PG8_BAR __builtin_amdgcn_s_barrier()
; #define PG8_SCHED __builtin_amdgcn_sched_barrier(0)
; template <class Epi, class Sched, bool ALIGN_EPI = false, bool SP2 = false>
; __device__ __forceinline__ void gemm_phase(PG8_LAS unsigned char* lds, const Gemm g, const Sched& S, const Epi& E) {
;     ...
;             PG8_WAIT_V(8); PG8_WAIT_L(0); PG8_BAR; PG8_MMA(0, 0, At, B0); PG8_MMA(0, 1, At, B1); PG8_BAR; PG8_SCHED;
;             PG8_LDA(At, 1, 1); PG8_STAGE(PG8_SB(1, 0), b3, voffB); PG8_STAGE(PG8_SB(1, 1), b3 + hstepB, voffB); PG8_STAGE(PG8_SA(1, 0), a3, voffA);
;             PG8_WAIT_V(8); PG8_WAIT_L(0); PG8_BAR; PG8_MMA(1, 0, At, B0); PG8_MMA(1, 1, At, B1); PG8_BAR; PG8_SCHED;
;     ...
;         if constexpr (ALIGN_EPI) { if (wr == 0) PG8_BAR; }
	s_waitcnt lgkmcnt(0)
	v_mfma_f32_16x16x32_bf16 v[124:127], v[146:149], v[190:193], v[124:127]
	v_mfma_f32_16x16x32_bf16 v[120:123], v[166:169], v[190:193], v[120:123]
	v_mfma_f32_16x16x32_bf16 v[108:111], v[146:149], v[198:201], v[108:111]
	v_mfma_f32_16x16x32_bf16 v[104:107], v[166:169], v[198:201], v[104:107]
	v_mfma_f32_16x16x32_bf16 v[92:95], v[146:149], v[206:209], v[92:95]
	v_mfma_f32_16x16x32_bf16 v[88:91], v[166:169], v[206:209], v[88:91]
	v_mfma_f32_16x16x32_bf16 v[76:79], v[146:149], v[214:217], v[76:79]
	v_mfma_f32_16x16x32_bf16 v[72:75], v[166:169], v[214:217], v[72:75]
	v_mfma_f32_16x16x32_bf16 v[124:127], v[162:165], v[194:197], v[124:127]
	v_mfma_f32_16x16x32_bf16 v[120:123], v[170:173], v[194:197], v[120:123]
	v_mfma_f32_16x16x32_bf16 v[108:111], v[162:165], v[202:205], v[108:111]
	v_mfma_f32_16x16x32_bf16 v[104:107], v[170:173], v[202:205], v[104:107]
	v_mfma_f32_16x16x32_bf16 v[92:95], v[162:165], v[210:213], v[92:95]
	v_mfma_f32_16x16x32_bf16 v[88:91], v[170:173], v[210:213], v[88:91]
	v_mfma_f32_16x16x32_bf16 v[76:79], v[162:165], v[218:221], v[76:79]
	v_mfma_f32_16x16x32_bf16 v[72:75], v[170:173], v[218:221], v[72:75]
	v_mfma_f32_16x16x32_bf16 v[116:119], v[174:177], v[190:193], v[116:119]
	v_mfma_f32_16x16x32_bf16 v[112:115], v[182:185], v[190:193], v[112:115]
	v_mfma_f32_16x16x32_bf16 v[100:103], v[174:177], v[198:201], v[100:103]
	v_mfma_f32_16x16x32_bf16 v[96:99], v[182:185], v[198:201], v[96:99]
	v_mfma_f32_16x16x32_bf16 v[84:87], v[174:177], v[206:209], v[84:87]
	v_mfma_f32_16x16x32_bf16 v[80:83], v[182:185], v[206:209], v[80:83]
	v_mfma_f32_16x16x32_bf16 v[68:71], v[174:177], v[214:217], v[68:71]
	v_mfma_f32_16x16x32_bf16 v[64:67], v[182:185], v[214:217], v[64:67]
	v_mfma_f32_16x16x32_bf16 v[116:119], v[178:181], v[194:197], v[116:119]
	v_mfma_f32_16x16x32_bf16 v[112:115], v[186:189], v[194:197], v[112:115]
	v_mfma_f32_16x16x32_bf16 v[100:103], v[178:181], v[202:205], v[100:103]
	v_mfma_f32_16x16x32_bf16 v[96:99], v[186:189], v[202:205], v[96:99]
	v_mfma_f32_16x16x32_bf16 v[84:87], v[178:181], v[210:213], v[84:87]
	v_mfma_f32_16x16x32_bf16 v[80:83], v[186:189], v[210:213], v[80:83]
	v_mfma_f32_16x16x32_bf16 v[68:71], v[178:181], v[218:221], v[68:71]
	v_mfma_f32_16x16x32_bf16 v[64:67], v[186:189], v[218:221], v[64:67]
	s_barrier
	s_add_i32 s22, s30, s34
	v_lshl_add_u64 v[222:223], v[222:223], 0, s[14:15]
	s_mov_b32 m0, s22
	ds_read_b128 v[190:193], v159 offset:49152
	ds_read_b128 v[194:197], v159 offset:50176
	ds_read_b128 v[198:201], v159 offset:51200
	ds_read_b128 v[202:205], v159 offset:52224
	ds_read_b128 v[206:209], v159 offset:53248
	ds_read_b128 v[210:213], v159 offset:54272
	ds_read_b128 v[214:217], v159 offset:55296
	ds_read_b128 v[218:221], v159 offset:56320
	global_load_lds_dwordx4 v[222:223], off
	s_add_i32 m0, s22, 0x2000
	s_add_u32 s20, s20, 0x10080
	v_lshl_add_u64 v[222:223], v[224:225], 0, s[14:15]
	s_addc_u32 s21, s21, 0
	s_add_i32 s22, s31, s34
	global_load_lds_dwordx4 v[222:223], off
	s_mov_b32 m0, s22
	v_lshl_add_u64 v[222:223], s[20:21], 0, v[130:131]
	global_load_lds_dwordx4 v[222:223], off
	s_add_i32 m0, s22, 0x2000
	v_lshl_add_u64 v[222:223], s[20:21], 0, v[134:135]
	global_load_lds_dwordx4 v[222:223], off
	s_mov_b32 m0, s57
	v_lshl_add_u64 v[222:223], v[226:227], 0, s[14:15]
	global_load_lds_dwordx4 v[222:223], off
	s_mov_b32 m0, s58
	v_lshl_add_u64 v[222:223], v[228:229], 0, s[14:15]
	global_load_lds_dwordx4 v[222:223], off
	s_waitcnt vmcnt(8)
	s_waitcnt lgkmcnt(0)
	s_barrier
	s_waitcnt lgkmcnt(0)
	v_mfma_f32_16x16x32_bf16 v[60:63], v[146:149], v[190:193], v[60:63]
	v_mfma_f32_16x16x32_bf16 v[56:59], v[166:169], v[190:193], v[56:59]
	v_mfma_f32_16x16x32_bf16 v[44:47], v[146:149], v[198:201], v[44:47]
	v_mfma_f32_16x16x32_bf16 v[40:43], v[166:169], v[198:201], v[40:43]
	v_mfma_f32_16x16x32_bf16 v[28:31], v[146:149], v[206:209], v[28:31]
	v_mfma_f32_16x16x32_bf16 v[24:27], v[166:169], v[206:209], v[24:27]
	v_mfma_f32_16x16x32_bf16 v[12:15], v[146:149], v[214:217], v[12:15]
	v_mfma_f32_16x16x32_bf16 v[8:11], v[166:169], v[214:217], v[8:11]
	v_mfma_f32_16x16x32_bf16 v[60:63], v[162:165], v[194:197], v[60:63]
	v_mfma_f32_16x16x32_bf16 v[56:59], v[170:173], v[194:197], v[56:59]
	v_mfma_f32_16x16x32_bf16 v[44:47], v[162:165], v[202:205], v[44:47]
	v_mfma_f32_16x16x32_bf16 v[40:43], v[170:173], v[202:205], v[40:43]
	v_mfma_f32_16x16x32_bf16 v[28:31], v[162:165], v[210:213], v[28:31]
	v_mfma_f32_16x16x32_bf16 v[24:27], v[170:173], v[210:213], v[24:27]
	v_mfma_f32_16x16x32_bf16 v[12:15], v[162:165], v[218:221], v[12:15]
	v_mfma_f32_16x16x32_bf16 v[8:11], v[170:173], v[218:221], v[8:11]
	v_mfma_f32_16x16x32_bf16 v[52:55], v[174:177], v[190:193], v[52:55]
	v_mfma_f32_16x16x32_bf16 v[48:51], v[182:185], v[190:193], v[48:51]
	v_mfma_f32_16x16x32_bf16 v[36:39], v[174:177], v[198:201], v[36:39]
	v_mfma_f32_16x16x32_bf16 v[32:35], v[182:185], v[198:201], v[32:35]
	v_mfma_f32_16x16x32_bf16 v[20:23], v[174:177], v[206:209], v[20:23]
	v_mfma_f32_16x16x32_bf16 v[16:19], v[182:185], v[206:209], v[16:19]
	v_mfma_f32_16x16x32_bf16 v[4:7], v[174:177], v[214:217], v[4:7]
	v_mfma_f32_16x16x32_bf16 v[0:3], v[182:185], v[214:217], v[0:3]
	v_mfma_f32_16x16x32_bf16 v[52:55], v[178:181], v[194:197], v[52:55]
	v_mfma_f32_16x16x32_bf16 v[48:51], v[186:189], v[194:197], v[48:51]
	v_mfma_f32_16x16x32_bf16 v[36:39], v[178:181], v[202:205], v[36:39]
	v_mfma_f32_16x16x32_bf16 v[32:35], v[186:189], v[202:205], v[32:35]
	v_mfma_f32_16x16x32_bf16 v[20:23], v[178:181], v[210:213], v[20:23]
	v_mfma_f32_16x16x32_bf16 v[16:19], v[186:189], v[210:213], v[16:19]
	v_mfma_f32_16x16x32_bf16 v[4:7], v[178:181], v[218:221], v[4:7]
	v_mfma_f32_16x16x32_bf16 v[0:3], v[186:189], v[218:221], v[0:3]
	s_barrier
	s_add_i32 s29, s29, 2
	s_add_u32 s0, s0, 0x100
	s_addc_u32 s1, s1, 0
	s_add_u32 s27, s27, 0x100
	s_addc_u32 s28, s28, 0
	s_cmp_gt_u32 s29, 13
	s_cbranch_scc0 .LBB0_585
	s_and_b64 vcc, exec, s[16:17]
	s_cbranch_vccz .LBB0_588
	s_barrier

; #define PG8_STAGE(bufoff, gbase, voff) do { _Pragma("unroll") for (int _i = 0; _i < 2; ++_i) \
;         __builtin_amdgcn_global_load_lds((const unsigned*)((const char*)(gbase) + (voff)[_i]), (PG8_LAS unsigned*)(lds + (bufoff) + ldsw + _i * 8192), 16, 0, PG8_LOAD_AUX); } while (0)
; #define PG8_WAIT_V(n) asm volatile("s_waitcnt vmcnt(" #n ")" ::: "memory")
; #define PG8_WAIT_L(n) asm volatile("s_waitcnt lgkmcnt(" #n ")" ::: "memory")
; #define PG8_BAR __builtin_amdgcn_s_barrier()
;     __host__ __device__ bool next(int i, Unit& u) const {
;         const long L = (long)i * G + c; if (L >= nwg) return false;
;         int wgid = (int)L; { const int q = nwg / NXCD, r = nwg % NXCD, xcd = wgid % NXCD, off = wgid / NXCD; wgid = (xcd < r ? xcd * (q + 1) : r * (q + 1) + (xcd - r) * q) + off; }
;         const int nig = WGM * nN, gid = wgid / nig, fm = gid * WGM, gsz = (nM - fm) < WGM ? (nM - fm) : WGM;
;         u.pm = fm + ((wgid % nig) % gsz); u.pn = (wgid % nig) / gsz; return true;
; template <class Epi, class Sched, bool ALIGN_EPI = false, bool SP2 = false>
; __device__ __forceinline__ void gemm_phase(PG8_LAS unsigned char* lds, const Gemm g, const Sched& S, const Epi& E) {
;     ...
;         const bool has_next = S.next(ui + 1, nxt);
;         const char* nA = has_next ? (const char*)g.A + (size_t)nxt.pm * tstepA + (size_t)nxt.pn * apn : cA; const char* nB = has_next ? (const char*)g.Bt + (size_t)nxt.pn * tstepB : cB;
;         for (int t = 0; t < nt; t += 2) {
;             const bool last = (t == nt - 2);
;             const char* a1 = cA + (size_t)(t + 1) * kstep;
;             const char* a2 = last ? nA : cA + (size_t)(t + 2) * kstep; const char* b2 = last ? nB : cB + (size_t)(t + 2) * kstep;
;             const char* a3 = a2 + kstep; const char* b3 = b2 + kstep;
;             if (last && has_next) S.a_ready(nxt);
;             if constexpr (SP2) {
;             PG8_LDB(B0, 0, 0); PG8_LDB(B1, 0, 1); PG8_SCHED; PG8_LDA(At, 0, 0); PG8_STAGE(PG8_SA(1, 1), a1 + hstepA, voffA);
;             PG8_WAIT_V(8); PG8_WAIT_L(0); PG8_BAR; PG8_MMA(0, 0, At, B0); PG8_MMA(0, 1, At, B1); PG8_BAR; PG8_SCHED;
;             PG8_LDA(At, 0, 1); PG8_STAGE(PG8_SB(0, 0), b2, voffB); PG8_STAGE(PG8_SB(0, 1), b2 + hstepB, voffB); PG8_STAGE(PG8_SA(0, 0), a2, voffA);
;             PG8_WAIT_V(8); PG8_WAIT_L(0); PG8_BAR; PG8_MMA(1, 0, At, B0); PG8_MMA(1, 1, At, B1); PG8_BAR; PG8_SCHED;
.LBB0_669:
	s_add_u32 s20, s20, 0x40080
	s_addc_u32 s21, s21, 0
	s_add_u32 s26, s22, 0x100
	s_addc_u32 s27, s23, 0
	s_mov_b32 s28, -2
	ds_read_b128 v[146:149], v158
	ds_read_b128 v[164:167], v158 offset:1024
	ds_read_b128 v[168:171], v158 offset:2048
	ds_read_b128 v[172:175], v158 offset:3072
	ds_read_b128 v[176:179], v159
	ds_read_b128 v[180:183], v159 offset:1024
	ds_read_b128 v[184:187], v159 offset:2048
	ds_read_b128 v[188:191], v159 offset:3072
	s_add_u32 s22, s20, 0xfffc0080
	s_addc_u32 s23, s21, -1
	s_cmp_eq_u32 s28, 12
	s_cselect_b32 s35, s17, s23
	s_cselect_b32 s34, s24, s22
	s_cselect_b32 s23, s15, s27
	s_cselect_b32 s22, s25, s26
	v_lshl_add_u64 v[150:151], s[20:21], 0, v[138:139]
	s_add_i32 m0, s43, 0xc000
	ds_read_b128 v[192:195], v160
	ds_read_b128 v[196:199], v160 offset:1024
	ds_read_b128 v[200:203], v160 offset:2048
	ds_read_b128 v[204:207], v160 offset:3072
	ds_read_b128 v[208:211], v160 offset:4096
	ds_read_b128 v[212:215], v160 offset:5120
	ds_read_b128 v[216:219], v160 offset:6144
	ds_read_b128 v[220:223], v160 offset:7168
	global_load_lds_dwordx4 v[150:151], off
	s_add_i32 m0, s43, 0xe000
	v_lshl_add_u64 v[150:151], s[20:21], 0, v[140:141]
	global_load_lds_dwordx4 v[150:151], off
	s_waitcnt vmcnt(8)
	s_waitcnt lgkmcnt(0)
	s_barrier
	s_waitcnt lgkmcnt(0)
	v_mfma_f32_16x16x32_bf16 v[124:127], v[146:149], v[192:195], 0
	s_add_i32 s49, s49, 1
	s_mul_i32 s2, s49, s50
	v_mfma_f32_16x16x32_bf16 v[120:123], v[168:171], v[192:195], 0
	s_mul_hi_u32 s3, s49, s53
	s_add_i32 s3, s3, s2
	v_mfma_f32_16x16x32_bf16 v[108:111], v[146:149], v[200:203], 0
	s_mul_i32 s2, s49, s53
	v_readlane_b32 s15, v239, 0
	v_mfma_f32_16x16x32_bf16 v[104:107], v[168:171], v[200:203], 0
	s_add_u32 s18, s2, s15
	s_addc_u32 s19, s3, s41
	v_mfma_f32_16x16x32_bf16 v[92:95], v[146:149], v[208:211], 0
	s_cmp_lt_u32 s18, 0xb00
	s_cselect_b64 s[2:3], -1, 0
	v_mfma_f32_16x16x32_bf16 v[88:91], v[168:171], v[208:211], 0
	s_ashr_i32 s14, s18, 31
	s_lshr_b32 s14, s14, 29
	v_mfma_f32_16x16x32_bf16 v[76:79], v[146:149], v[216:219], 0
	s_add_i32 s14, s18, s14
	s_ashr_i32 s15, s14, 3
	v_mfma_f32_16x16x32_bf16 v[72:75], v[168:171], v[216:219], 0
	s_and_b32 s14, s14, -8
	s_sub_i32 s14, s18, s14
	v_mfma_f32_16x16x32_bf16 v[124:127], v[164:167], v[196:199], v[124:127]
	s_cmp_lt_i32 s14, 0
	s_cselect_b32 s16, s42, 0x160
	v_mfma_f32_16x16x32_bf16 v[120:123], v[172:175], v[196:199], v[120:123]
	s_mul_i32 s14, s14, s16
	s_add_i32 s14, s14, s15
	v_mfma_f32_16x16x32_bf16 v[108:111], v[164:167], v[204:207], v[108:111]
	s_mul_hi_i32 s15, s14, 0x2e8ba2e9
	s_lshr_b32 s16, s15, 31
	v_mfma_f32_16x16x32_bf16 v[104:107], v[172:175], v[204:207], v[104:107]
	s_ashr_i32 s15, s15, 4
	s_add_i32 s15, s15, s16
	v_mfma_f32_16x16x32_bf16 v[92:95], v[164:167], v[212:215], v[92:95]
	s_lshl_b32 s16, s15, 2
	s_sub_i32 s17, 0x80, s16
	v_mfma_f32_16x16x32_bf16 v[88:91], v[172:175], v[212:215], v[88:91]
	s_min_i32 s17, s17, 4
	s_mulk_i32 s15, 0x58
	v_mfma_f32_16x16x32_bf16 v[76:79], v[164:167], v[220:223], v[76:79]
	s_sub_i32 s15, s14, s15
	s_lshr_b32 s14, s15, 2
	v_mfma_f32_16x16x32_bf16 v[72:75], v[172:175], v[220:223], v[72:75]
	s_and_b32 s15, s15, 3
	s_add_i32 s16, s16, s15
	v_mfma_f32_16x16x32_bf16 v[116:119], v[176:179], v[192:195], 0
	s_ashr_i32 s17, s16, 31
	s_lshl_b64 s[18:19], s[16:17], 19
	v_mfma_f32_16x16x32_bf16 v[112:115], v[184:187], v[192:195], 0
	s_add_u32 s18, s30, s18
	s_addc_u32 s19, s31, s19
	v_mfma_f32_16x16x32_bf16 v[100:103], v[176:179], v[200:203], 0
	s_sub_u32 s98, s20, 0x40080
	s_subb_u32 s99, s21, 0
	v_mfma_f32_16x16x32_bf16 v[96:99], v[184:187], v[200:203], 0
	s_cmp_lg_u64 s[2:3], 0
	s_cselect_b32 s17, s19, s99
	v_mfma_f32_16x16x32_bf16 v[84:87], v[176:179], v[208:211], 0
	s_cselect_b32 s24, s18, s98
	s_ashr_i32 s15, s14, 31
	v_mfma_f32_16x16x32_bf16 v[80:83], v[184:187], v[208:211], 0
	s_lshl_b64 s[98:99], s[14:15], 19
	v_readlane_b32 s15, v239, 40
	v_mfma_f32_16x16x32_bf16 v[68:71], v[176:179], v[216:219], 0
	s_add_u32 s36, s15, s98
	v_readlane_b32 s15, v239, 41
	v_mfma_f32_16x16x32_bf16 v[64:67], v[184:187], v[216:219], 0
	s_addc_u32 s37, s15, s99
	s_sub_u32 s98, s26, 0x100
	v_mfma_f32_16x16x32_bf16 v[116:119], v[180:183], v[196:199], v[116:119]
	s_subb_u32 s99, s27, 0
	s_cmp_lg_u64 s[2:3], 0
	v_mfma_f32_16x16x32_bf16 v[112:115], v[188:191], v[196:199], v[112:115]
	s_cselect_b32 s15, s37, s99
	s_cselect_b32 s25, s36, s98
	v_mfma_f32_16x16x32_bf16 v[100:103], v[180:183], v[204:207], v[100:103]
	v_mfma_f32_16x16x32_bf16 v[96:99], v[188:191], v[204:207], v[96:99]
	v_mfma_f32_16x16x32_bf16 v[84:87], v[180:183], v[212:215], v[84:87]
	v_mfma_f32_16x16x32_bf16 v[80:83], v[188:191], v[212:215], v[80:83]
	v_mfma_f32_16x16x32_bf16 v[68:71], v[180:183], v[220:223], v[68:71]
	v_mfma_f32_16x16x32_bf16 v[64:67], v[188:191], v[220:223], v[64:67]
	s_barrier
	s_add_i32 s29, s54, s40
	v_lshl_add_u64 v[150:151], s[22:23], 0, v[130:131]
	s_mov_b32 m0, s29
	ds_read_b128 v[192:195], v160 offset:16384
	ds_read_b128 v[196:199], v160 offset:17408
	ds_read_b128 v[200:203], v160 offset:18432
	ds_read_b128 v[204:207], v160 offset:19456
	ds_read_b128 v[208:211], v160 offset:20480
	ds_read_b128 v[212:215], v160 offset:21504
	ds_read_b128 v[216:219], v160 offset:22528
	ds_read_b128 v[220:223], v160 offset:23552
	global_load_lds_dwordx4 v[150:151], off
	s_add_i32 m0, s29, 0x2000
	s_add_u32 s30, s22, 0x40000
	v_lshl_add_u64 v[224:225], s[22:23], 0, v[134:135]
	s_addc_u32 s31, s23, 0
	s_add_i32 s29, s55, s40
	global_load_lds_dwordx4 v[224:225], off
	v_lshl_add_u64 v[226:227], s[30:31], 0, v[130:131]
	s_mov_b32 m0, s29
	v_lshl_add_u64 v[228:229], s[34:35], 0, v[132:133]
	global_load_lds_dwordx4 v[226:227], off
	s_add_i32 m0, s29, 0x2000
	v_lshl_add_u64 v[226:227], s[30:31], 0, v[134:135]
	global_load_lds_dwordx4 v[226:227], off
	s_mov_b32 m0, s43
	v_lshl_add_u64 v[226:227], s[34:35], 0, v[128:129]
	global_load_lds_dwordx4 v[226:227], off
	s_mov_b32 m0, s46
	s_nop 0
	global_load_lds_dwordx4 v[228:229], off
	s_waitcnt vmcnt(8)
	s_waitcnt lgkmcnt(0)
	s_barrier
; #define PG8_STAGE(bufoff, gbase, voff) do { _Pragma("unroll") for (int _i = 0; _i < 2; ++_i) \
;         __builtin_amdgcn_global_load_lds((const unsigned*)((const char*)(gbase) + (voff)[_i]), (PG8_LAS unsigned*)(lds + (bufoff) + ldsw + _i * 8192), 16, 0, PG8_LOAD_AUX); } while (0)
; #define PG8_LDA(dst, b, h) do { _Pragma("unroll") for (int m = 0; m < 4; ++m) _Pragma("unroll") for (int k = 0; k < 2; ++k) dst[m][k] = *(const PG8_LAS bf16x8*)(lds + PG8_SA(b, h) + aoff + m * 2048 + k * 1024); } while (0)
; #define PG8_LDB(dst, b, h) do { _Pragma("unroll") for (int n = 0; n < 2; ++n) _Pragma("unroll") for (int k = 0; k < 2; ++k) dst[n][k] = *(const PG8_LAS bf16x8*)(lds + PG8_SB(b, h) + boff + n * 2048 + k * 1024); } while (0)
; #define PG8_MMA(ai, bj, At, Bt) do { __builtin_amdgcn_s_setprio(1); _Pragma("unroll") for (int m = 0; m < 4; ++m) _Pragma("unroll") for (int n = 0; n < 2; ++n) _Pragma("unroll") for (int k = 0; k < 2; ++k) \
;         acc[ai][bj][m][n] = __builtin_amdgcn_mfma_f32_16x16x32_bf16(Bt[n][k], At[m][k], acc[ai][bj][m][n], 0, 0, 0); __builtin_amdgcn_s_setprio(0); } while (0)
; #define PG8_WAIT_V(n) asm volatile("s_waitcnt vmcnt(" #n ")" ::: "memory")
; #define PG8_WAIT_L(n) asm volatile("s_waitcnt lgkmcnt(" #n ")" ::: "memory")
; #define PG8_BAR __builtin_amdgcn_s_barrier()
; #define PG8_SCHED __builtin_amdgcn_sched_barrier(0)
; template <class Epi, class Sched, bool ALIGN_EPI = false, bool SP2 = false>
; __device__ __forceinline__ void gemm_phase(PG8_LAS unsigned char* lds, const Gemm g, const Sched& S, const Epi& E) {
;     ...
;             PG8_LDB(B0, 0, 0); PG8_LDB(B1, 0, 1); PG8_SCHED; PG8_LDA(At, 0, 0); PG8_STAGE(PG8_SA(1, 1), a1 + hstepA, voffA);
;             PG8_WAIT_V(8); PG8_WAIT_L(0); PG8_BAR; PG8_MMA(0, 0, At, B0); PG8_MMA(0, 1, At, B1); PG8_BAR; PG8_SCHED;
;             PG8_LDA(At, 0, 1); PG8_STAGE(PG8_SB(0, 0), b2, voffB); PG8_STAGE(PG8_SB(0, 1), b2 + hstepB, voffB); PG8_STAGE(PG8_SA(0, 0), a2, voffA);
;             PG8_WAIT_V(8); PG8_WAIT_L(0); PG8_BAR; PG8_MMA(1, 0, At, B0); PG8_MMA(1, 1, At, B1); PG8_BAR; PG8_SCHED;
	s_waitcnt lgkmcnt(0)
	v_mfma_f32_16x16x32_bf16 v[60:63], v[146:149], v[192:195], 0
	v_mfma_f32_16x16x32_bf16 v[56:59], v[168:171], v[192:195], 0
	v_mfma_f32_16x16x32_bf16 v[44:47], v[146:149], v[200:203], 0
	v_mfma_f32_16x16x32_bf16 v[40:43], v[168:171], v[200:203], 0
	v_mfma_f32_16x16x32_bf16 v[28:31], v[146:149], v[208:211], 0
	v_mfma_f32_16x16x32_bf16 v[24:27], v[168:171], v[208:211], 0
	v_mfma_f32_16x16x32_bf16 v[12:15], v[146:149], v[216:219], 0
	v_mfma_f32_16x16x32_bf16 v[8:11], v[168:171], v[216:219], 0
	v_mfma_f32_16x16x32_bf16 v[60:63], v[164:167], v[196:199], v[60:63]
	v_mfma_f32_16x16x32_bf16 v[56:59], v[172:175], v[196:199], v[56:59]
	v_mfma_f32_16x16x32_bf16 v[44:47], v[164:167], v[204:207], v[44:47]
	v_mfma_f32_16x16x32_bf16 v[40:43], v[172:175], v[204:207], v[40:43]
	v_mfma_f32_16x16x32_bf16 v[28:31], v[164:167], v[212:215], v[28:31]
	v_mfma_f32_16x16x32_bf16 v[24:27], v[172:175], v[212:215], v[24:27]
	v_mfma_f32_16x16x32_bf16 v[12:15], v[164:167], v[220:223], v[12:15]
	v_mfma_f32_16x16x32_bf16 v[8:11], v[172:175], v[220:223], v[8:11]
	v_mfma_f32_16x16x32_bf16 v[52:55], v[176:179], v[192:195], 0
	v_mfma_f32_16x16x32_bf16 v[48:51], v[184:187], v[192:195], 0
	v_mfma_f32_16x16x32_bf16 v[36:39], v[176:179], v[200:203], 0
	v_mfma_f32_16x16x32_bf16 v[32:35], v[184:187], v[200:203], 0
	v_mfma_f32_16x16x32_bf16 v[20:23], v[176:179], v[208:211], 0
	v_mfma_f32_16x16x32_bf16 v[16:19], v[184:187], v[208:211], 0
	v_mfma_f32_16x16x32_bf16 v[4:7], v[176:179], v[216:219], 0
	v_mfma_f32_16x16x32_bf16 v[0:3], v[184:187], v[216:219], 0
	v_mfma_f32_16x16x32_bf16 v[52:55], v[180:183], v[196:199], v[52:55]
	v_mfma_f32_16x16x32_bf16 v[48:51], v[188:191], v[196:199], v[48:51]
	v_mfma_f32_16x16x32_bf16 v[36:39], v[180:183], v[204:207], v[36:39]
	v_mfma_f32_16x16x32_bf16 v[32:35], v[188:191], v[204:207], v[32:35]
	v_mfma_f32_16x16x32_bf16 v[20:23], v[180:183], v[212:215], v[20:23]
	v_mfma_f32_16x16x32_bf16 v[16:19], v[188:191], v[212:215], v[16:19]
	v_mfma_f32_16x16x32_bf16 v[4:7], v[180:183], v[220:223], v[4:7]
	v_mfma_f32_16x16x32_bf16 v[0:3], v[188:191], v[220:223], v[0:3]
	s_barrier
	s_branch .Lkmid_P7
.LBB0_672:
	ds_read_b128 v[146:149], v158
	ds_read_b128 v[164:167], v158 offset:1024
	ds_read_b128 v[168:171], v158 offset:2048
	ds_read_b128 v[172:175], v158 offset:3072
	ds_read_b128 v[176:179], v159
	ds_read_b128 v[180:183], v159 offset:1024
	ds_read_b128 v[184:187], v159 offset:2048
	ds_read_b128 v[188:191], v159 offset:3072
	s_add_u32 s22, s20, 0xfffc0080
	s_addc_u32 s23, s21, -1
	s_cmp_eq_u32 s28, 12
	s_cselect_b32 s35, s17, s23
	s_cselect_b32 s34, s24, s22
	s_cselect_b32 s23, s15, s27
	s_cselect_b32 s22, s25, s26
	v_lshl_add_u64 v[150:151], s[20:21], 0, v[138:139]
	s_add_i32 m0, s43, 0xc000
	ds_read_b128 v[192:195], v160
	ds_read_b128 v[196:199], v160 offset:1024
	ds_read_b128 v[200:203], v160 offset:2048
	ds_read_b128 v[204:207], v160 offset:3072
	ds_read_b128 v[208:211], v160 offset:4096
	ds_read_b128 v[212:215], v160 offset:5120
	ds_read_b128 v[216:219], v160 offset:6144
	ds_read_b128 v[220:223], v160 offset:7168
	global_load_lds_dwordx4 v[150:151], off
	s_add_i32 m0, s43, 0xe000
	v_lshl_add_u64 v[150:151], s[20:21], 0, v[140:141]
	global_load_lds_dwordx4 v[150:151], off
	s_waitcnt vmcnt(8)
	s_waitcnt lgkmcnt(0)
	s_barrier
	s_waitcnt lgkmcnt(0)
	v_mfma_f32_16x16x32_bf16 v[124:127], v[146:149], v[192:195], v[124:127]
	v_mfma_f32_16x16x32_bf16 v[120:123], v[168:171], v[192:195], v[120:123]
	v_mfma_f32_16x16x32_bf16 v[108:111], v[146:149], v[200:203], v[108:111]
	v_mfma_f32_16x16x32_bf16 v[104:107], v[168:171], v[200:203], v[104:107]
	v_mfma_f32_16x16x32_bf16 v[92:95], v[146:149], v[208:211], v[92:95]
	v_mfma_f32_16x16x32_bf16 v[88:91], v[168:171], v[208:211], v[88:91]
	v_mfma_f32_16x16x32_bf16 v[76:79], v[146:149], v[216:219], v[76:79]
	v_mfma_f32_16x16x32_bf16 v[72:75], v[168:171], v[216:219], v[72:75]
	v_mfma_f32_16x16x32_bf16 v[124:127], v[164:167], v[196:199], v[124:127]
	v_mfma_f32_16x16x32_bf16 v[120:123], v[172:175], v[196:199], v[120:123]
	v_mfma_f32_16x16x32_bf16 v[108:111], v[164:167], v[204:207], v[108:111]
	v_mfma_f32_16x16x32_bf16 v[104:107], v[172:175], v[204:207], v[104:107]
	v_mfma_f32_16x16x32_bf16 v[92:95], v[164:167], v[212:215], v[92:95]
	v_mfma_f32_16x16x32_bf16 v[88:91], v[172:175], v[212:215], v[88:91]
	v_mfma_f32_16x16x32_bf16 v[76:79], v[164:167], v[220:223], v[76:79]
	v_mfma_f32_16x16x32_bf16 v[72:75], v[172:175], v[220:223], v[72:75]
	v_mfma_f32_16x16x32_bf16 v[116:119], v[176:179], v[192:195], v[116:119]
	v_mfma_f32_16x16x32_bf16 v[112:115], v[184:187], v[192:195], v[112:115]
	v_mfma_f32_16x16x32_bf16 v[100:103], v[176:179], v[200:203], v[100:103]
	v_mfma_f32_16x16x32_bf16 v[96:99], v[184:187], v[200:203], v[96:99]
	v_mfma_f32_16x16x32_bf16 v[84:87], v[176:179], v[208:211], v[84:87]
	v_mfma_f32_16x16x32_bf16 v[80:83], v[184:187], v[208:211], v[80:83]
	v_mfma_f32_16x16x32_bf16 v[68:71], v[176:179], v[216:219], v[68:71]
	v_mfma_f32_16x16x32_bf16 v[64:67], v[184:187], v[216:219], v[64:67]
	v_mfma_f32_16x16x32_bf16 v[116:119], v[180:183], v[196:199], v[116:119]
	v_mfma_f32_16x16x32_bf16 v[112:115], v[188:191], v[196:199], v[112:115]
	v_mfma_f32_16x16x32_bf16 v[100:103], v[180:183], v[204:207], v[100:103]
	v_mfma_f32_16x16x32_bf16 v[96:99], v[188:191], v[204:207], v[96:99]
	v_mfma_f32_16x16x32_bf16 v[84:87], v[180:183], v[212:215], v[84:87]
	v_mfma_f32_16x16x32_bf16 v[80:83], v[188:191], v[212:215], v[80:83]
	v_mfma_f32_16x16x32_bf16 v[68:71], v[180:183], v[220:223], v[68:71]
	v_mfma_f32_16x16x32_bf16 v[64:67], v[188:191], v[220:223], v[64:67]
	s_barrier
; #define PG8_STAGE(bufoff, gbase, voff) do { _Pragma("unroll") for (int _i = 0; _i < 2; ++_i) \
;         __builtin_amdgcn_global_load_lds((const unsigned*)((const char*)(gbase) + (voff)[_i]), (PG8_LAS unsigned*)(lds + (bufoff) + ldsw + _i * 8192), 16, 0, PG8_LOAD_AUX); } while (0)
; #define PG8_LDA(dst, b, h) do { _Pragma("unroll") for (int m = 0; m < 4; ++m) _Pragma("unroll") for (int k = 0; k < 2; ++k) dst[m][k] = *(const PG8_LAS bf16x8*)(lds + PG8_SA(b, h) + aoff + m * 2048 + k * 1024); } while (0)
; #define PG8_LDB(dst, b, h) do { _Pragma("unroll") for (int n = 0; n < 2; ++n) _Pragma("unroll") for (int k = 0; k < 2; ++k) dst[n][k] = *(const PG8_LAS bf16x8*)(lds + PG8_SB(b, h) + boff + n * 2048 + k * 1024); } while (0)
; #define PG8_MMA(ai, bj, At, Bt) do { __builtin_amdgcn_s_setprio(1); _Pragma("unroll") for (int m = 0; m < 4; ++m) _Pragma("unroll") for (int n = 0; n < 2; ++n) _Pragma("unroll") for (int k = 0; k < 2; ++k) \
;         acc[ai][bj][m][n] = __builtin_amdgcn_mfma_f32_16x16x32_bf16(Bt[n][k], At[m][k], acc[ai][bj][m][n], 0, 0, 0); __builtin_amdgcn_s_setprio(0); } while (0)
; #define PG8_WAIT_V(n) asm volatile("s_waitcnt vmcnt(" #n ")" ::: "memory")
; #define PG8_WAIT_L(n) asm volatile("s_waitcnt lgkmcnt(" #n ")" ::: "memory")
; #define PG8_BAR __builtin_amdgcn_s_barrier()
; #define PG8_SCHED __builtin_amdgcn_sched_barrier(0)
; template <class Epi, class Sched, bool ALIGN_EPI = false, bool SP2 = false>
; __device__ __forceinline__ void gemm_phase(PG8_LAS unsigned char* lds, const Gemm g, const Sched& S, const Epi& E) {
;     ...
;             PG8_WAIT_V(8); PG8_WAIT_L(0); PG8_BAR; PG8_MMA(1, 0, At, B0); PG8_MMA(1, 1, At, B1); PG8_BAR; PG8_SCHED;
;             PG8_LDB(B0, 1, 0); PG8_LDB(B1, 1, 1); PG8_SCHED; PG8_LDA(At, 1, 0); PG8_STAGE(PG8_SA(0, 1), a2 + hstepA, voffA);
;             PG8_WAIT_V(8); PG8_WAIT_L(0); PG8_BAR; PG8_MMA(0, 0, At, B0); PG8_MMA(0, 1, At, B1); PG8_BAR; PG8_SCHED;
;             PG8_LDA(At, 1, 1); PG8_STAGE(PG8_SB(1, 0), b3, voffB); PG8_STAGE(PG8_SB(1, 1), b3 + hstepB, voffB); PG8_STAGE(PG8_SA(1, 0), a3, voffA);
	s_add_i32 s29, s54, s40
	v_lshl_add_u64 v[150:151], s[22:23], 0, v[130:131]
	s_mov_b32 m0, s29
	ds_read_b128 v[192:195], v160 offset:16384
	ds_read_b128 v[196:199], v160 offset:17408
	ds_read_b128 v[200:203], v160 offset:18432
	ds_read_b128 v[204:207], v160 offset:19456
	ds_read_b128 v[208:211], v160 offset:20480
	ds_read_b128 v[212:215], v160 offset:21504
	ds_read_b128 v[216:219], v160 offset:22528
	ds_read_b128 v[220:223], v160 offset:23552
	global_load_lds_dwordx4 v[150:151], off
	s_add_i32 m0, s29, 0x2000
	s_add_u32 s30, s22, 0x40000
	v_lshl_add_u64 v[224:225], s[22:23], 0, v[134:135]
	s_addc_u32 s31, s23, 0
	s_add_i32 s29, s55, s40
	global_load_lds_dwordx4 v[224:225], off
	v_lshl_add_u64 v[226:227], s[30:31], 0, v[130:131]
	s_mov_b32 m0, s29
	v_lshl_add_u64 v[228:229], s[34:35], 0, v[132:133]
	global_load_lds_dwordx4 v[226:227], off
	s_add_i32 m0, s29, 0x2000
	v_lshl_add_u64 v[226:227], s[30:31], 0, v[134:135]
	global_load_lds_dwordx4 v[226:227], off
	s_mov_b32 m0, s43
	v_lshl_add_u64 v[226:227], s[34:35], 0, v[128:129]
	global_load_lds_dwordx4 v[226:227], off
	s_mov_b32 m0, s46
	s_nop 0
	global_load_lds_dwordx4 v[228:229], off
	s_waitcnt vmcnt(8)
	s_waitcnt lgkmcnt(0)
	s_barrier
	s_waitcnt lgkmcnt(0)
	v_mfma_f32_16x16x32_bf16 v[60:63], v[146:149], v[192:195], v[60:63]
	v_mfma_f32_16x16x32_bf16 v[56:59], v[168:171], v[192:195], v[56:59]
	v_mfma_f32_16x16x32_bf16 v[44:47], v[146:149], v[200:203], v[44:47]
	v_mfma_f32_16x16x32_bf16 v[40:43], v[168:171], v[200:203], v[40:43]
	v_mfma_f32_16x16x32_bf16 v[28:31], v[146:149], v[208:211], v[28:31]
	v_mfma_f32_16x16x32_bf16 v[24:27], v[168:171], v[208:211], v[24:27]
	v_mfma_f32_16x16x32_bf16 v[12:15], v[146:149], v[216:219], v[12:15]
	v_mfma_f32_16x16x32_bf16 v[8:11], v[168:171], v[216:219], v[8:11]
	v_mfma_f32_16x16x32_bf16 v[60:63], v[164:167], v[196:199], v[60:63]
	v_mfma_f32_16x16x32_bf16 v[56:59], v[172:175], v[196:199], v[56:59]
	v_mfma_f32_16x16x32_bf16 v[44:47], v[164:167], v[204:207], v[44:47]
	v_mfma_f32_16x16x32_bf16 v[40:43], v[172:175], v[204:207], v[40:43]
	v_mfma_f32_16x16x32_bf16 v[28:31], v[164:167], v[212:215], v[28:31]
	v_mfma_f32_16x16x32_bf16 v[24:27], v[172:175], v[212:215], v[24:27]
	v_mfma_f32_16x16x32_bf16 v[12:15], v[164:167], v[220:223], v[12:15]
	v_mfma_f32_16x16x32_bf16 v[8:11], v[172:175], v[220:223], v[8:11]
	v_mfma_f32_16x16x32_bf16 v[52:55], v[176:179], v[192:195], v[52:55]
	v_mfma_f32_16x16x32_bf16 v[48:51], v[184:187], v[192:195], v[48:51]
	v_mfma_f32_16x16x32_bf16 v[36:39], v[176:179], v[200:203], v[36:39]
	v_mfma_f32_16x16x32_bf16 v[32:35], v[184:187], v[200:203], v[32:35]
	v_mfma_f32_16x16x32_bf16 v[20:23], v[176:179], v[208:211], v[20:23]
	v_mfma_f32_16x16x32_bf16 v[16:19], v[184:187], v[208:211], v[16:19]
	v_mfma_f32_16x16x32_bf16 v[4:7], v[176:179], v[216:219], v[4:7]
	v_mfma_f32_16x16x32_bf16 v[0:3], v[184:187], v[216:219], v[0:3]
	v_mfma_f32_16x16x32_bf16 v[52:55], v[180:183], v[196:199], v[52:55]
	v_mfma_f32_16x16x32_bf16 v[48:51], v[188:191], v[196:199], v[48:51]
	v_mfma_f32_16x16x32_bf16 v[36:39], v[180:183], v[204:207], v[36:39]
	v_mfma_f32_16x16x32_bf16 v[32:35], v[188:191], v[204:207], v[32:35]
	v_mfma_f32_16x16x32_bf16 v[20:23], v[180:183], v[212:215], v[20:23]
	v_mfma_f32_16x16x32_bf16 v[16:19], v[188:191], v[212:215], v[16:19]
	v_mfma_f32_16x16x32_bf16 v[4:7], v[180:183], v[220:223], v[4:7]
	v_mfma_f32_16x16x32_bf16 v[0:3], v[188:191], v[220:223], v[0:3]
	s_barrier
.Lkmid_P7:
	s_add_i32 s29, 0, 0x18000
	v_add_u32_e32 v163, s29, v156
	s_add_i32 s33, 0, 0x1c000
	ds_read_b128 v[146:149], v163
	ds_read_b128 v[164:167], v163 offset:1024
	ds_read_b128 v[168:171], v163 offset:2048
	ds_read_b128 v[172:175], v163 offset:3072
	v_add_u32_e32 v163, s33, v156
	ds_read_b128 v[176:179], v163
	ds_read_b128 v[180:183], v163 offset:1024
	ds_read_b128 v[184:187], v163 offset:2048
	ds_read_b128 v[188:191], v163 offset:3072
	s_add_u32 s30, s34, 0x40000
	s_addc_u32 s31, s35, 0
	s_mov_b32 m0, s47
	v_lshl_add_u64 v[230:231], s[30:31], 0, v[128:129]
	ds_read_b128 v[192:195], v160 offset:32768
	ds_read_b128 v[196:199], v160 offset:33792
	ds_read_b128 v[200:203], v160 offset:34816
	ds_read_b128 v[204:207], v160 offset:35840
	ds_read_b128 v[208:211], v160 offset:36864
	ds_read_b128 v[212:215], v160 offset:37888
	ds_read_b128 v[216:219], v160 offset:38912
	ds_read_b128 v[220:223], v160 offset:39936
	global_load_lds_dwordx4 v[230:231], off
	s_mov_b32 m0, s48
	v_lshl_add_u64 v[230:231], s[30:31], 0, v[132:133]
	global_load_lds_dwordx4 v[230:231], off
	s_waitcnt vmcnt(8)
	s_waitcnt lgkmcnt(0)
	s_barrier
; #define PG8_STAGE(bufoff, gbase, voff) do { _Pragma("unroll") for (int _i = 0; _i < 2; ++_i) \
;         __builtin_amdgcn_global_load_lds((const unsigned*)((const char*)(gbase) + (voff)[_i]), (PG8_LAS unsigned*)(lds + (bufoff) + ldsw + _i * 8192), 16, 0, PG8_LOAD_AUX); } while (0)
; #define PG8_LDA(dst, b, h) do { _Pragma("unroll") for (int m = 0; m < 4; ++m) _Pragma("unroll") for (int k = 0; k < 2; ++k) dst[m][k] = *(const PG8_LAS bf16x8*)(lds + PG8_SA(b, h) + aoff + m * 2048 + k * 1024); } while (0)
; #define PG8_MMA(ai, bj, At, Bt) do { __builtin_amdgcn_s_setprio(1); _Pragma("unroll") for (int m = 0; m < 4; ++m) _Pragma("unroll") for (int n = 0; n < 2; ++n) _Pragma("unroll") for (int k = 0; k < 2; ++k) \
;         acc[ai][bj][m][n] = __builtin_amdgcn_mfma_f32_16x16x32_bf16(Bt[n][k], At[m][k], acc[ai][bj][m][n], 0, 0, 0); __builtin_amdgcn_s_setprio(0); } while (0)
; #define PG8_WAIT_V(n) asm volatile("s_waitcnt vmcnt(" #n ")" ::: "memory")
; #define PG8_WAIT_L(n) asm volatile("s_waitcnt lgkmcnt(" #n ")" ::: "memory")
; #define PG8_BAR __builtin_amdgcn_s_barrier()
; #define PG8_SCHED __builtin_amdgcn_sched_barrier(0)
; __device__ __forceinline__ float rstd_from_slots(const float* slots, int row, int fq) {
;     const f32x4 s4 = *(const f32x4*)(slots + (size_t)row * 16 + 4 * fq);
;     float s = (s4[0] + s4[1]) + (s4[2] + s4[3]);
; template <class Epi, class Sched, bool ALIGN_EPI = false, bool SP2 = false>
; __device__ __forceinline__ void gemm_phase(PG8_LAS unsigned char* lds, const Gemm g, const Sched& S, const Epi& E) {
;     ...
;             PG8_WAIT_V(8); PG8_WAIT_L(0); PG8_BAR; PG8_MMA(0, 0, At, B0); PG8_MMA(0, 1, At, B1); PG8_BAR; PG8_SCHED;
;             PG8_LDA(At, 1, 1); PG8_STAGE(PG8_SB(1, 0), b3, voffB); PG8_STAGE(PG8_SB(1, 1), b3 + hstepB, voffB); PG8_STAGE(PG8_SA(1, 0), a3, voffA);
;             PG8_WAIT_V(8); PG8_WAIT_L(0); PG8_BAR; PG8_MMA(1, 0, At, B0); PG8_MMA(1, 1, At, B1); PG8_BAR; PG8_SCHED;
	s_waitcnt lgkmcnt(0)
	v_mfma_f32_16x16x32_bf16 v[124:127], v[146:149], v[192:195], v[124:127]
	v_mfma_f32_16x16x32_bf16 v[120:123], v[168:171], v[192:195], v[120:123]
	v_mfma_f32_16x16x32_bf16 v[108:111], v[146:149], v[200:203], v[108:111]
	v_mfma_f32_16x16x32_bf16 v[104:107], v[168:171], v[200:203], v[104:107]
	v_mfma_f32_16x16x32_bf16 v[92:95], v[146:149], v[208:211], v[92:95]
	v_mfma_f32_16x16x32_bf16 v[88:91], v[168:171], v[208:211], v[88:91]
	v_mfma_f32_16x16x32_bf16 v[76:79], v[146:149], v[216:219], v[76:79]
	v_mfma_f32_16x16x32_bf16 v[72:75], v[168:171], v[216:219], v[72:75]
	v_mfma_f32_16x16x32_bf16 v[124:127], v[164:167], v[196:199], v[124:127]
	v_mfma_f32_16x16x32_bf16 v[120:123], v[172:175], v[196:199], v[120:123]
	v_mfma_f32_16x16x32_bf16 v[108:111], v[164:167], v[204:207], v[108:111]
	v_mfma_f32_16x16x32_bf16 v[104:107], v[172:175], v[204:207], v[104:107]
	v_mfma_f32_16x16x32_bf16 v[92:95], v[164:167], v[212:215], v[92:95]
	v_mfma_f32_16x16x32_bf16 v[88:91], v[172:175], v[212:215], v[88:91]
	v_mfma_f32_16x16x32_bf16 v[76:79], v[164:167], v[220:223], v[76:79]
	v_mfma_f32_16x16x32_bf16 v[72:75], v[172:175], v[220:223], v[72:75]
	v_mfma_f32_16x16x32_bf16 v[116:119], v[176:179], v[192:195], v[116:119]
	v_mfma_f32_16x16x32_bf16 v[112:115], v[184:187], v[192:195], v[112:115]
	v_mfma_f32_16x16x32_bf16 v[100:103], v[176:179], v[200:203], v[100:103]
	v_mfma_f32_16x16x32_bf16 v[96:99], v[184:187], v[200:203], v[96:99]
	v_mfma_f32_16x16x32_bf16 v[84:87], v[176:179], v[208:211], v[84:87]
	v_mfma_f32_16x16x32_bf16 v[80:83], v[184:187], v[208:211], v[80:83]
	v_mfma_f32_16x16x32_bf16 v[68:71], v[176:179], v[216:219], v[68:71]
	v_mfma_f32_16x16x32_bf16 v[64:67], v[184:187], v[216:219], v[64:67]
	v_mfma_f32_16x16x32_bf16 v[116:119], v[180:183], v[196:199], v[116:119]
	v_mfma_f32_16x16x32_bf16 v[112:115], v[188:191], v[196:199], v[112:115]
	v_mfma_f32_16x16x32_bf16 v[100:103], v[180:183], v[204:207], v[100:103]
	v_mfma_f32_16x16x32_bf16 v[96:99], v[188:191], v[204:207], v[96:99]
	v_mfma_f32_16x16x32_bf16 v[84:87], v[180:183], v[212:215], v[84:87]
	v_mfma_f32_16x16x32_bf16 v[80:83], v[188:191], v[212:215], v[80:83]
	v_mfma_f32_16x16x32_bf16 v[68:71], v[180:183], v[220:223], v[68:71]
	v_mfma_f32_16x16x32_bf16 v[64:67], v[188:191], v[220:223], v[64:67]
	s_barrier
	s_add_i32 s29, s29, s40
	v_lshl_add_u64 v[150:151], v[150:151], 0, s[8:9]
	s_mov_b32 m0, s29
	ds_read_b128 v[192:195], v160 offset:49152
	ds_read_b128 v[196:199], v160 offset:50176
	ds_read_b128 v[200:203], v160 offset:51200
	ds_read_b128 v[204:207], v160 offset:52224
	ds_read_b128 v[208:211], v160 offset:53248
	ds_read_b128 v[212:215], v160 offset:54272
	ds_read_b128 v[216:219], v160 offset:55296
	ds_read_b128 v[220:223], v160 offset:56320
	global_load_lds_dwordx4 v[150:151], off
	s_add_i32 m0, s29, 0x2000
	s_add_u32 s22, s22, 0x40080
	v_lshl_add_u64 v[150:151], v[224:225], 0, s[8:9]
	s_addc_u32 s23, s23, 0
	s_add_i32 s29, s33, s40
	global_load_lds_dwordx4 v[150:151], off
	s_mov_b32 m0, s29
	v_lshl_add_u64 v[150:151], s[22:23], 0, v[130:131]
	global_load_lds_dwordx4 v[150:151], off
	s_add_i32 m0, s29, 0x2000
	v_lshl_add_u64 v[150:151], s[22:23], 0, v[134:135]
	global_load_lds_dwordx4 v[150:151], off
	s_mov_b32 m0, s51
	v_lshl_add_u64 v[150:151], v[226:227], 0, s[8:9]
	global_load_lds_dwordx4 v[150:151], off
	s_mov_b32 m0, s52
	v_lshl_add_u64 v[150:151], v[228:229], 0, s[8:9]
	global_load_lds_dwordx4 v[150:151], off
	s_waitcnt vmcnt(8)
	s_waitcnt lgkmcnt(0)
	s_barrier
	s_waitcnt lgkmcnt(0)
	v_mfma_f32_16x16x32_bf16 v[60:63], v[146:149], v[192:195], v[60:63]
	v_mfma_f32_16x16x32_bf16 v[56:59], v[168:171], v[192:195], v[56:59]
	v_mfma_f32_16x16x32_bf16 v[44:47], v[146:149], v[200:203], v[44:47]
	v_mfma_f32_16x16x32_bf16 v[40:43], v[168:171], v[200:203], v[40:43]
	v_mfma_f32_16x16x32_bf16 v[28:31], v[146:149], v[208:211], v[28:31]
	v_mfma_f32_16x16x32_bf16 v[24:27], v[168:171], v[208:211], v[24:27]
	v_mfma_f32_16x16x32_bf16 v[12:15], v[146:149], v[216:219], v[12:15]
	v_mfma_f32_16x16x32_bf16 v[8:11], v[168:171], v[216:219], v[8:11]
	v_mfma_f32_16x16x32_bf16 v[60:63], v[164:167], v[196:199], v[60:63]
	v_mfma_f32_16x16x32_bf16 v[56:59], v[172:175], v[196:199], v[56:59]
	v_mfma_f32_16x16x32_bf16 v[44:47], v[164:167], v[204:207], v[44:47]
	v_mfma_f32_16x16x32_bf16 v[40:43], v[172:175], v[204:207], v[40:43]
	v_mfma_f32_16x16x32_bf16 v[28:31], v[164:167], v[212:215], v[28:31]
	v_mfma_f32_16x16x32_bf16 v[24:27], v[172:175], v[212:215], v[24:27]
	v_mfma_f32_16x16x32_bf16 v[12:15], v[164:167], v[220:223], v[12:15]
	v_mfma_f32_16x16x32_bf16 v[8:11], v[172:175], v[220:223], v[8:11]
	v_mfma_f32_16x16x32_bf16 v[52:55], v[176:179], v[192:195], v[52:55]
	v_mfma_f32_16x16x32_bf16 v[48:51], v[184:187], v[192:195], v[48:51]
	v_mfma_f32_16x16x32_bf16 v[36:39], v[176:179], v[200:203], v[36:39]
	v_mfma_f32_16x16x32_bf16 v[32:35], v[184:187], v[200:203], v[32:35]
	v_mfma_f32_16x16x32_bf16 v[20:23], v[176:179], v[208:211], v[20:23]
	v_mfma_f32_16x16x32_bf16 v[16:19], v[184:187], v[208:211], v[16:19]
	v_mfma_f32_16x16x32_bf16 v[4:7], v[176:179], v[216:219], v[4:7]
	v_mfma_f32_16x16x32_bf16 v[0:3], v[184:187], v[216:219], v[0:3]
	v_mfma_f32_16x16x32_bf16 v[52:55], v[180:183], v[196:199], v[52:55]
	v_mfma_f32_16x16x32_bf16 v[48:51], v[188:191], v[196:199], v[48:51]
	v_mfma_f32_16x16x32_bf16 v[36:39], v[180:183], v[204:207], v[36:39]
	v_mfma_f32_16x16x32_bf16 v[32:35], v[188:191], v[204:207], v[32:35]
	v_mfma_f32_16x16x32_bf16 v[20:23], v[180:183], v[212:215], v[20:23]
	v_mfma_f32_16x16x32_bf16 v[16:19], v[188:191], v[212:215], v[16:19]
	v_mfma_f32_16x16x32_bf16 v[4:7], v[180:183], v[220:223], v[4:7]
	v_mfma_f32_16x16x32_bf16 v[0:3], v[188:191], v[220:223], v[0:3]
	s_barrier
	s_add_i32 s28, s28, 2
	s_add_u32 s20, s20, 0x100
	s_addc_u32 s21, s21, 0
	s_add_u32 s26, s26, 0x100
	s_addc_u32 s27, s27, 0
	s_cmp_gt_u32 s28, 13
	s_cbranch_scc0 .LBB0_672
	v_lshl_add_u32 v204, s0, 8, v152
	v_ashrrev_i32_e32 v205, 31, v204
	v_lshlrev_b64 v[204:205], 6, v[204:205]
	v_lshl_add_u64 v[204:205], v[136:137], 0, v[204:205]
	v_add_co_u32_e32 v206, vcc, 0x2000, v204
	s_nop 1
	v_addc_co_u32_e32 v207, vcc, 0, v205, vcc
	global_load_dwordx4 v[172:175], v[204:205], off
	global_load_dwordx4 v[176:179], v[204:205], off offset:1024
	global_load_dwordx4 v[180:183], v[204:205], off offset:2048
	global_load_dwordx4 v[184:187], v[204:205], off offset:3072
	global_load_dwordx4 v[188:191], v[206:207], off
	global_load_dwordx4 v[192:195], v[206:207], off offset:1024
	global_load_dwordx4 v[196:199], v[206:207], off offset:2048
	global_load_dwordx4 v[200:203], v[206:207], off offset:3072
	s_and_b64 vcc, exec, s[12:13]
	s_cbranch_vccz .LBB0_675
	s_barrier

; #define PG8_STAGE(bufoff, gbase, voff) do { _Pragma("unroll") for (int _i = 0; _i < 2; ++_i) \
;         __builtin_amdgcn_global_load_lds((const unsigned*)((const char*)(gbase) + (voff)[_i]), (PG8_LAS unsigned*)(lds + (bufoff) + ldsw + _i * 8192), 16, 0, PG8_LOAD_AUX); } while (0)
; #define PG8_LDA(dst, b, h) do { _Pragma("unroll") for (int m = 0; m < 4; ++m) _Pragma("unroll") for (int k = 0; k < 2; ++k) dst[m][k] = *(const PG8_LAS bf16x8*)(lds + PG8_SA(b, h) + aoff + m * 2048 + k * 1024); } while (0)
; #define PG8_LDB(dst, b, h) do { _Pragma("unroll") for (int n = 0; n < 2; ++n) _Pragma("unroll") for (int k = 0; k < 2; ++k) dst[n][k] = *(const PG8_LAS bf16x8*)(lds + PG8_SB(b, h) + boff + n * 2048 + k * 1024); } while (0)
; #define PG8_WAIT_V(n) asm volatile("s_waitcnt vmcnt(" #n ")" ::: "memory")
; #define PG8_WAIT_L(n) asm volatile("s_waitcnt lgkmcnt(" #n ")" ::: "memory")
; #define PG8_BAR __builtin_amdgcn_s_barrier()
; #define PG8_SCHED __builtin_amdgcn_sched_barrier(0)
; template <class Epi, class Sched, bool ALIGN_EPI = false, bool SP2 = false>
; __device__ __forceinline__ void gemm_phase(PG8_LAS unsigned char* lds, const Gemm g, const Sched& S, const Epi& E) {
;     ...
;         const bool has_next = S.next(ui + 1, nxt);
;         const char* nA = has_next ? (const char*)g.A + (size_t)nxt.pm * tstepA + (size_t)nxt.pn * apn : cA; const char* nB = has_next ? (const char*)g.Bt + (size_t)nxt.pn * tstepB : cB;
;         for (int t = 0; t < nt; t += 2) {
;             const bool last = (t == nt - 2);
;             const char* a1 = cA + (size_t)(t + 1) * kstep;
;             const char* a2 = last ? nA : cA + (size_t)(t + 2) * kstep; const char* b2 = last ? nB : cB + (size_t)(t + 2) * kstep;
;             const char* a3 = a2 + kstep; const char* b3 = b2 + kstep;
;             if (last && has_next) S.a_ready(nxt);
;             if constexpr (SP2) {
;             PG8_LDB(B0, 0, 0); PG8_LDB(B1, 0, 1); PG8_SCHED; PG8_LDA(At, 0, 0); PG8_STAGE(PG8_SA(1, 1), a1 + hstepA, voffA);
;             PG8_WAIT_V(8); PG8_WAIT_L(0); PG8_BAR; PG8_MMA(0, 0, At, B0); PG8_MMA(0, 1, At, B1); PG8_BAR; PG8_SCHED;
;             PG8_LDA(At, 0, 1); PG8_STAGE(PG8_SB(0, 0), b2, voffB); PG8_STAGE(PG8_SB(0, 1), b2 + hstepB, voffB); PG8_STAGE(PG8_SA(0, 0), a2, voffA);
;             PG8_WAIT_V(8); PG8_WAIT_L(0); PG8_BAR; PG8_MMA(1, 0, At, B0); PG8_MMA(1, 1, At, B1); PG8_BAR; PG8_SCHED;
.LBB0_756:
	s_add_u32 s0, s0, 0xb0080
	s_addc_u32 s1, s1, 0
	s_add_u32 s25, s20, 0x100
	s_addc_u32 s26, s21, 0
	s_mov_b32 s27, -2
	s_waitcnt lgkmcnt(0)
	ds_read_b128 v[146:149], v157
	ds_read_b128 v[162:165], v157 offset:1024
	ds_read_b128 v[166:169], v157 offset:2048
	ds_read_b128 v[170:173], v157 offset:3072
	ds_read_b128 v[174:177], v158
	ds_read_b128 v[178:181], v158 offset:1024
	ds_read_b128 v[182:185], v158 offset:2048
	ds_read_b128 v[186:189], v158 offset:3072
	s_add_u32 s20, s0, 0xfff50080
	s_addc_u32 s21, s1, -1
	s_cmp_eq_u32 s27, 40
	s_cselect_b32 s23, s9, s21
	s_cselect_b32 s22, s8, s20
	s_cselect_b32 s21, s41, s26
	s_cselect_b32 s20, s40, s25
	v_lshl_add_u64 v[222:223], s[0:1], 0, v[138:139]
	s_add_i32 m0, s35, 0xc000
	ds_read_b128 v[190:193], v159
	ds_read_b128 v[194:197], v159 offset:1024
	ds_read_b128 v[198:201], v159 offset:2048
	ds_read_b128 v[202:205], v159 offset:3072
	ds_read_b128 v[206:209], v159 offset:4096
	ds_read_b128 v[210:213], v159 offset:5120
	ds_read_b128 v[214:217], v159 offset:6144
	ds_read_b128 v[218:221], v159 offset:7168
	global_load_lds_dwordx4 v[222:223], off
	s_add_i32 m0, s35, 0xe000
	v_lshl_add_u64 v[222:223], s[0:1], 0, v[140:141]
	global_load_lds_dwordx4 v[222:223], off
	s_waitcnt vmcnt(8)
	s_waitcnt lgkmcnt(0)
	s_barrier
	s_waitcnt lgkmcnt(0)
	v_mfma_f32_16x16x32_bf16 v[124:127], v[146:149], v[190:193], 0
	v_mfma_f32_16x16x32_bf16 v[120:123], v[166:169], v[190:193], 0
	v_mfma_f32_16x16x32_bf16 v[108:111], v[146:149], v[198:201], 0
	v_mfma_f32_16x16x32_bf16 v[104:107], v[166:169], v[198:201], 0
	v_mfma_f32_16x16x32_bf16 v[92:95], v[146:149], v[206:209], 0
	v_mfma_f32_16x16x32_bf16 v[88:91], v[166:169], v[206:209], 0
	v_mfma_f32_16x16x32_bf16 v[76:79], v[146:149], v[214:217], 0
	v_mfma_f32_16x16x32_bf16 v[72:75], v[166:169], v[214:217], 0
	v_mfma_f32_16x16x32_bf16 v[124:127], v[162:165], v[194:197], v[124:127]
	v_mfma_f32_16x16x32_bf16 v[120:123], v[170:173], v[194:197], v[120:123]
	v_mfma_f32_16x16x32_bf16 v[108:111], v[162:165], v[202:205], v[108:111]
	v_mfma_f32_16x16x32_bf16 v[104:107], v[170:173], v[202:205], v[104:107]
	v_mfma_f32_16x16x32_bf16 v[92:95], v[162:165], v[210:213], v[92:95]
	v_mfma_f32_16x16x32_bf16 v[88:91], v[170:173], v[210:213], v[88:91]
	v_mfma_f32_16x16x32_bf16 v[76:79], v[162:165], v[218:221], v[76:79]
	v_mfma_f32_16x16x32_bf16 v[72:75], v[170:173], v[218:221], v[72:75]
	v_mfma_f32_16x16x32_bf16 v[116:119], v[174:177], v[190:193], 0
	v_mfma_f32_16x16x32_bf16 v[112:115], v[182:185], v[190:193], 0
	v_mfma_f32_16x16x32_bf16 v[100:103], v[174:177], v[198:201], 0
	v_mfma_f32_16x16x32_bf16 v[96:99], v[182:185], v[198:201], 0
	v_mfma_f32_16x16x32_bf16 v[84:87], v[174:177], v[206:209], 0
	v_mfma_f32_16x16x32_bf16 v[80:83], v[182:185], v[206:209], 0
	v_mfma_f32_16x16x32_bf16 v[68:71], v[174:177], v[214:217], 0
	v_mfma_f32_16x16x32_bf16 v[64:67], v[182:185], v[214:217], 0
	v_mfma_f32_16x16x32_bf16 v[116:119], v[178:181], v[194:197], v[116:119]
	v_mfma_f32_16x16x32_bf16 v[112:115], v[186:189], v[194:197], v[112:115]
	v_mfma_f32_16x16x32_bf16 v[100:103], v[178:181], v[202:205], v[100:103]
	v_mfma_f32_16x16x32_bf16 v[96:99], v[186:189], v[202:205], v[96:99]
	v_mfma_f32_16x16x32_bf16 v[84:87], v[178:181], v[210:213], v[84:87]
	v_mfma_f32_16x16x32_bf16 v[80:83], v[186:189], v[210:213], v[80:83]
	v_mfma_f32_16x16x32_bf16 v[68:71], v[178:181], v[218:221], v[68:71]
	v_mfma_f32_16x16x32_bf16 v[64:67], v[186:189], v[218:221], v[64:67]
	s_barrier
	s_add_i32 s28, s55, s34
	v_lshl_add_u64 v[222:223], s[20:21], 0, v[130:131]
	s_mov_b32 m0, s28
	ds_read_b128 v[190:193], v159 offset:16384
	ds_read_b128 v[194:197], v159 offset:17408
	ds_read_b128 v[198:201], v159 offset:18432
	ds_read_b128 v[202:205], v159 offset:19456
	ds_read_b128 v[206:209], v159 offset:20480
	ds_read_b128 v[210:213], v159 offset:21504
	ds_read_b128 v[214:217], v159 offset:22528
	ds_read_b128 v[218:221], v159 offset:23552
	global_load_lds_dwordx4 v[222:223], off
	s_add_i32 m0, s28, 0x2000
	s_add_u32 s28, s20, 0x2c000
	v_lshl_add_u64 v[224:225], s[20:21], 0, v[134:135]
	s_addc_u32 s29, s21, 0
	s_add_i32 s30, s56, s34
	global_load_lds_dwordx4 v[224:225], off
	v_lshl_add_u64 v[226:227], s[28:29], 0, v[130:131]
	s_mov_b32 m0, s30
	v_lshl_add_u64 v[228:229], s[22:23], 0, v[132:133]
	global_load_lds_dwordx4 v[226:227], off
	s_add_i32 m0, s30, 0x2000
	v_lshl_add_u64 v[226:227], s[28:29], 0, v[134:135]
	global_load_lds_dwordx4 v[226:227], off
	s_mov_b32 m0, s35
	v_lshl_add_u64 v[226:227], s[22:23], 0, v[128:129]
	global_load_lds_dwordx4 v[226:227], off
	s_mov_b32 m0, s42
	s_nop 0
	global_load_lds_dwordx4 v[228:229], off
	s_waitcnt vmcnt(8)
	s_waitcnt lgkmcnt(0)
	s_barrier
	s_waitcnt lgkmcnt(0)
	v_mfma_f32_16x16x32_bf16 v[60:63], v[146:149], v[190:193], 0
	v_mfma_f32_16x16x32_bf16 v[56:59], v[166:169], v[190:193], 0
	v_mfma_f32_16x16x32_bf16 v[44:47], v[146:149], v[198:201], 0
	v_mfma_f32_16x16x32_bf16 v[40:43], v[166:169], v[198:201], 0
	v_mfma_f32_16x16x32_bf16 v[28:31], v[146:149], v[206:209], 0
	v_mfma_f32_16x16x32_bf16 v[24:27], v[166:169], v[206:209], 0
	v_mfma_f32_16x16x32_bf16 v[12:15], v[146:149], v[214:217], 0
	v_mfma_f32_16x16x32_bf16 v[8:11], v[166:169], v[214:217], 0
	v_mfma_f32_16x16x32_bf16 v[60:63], v[162:165], v[194:197], v[60:63]
	v_mfma_f32_16x16x32_bf16 v[56:59], v[170:173], v[194:197], v[56:59]
	v_mfma_f32_16x16x32_bf16 v[44:47], v[162:165], v[202:205], v[44:47]
	v_mfma_f32_16x16x32_bf16 v[40:43], v[170:173], v[202:205], v[40:43]
	v_mfma_f32_16x16x32_bf16 v[28:31], v[162:165], v[210:213], v[28:31]
	v_mfma_f32_16x16x32_bf16 v[24:27], v[170:173], v[210:213], v[24:27]
	v_mfma_f32_16x16x32_bf16 v[12:15], v[162:165], v[218:221], v[12:15]
	v_mfma_f32_16x16x32_bf16 v[8:11], v[170:173], v[218:221], v[8:11]
	v_mfma_f32_16x16x32_bf16 v[52:55], v[174:177], v[190:193], 0
	v_mfma_f32_16x16x32_bf16 v[48:51], v[182:185], v[190:193], 0
	v_mfma_f32_16x16x32_bf16 v[36:39], v[174:177], v[198:201], 0
	v_mfma_f32_16x16x32_bf16 v[32:35], v[182:185], v[198:201], 0
	v_mfma_f32_16x16x32_bf16 v[20:23], v[174:177], v[206:209], 0
	v_mfma_f32_16x16x32_bf16 v[16:19], v[182:185], v[206:209], 0
	v_mfma_f32_16x16x32_bf16 v[4:7], v[174:177], v[214:217], 0
	v_mfma_f32_16x16x32_bf16 v[0:3], v[182:185], v[214:217], 0
	v_mfma_f32_16x16x32_bf16 v[52:55], v[178:181], v[194:197], v[52:55]
	v_mfma_f32_16x16x32_bf16 v[48:51], v[186:189], v[194:197], v[48:51]
	v_mfma_f32_16x16x32_bf16 v[36:39], v[178:181], v[202:205], v[36:39]
	v_mfma_f32_16x16x32_bf16 v[32:35], v[186:189], v[202:205], v[32:35]
	v_mfma_f32_16x16x32_bf16 v[20:23], v[178:181], v[210:213], v[20:23]
	v_mfma_f32_16x16x32_bf16 v[16:19], v[186:189], v[210:213], v[16:19]
	v_mfma_f32_16x16x32_bf16 v[4:7], v[178:181], v[218:221], v[4:7]
	v_mfma_f32_16x16x32_bf16 v[0:3], v[186:189], v[218:221], v[0:3]
	s_barrier
	s_branch .Lkmid_P8
; #define PG8_STAGE(bufoff, gbase, voff) do { _Pragma("unroll") for (int _i = 0; _i < 2; ++_i) \
;         __builtin_amdgcn_global_load_lds((const unsigned*)((const char*)(gbase) + (voff)[_i]), (PG8_LAS unsigned*)(lds + (bufoff) + ldsw + _i * 8192), 16, 0, PG8_LOAD_AUX); } while (0)
; #define PG8_LDA(dst, b, h) do { _Pragma("unroll") for (int m = 0; m < 4; ++m) _Pragma("unroll") for (int k = 0; k < 2; ++k) dst[m][k] = *(const PG8_LAS bf16x8*)(lds + PG8_SA(b, h) + aoff + m * 2048 + k * 1024); } while (0)
; #define PG8_LDB(dst, b, h) do { _Pragma("unroll") for (int n = 0; n < 2; ++n) _Pragma("unroll") for (int k = 0; k < 2; ++k) dst[n][k] = *(const PG8_LAS bf16x8*)(lds + PG8_SB(b, h) + boff + n * 2048 + k * 1024); } while (0)
; #define PG8_MMA(ai, bj, At, Bt) do { __builtin_amdgcn_s_setprio(1); _Pragma("unroll") for (int m = 0; m < 4; ++m) _Pragma("unroll") for (int n = 0; n < 2; ++n) _Pragma("unroll") for (int k = 0; k < 2; ++k) \
;         acc[ai][bj][m][n] = __builtin_amdgcn_mfma_f32_16x16x32_bf16(Bt[n][k], At[m][k], acc[ai][bj][m][n], 0, 0, 0); __builtin_amdgcn_s_setprio(0); } while (0)
; #define PG8_WAIT_V(n) asm volatile("s_waitcnt vmcnt(" #n ")" ::: "memory")
; #define PG8_WAIT_L(n) asm volatile("s_waitcnt lgkmcnt(" #n ")" ::: "memory")
; #define PG8_BAR __builtin_amdgcn_s_barrier()
; #define PG8_SCHED __builtin_amdgcn_sched_barrier(0)
; template <class Epi, class Sched, bool ALIGN_EPI = false, bool SP2 = false>
; __device__ __forceinline__ void gemm_phase(PG8_LAS unsigned char* lds, const Gemm g, const Sched& S, const Epi& E) {
;     ...
;             PG8_LDB(B0, 0, 0); PG8_LDB(B1, 0, 1); PG8_SCHED; PG8_LDA(At, 0, 0); PG8_STAGE(PG8_SA(1, 1), a1 + hstepA, voffA);
;             PG8_WAIT_V(8); PG8_WAIT_L(0); PG8_BAR; PG8_MMA(0, 0, At, B0); PG8_MMA(0, 1, At, B1); PG8_BAR; PG8_SCHED;
;             PG8_LDA(At, 0, 1); PG8_STAGE(PG8_SB(0, 0), b2, voffB); PG8_STAGE(PG8_SB(0, 1), b2 + hstepB, voffB); PG8_STAGE(PG8_SA(0, 0), a2, voffA);
;             PG8_WAIT_V(8); PG8_WAIT_L(0); PG8_BAR; PG8_MMA(1, 0, At, B0); PG8_MMA(1, 1, At, B1); PG8_BAR; PG8_SCHED;
.LBB0_757:
	ds_read_b128 v[146:149], v157
	ds_read_b128 v[162:165], v157 offset:1024
	ds_read_b128 v[166:169], v157 offset:2048
	ds_read_b128 v[170:173], v157 offset:3072
	ds_read_b128 v[174:177], v158
	ds_read_b128 v[178:181], v158 offset:1024
	ds_read_b128 v[182:185], v158 offset:2048
	ds_read_b128 v[186:189], v158 offset:3072
	s_add_u32 s20, s0, 0xfff50080
	s_addc_u32 s21, s1, -1
	s_cmp_eq_u32 s27, 40
	s_cselect_b32 s23, s9, s21
	s_cselect_b32 s22, s8, s20
	s_cselect_b32 s21, s41, s26
	s_cselect_b32 s20, s40, s25
	v_lshl_add_u64 v[222:223], s[0:1], 0, v[138:139]
	s_add_i32 m0, s35, 0xc000
	ds_read_b128 v[190:193], v159
	ds_read_b128 v[194:197], v159 offset:1024
	ds_read_b128 v[198:201], v159 offset:2048
	ds_read_b128 v[202:205], v159 offset:3072
	ds_read_b128 v[206:209], v159 offset:4096
	ds_read_b128 v[210:213], v159 offset:5120
	ds_read_b128 v[214:217], v159 offset:6144
	ds_read_b128 v[218:221], v159 offset:7168
	global_load_lds_dwordx4 v[222:223], off
	s_add_i32 m0, s35, 0xe000
	v_lshl_add_u64 v[222:223], s[0:1], 0, v[140:141]
	global_load_lds_dwordx4 v[222:223], off
	s_waitcnt vmcnt(8)
	s_waitcnt lgkmcnt(0)
	s_barrier
	s_waitcnt lgkmcnt(0)
	v_mfma_f32_16x16x32_bf16 v[124:127], v[146:149], v[190:193], v[124:127]
	v_mfma_f32_16x16x32_bf16 v[120:123], v[166:169], v[190:193], v[120:123]
	v_mfma_f32_16x16x32_bf16 v[108:111], v[146:149], v[198:201], v[108:111]
	v_mfma_f32_16x16x32_bf16 v[104:107], v[166:169], v[198:201], v[104:107]
	v_mfma_f32_16x16x32_bf16 v[92:95], v[146:149], v[206:209], v[92:95]
	v_mfma_f32_16x16x32_bf16 v[88:91], v[166:169], v[206:209], v[88:91]
	v_mfma_f32_16x16x32_bf16 v[76:79], v[146:149], v[214:217], v[76:79]
	v_mfma_f32_16x16x32_bf16 v[72:75], v[166:169], v[214:217], v[72:75]
	v_mfma_f32_16x16x32_bf16 v[124:127], v[162:165], v[194:197], v[124:127]
	v_mfma_f32_16x16x32_bf16 v[120:123], v[170:173], v[194:197], v[120:123]
	v_mfma_f32_16x16x32_bf16 v[108:111], v[162:165], v[202:205], v[108:111]
	v_mfma_f32_16x16x32_bf16 v[104:107], v[170:173], v[202:205], v[104:107]
	v_mfma_f32_16x16x32_bf16 v[92:95], v[162:165], v[210:213], v[92:95]
	v_mfma_f32_16x16x32_bf16 v[88:91], v[170:173], v[210:213], v[88:91]
	v_mfma_f32_16x16x32_bf16 v[76:79], v[162:165], v[218:221], v[76:79]
	v_mfma_f32_16x16x32_bf16 v[72:75], v[170:173], v[218:221], v[72:75]
	v_mfma_f32_16x16x32_bf16 v[116:119], v[174:177], v[190:193], v[116:119]
	v_mfma_f32_16x16x32_bf16 v[112:115], v[182:185], v[190:193], v[112:115]
	v_mfma_f32_16x16x32_bf16 v[100:103], v[174:177], v[198:201], v[100:103]
	v_mfma_f32_16x16x32_bf16 v[96:99], v[182:185], v[198:201], v[96:99]
	v_mfma_f32_16x16x32_bf16 v[84:87], v[174:177], v[206:209], v[84:87]
	v_mfma_f32_16x16x32_bf16 v[80:83], v[182:185], v[206:209], v[80:83]
	v_mfma_f32_16x16x32_bf16 v[68:71], v[174:177], v[214:217], v[68:71]
	v_mfma_f32_16x16x32_bf16 v[64:67], v[182:185], v[214:217], v[64:67]
	v_mfma_f32_16x16x32_bf16 v[116:119], v[178:181], v[194:197], v[116:119]
	v_mfma_f32_16x16x32_bf16 v[112:115], v[186:189], v[194:197], v[112:115]
	v_mfma_f32_16x16x32_bf16 v[100:103], v[178:181], v[202:205], v[100:103]
	v_mfma_f32_16x16x32_bf16 v[96:99], v[186:189], v[202:205], v[96:99]
	v_mfma_f32_16x16x32_bf16 v[84:87], v[178:181], v[210:213], v[84:87]
	v_mfma_f32_16x16x32_bf16 v[80:83], v[186:189], v[210:213], v[80:83]
	v_mfma_f32_16x16x32_bf16 v[68:71], v[178:181], v[218:221], v[68:71]
	v_mfma_f32_16x16x32_bf16 v[64:67], v[186:189], v[218:221], v[64:67]
	s_barrier
	s_add_i32 s28, s55, s34
	v_lshl_add_u64 v[222:223], s[20:21], 0, v[130:131]
	s_mov_b32 m0, s28
	ds_read_b128 v[190:193], v159 offset:16384
	ds_read_b128 v[194:197], v159 offset:17408
	ds_read_b128 v[198:201], v159 offset:18432
	ds_read_b128 v[202:205], v159 offset:19456
	ds_read_b128 v[206:209], v159 offset:20480
	ds_read_b128 v[210:213], v159 offset:21504
	ds_read_b128 v[214:217], v159 offset:22528
	ds_read_b128 v[218:221], v159 offset:23552
	global_load_lds_dwordx4 v[222:223], off
	s_add_i32 m0, s28, 0x2000
	s_add_u32 s28, s20, 0x2c000
	v_lshl_add_u64 v[224:225], s[20:21], 0, v[134:135]
	s_addc_u32 s29, s21, 0
	s_add_i32 s30, s56, s34
	global_load_lds_dwordx4 v[224:225], off
	v_lshl_add_u64 v[226:227], s[28:29], 0, v[130:131]
	s_mov_b32 m0, s30
	v_lshl_add_u64 v[228:229], s[22:23], 0, v[132:133]
	global_load_lds_dwordx4 v[226:227], off
	s_add_i32 m0, s30, 0x2000
	v_lshl_add_u64 v[226:227], s[28:29], 0, v[134:135]
	global_load_lds_dwordx4 v[226:227], off
	s_mov_b32 m0, s35
	v_lshl_add_u64 v[226:227], s[22:23], 0, v[128:129]
	global_load_lds_dwordx4 v[226:227], off
	s_mov_b32 m0, s42
	s_nop 0
	global_load_lds_dwordx4 v[228:229], off
	s_waitcnt vmcnt(8)
	s_waitcnt lgkmcnt(0)
	s_barrier
	s_waitcnt lgkmcnt(0)
	v_mfma_f32_16x16x32_bf16 v[60:63], v[146:149], v[190:193], v[60:63]
	v_mfma_f32_16x16x32_bf16 v[56:59], v[166:169], v[190:193], v[56:59]
	v_mfma_f32_16x16x32_bf16 v[44:47], v[146:149], v[198:201], v[44:47]
	v_mfma_f32_16x16x32_bf16 v[40:43], v[166:169], v[198:201], v[40:43]
	v_mfma_f32_16x16x32_bf16 v[28:31], v[146:149], v[206:209], v[28:31]
	v_mfma_f32_16x16x32_bf16 v[24:27], v[166:169], v[206:209], v[24:27]
	v_mfma_f32_16x16x32_bf16 v[12:15], v[146:149], v[214:217], v[12:15]
	v_mfma_f32_16x16x32_bf16 v[8:11], v[166:169], v[214:217], v[8:11]
	v_mfma_f32_16x16x32_bf16 v[60:63], v[162:165], v[194:197], v[60:63]
	v_mfma_f32_16x16x32_bf16 v[56:59], v[170:173], v[194:197], v[56:59]
	v_mfma_f32_16x16x32_bf16 v[44:47], v[162:165], v[202:205], v[44:47]
	v_mfma_f32_16x16x32_bf16 v[40:43], v[170:173], v[202:205], v[40:43]
	v_mfma_f32_16x16x32_bf16 v[28:31], v[162:165], v[210:213], v[28:31]
	v_mfma_f32_16x16x32_bf16 v[24:27], v[170:173], v[210:213], v[24:27]
	v_mfma_f32_16x16x32_bf16 v[12:15], v[162:165], v[218:221], v[12:15]
	v_mfma_f32_16x16x32_bf16 v[8:11], v[170:173], v[218:221], v[8:11]
	v_mfma_f32_16x16x32_bf16 v[52:55], v[174:177], v[190:193], v[52:55]
	v_mfma_f32_16x16x32_bf16 v[48:51], v[182:185], v[190:193], v[48:51]
	v_mfma_f32_16x16x32_bf16 v[36:39], v[174:177], v[198:201], v[36:39]
	v_mfma_f32_16x16x32_bf16 v[32:35], v[182:185], v[198:201], v[32:35]
	v_mfma_f32_16x16x32_bf16 v[20:23], v[174:177], v[206:209], v[20:23]
	v_mfma_f32_16x16x32_bf16 v[16:19], v[182:185], v[206:209], v[16:19]
	v_mfma_f32_16x16x32_bf16 v[4:7], v[174:177], v[214:217], v[4:7]
	v_mfma_f32_16x16x32_bf16 v[0:3], v[182:185], v[214:217], v[0:3]
	v_mfma_f32_16x16x32_bf16 v[52:55], v[178:181], v[194:197], v[52:55]
	v_mfma_f32_16x16x32_bf16 v[48:51], v[186:189], v[194:197], v[48:51]
	v_mfma_f32_16x16x32_bf16 v[36:39], v[178:181], v[202:205], v[36:39]
	v_mfma_f32_16x16x32_bf16 v[32:35], v[186:189], v[202:205], v[32:35]
	v_mfma_f32_16x16x32_bf16 v[20:23], v[178:181], v[210:213], v[20:23]
	v_mfma_f32_16x16x32_bf16 v[16:19], v[186:189], v[210:213], v[16:19]
	v_mfma_f32_16x16x32_bf16 v[4:7], v[178:181], v[218:221], v[4:7]
	v_mfma_f32_16x16x32_bf16 v[0:3], v[186:189], v[218:221], v[0:3]
	s_barrier
; #define PG8_STAGE(bufoff, gbase, voff) do { _Pragma("unroll") for (int _i = 0; _i < 2; ++_i) \
;         __builtin_amdgcn_global_load_lds((const unsigned*)((const char*)(gbase) + (voff)[_i]), (PG8_LAS unsigned*)(lds + (bufoff) + ldsw + _i * 8192), 16, 0, PG8_LOAD_AUX); } while (0)
; #define PG8_LDA(dst, b, h) do { _Pragma("unroll") for (int m = 0; m < 4; ++m) _Pragma("unroll") for (int k = 0; k < 2; ++k) dst[m][k] = *(const PG8_LAS bf16x8*)(lds + PG8_SA(b, h) + aoff + m * 2048 + k * 1024); } while (0)
; #define PG8_LDB(dst, b, h) do { _Pragma("unroll") for (int n = 0; n < 2; ++n) _Pragma("unroll") for (int k = 0; k < 2; ++k) dst[n][k] = *(const PG8_LAS bf16x8*)(lds + PG8_SB(b, h) + boff + n * 2048 + k * 1024); } while (0)
; #define PG8_MMA(ai, bj, At, Bt) do { __builtin_amdgcn_s_setprio(1); _Pragma("unroll") for (int m = 0; m < 4; ++m) _Pragma("unroll") for (int n = 0; n < 2; ++n) _Pragma("unroll") for (int k = 0; k < 2; ++k) \
;         acc[ai][bj][m][n] = __builtin_amdgcn_mfma_f32_16x16x32_bf16(Bt[n][k], At[m][k], acc[ai][bj][m][n], 0, 0, 0); __builtin_amdgcn_s_setprio(0); } while (0)
; #define PG8_WAIT_V(n) asm volatile("s_waitcnt vmcnt(" #n ")" ::: "memory")
; #define PG8_WAIT_L(n) asm volatile("s_waitcnt lgkmcnt(" #n ")" ::: "memory")
; #define PG8_BAR __builtin_amdgcn_s_barrier()
; #define PG8_SCHED __builtin_amdgcn_sched_barrier(0)
; template <class Epi, class Sched, bool ALIGN_EPI = false, bool SP2 = false>
; __device__ __forceinline__ void gemm_phase(PG8_LAS unsigned char* lds, const Gemm g, const Sched& S, const Epi& E) {
;     ...
;             PG8_LDB(B0, 1, 0); PG8_LDB(B1, 1, 1); PG8_SCHED; PG8_LDA(At, 1, 0); PG8_STAGE(PG8_SA(0, 1), a2 + hstepA, voffA);
;             PG8_WAIT_V(8); PG8_WAIT_L(0); PG8_BAR; PG8_MMA(0, 0, At, B0); PG8_MMA(0, 1, At, B1); PG8_BAR; PG8_SCHED;
.Lkmid_P8:
	s_add_i32 s28, 0, 0x18000
	v_add_u32_e32 v161, s28, v151
	s_add_i32 s29, 0, 0x1c000
	ds_read_b128 v[146:149], v161
	ds_read_b128 v[162:165], v161 offset:1024
	ds_read_b128 v[166:169], v161 offset:2048
	ds_read_b128 v[170:173], v161 offset:3072
	v_add_u32_e32 v161, s29, v151
	ds_read_b128 v[174:177], v161
	ds_read_b128 v[178:181], v161 offset:1024
	ds_read_b128 v[182:185], v161 offset:2048
	ds_read_b128 v[186:189], v161 offset:3072
	s_add_u32 s22, s22, 0xb0000
	s_addc_u32 s23, s23, 0
	s_mov_b32 m0, s43
	v_lshl_add_u64 v[230:231], s[22:23], 0, v[128:129]
	ds_read_b128 v[190:193], v159 offset:32768
	ds_read_b128 v[194:197], v159 offset:33792
	ds_read_b128 v[198:201], v159 offset:34816
	ds_read_b128 v[202:205], v159 offset:35840
	ds_read_b128 v[206:209], v159 offset:36864
	ds_read_b128 v[210:213], v159 offset:37888
	ds_read_b128 v[214:217], v159 offset:38912
	ds_read_b128 v[218:221], v159 offset:39936
	global_load_lds_dwordx4 v[230:231], off
	s_mov_b32 m0, s46
	v_lshl_add_u64 v[230:231], s[22:23], 0, v[132:133]
	global_load_lds_dwordx4 v[230:231], off
	s_waitcnt vmcnt(8)
	s_waitcnt lgkmcnt(0)
	s_barrier
	s_waitcnt lgkmcnt(0)
	v_mfma_f32_16x16x32_bf16 v[124:127], v[146:149], v[190:193], v[124:127]
	v_mfma_f32_16x16x32_bf16 v[120:123], v[166:169], v[190:193], v[120:123]
	v_mfma_f32_16x16x32_bf16 v[108:111], v[146:149], v[198:201], v[108:111]
	v_mfma_f32_16x16x32_bf16 v[104:107], v[166:169], v[198:201], v[104:107]
	v_mfma_f32_16x16x32_bf16 v[92:95], v[146:149], v[206:209], v[92:95]
	v_mfma_f32_16x16x32_bf16 v[88:91], v[166:169], v[206:209], v[88:91]
	v_mfma_f32_16x16x32_bf16 v[76:79], v[146:149], v[214:217], v[76:79]
	v_mfma_f32_16x16x32_bf16 v[72:75], v[166:169], v[214:217], v[72:75]
	v_mfma_f32_16x16x32_bf16 v[124:127], v[162:165], v[194:197], v[124:127]
	v_mfma_f32_16x16x32_bf16 v[120:123], v[170:173], v[194:197], v[120:123]
	v_mfma_f32_16x16x32_bf16 v[108:111], v[162:165], v[202:205], v[108:111]
	v_mfma_f32_16x16x32_bf16 v[104:107], v[170:173], v[202:205], v[104:107]
	v_mfma_f32_16x16x32_bf16 v[92:95], v[162:165], v[210:213], v[92:95]
	v_mfma_f32_16x16x32_bf16 v[88:91], v[170:173], v[210:213], v[88:91]
	v_mfma_f32_16x16x32_bf16 v[76:79], v[162:165], v[218:221], v[76:79]
	v_mfma_f32_16x16x32_bf16 v[72:75], v[170:173], v[218:221], v[72:75]
	v_mfma_f32_16x16x32_bf16 v[116:119], v[174:177], v[190:193], v[116:119]
	v_mfma_f32_16x16x32_bf16 v[112:115], v[182:185], v[190:193], v[112:115]
	v_mfma_f32_16x16x32_bf16 v[100:103], v[174:177], v[198:201], v[100:103]
	v_mfma_f32_16x16x32_bf16 v[96:99], v[182:185], v[198:201], v[96:99]
	v_mfma_f32_16x16x32_bf16 v[84:87], v[174:177], v[206:209], v[84:87]
	v_mfma_f32_16x16x32_bf16 v[80:83], v[182:185], v[206:209], v[80:83]
	v_mfma_f32_16x16x32_bf16 v[68:71], v[174:177], v[214:217], v[68:71]
	v_mfma_f32_16x16x32_bf16 v[64:67], v[182:185], v[214:217], v[64:67]
	v_mfma_f32_16x16x32_bf16 v[116:119], v[178:181], v[194:197], v[116:119]
	v_mfma_f32_16x16x32_bf16 v[112:115], v[186:189], v[194:197], v[112:115]
	v_mfma_f32_16x16x32_bf16 v[100:103], v[178:181], v[202:205], v[100:103]
	v_mfma_f32_16x16x32_bf16 v[96:99], v[186:189], v[202:205], v[96:99]
	v_mfma_f32_16x16x32_bf16 v[84:87], v[178:181], v[210:213], v[84:87]
	v_mfma_f32_16x16x32_bf16 v[80:83], v[186:189], v[210:213], v[80:83]
	v_mfma_f32_16x16x32_bf16 v[68:71], v[178:181], v[218:221], v[68:71]
	v_mfma_f32_16x16x32_bf16 v[64:67], v[186:189], v[218:221], v[64:67]
	s_barrier
; #define PG8_STAGE(bufoff, gbase, voff) do { _Pragma("unroll") for (int _i = 0; _i < 2; ++_i) \
;         __builtin_amdgcn_global_load_lds((const unsigned*)((const char*)(gbase) + (voff)[_i]), (PG8_LAS unsigned*)(lds + (bufoff) + ldsw + _i * 8192), 16, 0, PG8_LOAD_AUX); } while (0)
; #define PG8_LDA(dst, b, h) do { _Pragma("unroll") for (int m = 0; m < 4; ++m) _Pragma("unroll") for (int k = 0; k < 2; ++k) dst[m][k] = *(const PG8_LAS bf16x8*)(lds + PG8_SA(b, h) + aoff + m * 2048 + k * 1024); } while (0)
; #define PG8_MMA(ai, bj, At, Bt) do { __builtin_amdgcn_s_setprio(1); _Pragma("unroll") for (int m = 0; m < 4; ++m) _Pragma("unroll") for (int n = 0; n < 2; ++n) _Pragma("unroll") for (int k = 0; k < 2; ++k) \
;         acc[ai][bj][m][n] = __builtin_amdgcn_mfma_f32_16x16x32_bf16(Bt[n][k], At[m][k], acc[ai][bj][m][n], 0, 0, 0); __builtin_amdgcn_s_setprio(0); } while (0)
; #define PG8_WAIT_V(n) asm volatile("s_waitcnt vmcnt(" #n ")" ::: "memory")
; #define PG8_WAIT_L(n) asm volatile("s_waitcnt lgkmcnt(" #n ")" ::: "memory")
; #define PG8_BAR __builtin_amdgcn_s_barrier()
; #define PG8_SCHED __builtin_amdgcn_sched_barrier(0)
; template <class Epi, class Sched, bool ALIGN_EPI = false, bool SP2 = false>
; __device__ __forceinline__ void gemm_phase(PG8_LAS unsigned char* lds, const Gemm g, const Sched& S, const Epi& E) {
;     ...
;             PG8_LDA(At, 1, 1); PG8_STAGE(PG8_SB(1, 0), b3, voffB); PG8_STAGE(PG8_SB(1, 1), b3 + hstepB, voffB); PG8_STAGE(PG8_SA(1, 0), a3, voffA);
;             PG8_WAIT_V(8); PG8_WAIT_L(0); PG8_BAR; PG8_MMA(1, 0, At, B0); PG8_MMA(1, 1, At, B1); PG8_BAR; PG8_SCHED;
;     ...
;         if constexpr (ALIGN_EPI) { if (wr == 0) PG8_BAR; }
	s_add_i32 s22, s28, s34
	v_lshl_add_u64 v[222:223], v[222:223], 0, s[18:19]
	s_mov_b32 m0, s22
	ds_read_b128 v[190:193], v159 offset:49152
	ds_read_b128 v[194:197], v159 offset:50176
	ds_read_b128 v[198:201], v159 offset:51200
	ds_read_b128 v[202:205], v159 offset:52224
	ds_read_b128 v[206:209], v159 offset:53248
	ds_read_b128 v[210:213], v159 offset:54272
	ds_read_b128 v[214:217], v159 offset:55296
	ds_read_b128 v[218:221], v159 offset:56320
	global_load_lds_dwordx4 v[222:223], off
	s_add_i32 m0, s22, 0x2000
	s_add_u32 s20, s20, 0x2c080
	v_lshl_add_u64 v[222:223], v[224:225], 0, s[18:19]
	s_addc_u32 s21, s21, 0
	s_add_i32 s22, s29, s34
	global_load_lds_dwordx4 v[222:223], off
	s_mov_b32 m0, s22
	v_lshl_add_u64 v[222:223], s[20:21], 0, v[130:131]
	global_load_lds_dwordx4 v[222:223], off
	s_add_i32 m0, s22, 0x2000
	v_lshl_add_u64 v[222:223], s[20:21], 0, v[134:135]
	global_load_lds_dwordx4 v[222:223], off
	s_mov_b32 m0, s50
	v_lshl_add_u64 v[222:223], v[226:227], 0, s[18:19]
	global_load_lds_dwordx4 v[222:223], off
	s_mov_b32 m0, s51
	v_lshl_add_u64 v[222:223], v[228:229], 0, s[18:19]
	global_load_lds_dwordx4 v[222:223], off
	s_waitcnt vmcnt(8)
	s_waitcnt lgkmcnt(0)
	s_barrier
	s_waitcnt lgkmcnt(0)
	v_mfma_f32_16x16x32_bf16 v[60:63], v[146:149], v[190:193], v[60:63]
	v_mfma_f32_16x16x32_bf16 v[56:59], v[166:169], v[190:193], v[56:59]
	v_mfma_f32_16x16x32_bf16 v[44:47], v[146:149], v[198:201], v[44:47]
	v_mfma_f32_16x16x32_bf16 v[40:43], v[166:169], v[198:201], v[40:43]
	v_mfma_f32_16x16x32_bf16 v[28:31], v[146:149], v[206:209], v[28:31]
	v_mfma_f32_16x16x32_bf16 v[24:27], v[166:169], v[206:209], v[24:27]
	v_mfma_f32_16x16x32_bf16 v[12:15], v[146:149], v[214:217], v[12:15]
	v_mfma_f32_16x16x32_bf16 v[8:11], v[166:169], v[214:217], v[8:11]
	v_mfma_f32_16x16x32_bf16 v[60:63], v[162:165], v[194:197], v[60:63]
	v_mfma_f32_16x16x32_bf16 v[56:59], v[170:173], v[194:197], v[56:59]
	v_mfma_f32_16x16x32_bf16 v[44:47], v[162:165], v[202:205], v[44:47]
	v_mfma_f32_16x16x32_bf16 v[40:43], v[170:173], v[202:205], v[40:43]
	v_mfma_f32_16x16x32_bf16 v[28:31], v[162:165], v[210:213], v[28:31]
	v_mfma_f32_16x16x32_bf16 v[24:27], v[170:173], v[210:213], v[24:27]
	v_mfma_f32_16x16x32_bf16 v[12:15], v[162:165], v[218:221], v[12:15]
	v_mfma_f32_16x16x32_bf16 v[8:11], v[170:173], v[218:221], v[8:11]
	v_mfma_f32_16x16x32_bf16 v[52:55], v[174:177], v[190:193], v[52:55]
	v_mfma_f32_16x16x32_bf16 v[48:51], v[182:185], v[190:193], v[48:51]
	v_mfma_f32_16x16x32_bf16 v[36:39], v[174:177], v[198:201], v[36:39]
	v_mfma_f32_16x16x32_bf16 v[32:35], v[182:185], v[198:201], v[32:35]
	v_mfma_f32_16x16x32_bf16 v[20:23], v[174:177], v[206:209], v[20:23]
	v_mfma_f32_16x16x32_bf16 v[16:19], v[182:185], v[206:209], v[16:19]
	v_mfma_f32_16x16x32_bf16 v[4:7], v[174:177], v[214:217], v[4:7]
	v_mfma_f32_16x16x32_bf16 v[0:3], v[182:185], v[214:217], v[0:3]
	v_mfma_f32_16x16x32_bf16 v[52:55], v[178:181], v[194:197], v[52:55]
	v_mfma_f32_16x16x32_bf16 v[48:51], v[186:189], v[194:197], v[48:51]
	v_mfma_f32_16x16x32_bf16 v[36:39], v[178:181], v[202:205], v[36:39]
	v_mfma_f32_16x16x32_bf16 v[32:35], v[186:189], v[202:205], v[32:35]
	v_mfma_f32_16x16x32_bf16 v[20:23], v[178:181], v[210:213], v[20:23]
	v_mfma_f32_16x16x32_bf16 v[16:19], v[186:189], v[210:213], v[16:19]
	v_mfma_f32_16x16x32_bf16 v[4:7], v[178:181], v[218:221], v[4:7]
	v_mfma_f32_16x16x32_bf16 v[0:3], v[186:189], v[218:221], v[0:3]
	s_barrier
	s_add_i32 s27, s27, 2
	s_add_u32 s0, s0, 0x100
	s_addc_u32 s1, s1, 0
	s_add_u32 s25, s25, 0x100
	s_addc_u32 s26, s26, 0
	s_cmp_gt_u32 s27, 41
	s_cbranch_scc0 .LBB0_757
	s_and_b64 vcc, exec, s[36:37]
	s_cbranch_vccz .LBB0_760
	s_barrier

; #define PG8_STAGE(bufoff, gbase, voff) do { _Pragma("unroll") for (int _i = 0; _i < 2; ++_i) \
;         __builtin_amdgcn_global_load_lds((const unsigned*)((const char*)(gbase) + (voff)[_i]), (PG8_LAS unsigned*)(lds + (bufoff) + ldsw + _i * 8192), 16, 0, PG8_LOAD_AUX); } while (0)
; #define PG8_LDA(dst, b, h) do { _Pragma("unroll") for (int m = 0; m < 4; ++m) _Pragma("unroll") for (int k = 0; k < 2; ++k) dst[m][k] = *(const PG8_LAS bf16x8*)(lds + PG8_SA(b, h) + aoff + m * 2048 + k * 1024); } while (0)
; #define PG8_LDB(dst, b, h) do { _Pragma("unroll") for (int n = 0; n < 2; ++n) _Pragma("unroll") for (int k = 0; k < 2; ++k) dst[n][k] = *(const PG8_LAS bf16x8*)(lds + PG8_SB(b, h) + boff + n * 2048 + k * 1024); } while (0)
; #define PG8_WAIT_V(n) asm volatile("s_waitcnt vmcnt(" #n ")" ::: "memory")
; #define PG8_WAIT_L(n) asm volatile("s_waitcnt lgkmcnt(" #n ")" ::: "memory")
; #define PG8_BAR __builtin_amdgcn_s_barrier()
; #define PG8_SCHED __builtin_amdgcn_sched_barrier(0)
; template <class Epi, class Sched, bool ALIGN_EPI = false, bool SP2 = false>
; __device__ __forceinline__ void gemm_phase(PG8_LAS unsigned char* lds, const Gemm g, const Sched& S, const Epi& E) {
;     ...
;         const bool has_next = S.next(ui + 1, nxt);
;         const char* nA = has_next ? (const char*)g.A + (size_t)nxt.pm * tstepA + (size_t)nxt.pn * apn : cA; const char* nB = has_next ? (const char*)g.Bt + (size_t)nxt.pn * tstepB : cB;
;         for (int t = 0; t < nt; t += 2) {
;             const bool last = (t == nt - 2);
;             const char* a1 = cA + (size_t)(t + 1) * kstep;
;             const char* a2 = last ? nA : cA + (size_t)(t + 2) * kstep; const char* b2 = last ? nB : cB + (size_t)(t + 2) * kstep;
;             const char* a3 = a2 + kstep; const char* b3 = b2 + kstep;
;             if (last && has_next) S.a_ready(nxt);
;             if constexpr (SP2) {
;             PG8_LDB(B0, 0, 0); PG8_LDB(B1, 0, 1); PG8_SCHED; PG8_LDA(At, 0, 0); PG8_STAGE(PG8_SA(1, 1), a1 + hstepA, voffA);
;             PG8_WAIT_V(8); PG8_WAIT_L(0); PG8_BAR; PG8_MMA(0, 0, At, B0); PG8_MMA(0, 1, At, B1); PG8_BAR; PG8_SCHED;
;             PG8_LDA(At, 0, 1); PG8_STAGE(PG8_SB(0, 0), b2, voffB); PG8_STAGE(PG8_SB(0, 1), b2 + hstepB, voffB); PG8_STAGE(PG8_SA(0, 0), a2, voffA);
;             PG8_WAIT_V(8); PG8_WAIT_L(0); PG8_BAR; PG8_MMA(1, 0, At, B0); PG8_MMA(1, 1, At, B1); PG8_BAR; PG8_SCHED;
.LBB0_849:
	s_ashr_i32 s41, s40, 31
	s_lshl_b64 s[22:23], s[40:41], 19
	s_add_u32 s42, s30, s22
	s_addc_u32 s43, s31, s23
	s_and_b64 s[22:23], s[4:5], exec
	s_cselect_b32 s7, s43, s1
	s_cselect_b32 s24, s42, s0
	s_ashr_i32 s37, s36, 31
	s_lshl_b64 s[22:23], s[36:37], 19
	v_readlane_b32 s26, v239, 36
	v_readlane_b32 s27, v239, 37
	s_add_u32 s46, s26, s22
	s_addc_u32 s47, s27, s23
	s_and_b64 s[22:23], s[4:5], exec
	s_cselect_b32 s25, s47, s21
	s_cselect_b32 s26, s46, s20
	s_add_u32 s0, s0, 0x40080
	s_addc_u32 s1, s1, 0
	s_add_u32 s27, s20, 0x100
	s_addc_u32 s28, s21, 0
	s_mov_b32 s29, -2
	s_waitcnt lgkmcnt(0)
	ds_read_b128 v[164:167], v159
	ds_read_b128 v[168:171], v159 offset:1024
	ds_read_b128 v[172:175], v159 offset:2048
	ds_read_b128 v[176:179], v159 offset:3072
	ds_read_b128 v[180:183], v160
	ds_read_b128 v[184:187], v160 offset:1024
	ds_read_b128 v[188:191], v160 offset:2048
	ds_read_b128 v[192:195], v160 offset:3072
	s_add_u32 s20, s0, 0xfffc0080
	s_addc_u32 s21, s1, -1
	s_cmp_eq_u32 s29, 12
	s_cselect_b32 s23, s7, s21
	s_cselect_b32 s22, s24, s20
	s_cselect_b32 s21, s25, s28
	s_cselect_b32 s20, s26, s27
	v_lshl_add_u64 v[148:149], s[0:1], 0, v[140:141]
	s_add_i32 m0, s35, 0xc000
	ds_read_b128 v[196:199], v161
	ds_read_b128 v[200:203], v161 offset:1024
	ds_read_b128 v[204:207], v161 offset:2048
	ds_read_b128 v[208:211], v161 offset:3072
	ds_read_b128 v[212:215], v161 offset:4096
	ds_read_b128 v[216:219], v161 offset:5120
	ds_read_b128 v[220:223], v161 offset:6144
	ds_read_b128 v[224:227], v161 offset:7168
	global_load_lds_dwordx4 v[148:149], off
	s_add_i32 m0, s35, 0xe000
	v_lshl_add_u64 v[148:149], s[0:1], 0, v[142:143]
	global_load_lds_dwordx4 v[148:149], off
	s_waitcnt vmcnt(8)
	s_waitcnt lgkmcnt(0)
	s_barrier
	s_waitcnt lgkmcnt(0)
	v_mfma_f32_16x16x32_bf16 v[124:127], v[164:167], v[196:199], 0
	v_mfma_f32_16x16x32_bf16 v[120:123], v[172:175], v[196:199], 0
	v_mfma_f32_16x16x32_bf16 v[108:111], v[164:167], v[204:207], 0
	v_mfma_f32_16x16x32_bf16 v[104:107], v[172:175], v[204:207], 0
	v_mfma_f32_16x16x32_bf16 v[92:95], v[164:167], v[212:215], 0
	v_mfma_f32_16x16x32_bf16 v[88:91], v[172:175], v[212:215], 0
	v_mfma_f32_16x16x32_bf16 v[76:79], v[164:167], v[220:223], 0
	v_mfma_f32_16x16x32_bf16 v[72:75], v[172:175], v[220:223], 0
	v_mfma_f32_16x16x32_bf16 v[124:127], v[168:171], v[200:203], v[124:127]
	v_mfma_f32_16x16x32_bf16 v[120:123], v[176:179], v[200:203], v[120:123]
	v_mfma_f32_16x16x32_bf16 v[108:111], v[168:171], v[208:211], v[108:111]
	v_mfma_f32_16x16x32_bf16 v[104:107], v[176:179], v[208:211], v[104:107]
	v_mfma_f32_16x16x32_bf16 v[92:95], v[168:171], v[216:219], v[92:95]
	v_mfma_f32_16x16x32_bf16 v[88:91], v[176:179], v[216:219], v[88:91]
	v_mfma_f32_16x16x32_bf16 v[76:79], v[168:171], v[224:227], v[76:79]
	v_mfma_f32_16x16x32_bf16 v[72:75], v[176:179], v[224:227], v[72:75]
	v_mfma_f32_16x16x32_bf16 v[116:119], v[180:183], v[196:199], 0
	v_mfma_f32_16x16x32_bf16 v[112:115], v[188:191], v[196:199], 0
	v_mfma_f32_16x16x32_bf16 v[100:103], v[180:183], v[204:207], 0
	v_mfma_f32_16x16x32_bf16 v[96:99], v[188:191], v[204:207], 0
	v_mfma_f32_16x16x32_bf16 v[84:87], v[180:183], v[212:215], 0
	v_mfma_f32_16x16x32_bf16 v[80:83], v[188:191], v[212:215], 0
	v_mfma_f32_16x16x32_bf16 v[68:71], v[180:183], v[220:223], 0
	v_mfma_f32_16x16x32_bf16 v[64:67], v[188:191], v[220:223], 0
	v_mfma_f32_16x16x32_bf16 v[116:119], v[184:187], v[200:203], v[116:119]
	v_mfma_f32_16x16x32_bf16 v[112:115], v[192:195], v[200:203], v[112:115]
	v_mfma_f32_16x16x32_bf16 v[100:103], v[184:187], v[208:211], v[100:103]
	v_mfma_f32_16x16x32_bf16 v[96:99], v[192:195], v[208:211], v[96:99]
	v_mfma_f32_16x16x32_bf16 v[84:87], v[184:187], v[216:219], v[84:87]
	v_mfma_f32_16x16x32_bf16 v[80:83], v[192:195], v[216:219], v[80:83]
	v_mfma_f32_16x16x32_bf16 v[68:71], v[184:187], v[224:227], v[68:71]
	v_mfma_f32_16x16x32_bf16 v[64:67], v[192:195], v[224:227], v[64:67]
	s_barrier
	s_add_i32 s30, s61, s34
	v_lshl_add_u64 v[148:149], s[20:21], 0, v[130:131]
	s_mov_b32 m0, s30
	ds_read_b128 v[196:199], v161 offset:16384
	ds_read_b128 v[200:203], v161 offset:17408
	ds_read_b128 v[204:207], v161 offset:18432
	ds_read_b128 v[208:211], v161 offset:19456
	ds_read_b128 v[212:215], v161 offset:20480
	ds_read_b128 v[216:219], v161 offset:21504
	ds_read_b128 v[220:223], v161 offset:22528
	ds_read_b128 v[224:227], v161 offset:23552
	global_load_lds_dwordx4 v[148:149], off
	s_add_i32 m0, s30, 0x2000
	s_add_u32 s30, s20, 0x10000
	v_lshl_add_u64 v[228:229], s[20:21], 0, v[134:135]
	s_addc_u32 s31, s21, 0
	s_add_i32 s37, s62, s34
	global_load_lds_dwordx4 v[228:229], off
	v_lshl_add_u64 v[230:231], s[30:31], 0, v[130:131]
	s_mov_b32 m0, s37
	v_lshl_add_u64 v[232:233], s[22:23], 0, v[132:133]
	global_load_lds_dwordx4 v[230:231], off
	s_add_i32 m0, s37, 0x2000
	v_lshl_add_u64 v[230:231], s[30:31], 0, v[134:135]
	global_load_lds_dwordx4 v[230:231], off
	s_mov_b32 m0, s35
	v_lshl_add_u64 v[230:231], s[22:23], 0, v[128:129]
	global_load_lds_dwordx4 v[230:231], off
	s_mov_b32 m0, s49
	s_nop 0
	global_load_lds_dwordx4 v[232:233], off
	s_waitcnt vmcnt(8)
	s_waitcnt lgkmcnt(0)
	s_barrier
; #define PG8_STAGE(bufoff, gbase, voff) do { _Pragma("unroll") for (int _i = 0; _i < 2; ++_i) \
;         __builtin_amdgcn_global_load_lds((const unsigned*)((const char*)(gbase) + (voff)[_i]), (PG8_LAS unsigned*)(lds + (bufoff) + ldsw + _i * 8192), 16, 0, PG8_LOAD_AUX); } while (0)
; #define PG8_LDA(dst, b, h) do { _Pragma("unroll") for (int m = 0; m < 4; ++m) _Pragma("unroll") for (int k = 0; k < 2; ++k) dst[m][k] = *(const PG8_LAS bf16x8*)(lds + PG8_SA(b, h) + aoff + m * 2048 + k * 1024); } while (0)
; #define PG8_LDB(dst, b, h) do { _Pragma("unroll") for (int n = 0; n < 2; ++n) _Pragma("unroll") for (int k = 0; k < 2; ++k) dst[n][k] = *(const PG8_LAS bf16x8*)(lds + PG8_SB(b, h) + boff + n * 2048 + k * 1024); } while (0)
; #define PG8_MMA(ai, bj, At, Bt) do { __builtin_amdgcn_s_setprio(1); _Pragma("unroll") for (int m = 0; m < 4; ++m) _Pragma("unroll") for (int n = 0; n < 2; ++n) _Pragma("unroll") for (int k = 0; k < 2; ++k) \
;         acc[ai][bj][m][n] = __builtin_amdgcn_mfma_f32_16x16x32_bf16(Bt[n][k], At[m][k], acc[ai][bj][m][n], 0, 0, 0); __builtin_amdgcn_s_setprio(0); } while (0)
; #define PG8_WAIT_V(n) asm volatile("s_waitcnt vmcnt(" #n ")" ::: "memory")
; #define PG8_WAIT_L(n) asm volatile("s_waitcnt lgkmcnt(" #n ")" ::: "memory")
; #define PG8_BAR __builtin_amdgcn_s_barrier()
; #define PG8_SCHED __builtin_amdgcn_sched_barrier(0)
; template <class Epi, class Sched, bool ALIGN_EPI = false, bool SP2 = false>
; __device__ __forceinline__ void gemm_phase(PG8_LAS unsigned char* lds, const Gemm g, const Sched& S, const Epi& E) {
;     ...
;             PG8_LDB(B0, 0, 0); PG8_LDB(B1, 0, 1); PG8_SCHED; PG8_LDA(At, 0, 0); PG8_STAGE(PG8_SA(1, 1), a1 + hstepA, voffA);
;             PG8_WAIT_V(8); PG8_WAIT_L(0); PG8_BAR; PG8_MMA(0, 0, At, B0); PG8_MMA(0, 1, At, B1); PG8_BAR; PG8_SCHED;
;             PG8_LDA(At, 0, 1); PG8_STAGE(PG8_SB(0, 0), b2, voffB); PG8_STAGE(PG8_SB(0, 1), b2 + hstepB, voffB); PG8_STAGE(PG8_SA(0, 0), a2, voffA);
;             PG8_WAIT_V(8); PG8_WAIT_L(0); PG8_BAR; PG8_MMA(1, 0, At, B0); PG8_MMA(1, 1, At, B1); PG8_BAR; PG8_SCHED;
	s_waitcnt lgkmcnt(0)
	v_mfma_f32_16x16x32_bf16 v[60:63], v[164:167], v[196:199], 0
	v_mfma_f32_16x16x32_bf16 v[56:59], v[172:175], v[196:199], 0
	v_mfma_f32_16x16x32_bf16 v[44:47], v[164:167], v[204:207], 0
	v_mfma_f32_16x16x32_bf16 v[40:43], v[172:175], v[204:207], 0
	v_mfma_f32_16x16x32_bf16 v[28:31], v[164:167], v[212:215], 0
	v_mfma_f32_16x16x32_bf16 v[24:27], v[172:175], v[212:215], 0
	v_mfma_f32_16x16x32_bf16 v[12:15], v[164:167], v[220:223], 0
	v_mfma_f32_16x16x32_bf16 v[8:11], v[172:175], v[220:223], 0
	v_mfma_f32_16x16x32_bf16 v[60:63], v[168:171], v[200:203], v[60:63]
	v_mfma_f32_16x16x32_bf16 v[56:59], v[176:179], v[200:203], v[56:59]
	v_mfma_f32_16x16x32_bf16 v[44:47], v[168:171], v[208:211], v[44:47]
	v_mfma_f32_16x16x32_bf16 v[40:43], v[176:179], v[208:211], v[40:43]
	v_mfma_f32_16x16x32_bf16 v[28:31], v[168:171], v[216:219], v[28:31]
	v_mfma_f32_16x16x32_bf16 v[24:27], v[176:179], v[216:219], v[24:27]
	v_mfma_f32_16x16x32_bf16 v[12:15], v[168:171], v[224:227], v[12:15]
	v_mfma_f32_16x16x32_bf16 v[8:11], v[176:179], v[224:227], v[8:11]
	v_mfma_f32_16x16x32_bf16 v[52:55], v[180:183], v[196:199], 0
	v_mfma_f32_16x16x32_bf16 v[48:51], v[188:191], v[196:199], 0
	v_mfma_f32_16x16x32_bf16 v[36:39], v[180:183], v[204:207], 0
	v_mfma_f32_16x16x32_bf16 v[32:35], v[188:191], v[204:207], 0
	v_mfma_f32_16x16x32_bf16 v[20:23], v[180:183], v[212:215], 0
	v_mfma_f32_16x16x32_bf16 v[16:19], v[188:191], v[212:215], 0
	v_mfma_f32_16x16x32_bf16 v[4:7], v[180:183], v[220:223], 0
	v_mfma_f32_16x16x32_bf16 v[0:3], v[188:191], v[220:223], 0
	v_mfma_f32_16x16x32_bf16 v[52:55], v[184:187], v[200:203], v[52:55]
	v_mfma_f32_16x16x32_bf16 v[48:51], v[192:195], v[200:203], v[48:51]
	v_mfma_f32_16x16x32_bf16 v[36:39], v[184:187], v[208:211], v[36:39]
	v_mfma_f32_16x16x32_bf16 v[32:35], v[192:195], v[208:211], v[32:35]
	v_mfma_f32_16x16x32_bf16 v[20:23], v[184:187], v[216:219], v[20:23]
	v_mfma_f32_16x16x32_bf16 v[16:19], v[192:195], v[216:219], v[16:19]
	v_mfma_f32_16x16x32_bf16 v[4:7], v[184:187], v[224:227], v[4:7]
	v_mfma_f32_16x16x32_bf16 v[0:3], v[192:195], v[224:227], v[0:3]
	s_barrier
	s_branch .Lkmid_P9
.LBB0_850:
	ds_read_b128 v[164:167], v159
	ds_read_b128 v[168:171], v159 offset:1024
	ds_read_b128 v[172:175], v159 offset:2048
	ds_read_b128 v[176:179], v159 offset:3072
	ds_read_b128 v[180:183], v160
	ds_read_b128 v[184:187], v160 offset:1024
	ds_read_b128 v[188:191], v160 offset:2048
	ds_read_b128 v[192:195], v160 offset:3072
	s_add_u32 s20, s0, 0xfffc0080
	s_addc_u32 s21, s1, -1
	s_cmp_eq_u32 s29, 12
	s_cselect_b32 s23, s7, s21
	s_cselect_b32 s22, s24, s20
	s_cselect_b32 s21, s25, s28
	s_cselect_b32 s20, s26, s27
	v_lshl_add_u64 v[148:149], s[0:1], 0, v[140:141]
	s_add_i32 m0, s35, 0xc000
	ds_read_b128 v[196:199], v161
	ds_read_b128 v[200:203], v161 offset:1024
	ds_read_b128 v[204:207], v161 offset:2048
	ds_read_b128 v[208:211], v161 offset:3072
	ds_read_b128 v[212:215], v161 offset:4096
	ds_read_b128 v[216:219], v161 offset:5120
	ds_read_b128 v[220:223], v161 offset:6144
	ds_read_b128 v[224:227], v161 offset:7168
	global_load_lds_dwordx4 v[148:149], off
	s_add_i32 m0, s35, 0xe000
	v_lshl_add_u64 v[148:149], s[0:1], 0, v[142:143]
	global_load_lds_dwordx4 v[148:149], off
	s_waitcnt vmcnt(8)
	s_waitcnt lgkmcnt(0)
	s_barrier
	s_waitcnt lgkmcnt(0)
	v_mfma_f32_16x16x32_bf16 v[124:127], v[164:167], v[196:199], v[124:127]
	v_mfma_f32_16x16x32_bf16 v[120:123], v[172:175], v[196:199], v[120:123]
	v_mfma_f32_16x16x32_bf16 v[108:111], v[164:167], v[204:207], v[108:111]
	v_mfma_f32_16x16x32_bf16 v[104:107], v[172:175], v[204:207], v[104:107]
	v_mfma_f32_16x16x32_bf16 v[92:95], v[164:167], v[212:215], v[92:95]
	v_mfma_f32_16x16x32_bf16 v[88:91], v[172:175], v[212:215], v[88:91]
	v_mfma_f32_16x16x32_bf16 v[76:79], v[164:167], v[220:223], v[76:79]
	v_mfma_f32_16x16x32_bf16 v[72:75], v[172:175], v[220:223], v[72:75]
	v_mfma_f32_16x16x32_bf16 v[124:127], v[168:171], v[200:203], v[124:127]
	v_mfma_f32_16x16x32_bf16 v[120:123], v[176:179], v[200:203], v[120:123]
	v_mfma_f32_16x16x32_bf16 v[108:111], v[168:171], v[208:211], v[108:111]
	v_mfma_f32_16x16x32_bf16 v[104:107], v[176:179], v[208:211], v[104:107]
	v_mfma_f32_16x16x32_bf16 v[92:95], v[168:171], v[216:219], v[92:95]
	v_mfma_f32_16x16x32_bf16 v[88:91], v[176:179], v[216:219], v[88:91]
	v_mfma_f32_16x16x32_bf16 v[76:79], v[168:171], v[224:227], v[76:79]
	v_mfma_f32_16x16x32_bf16 v[72:75], v[176:179], v[224:227], v[72:75]
	v_mfma_f32_16x16x32_bf16 v[116:119], v[180:183], v[196:199], v[116:119]
	v_mfma_f32_16x16x32_bf16 v[112:115], v[188:191], v[196:199], v[112:115]
	v_mfma_f32_16x16x32_bf16 v[100:103], v[180:183], v[204:207], v[100:103]
	v_mfma_f32_16x16x32_bf16 v[96:99], v[188:191], v[204:207], v[96:99]
	v_mfma_f32_16x16x32_bf16 v[84:87], v[180:183], v[212:215], v[84:87]
	v_mfma_f32_16x16x32_bf16 v[80:83], v[188:191], v[212:215], v[80:83]
	v_mfma_f32_16x16x32_bf16 v[68:71], v[180:183], v[220:223], v[68:71]
	v_mfma_f32_16x16x32_bf16 v[64:67], v[188:191], v[220:223], v[64:67]
	v_mfma_f32_16x16x32_bf16 v[116:119], v[184:187], v[200:203], v[116:119]
	v_mfma_f32_16x16x32_bf16 v[112:115], v[192:195], v[200:203], v[112:115]
	v_mfma_f32_16x16x32_bf16 v[100:103], v[184:187], v[208:211], v[100:103]
	v_mfma_f32_16x16x32_bf16 v[96:99], v[192:195], v[208:211], v[96:99]
	v_mfma_f32_16x16x32_bf16 v[84:87], v[184:187], v[216:219], v[84:87]
	v_mfma_f32_16x16x32_bf16 v[80:83], v[192:195], v[216:219], v[80:83]
	v_mfma_f32_16x16x32_bf16 v[68:71], v[184:187], v[224:227], v[68:71]
	v_mfma_f32_16x16x32_bf16 v[64:67], v[192:195], v[224:227], v[64:67]
	s_barrier
; #define PG8_STAGE(bufoff, gbase, voff) do { _Pragma("unroll") for (int _i = 0; _i < 2; ++_i) \
;         __builtin_amdgcn_global_load_lds((const unsigned*)((const char*)(gbase) + (voff)[_i]), (PG8_LAS unsigned*)(lds + (bufoff) + ldsw + _i * 8192), 16, 0, PG8_LOAD_AUX); } while (0)
; #define PG8_LDA(dst, b, h) do { _Pragma("unroll") for (int m = 0; m < 4; ++m) _Pragma("unroll") for (int k = 0; k < 2; ++k) dst[m][k] = *(const PG8_LAS bf16x8*)(lds + PG8_SA(b, h) + aoff + m * 2048 + k * 1024); } while (0)
; #define PG8_LDB(dst, b, h) do { _Pragma("unroll") for (int n = 0; n < 2; ++n) _Pragma("unroll") for (int k = 0; k < 2; ++k) dst[n][k] = *(const PG8_LAS bf16x8*)(lds + PG8_SB(b, h) + boff + n * 2048 + k * 1024); } while (0)
; #define PG8_MMA(ai, bj, At, Bt) do { __builtin_amdgcn_s_setprio(1); _Pragma("unroll") for (int m = 0; m < 4; ++m) _Pragma("unroll") for (int n = 0; n < 2; ++n) _Pragma("unroll") for (int k = 0; k < 2; ++k) \
;         acc[ai][bj][m][n] = __builtin_amdgcn_mfma_f32_16x16x32_bf16(Bt[n][k], At[m][k], acc[ai][bj][m][n], 0, 0, 0); __builtin_amdgcn_s_setprio(0); } while (0)
; #define PG8_WAIT_V(n) asm volatile("s_waitcnt vmcnt(" #n ")" ::: "memory")
; #define PG8_WAIT_L(n) asm volatile("s_waitcnt lgkmcnt(" #n ")" ::: "memory")
; #define PG8_BAR __builtin_amdgcn_s_barrier()
; #define PG8_SCHED __builtin_amdgcn_sched_barrier(0)
; template <class Epi, class Sched, bool ALIGN_EPI = false, bool SP2 = false>
; __device__ __forceinline__ void gemm_phase(PG8_LAS unsigned char* lds, const Gemm g, const Sched& S, const Epi& E) {
;     ...
;             PG8_WAIT_V(8); PG8_WAIT_L(0); PG8_BAR; PG8_MMA(1, 0, At, B0); PG8_MMA(1, 1, At, B1); PG8_BAR; PG8_SCHED;
;             PG8_LDB(B0, 1, 0); PG8_LDB(B1, 1, 1); PG8_SCHED; PG8_LDA(At, 1, 0); PG8_STAGE(PG8_SA(0, 1), a2 + hstepA, voffA);
;             PG8_WAIT_V(8); PG8_WAIT_L(0); PG8_BAR; PG8_MMA(0, 0, At, B0); PG8_MMA(0, 1, At, B1); PG8_BAR; PG8_SCHED;
;             PG8_LDA(At, 1, 1); PG8_STAGE(PG8_SB(1, 0), b3, voffB); PG8_STAGE(PG8_SB(1, 1), b3 + hstepB, voffB); PG8_STAGE(PG8_SA(1, 0), a3, voffA);
	s_add_i32 s30, s61, s34
	v_lshl_add_u64 v[148:149], s[20:21], 0, v[130:131]
	s_mov_b32 m0, s30
	ds_read_b128 v[196:199], v161 offset:16384
	ds_read_b128 v[200:203], v161 offset:17408
	ds_read_b128 v[204:207], v161 offset:18432
	ds_read_b128 v[208:211], v161 offset:19456
	ds_read_b128 v[212:215], v161 offset:20480
	ds_read_b128 v[216:219], v161 offset:21504
	ds_read_b128 v[220:223], v161 offset:22528
	ds_read_b128 v[224:227], v161 offset:23552
	global_load_lds_dwordx4 v[148:149], off
	s_add_i32 m0, s30, 0x2000
	s_add_u32 s30, s20, 0x10000
	v_lshl_add_u64 v[228:229], s[20:21], 0, v[134:135]
	s_addc_u32 s31, s21, 0
	s_add_i32 s37, s62, s34
	global_load_lds_dwordx4 v[228:229], off
	v_lshl_add_u64 v[230:231], s[30:31], 0, v[130:131]
	s_mov_b32 m0, s37
	v_lshl_add_u64 v[232:233], s[22:23], 0, v[132:133]
	global_load_lds_dwordx4 v[230:231], off
	s_add_i32 m0, s37, 0x2000
	v_lshl_add_u64 v[230:231], s[30:31], 0, v[134:135]
	global_load_lds_dwordx4 v[230:231], off
	s_mov_b32 m0, s35
	v_lshl_add_u64 v[230:231], s[22:23], 0, v[128:129]
	global_load_lds_dwordx4 v[230:231], off
	s_mov_b32 m0, s49
	s_nop 0
	global_load_lds_dwordx4 v[232:233], off
	s_waitcnt vmcnt(8)
	s_waitcnt lgkmcnt(0)
	s_barrier
	s_waitcnt lgkmcnt(0)
	v_mfma_f32_16x16x32_bf16 v[60:63], v[164:167], v[196:199], v[60:63]
	v_mfma_f32_16x16x32_bf16 v[56:59], v[172:175], v[196:199], v[56:59]
	v_mfma_f32_16x16x32_bf16 v[44:47], v[164:167], v[204:207], v[44:47]
	v_mfma_f32_16x16x32_bf16 v[40:43], v[172:175], v[204:207], v[40:43]
	v_mfma_f32_16x16x32_bf16 v[28:31], v[164:167], v[212:215], v[28:31]
	v_mfma_f32_16x16x32_bf16 v[24:27], v[172:175], v[212:215], v[24:27]
	v_mfma_f32_16x16x32_bf16 v[12:15], v[164:167], v[220:223], v[12:15]
	v_mfma_f32_16x16x32_bf16 v[8:11], v[172:175], v[220:223], v[8:11]
	v_mfma_f32_16x16x32_bf16 v[60:63], v[168:171], v[200:203], v[60:63]
	v_mfma_f32_16x16x32_bf16 v[56:59], v[176:179], v[200:203], v[56:59]
	v_mfma_f32_16x16x32_bf16 v[44:47], v[168:171], v[208:211], v[44:47]
	v_mfma_f32_16x16x32_bf16 v[40:43], v[176:179], v[208:211], v[40:43]
	v_mfma_f32_16x16x32_bf16 v[28:31], v[168:171], v[216:219], v[28:31]
	v_mfma_f32_16x16x32_bf16 v[24:27], v[176:179], v[216:219], v[24:27]
	v_mfma_f32_16x16x32_bf16 v[12:15], v[168:171], v[224:227], v[12:15]
	v_mfma_f32_16x16x32_bf16 v[8:11], v[176:179], v[224:227], v[8:11]
	v_mfma_f32_16x16x32_bf16 v[52:55], v[180:183], v[196:199], v[52:55]
	v_mfma_f32_16x16x32_bf16 v[48:51], v[188:191], v[196:199], v[48:51]
	v_mfma_f32_16x16x32_bf16 v[36:39], v[180:183], v[204:207], v[36:39]
	v_mfma_f32_16x16x32_bf16 v[32:35], v[188:191], v[204:207], v[32:35]
	v_mfma_f32_16x16x32_bf16 v[20:23], v[180:183], v[212:215], v[20:23]
	v_mfma_f32_16x16x32_bf16 v[16:19], v[188:191], v[212:215], v[16:19]
	v_mfma_f32_16x16x32_bf16 v[4:7], v[180:183], v[220:223], v[4:7]
	v_mfma_f32_16x16x32_bf16 v[0:3], v[188:191], v[220:223], v[0:3]
	v_mfma_f32_16x16x32_bf16 v[52:55], v[184:187], v[200:203], v[52:55]
	v_mfma_f32_16x16x32_bf16 v[48:51], v[192:195], v[200:203], v[48:51]
	v_mfma_f32_16x16x32_bf16 v[36:39], v[184:187], v[208:211], v[36:39]
	v_mfma_f32_16x16x32_bf16 v[32:35], v[192:195], v[208:211], v[32:35]
	v_mfma_f32_16x16x32_bf16 v[20:23], v[184:187], v[216:219], v[20:23]
	v_mfma_f32_16x16x32_bf16 v[16:19], v[192:195], v[216:219], v[16:19]
	v_mfma_f32_16x16x32_bf16 v[4:7], v[184:187], v[224:227], v[4:7]
	v_mfma_f32_16x16x32_bf16 v[0:3], v[192:195], v[224:227], v[0:3]
	s_barrier
.Lkmid_P9:
	s_add_i32 s30, 0, 0x18000
	v_add_u32_e32 v150, s30, v157
	s_add_i32 s31, 0, 0x1c000
	ds_read_b128 v[164:167], v150
	ds_read_b128 v[168:171], v150 offset:1024
	ds_read_b128 v[172:175], v150 offset:2048
	ds_read_b128 v[176:179], v150 offset:3072
	v_add_u32_e32 v150, s31, v157
	ds_read_b128 v[180:183], v150
	ds_read_b128 v[184:187], v150 offset:1024
	ds_read_b128 v[188:191], v150 offset:2048
	ds_read_b128 v[192:195], v150 offset:3072
	s_add_u32 s22, s22, 0x40000
	s_addc_u32 s23, s23, 0
	s_mov_b32 m0, s50
	v_lshl_add_u64 v[234:235], s[22:23], 0, v[128:129]
	ds_read_b128 v[196:199], v161 offset:32768
	ds_read_b128 v[200:203], v161 offset:33792
	ds_read_b128 v[204:207], v161 offset:34816
	ds_read_b128 v[208:211], v161 offset:35840
	ds_read_b128 v[212:215], v161 offset:36864
	ds_read_b128 v[216:219], v161 offset:37888
	ds_read_b128 v[220:223], v161 offset:38912
	ds_read_b128 v[224:227], v161 offset:39936
	global_load_lds_dwordx4 v[234:235], off
	s_mov_b32 m0, s51
	v_lshl_add_u64 v[234:235], s[22:23], 0, v[132:133]
	global_load_lds_dwordx4 v[234:235], off
	s_waitcnt vmcnt(8)
	s_waitcnt lgkmcnt(0)
	s_barrier
; #define PG8_STAGE(bufoff, gbase, voff) do { _Pragma("unroll") for (int _i = 0; _i < 2; ++_i) \
;         __builtin_amdgcn_global_load_lds((const unsigned*)((const char*)(gbase) + (voff)[_i]), (PG8_LAS unsigned*)(lds + (bufoff) + ldsw + _i * 8192), 16, 0, PG8_LOAD_AUX); } while (0)
; #define PG8_LDA(dst, b, h) do { _Pragma("unroll") for (int m = 0; m < 4; ++m) _Pragma("unroll") for (int k = 0; k < 2; ++k) dst[m][k] = *(const PG8_LAS bf16x8*)(lds + PG8_SA(b, h) + aoff + m * 2048 + k * 1024); } while (0)
; #define PG8_MMA(ai, bj, At, Bt) do { __builtin_amdgcn_s_setprio(1); _Pragma("unroll") for (int m = 0; m < 4; ++m) _Pragma("unroll") for (int n = 0; n < 2; ++n) _Pragma("unroll") for (int k = 0; k < 2; ++k) \
;         acc[ai][bj][m][n] = __builtin_amdgcn_mfma_f32_16x16x32_bf16(Bt[n][k], At[m][k], acc[ai][bj][m][n], 0, 0, 0); __builtin_amdgcn_s_setprio(0); } while (0)
; #define PG8_WAIT_V(n) asm volatile("s_waitcnt vmcnt(" #n ")" ::: "memory")
; #define PG8_WAIT_L(n) asm volatile("s_waitcnt lgkmcnt(" #n ")" ::: "memory")
; #define PG8_BAR __builtin_amdgcn_s_barrier()
; #define PG8_SCHED __builtin_amdgcn_sched_barrier(0)
; template <class Epi, class Sched, bool ALIGN_EPI = false, bool SP2 = false>
; __device__ __forceinline__ void gemm_phase(PG8_LAS unsigned char* lds, const Gemm g, const Sched& S, const Epi& E) {
;     ...
;             PG8_WAIT_V(8); PG8_WAIT_L(0); PG8_BAR; PG8_MMA(0, 0, At, B0); PG8_MMA(0, 1, At, B1); PG8_BAR; PG8_SCHED;
;             PG8_LDA(At, 1, 1); PG8_STAGE(PG8_SB(1, 0), b3, voffB); PG8_STAGE(PG8_SB(1, 1), b3 + hstepB, voffB); PG8_STAGE(PG8_SA(1, 0), a3, voffA);
;             PG8_WAIT_V(8); PG8_WAIT_L(0); PG8_BAR; PG8_MMA(1, 0, At, B0); PG8_MMA(1, 1, At, B1); PG8_BAR; PG8_SCHED;
;     ...
;         if constexpr (ALIGN_EPI) { if (wr == 0) PG8_BAR; }
	s_waitcnt lgkmcnt(0)
	v_mfma_f32_16x16x32_bf16 v[124:127], v[164:167], v[196:199], v[124:127]
	v_mfma_f32_16x16x32_bf16 v[120:123], v[172:175], v[196:199], v[120:123]
	v_mfma_f32_16x16x32_bf16 v[108:111], v[164:167], v[204:207], v[108:111]
	v_mfma_f32_16x16x32_bf16 v[104:107], v[172:175], v[204:207], v[104:107]
	v_mfma_f32_16x16x32_bf16 v[92:95], v[164:167], v[212:215], v[92:95]
	v_mfma_f32_16x16x32_bf16 v[88:91], v[172:175], v[212:215], v[88:91]
	v_mfma_f32_16x16x32_bf16 v[76:79], v[164:167], v[220:223], v[76:79]
	v_mfma_f32_16x16x32_bf16 v[72:75], v[172:175], v[220:223], v[72:75]
	v_mfma_f32_16x16x32_bf16 v[124:127], v[168:171], v[200:203], v[124:127]
	v_mfma_f32_16x16x32_bf16 v[120:123], v[176:179], v[200:203], v[120:123]
	v_mfma_f32_16x16x32_bf16 v[108:111], v[168:171], v[208:211], v[108:111]
	v_mfma_f32_16x16x32_bf16 v[104:107], v[176:179], v[208:211], v[104:107]
	v_mfma_f32_16x16x32_bf16 v[92:95], v[168:171], v[216:219], v[92:95]
	v_mfma_f32_16x16x32_bf16 v[88:91], v[176:179], v[216:219], v[88:91]
	v_mfma_f32_16x16x32_bf16 v[76:79], v[168:171], v[224:227], v[76:79]
	v_mfma_f32_16x16x32_bf16 v[72:75], v[176:179], v[224:227], v[72:75]
	v_mfma_f32_16x16x32_bf16 v[116:119], v[180:183], v[196:199], v[116:119]
	v_mfma_f32_16x16x32_bf16 v[112:115], v[188:191], v[196:199], v[112:115]
	v_mfma_f32_16x16x32_bf16 v[100:103], v[180:183], v[204:207], v[100:103]
	v_mfma_f32_16x16x32_bf16 v[96:99], v[188:191], v[204:207], v[96:99]
	v_mfma_f32_16x16x32_bf16 v[84:87], v[180:183], v[212:215], v[84:87]
	v_mfma_f32_16x16x32_bf16 v[80:83], v[188:191], v[212:215], v[80:83]
	v_mfma_f32_16x16x32_bf16 v[68:71], v[180:183], v[220:223], v[68:71]
	v_mfma_f32_16x16x32_bf16 v[64:67], v[188:191], v[220:223], v[64:67]
	v_mfma_f32_16x16x32_bf16 v[116:119], v[184:187], v[200:203], v[116:119]
	v_mfma_f32_16x16x32_bf16 v[112:115], v[192:195], v[200:203], v[112:115]
	v_mfma_f32_16x16x32_bf16 v[100:103], v[184:187], v[208:211], v[100:103]
	v_mfma_f32_16x16x32_bf16 v[96:99], v[192:195], v[208:211], v[96:99]
	v_mfma_f32_16x16x32_bf16 v[84:87], v[184:187], v[216:219], v[84:87]
	v_mfma_f32_16x16x32_bf16 v[80:83], v[192:195], v[216:219], v[80:83]
	v_mfma_f32_16x16x32_bf16 v[68:71], v[184:187], v[224:227], v[68:71]
	v_mfma_f32_16x16x32_bf16 v[64:67], v[192:195], v[224:227], v[64:67]
	s_barrier
	s_add_i32 s22, s30, s34
	v_lshl_add_u64 v[148:149], v[148:149], 0, s[16:17]
	s_mov_b32 m0, s22
	ds_read_b128 v[196:199], v161 offset:49152
	ds_read_b128 v[200:203], v161 offset:50176
	ds_read_b128 v[204:207], v161 offset:51200
	ds_read_b128 v[208:211], v161 offset:52224
	ds_read_b128 v[212:215], v161 offset:53248
	ds_read_b128 v[216:219], v161 offset:54272
	ds_read_b128 v[220:223], v161 offset:55296
	ds_read_b128 v[224:227], v161 offset:56320
	global_load_lds_dwordx4 v[148:149], off
	s_add_i32 m0, s22, 0x2000
	s_add_u32 s20, s20, 0x10080
	v_lshl_add_u64 v[148:149], v[228:229], 0, s[16:17]
	s_addc_u32 s21, s21, 0
	s_add_i32 s22, s31, s34
	global_load_lds_dwordx4 v[148:149], off
	s_mov_b32 m0, s22
	v_lshl_add_u64 v[148:149], s[20:21], 0, v[130:131]
	global_load_lds_dwordx4 v[148:149], off
	s_add_i32 m0, s22, 0x2000
	v_lshl_add_u64 v[148:149], s[20:21], 0, v[134:135]
	global_load_lds_dwordx4 v[148:149], off
	s_mov_b32 m0, s56
	v_lshl_add_u64 v[148:149], v[230:231], 0, s[16:17]
	global_load_lds_dwordx4 v[148:149], off
	s_mov_b32 m0, s57
	v_lshl_add_u64 v[148:149], v[232:233], 0, s[16:17]
	global_load_lds_dwordx4 v[148:149], off
	s_waitcnt vmcnt(8)
	s_waitcnt lgkmcnt(0)
	s_barrier
	s_waitcnt lgkmcnt(0)
	v_mfma_f32_16x16x32_bf16 v[60:63], v[164:167], v[196:199], v[60:63]
	v_mfma_f32_16x16x32_bf16 v[56:59], v[172:175], v[196:199], v[56:59]
	v_mfma_f32_16x16x32_bf16 v[44:47], v[164:167], v[204:207], v[44:47]
	v_mfma_f32_16x16x32_bf16 v[40:43], v[172:175], v[204:207], v[40:43]
	v_mfma_f32_16x16x32_bf16 v[28:31], v[164:167], v[212:215], v[28:31]
	v_mfma_f32_16x16x32_bf16 v[24:27], v[172:175], v[212:215], v[24:27]
	v_mfma_f32_16x16x32_bf16 v[12:15], v[164:167], v[220:223], v[12:15]
	v_mfma_f32_16x16x32_bf16 v[8:11], v[172:175], v[220:223], v[8:11]
	v_mfma_f32_16x16x32_bf16 v[60:63], v[168:171], v[200:203], v[60:63]
	v_mfma_f32_16x16x32_bf16 v[56:59], v[176:179], v[200:203], v[56:59]
	v_mfma_f32_16x16x32_bf16 v[44:47], v[168:171], v[208:211], v[44:47]
	v_mfma_f32_16x16x32_bf16 v[40:43], v[176:179], v[208:211], v[40:43]
	v_mfma_f32_16x16x32_bf16 v[28:31], v[168:171], v[216:219], v[28:31]
	v_mfma_f32_16x16x32_bf16 v[24:27], v[176:179], v[216:219], v[24:27]
	v_mfma_f32_16x16x32_bf16 v[12:15], v[168:171], v[224:227], v[12:15]
	v_mfma_f32_16x16x32_bf16 v[8:11], v[176:179], v[224:227], v[8:11]
	v_mfma_f32_16x16x32_bf16 v[52:55], v[180:183], v[196:199], v[52:55]
	v_mfma_f32_16x16x32_bf16 v[48:51], v[188:191], v[196:199], v[48:51]
	v_mfma_f32_16x16x32_bf16 v[36:39], v[180:183], v[204:207], v[36:39]
	v_mfma_f32_16x16x32_bf16 v[32:35], v[188:191], v[204:207], v[32:35]
	v_mfma_f32_16x16x32_bf16 v[20:23], v[180:183], v[212:215], v[20:23]
	v_mfma_f32_16x16x32_bf16 v[16:19], v[188:191], v[212:215], v[16:19]
	v_mfma_f32_16x16x32_bf16 v[4:7], v[180:183], v[220:223], v[4:7]
	v_mfma_f32_16x16x32_bf16 v[0:3], v[188:191], v[220:223], v[0:3]
	v_mfma_f32_16x16x32_bf16 v[52:55], v[184:187], v[200:203], v[52:55]
	v_mfma_f32_16x16x32_bf16 v[48:51], v[192:195], v[200:203], v[48:51]
	v_mfma_f32_16x16x32_bf16 v[36:39], v[184:187], v[208:211], v[36:39]
	v_mfma_f32_16x16x32_bf16 v[32:35], v[192:195], v[208:211], v[32:35]
	v_mfma_f32_16x16x32_bf16 v[20:23], v[184:187], v[216:219], v[20:23]
	v_mfma_f32_16x16x32_bf16 v[16:19], v[192:195], v[216:219], v[16:19]
	v_mfma_f32_16x16x32_bf16 v[4:7], v[184:187], v[224:227], v[4:7]
	v_mfma_f32_16x16x32_bf16 v[0:3], v[192:195], v[224:227], v[0:3]
	s_barrier
	s_add_i32 s29, s29, 2
	s_add_u32 s0, s0, 0x100
	s_addc_u32 s1, s1, 0
	s_add_u32 s27, s27, 0x100
	s_addc_u32 s28, s28, 0
	s_cmp_gt_u32 s29, 13
	s_cbranch_scc0 .LBB0_850
	s_and_b64 vcc, exec, s[18:19]
	s_cbranch_vccz .LBB0_853
	s_barrier

; #define PG8_STAGE(bufoff, gbase, voff) do { _Pragma("unroll") for (int _i = 0; _i < 2; ++_i) \
;         __builtin_amdgcn_global_load_lds((const unsigned*)((const char*)(gbase) + (voff)[_i]), (PG8_LAS unsigned*)(lds + (bufoff) + ldsw + _i * 8192), 16, 0, PG8_LOAD_AUX); } while (0)
; #define PG8_LDA(dst, b, h) do { _Pragma("unroll") for (int m = 0; m < 4; ++m) _Pragma("unroll") for (int k = 0; k < 2; ++k) dst[m][k] = *(const PG8_LAS bf16x8*)(lds + PG8_SA(b, h) + aoff + m * 2048 + k * 1024); } while (0)
; #define PG8_LDB(dst, b, h) do { _Pragma("unroll") for (int n = 0; n < 2; ++n) _Pragma("unroll") for (int k = 0; k < 2; ++k) dst[n][k] = *(const PG8_LAS bf16x8*)(lds + PG8_SB(b, h) + boff + n * 2048 + k * 1024); } while (0)
; #define PG8_WAIT_V(n) asm volatile("s_waitcnt vmcnt(" #n ")" ::: "memory")
; #define PG8_WAIT_L(n) asm volatile("s_waitcnt lgkmcnt(" #n ")" ::: "memory")
; #define PG8_BAR __builtin_amdgcn_s_barrier()
; #define PG8_SCHED __builtin_amdgcn_sched_barrier(0)
; template <class Epi, class Sched, bool ALIGN_EPI = false, bool SP2 = false>
; __device__ __forceinline__ void gemm_phase(PG8_LAS unsigned char* lds, const Gemm g, const Sched& S, const Epi& E) {
;     ...
;         const bool has_next = S.next(ui + 1, nxt);
;         const char* nA = has_next ? (const char*)g.A + (size_t)nxt.pm * tstepA + (size_t)nxt.pn * apn : cA; const char* nB = has_next ? (const char*)g.Bt + (size_t)nxt.pn * tstepB : cB;
;         for (int t = 0; t < nt; t += 2) {
;             const bool last = (t == nt - 2);
;             const char* a1 = cA + (size_t)(t + 1) * kstep;
;             const char* a2 = last ? nA : cA + (size_t)(t + 2) * kstep; const char* b2 = last ? nB : cB + (size_t)(t + 2) * kstep;
;             const char* a3 = a2 + kstep; const char* b3 = b2 + kstep;
;             if (last && has_next) S.a_ready(nxt);
;             if constexpr (SP2) {
;             PG8_LDB(B0, 0, 0); PG8_LDB(B1, 0, 1); PG8_SCHED; PG8_LDA(At, 0, 0); PG8_STAGE(PG8_SA(1, 1), a1 + hstepA, voffA);
;             PG8_WAIT_V(8); PG8_WAIT_L(0); PG8_BAR; PG8_MMA(0, 0, At, B0); PG8_MMA(0, 1, At, B1); PG8_BAR; PG8_SCHED;
;             PG8_LDA(At, 0, 1); PG8_STAGE(PG8_SB(0, 0), b2, voffB); PG8_STAGE(PG8_SB(0, 1), b2 + hstepB, voffB); PG8_STAGE(PG8_SA(0, 0), a2, voffA);
;             PG8_WAIT_V(8); PG8_WAIT_L(0); PG8_BAR; PG8_MMA(1, 0, At, B0); PG8_MMA(1, 1, At, B1); PG8_BAR; PG8_SCHED;
.LBB0_1017:
	s_lshl_b64 s[22:23], s[40:41], 17
	v_readlane_b32 s24, v239, 38
	s_add_u32 s44, s24, s22
	v_readlane_b32 s22, v239, 39
	s_addc_u32 s45, s22, s23
	s_and_b64 s[22:23], s[6:7], exec
	s_cselect_b32 s24, s45, s1
	s_cselect_b32 s25, s44, s0
	s_mov_b32 s26, 0
	s_mov_b64 s[22:23], -1
	s_mov_b64 s[34:35], 0
	s_waitcnt lgkmcnt(0)
	s_add_u32 s30, s20, s26
	s_addc_u32 s31, s21, 0
	s_add_u32 s27, s30, 0x100
	s_addc_u32 s33, s31, 0
	s_and_b64 s[28:29], s[34:35], exec
	s_cselect_b32 s51, s9, s33
	s_cselect_b32 s50, s8, s27
	s_add_u32 s26, s0, s26
	s_addc_u32 s27, s1, 0
	s_add_u32 s28, s26, 0x100
	s_addc_u32 s29, s27, 0
	s_and_b64 s[26:27], s[34:35], exec
	s_cselect_b32 s53, s24, s29
	s_cselect_b32 s52, s25, s28
	s_add_u32 s56, s30, 0x40080
	ds_read_b128 v[142:145], v150
	ds_read_b128 v[156:159], v150 offset:1024
	ds_read_b128 v[160:163], v150 offset:2048
	ds_read_b128 v[164:167], v150 offset:3072
	ds_read_b128 v[168:171], v151
	ds_read_b128 v[172:175], v151 offset:1024
	ds_read_b128 v[176:179], v151 offset:2048
	ds_read_b128 v[180:183], v151 offset:3072
	s_addc_u32 s57, s31, 0
	s_add_i32 s38, s70, s58
	s_add_i32 m0, s47, 0xc000
	s_add_i32 s43, s47, 0xe000
	s_add_i32 s30, s38, 0x2000
	s_add_u32 s54, s52, 0x4000
	s_addc_u32 s55, s53, 0
	s_add_i32 s33, s71, s58
	s_add_i32 s31, s33, 0x2000
	s_add_i32 s29, 0, 0x18000
	s_add_i32 s28, 0, 0x1c000
	s_add_u32 s48, s50, 0x40000
	s_addc_u32 s49, s51, 0
	s_add_i32 s27, s29, s58
	s_add_i32 s26, s27, 0x2000
	s_add_u32 s34, s52, 0x4080
	s_addc_u32 s35, s53, 0
	s_add_i32 s41, s28, s58
	s_add_i32 s39, s41, 0x2000
	v_lshl_add_u64 v[216:217], s[56:57], 0, v[128:129]
	ds_read_b128 v[184:187], v152
	ds_read_b128 v[188:191], v152 offset:1024
	ds_read_b128 v[192:195], v152 offset:2048
	ds_read_b128 v[196:199], v152 offset:3072
	ds_read_b128 v[200:203], v152 offset:4096
	ds_read_b128 v[204:207], v152 offset:5120
	ds_read_b128 v[208:211], v152 offset:6144
	ds_read_b128 v[212:215], v152 offset:7168
	global_load_lds_dwordx4 v[216:217], off
	s_mov_b32 m0, s43
	v_lshl_add_u64 v[216:217], s[56:57], 0, v[132:133]
	global_load_lds_dwordx4 v[216:217], off
	s_waitcnt vmcnt(8)
	s_waitcnt lgkmcnt(0)
	s_barrier
	s_waitcnt lgkmcnt(0)
	v_mfma_f32_16x16x32_bf16 v[124:127], v[142:145], v[184:187], 0
	v_mfma_f32_16x16x32_bf16 v[120:123], v[160:163], v[184:187], 0
	v_mfma_f32_16x16x32_bf16 v[108:111], v[142:145], v[192:195], 0
	v_mfma_f32_16x16x32_bf16 v[104:107], v[160:163], v[192:195], 0
	v_mfma_f32_16x16x32_bf16 v[92:95], v[142:145], v[200:203], 0
	v_mfma_f32_16x16x32_bf16 v[88:91], v[160:163], v[200:203], 0
	v_mfma_f32_16x16x32_bf16 v[76:79], v[142:145], v[208:211], 0
	v_mfma_f32_16x16x32_bf16 v[72:75], v[160:163], v[208:211], 0
	v_mfma_f32_16x16x32_bf16 v[124:127], v[156:159], v[188:191], v[124:127]
	v_mfma_f32_16x16x32_bf16 v[120:123], v[164:167], v[188:191], v[120:123]
	v_mfma_f32_16x16x32_bf16 v[108:111], v[156:159], v[196:199], v[108:111]
	v_mfma_f32_16x16x32_bf16 v[104:107], v[164:167], v[196:199], v[104:107]
	v_mfma_f32_16x16x32_bf16 v[92:95], v[156:159], v[204:207], v[92:95]
	v_mfma_f32_16x16x32_bf16 v[88:91], v[164:167], v[204:207], v[88:91]
	v_mfma_f32_16x16x32_bf16 v[76:79], v[156:159], v[212:215], v[76:79]
	v_mfma_f32_16x16x32_bf16 v[72:75], v[164:167], v[212:215], v[72:75]
	v_mfma_f32_16x16x32_bf16 v[116:119], v[168:171], v[184:187], 0
	v_mfma_f32_16x16x32_bf16 v[112:115], v[176:179], v[184:187], 0
	v_mfma_f32_16x16x32_bf16 v[100:103], v[168:171], v[192:195], 0
	v_mfma_f32_16x16x32_bf16 v[96:99], v[176:179], v[192:195], 0
	v_mfma_f32_16x16x32_bf16 v[84:87], v[168:171], v[200:203], 0
	v_mfma_f32_16x16x32_bf16 v[80:83], v[176:179], v[200:203], 0
	v_mfma_f32_16x16x32_bf16 v[68:71], v[168:171], v[208:211], 0
	v_mfma_f32_16x16x32_bf16 v[64:67], v[176:179], v[208:211], 0
	v_mfma_f32_16x16x32_bf16 v[116:119], v[172:175], v[188:191], v[116:119]
	v_mfma_f32_16x16x32_bf16 v[112:115], v[180:183], v[188:191], v[112:115]
	v_mfma_f32_16x16x32_bf16 v[100:103], v[172:175], v[196:199], v[100:103]
	v_mfma_f32_16x16x32_bf16 v[96:99], v[180:183], v[196:199], v[96:99]
	v_mfma_f32_16x16x32_bf16 v[84:87], v[172:175], v[204:207], v[84:87]
	v_mfma_f32_16x16x32_bf16 v[80:83], v[180:183], v[204:207], v[80:83]
	v_mfma_f32_16x16x32_bf16 v[68:71], v[172:175], v[212:215], v[68:71]
	v_mfma_f32_16x16x32_bf16 v[64:67], v[180:183], v[212:215], v[64:67]
	s_barrier
	s_mov_b32 m0, s38
	v_lshl_add_u64 v[216:217], s[52:53], 0, v[130:131]
	ds_read_b128 v[184:187], v152 offset:16384
	ds_read_b128 v[188:191], v152 offset:17408
	ds_read_b128 v[192:195], v152 offset:18432
	ds_read_b128 v[196:199], v152 offset:19456
	ds_read_b128 v[200:203], v152 offset:20480
	ds_read_b128 v[204:207], v152 offset:21504
	ds_read_b128 v[208:211], v152 offset:22528
	ds_read_b128 v[212:215], v152 offset:23552
	global_load_lds_dwordx4 v[216:217], off
	v_lshl_add_u64 v[218:219], s[52:53], 0, v[134:135]
	s_mov_b32 m0, s30
	v_lshl_add_u64 v[220:221], s[54:55], 0, v[130:131]
	global_load_lds_dwordx4 v[218:219], off
	s_mov_b32 m0, s33
	v_lshl_add_u64 v[222:223], s[50:51], 0, v[132:133]
	global_load_lds_dwordx4 v[220:221], off
	s_mov_b32 m0, s31
	v_lshl_add_u64 v[220:221], s[54:55], 0, v[134:135]
	global_load_lds_dwordx4 v[220:221], off
	s_mov_b32 m0, s47
	v_lshl_add_u64 v[220:221], s[50:51], 0, v[128:129]
	global_load_lds_dwordx4 v[220:221], off
	s_mov_b32 m0, s59
	s_nop 0
	global_load_lds_dwordx4 v[222:223], off
	s_waitcnt vmcnt(8)
	s_waitcnt lgkmcnt(0)
	s_barrier
; #define PG8_STAGE(bufoff, gbase, voff) do { _Pragma("unroll") for (int _i = 0; _i < 2; ++_i) \
;         __builtin_amdgcn_global_load_lds((const unsigned*)((const char*)(gbase) + (voff)[_i]), (PG8_LAS unsigned*)(lds + (bufoff) + ldsw + _i * 8192), 16, 0, PG8_LOAD_AUX); } while (0)
; #define PG8_LDA(dst, b, h) do { _Pragma("unroll") for (int m = 0; m < 4; ++m) _Pragma("unroll") for (int k = 0; k < 2; ++k) dst[m][k] = *(const PG8_LAS bf16x8*)(lds + PG8_SA(b, h) + aoff + m * 2048 + k * 1024); } while (0)
; #define PG8_LDB(dst, b, h) do { _Pragma("unroll") for (int n = 0; n < 2; ++n) _Pragma("unroll") for (int k = 0; k < 2; ++k) dst[n][k] = *(const PG8_LAS bf16x8*)(lds + PG8_SB(b, h) + boff + n * 2048 + k * 1024); } while (0)
; #define PG8_MMA(ai, bj, At, Bt) do { __builtin_amdgcn_s_setprio(1); _Pragma("unroll") for (int m = 0; m < 4; ++m) _Pragma("unroll") for (int n = 0; n < 2; ++n) _Pragma("unroll") for (int k = 0; k < 2; ++k) \
;         acc[ai][bj][m][n] = __builtin_amdgcn_mfma_f32_16x16x32_bf16(Bt[n][k], At[m][k], acc[ai][bj][m][n], 0, 0, 0); __builtin_amdgcn_s_setprio(0); } while (0)
; #define PG8_WAIT_V(n) asm volatile("s_waitcnt vmcnt(" #n ")" ::: "memory")
; #define PG8_WAIT_L(n) asm volatile("s_waitcnt lgkmcnt(" #n ")" ::: "memory")
; #define PG8_BAR __builtin_amdgcn_s_barrier()
; #define PG8_SCHED __builtin_amdgcn_sched_barrier(0)
; template <class Epi, class Sched, bool ALIGN_EPI = false, bool SP2 = false>
; __device__ __forceinline__ void gemm_phase(PG8_LAS unsigned char* lds, const Gemm g, const Sched& S, const Epi& E) {
;     ...
;             PG8_LDB(B0, 0, 0); PG8_LDB(B1, 0, 1); PG8_SCHED; PG8_LDA(At, 0, 0); PG8_STAGE(PG8_SA(1, 1), a1 + hstepA, voffA);
;             PG8_WAIT_V(8); PG8_WAIT_L(0); PG8_BAR; PG8_MMA(0, 0, At, B0); PG8_MMA(0, 1, At, B1); PG8_BAR; PG8_SCHED;
;             PG8_LDA(At, 0, 1); PG8_STAGE(PG8_SB(0, 0), b2, voffB); PG8_STAGE(PG8_SB(0, 1), b2 + hstepB, voffB); PG8_STAGE(PG8_SA(0, 0), a2, voffA);
;             PG8_WAIT_V(8); PG8_WAIT_L(0); PG8_BAR; PG8_MMA(1, 0, At, B0); PG8_MMA(1, 1, At, B1); PG8_BAR; PG8_SCHED;
	s_waitcnt lgkmcnt(0)
	v_mfma_f32_16x16x32_bf16 v[60:63], v[142:145], v[184:187], 0
	v_mfma_f32_16x16x32_bf16 v[56:59], v[160:163], v[184:187], 0
	v_mfma_f32_16x16x32_bf16 v[44:47], v[142:145], v[192:195], 0
	v_mfma_f32_16x16x32_bf16 v[40:43], v[160:163], v[192:195], 0
	v_mfma_f32_16x16x32_bf16 v[28:31], v[142:145], v[200:203], 0
	v_mfma_f32_16x16x32_bf16 v[24:27], v[160:163], v[200:203], 0
	v_mfma_f32_16x16x32_bf16 v[12:15], v[142:145], v[208:211], 0
	v_mfma_f32_16x16x32_bf16 v[8:11], v[160:163], v[208:211], 0
	v_mfma_f32_16x16x32_bf16 v[60:63], v[156:159], v[188:191], v[60:63]
	v_mfma_f32_16x16x32_bf16 v[56:59], v[164:167], v[188:191], v[56:59]
	v_mfma_f32_16x16x32_bf16 v[44:47], v[156:159], v[196:199], v[44:47]
	v_mfma_f32_16x16x32_bf16 v[40:43], v[164:167], v[196:199], v[40:43]
	v_mfma_f32_16x16x32_bf16 v[28:31], v[156:159], v[204:207], v[28:31]
	v_mfma_f32_16x16x32_bf16 v[24:27], v[164:167], v[204:207], v[24:27]
	v_mfma_f32_16x16x32_bf16 v[12:15], v[156:159], v[212:215], v[12:15]
	v_mfma_f32_16x16x32_bf16 v[8:11], v[164:167], v[212:215], v[8:11]
	v_mfma_f32_16x16x32_bf16 v[52:55], v[168:171], v[184:187], 0
	v_mfma_f32_16x16x32_bf16 v[48:51], v[176:179], v[184:187], 0
	v_mfma_f32_16x16x32_bf16 v[36:39], v[168:171], v[192:195], 0
	v_mfma_f32_16x16x32_bf16 v[32:35], v[176:179], v[192:195], 0
	v_mfma_f32_16x16x32_bf16 v[20:23], v[168:171], v[200:203], 0
	v_mfma_f32_16x16x32_bf16 v[16:19], v[176:179], v[200:203], 0
	v_mfma_f32_16x16x32_bf16 v[4:7], v[168:171], v[208:211], 0
	v_mfma_f32_16x16x32_bf16 v[0:3], v[176:179], v[208:211], 0
	v_mfma_f32_16x16x32_bf16 v[52:55], v[172:175], v[188:191], v[52:55]
	v_mfma_f32_16x16x32_bf16 v[48:51], v[180:183], v[188:191], v[48:51]
	v_mfma_f32_16x16x32_bf16 v[36:39], v[172:175], v[196:199], v[36:39]
	v_mfma_f32_16x16x32_bf16 v[32:35], v[180:183], v[196:199], v[32:35]
	v_mfma_f32_16x16x32_bf16 v[20:23], v[172:175], v[204:207], v[20:23]
	v_mfma_f32_16x16x32_bf16 v[16:19], v[180:183], v[204:207], v[16:19]
	v_mfma_f32_16x16x32_bf16 v[4:7], v[172:175], v[212:215], v[4:7]
	v_mfma_f32_16x16x32_bf16 v[0:3], v[180:183], v[212:215], v[0:3]
	s_barrier
	s_branch .Lkmid_P11
.LBB0_1018:
	s_add_u32 s30, s20, s26
	s_addc_u32 s31, s21, 0
	s_add_u32 s27, s30, 0x100
	s_addc_u32 s33, s31, 0
	s_and_b64 s[28:29], s[34:35], exec
	s_cselect_b32 s51, s9, s33
	s_cselect_b32 s50, s8, s27
	s_add_u32 s26, s0, s26
	s_addc_u32 s27, s1, 0
	s_add_u32 s28, s26, 0x100
	s_addc_u32 s29, s27, 0
	s_and_b64 s[26:27], s[34:35], exec
	s_cselect_b32 s53, s24, s29
	s_cselect_b32 s52, s25, s28
	s_add_u32 s56, s30, 0x40080
	ds_read_b128 v[142:145], v150
	ds_read_b128 v[156:159], v150 offset:1024
	ds_read_b128 v[160:163], v150 offset:2048
	ds_read_b128 v[164:167], v150 offset:3072
	ds_read_b128 v[168:171], v151
	ds_read_b128 v[172:175], v151 offset:1024
	ds_read_b128 v[176:179], v151 offset:2048
	ds_read_b128 v[180:183], v151 offset:3072
	s_addc_u32 s57, s31, 0
	s_add_i32 s38, s70, s58
	s_add_i32 m0, s47, 0xc000
	s_add_i32 s43, s47, 0xe000
	s_add_i32 s30, s38, 0x2000
	s_add_u32 s54, s52, 0x4000
	s_addc_u32 s55, s53, 0
	s_add_i32 s33, s71, s58
	s_add_i32 s31, s33, 0x2000
	s_add_i32 s29, 0, 0x18000
	s_add_i32 s28, 0, 0x1c000
	s_add_u32 s48, s50, 0x40000
	s_addc_u32 s49, s51, 0
	s_add_i32 s27, s29, s58
	s_add_i32 s26, s27, 0x2000
	s_add_u32 s34, s52, 0x4080
	s_addc_u32 s35, s53, 0
	s_add_i32 s41, s28, s58
	s_add_i32 s39, s41, 0x2000
	v_lshl_add_u64 v[216:217], s[56:57], 0, v[128:129]
	ds_read_b128 v[184:187], v152
	ds_read_b128 v[188:191], v152 offset:1024
	ds_read_b128 v[192:195], v152 offset:2048
	ds_read_b128 v[196:199], v152 offset:3072
	ds_read_b128 v[200:203], v152 offset:4096
	ds_read_b128 v[204:207], v152 offset:5120
	ds_read_b128 v[208:211], v152 offset:6144
	ds_read_b128 v[212:215], v152 offset:7168
	global_load_lds_dwordx4 v[216:217], off
	s_mov_b32 m0, s43
	v_lshl_add_u64 v[216:217], s[56:57], 0, v[132:133]
	global_load_lds_dwordx4 v[216:217], off
	s_waitcnt vmcnt(8)
	s_waitcnt lgkmcnt(0)
	s_barrier
	s_waitcnt lgkmcnt(0)
	v_mfma_f32_16x16x32_bf16 v[124:127], v[142:145], v[184:187], v[124:127]
	v_mfma_f32_16x16x32_bf16 v[120:123], v[160:163], v[184:187], v[120:123]
	v_mfma_f32_16x16x32_bf16 v[108:111], v[142:145], v[192:195], v[108:111]
	v_mfma_f32_16x16x32_bf16 v[104:107], v[160:163], v[192:195], v[104:107]
	v_mfma_f32_16x16x32_bf16 v[92:95], v[142:145], v[200:203], v[92:95]
	v_mfma_f32_16x16x32_bf16 v[88:91], v[160:163], v[200:203], v[88:91]
	v_mfma_f32_16x16x32_bf16 v[76:79], v[142:145], v[208:211], v[76:79]
	v_mfma_f32_16x16x32_bf16 v[72:75], v[160:163], v[208:211], v[72:75]
	v_mfma_f32_16x16x32_bf16 v[124:127], v[156:159], v[188:191], v[124:127]
	v_mfma_f32_16x16x32_bf16 v[120:123], v[164:167], v[188:191], v[120:123]
	v_mfma_f32_16x16x32_bf16 v[108:111], v[156:159], v[196:199], v[108:111]
	v_mfma_f32_16x16x32_bf16 v[104:107], v[164:167], v[196:199], v[104:107]
	v_mfma_f32_16x16x32_bf16 v[92:95], v[156:159], v[204:207], v[92:95]
	v_mfma_f32_16x16x32_bf16 v[88:91], v[164:167], v[204:207], v[88:91]
	v_mfma_f32_16x16x32_bf16 v[76:79], v[156:159], v[212:215], v[76:79]
	v_mfma_f32_16x16x32_bf16 v[72:75], v[164:167], v[212:215], v[72:75]
	v_mfma_f32_16x16x32_bf16 v[116:119], v[168:171], v[184:187], v[116:119]
	v_mfma_f32_16x16x32_bf16 v[112:115], v[176:179], v[184:187], v[112:115]
	v_mfma_f32_16x16x32_bf16 v[100:103], v[168:171], v[192:195], v[100:103]
	v_mfma_f32_16x16x32_bf16 v[96:99], v[176:179], v[192:195], v[96:99]
	v_mfma_f32_16x16x32_bf16 v[84:87], v[168:171], v[200:203], v[84:87]
	v_mfma_f32_16x16x32_bf16 v[80:83], v[176:179], v[200:203], v[80:83]
	v_mfma_f32_16x16x32_bf16 v[68:71], v[168:171], v[208:211], v[68:71]
	v_mfma_f32_16x16x32_bf16 v[64:67], v[176:179], v[208:211], v[64:67]
	v_mfma_f32_16x16x32_bf16 v[116:119], v[172:175], v[188:191], v[116:119]
	v_mfma_f32_16x16x32_bf16 v[112:115], v[180:183], v[188:191], v[112:115]
	v_mfma_f32_16x16x32_bf16 v[100:103], v[172:175], v[196:199], v[100:103]
	v_mfma_f32_16x16x32_bf16 v[96:99], v[180:183], v[196:199], v[96:99]
	v_mfma_f32_16x16x32_bf16 v[84:87], v[172:175], v[204:207], v[84:87]
	v_mfma_f32_16x16x32_bf16 v[80:83], v[180:183], v[204:207], v[80:83]
	v_mfma_f32_16x16x32_bf16 v[68:71], v[172:175], v[212:215], v[68:71]
	v_mfma_f32_16x16x32_bf16 v[64:67], v[180:183], v[212:215], v[64:67]
	s_barrier
; #define PG8_STAGE(bufoff, gbase, voff) do { _Pragma("unroll") for (int _i = 0; _i < 2; ++_i) \
;         __builtin_amdgcn_global_load_lds((const unsigned*)((const char*)(gbase) + (voff)[_i]), (PG8_LAS unsigned*)(lds + (bufoff) + ldsw + _i * 8192), 16, 0, PG8_LOAD_AUX); } while (0)
; #define PG8_LDA(dst, b, h) do { _Pragma("unroll") for (int m = 0; m < 4; ++m) _Pragma("unroll") for (int k = 0; k < 2; ++k) dst[m][k] = *(const PG8_LAS bf16x8*)(lds + PG8_SA(b, h) + aoff + m * 2048 + k * 1024); } while (0)
; #define PG8_LDB(dst, b, h) do { _Pragma("unroll") for (int n = 0; n < 2; ++n) _Pragma("unroll") for (int k = 0; k < 2; ++k) dst[n][k] = *(const PG8_LAS bf16x8*)(lds + PG8_SB(b, h) + boff + n * 2048 + k * 1024); } while (0)
; #define PG8_MMA(ai, bj, At, Bt) do { __builtin_amdgcn_s_setprio(1); _Pragma("unroll") for (int m = 0; m < 4; ++m) _Pragma("unroll") for (int n = 0; n < 2; ++n) _Pragma("unroll") for (int k = 0; k < 2; ++k) \
;         acc[ai][bj][m][n] = __builtin_amdgcn_mfma_f32_16x16x32_bf16(Bt[n][k], At[m][k], acc[ai][bj][m][n], 0, 0, 0); __builtin_amdgcn_s_setprio(0); } while (0)
; #define PG8_WAIT_V(n) asm volatile("s_waitcnt vmcnt(" #n ")" ::: "memory")
; #define PG8_WAIT_L(n) asm volatile("s_waitcnt lgkmcnt(" #n ")" ::: "memory")
; #define PG8_BAR __builtin_amdgcn_s_barrier()
; #define PG8_SCHED __builtin_amdgcn_sched_barrier(0)
; template <class Epi, class Sched, bool ALIGN_EPI = false, bool SP2 = false>
; __device__ __forceinline__ void gemm_phase(PG8_LAS unsigned char* lds, const Gemm g, const Sched& S, const Epi& E) {
;     ...
;             PG8_WAIT_V(8); PG8_WAIT_L(0); PG8_BAR; PG8_MMA(1, 0, At, B0); PG8_MMA(1, 1, At, B1); PG8_BAR; PG8_SCHED;
;             PG8_LDB(B0, 1, 0); PG8_LDB(B1, 1, 1); PG8_SCHED; PG8_LDA(At, 1, 0); PG8_STAGE(PG8_SA(0, 1), a2 + hstepA, voffA);
;             PG8_WAIT_V(8); PG8_WAIT_L(0); PG8_BAR; PG8_MMA(0, 0, At, B0); PG8_MMA(0, 1, At, B1); PG8_BAR; PG8_SCHED;
	s_mov_b32 m0, s38
	v_lshl_add_u64 v[216:217], s[52:53], 0, v[130:131]
	ds_read_b128 v[184:187], v152 offset:16384
	ds_read_b128 v[188:191], v152 offset:17408
	ds_read_b128 v[192:195], v152 offset:18432
	ds_read_b128 v[196:199], v152 offset:19456
	ds_read_b128 v[200:203], v152 offset:20480
	ds_read_b128 v[204:207], v152 offset:21504
	ds_read_b128 v[208:211], v152 offset:22528
	ds_read_b128 v[212:215], v152 offset:23552
	global_load_lds_dwordx4 v[216:217], off
	v_lshl_add_u64 v[218:219], s[52:53], 0, v[134:135]
	s_mov_b32 m0, s30
	v_lshl_add_u64 v[220:221], s[54:55], 0, v[130:131]
	global_load_lds_dwordx4 v[218:219], off
	s_mov_b32 m0, s33
	v_lshl_add_u64 v[222:223], s[50:51], 0, v[132:133]
	global_load_lds_dwordx4 v[220:221], off
	s_mov_b32 m0, s31
	v_lshl_add_u64 v[220:221], s[54:55], 0, v[134:135]
	global_load_lds_dwordx4 v[220:221], off
	s_mov_b32 m0, s47
	v_lshl_add_u64 v[220:221], s[50:51], 0, v[128:129]
	global_load_lds_dwordx4 v[220:221], off
	s_mov_b32 m0, s59
	s_nop 0
	global_load_lds_dwordx4 v[222:223], off
	s_waitcnt vmcnt(8)
	s_waitcnt lgkmcnt(0)
	s_barrier
	s_waitcnt lgkmcnt(0)
	v_mfma_f32_16x16x32_bf16 v[60:63], v[142:145], v[184:187], v[60:63]
	v_mfma_f32_16x16x32_bf16 v[56:59], v[160:163], v[184:187], v[56:59]
	v_mfma_f32_16x16x32_bf16 v[44:47], v[142:145], v[192:195], v[44:47]
	v_mfma_f32_16x16x32_bf16 v[40:43], v[160:163], v[192:195], v[40:43]
	v_mfma_f32_16x16x32_bf16 v[28:31], v[142:145], v[200:203], v[28:31]
	v_mfma_f32_16x16x32_bf16 v[24:27], v[160:163], v[200:203], v[24:27]
	v_mfma_f32_16x16x32_bf16 v[12:15], v[142:145], v[208:211], v[12:15]
	v_mfma_f32_16x16x32_bf16 v[8:11], v[160:163], v[208:211], v[8:11]
	v_mfma_f32_16x16x32_bf16 v[60:63], v[156:159], v[188:191], v[60:63]
	v_mfma_f32_16x16x32_bf16 v[56:59], v[164:167], v[188:191], v[56:59]
	v_mfma_f32_16x16x32_bf16 v[44:47], v[156:159], v[196:199], v[44:47]
	v_mfma_f32_16x16x32_bf16 v[40:43], v[164:167], v[196:199], v[40:43]
	v_mfma_f32_16x16x32_bf16 v[28:31], v[156:159], v[204:207], v[28:31]
	v_mfma_f32_16x16x32_bf16 v[24:27], v[164:167], v[204:207], v[24:27]
	v_mfma_f32_16x16x32_bf16 v[12:15], v[156:159], v[212:215], v[12:15]
	v_mfma_f32_16x16x32_bf16 v[8:11], v[164:167], v[212:215], v[8:11]
	v_mfma_f32_16x16x32_bf16 v[52:55], v[168:171], v[184:187], v[52:55]
	v_mfma_f32_16x16x32_bf16 v[48:51], v[176:179], v[184:187], v[48:51]
	v_mfma_f32_16x16x32_bf16 v[36:39], v[168:171], v[192:195], v[36:39]
	v_mfma_f32_16x16x32_bf16 v[32:35], v[176:179], v[192:195], v[32:35]
	v_mfma_f32_16x16x32_bf16 v[20:23], v[168:171], v[200:203], v[20:23]
	v_mfma_f32_16x16x32_bf16 v[16:19], v[176:179], v[200:203], v[16:19]
	v_mfma_f32_16x16x32_bf16 v[4:7], v[168:171], v[208:211], v[4:7]
	v_mfma_f32_16x16x32_bf16 v[0:3], v[176:179], v[208:211], v[0:3]
	v_mfma_f32_16x16x32_bf16 v[52:55], v[172:175], v[188:191], v[52:55]
	v_mfma_f32_16x16x32_bf16 v[48:51], v[180:183], v[188:191], v[48:51]
	v_mfma_f32_16x16x32_bf16 v[36:39], v[172:175], v[196:199], v[36:39]
	v_mfma_f32_16x16x32_bf16 v[32:35], v[180:183], v[196:199], v[32:35]
	v_mfma_f32_16x16x32_bf16 v[20:23], v[172:175], v[204:207], v[20:23]
	v_mfma_f32_16x16x32_bf16 v[16:19], v[180:183], v[204:207], v[16:19]
	v_mfma_f32_16x16x32_bf16 v[4:7], v[172:175], v[212:215], v[4:7]
	v_mfma_f32_16x16x32_bf16 v[0:3], v[180:183], v[212:215], v[0:3]
	s_barrier
; #define PG8_STAGE(bufoff, gbase, voff) do { _Pragma("unroll") for (int _i = 0; _i < 2; ++_i) \
;         __builtin_amdgcn_global_load_lds((const unsigned*)((const char*)(gbase) + (voff)[_i]), (PG8_LAS unsigned*)(lds + (bufoff) + ldsw + _i * 8192), 16, 0, PG8_LOAD_AUX); } while (0)
; #define PG8_LDA(dst, b, h) do { _Pragma("unroll") for (int m = 0; m < 4; ++m) _Pragma("unroll") for (int k = 0; k < 2; ++k) dst[m][k] = *(const PG8_LAS bf16x8*)(lds + PG8_SA(b, h) + aoff + m * 2048 + k * 1024); } while (0)
; #define PG8_LDB(dst, b, h) do { _Pragma("unroll") for (int n = 0; n < 2; ++n) _Pragma("unroll") for (int k = 0; k < 2; ++k) dst[n][k] = *(const PG8_LAS bf16x8*)(lds + PG8_SB(b, h) + boff + n * 2048 + k * 1024); } while (0)
; #define PG8_MMA(ai, bj, At, Bt) do { __builtin_amdgcn_s_setprio(1); _Pragma("unroll") for (int m = 0; m < 4; ++m) _Pragma("unroll") for (int n = 0; n < 2; ++n) _Pragma("unroll") for (int k = 0; k < 2; ++k) \
;         acc[ai][bj][m][n] = __builtin_amdgcn_mfma_f32_16x16x32_bf16(Bt[n][k], At[m][k], acc[ai][bj][m][n], 0, 0, 0); __builtin_amdgcn_s_setprio(0); } while (0)
; #define PG8_WAIT_V(n) asm volatile("s_waitcnt vmcnt(" #n ")" ::: "memory")
; #define PG8_WAIT_L(n) asm volatile("s_waitcnt lgkmcnt(" #n ")" ::: "memory")
; #define PG8_BAR __builtin_amdgcn_s_barrier()
; #define PG8_SCHED __builtin_amdgcn_sched_barrier(0)
; template <class Epi, class Sched, bool ALIGN_EPI = false, bool SP2 = false>
; __device__ __forceinline__ void gemm_phase(PG8_LAS unsigned char* lds, const Gemm g, const Sched& S, const Epi& E) {
;     ...
;             PG8_LDB(B0, 1, 0); PG8_LDB(B1, 1, 1); PG8_SCHED; PG8_LDA(At, 1, 0); PG8_STAGE(PG8_SA(0, 1), a2 + hstepA, voffA);
;             PG8_WAIT_V(8); PG8_WAIT_L(0); PG8_BAR; PG8_MMA(0, 0, At, B0); PG8_MMA(0, 1, At, B1); PG8_BAR; PG8_SCHED;
;             PG8_LDA(At, 1, 1); PG8_STAGE(PG8_SB(1, 0), b3, voffB); PG8_STAGE(PG8_SB(1, 1), b3 + hstepB, voffB); PG8_STAGE(PG8_SA(1, 0), a3, voffA);
;             PG8_WAIT_V(8); PG8_WAIT_L(0); PG8_BAR; PG8_MMA(1, 0, At, B0); PG8_MMA(1, 1, At, B1); PG8_BAR; PG8_SCHED;
;     ...
;         if constexpr (ALIGN_EPI) { if (wr == 0) PG8_BAR; }
.Lkmid_P11:
	v_add_u32_e32 v164, s29, v147
	v_add_u32_e32 v180, s28, v147
	ds_read_b128 v[142:145], v164
	ds_read_b128 v[156:159], v164 offset:1024
	ds_read_b128 v[160:163], v164 offset:2048
	ds_read_b128 v[164:167], v164 offset:3072
	ds_read_b128 v[168:171], v180
	ds_read_b128 v[172:175], v180 offset:1024
	ds_read_b128 v[176:179], v180 offset:2048
	ds_read_b128 v[180:183], v180 offset:3072
	s_mov_b32 m0, s60
	v_lshl_add_u64 v[224:225], s[48:49], 0, v[128:129]
	ds_read_b128 v[184:187], v152 offset:32768
	ds_read_b128 v[188:191], v152 offset:33792
	ds_read_b128 v[192:195], v152 offset:34816
	ds_read_b128 v[196:199], v152 offset:35840
	ds_read_b128 v[200:203], v152 offset:36864
	ds_read_b128 v[204:207], v152 offset:37888
	ds_read_b128 v[208:211], v152 offset:38912
	ds_read_b128 v[212:215], v152 offset:39936
	global_load_lds_dwordx4 v[224:225], off
	s_mov_b32 m0, s61
	v_lshl_add_u64 v[224:225], s[48:49], 0, v[132:133]
	global_load_lds_dwordx4 v[224:225], off
	s_waitcnt vmcnt(8)
	s_waitcnt lgkmcnt(0)
	s_barrier
	s_waitcnt lgkmcnt(0)
	v_mfma_f32_16x16x32_bf16 v[124:127], v[142:145], v[184:187], v[124:127]
	v_mfma_f32_16x16x32_bf16 v[120:123], v[160:163], v[184:187], v[120:123]
	v_mfma_f32_16x16x32_bf16 v[108:111], v[142:145], v[192:195], v[108:111]
	v_mfma_f32_16x16x32_bf16 v[104:107], v[160:163], v[192:195], v[104:107]
	v_mfma_f32_16x16x32_bf16 v[92:95], v[142:145], v[200:203], v[92:95]
	v_mfma_f32_16x16x32_bf16 v[88:91], v[160:163], v[200:203], v[88:91]
	v_mfma_f32_16x16x32_bf16 v[76:79], v[142:145], v[208:211], v[76:79]
	v_mfma_f32_16x16x32_bf16 v[72:75], v[160:163], v[208:211], v[72:75]
	v_mfma_f32_16x16x32_bf16 v[124:127], v[156:159], v[188:191], v[124:127]
	v_mfma_f32_16x16x32_bf16 v[120:123], v[164:167], v[188:191], v[120:123]
	v_mfma_f32_16x16x32_bf16 v[108:111], v[156:159], v[196:199], v[108:111]
	v_mfma_f32_16x16x32_bf16 v[104:107], v[164:167], v[196:199], v[104:107]
	v_mfma_f32_16x16x32_bf16 v[92:95], v[156:159], v[204:207], v[92:95]
	v_mfma_f32_16x16x32_bf16 v[88:91], v[164:167], v[204:207], v[88:91]
	v_mfma_f32_16x16x32_bf16 v[76:79], v[156:159], v[212:215], v[76:79]
	v_mfma_f32_16x16x32_bf16 v[72:75], v[164:167], v[212:215], v[72:75]
	v_mfma_f32_16x16x32_bf16 v[116:119], v[168:171], v[184:187], v[116:119]
	v_mfma_f32_16x16x32_bf16 v[112:115], v[176:179], v[184:187], v[112:115]
	v_mfma_f32_16x16x32_bf16 v[100:103], v[168:171], v[192:195], v[100:103]
	v_mfma_f32_16x16x32_bf16 v[96:99], v[176:179], v[192:195], v[96:99]
	v_mfma_f32_16x16x32_bf16 v[84:87], v[168:171], v[200:203], v[84:87]
	v_mfma_f32_16x16x32_bf16 v[80:83], v[176:179], v[200:203], v[80:83]
	v_mfma_f32_16x16x32_bf16 v[68:71], v[168:171], v[208:211], v[68:71]
	v_mfma_f32_16x16x32_bf16 v[64:67], v[176:179], v[208:211], v[64:67]
	v_mfma_f32_16x16x32_bf16 v[116:119], v[172:175], v[188:191], v[116:119]
	v_mfma_f32_16x16x32_bf16 v[112:115], v[180:183], v[188:191], v[112:115]
	v_mfma_f32_16x16x32_bf16 v[100:103], v[172:175], v[196:199], v[100:103]
	v_mfma_f32_16x16x32_bf16 v[96:99], v[180:183], v[196:199], v[96:99]
	v_mfma_f32_16x16x32_bf16 v[84:87], v[172:175], v[204:207], v[84:87]
	v_mfma_f32_16x16x32_bf16 v[80:83], v[180:183], v[204:207], v[80:83]
	v_mfma_f32_16x16x32_bf16 v[68:71], v[172:175], v[212:215], v[68:71]
	v_mfma_f32_16x16x32_bf16 v[64:67], v[180:183], v[212:215], v[64:67]
	s_barrier
	s_mov_b32 m0, s27
	v_lshl_add_u64 v[216:217], v[216:217], 0, s[18:19]
	ds_read_b128 v[184:187], v152 offset:49152
	ds_read_b128 v[188:191], v152 offset:50176
	ds_read_b128 v[192:195], v152 offset:51200
	ds_read_b128 v[196:199], v152 offset:52224
	ds_read_b128 v[200:203], v152 offset:53248
	ds_read_b128 v[204:207], v152 offset:54272
	ds_read_b128 v[208:211], v152 offset:55296
	ds_read_b128 v[212:215], v152 offset:56320
	global_load_lds_dwordx4 v[216:217], off
	s_mov_b32 m0, s26
	v_lshl_add_u64 v[216:217], v[218:219], 0, s[18:19]
	global_load_lds_dwordx4 v[216:217], off
	s_mov_b32 m0, s41
	v_lshl_add_u64 v[216:217], s[34:35], 0, v[130:131]
	global_load_lds_dwordx4 v[216:217], off
	s_mov_b32 m0, s39
	v_lshl_add_u64 v[216:217], s[34:35], 0, v[134:135]
	global_load_lds_dwordx4 v[216:217], off
	s_mov_b32 m0, s65
	v_lshl_add_u64 v[216:217], v[220:221], 0, s[18:19]
	global_load_lds_dwordx4 v[216:217], off
	s_mov_b32 m0, s66
	v_lshl_add_u64 v[216:217], v[222:223], 0, s[18:19]
	global_load_lds_dwordx4 v[216:217], off
	s_waitcnt vmcnt(8)
	s_waitcnt lgkmcnt(0)
	s_barrier
	s_waitcnt lgkmcnt(0)
	v_mfma_f32_16x16x32_bf16 v[60:63], v[142:145], v[184:187], v[60:63]
	v_mfma_f32_16x16x32_bf16 v[56:59], v[160:163], v[184:187], v[56:59]
	v_mfma_f32_16x16x32_bf16 v[44:47], v[142:145], v[192:195], v[44:47]
	v_mfma_f32_16x16x32_bf16 v[40:43], v[160:163], v[192:195], v[40:43]
	v_mfma_f32_16x16x32_bf16 v[28:31], v[142:145], v[200:203], v[28:31]
	v_mfma_f32_16x16x32_bf16 v[24:27], v[160:163], v[200:203], v[24:27]
	v_mfma_f32_16x16x32_bf16 v[12:15], v[142:145], v[208:211], v[12:15]
	v_mfma_f32_16x16x32_bf16 v[8:11], v[160:163], v[208:211], v[8:11]
	v_mfma_f32_16x16x32_bf16 v[60:63], v[156:159], v[188:191], v[60:63]
	v_mfma_f32_16x16x32_bf16 v[56:59], v[164:167], v[188:191], v[56:59]
	v_mfma_f32_16x16x32_bf16 v[44:47], v[156:159], v[196:199], v[44:47]
	v_mfma_f32_16x16x32_bf16 v[40:43], v[164:167], v[196:199], v[40:43]
	v_mfma_f32_16x16x32_bf16 v[28:31], v[156:159], v[204:207], v[28:31]
	v_mfma_f32_16x16x32_bf16 v[24:27], v[164:167], v[204:207], v[24:27]
	v_mfma_f32_16x16x32_bf16 v[12:15], v[156:159], v[212:215], v[12:15]
	v_mfma_f32_16x16x32_bf16 v[8:11], v[164:167], v[212:215], v[8:11]
	v_mfma_f32_16x16x32_bf16 v[52:55], v[168:171], v[184:187], v[52:55]
	v_mfma_f32_16x16x32_bf16 v[48:51], v[176:179], v[184:187], v[48:51]
	v_mfma_f32_16x16x32_bf16 v[36:39], v[168:171], v[192:195], v[36:39]
	v_mfma_f32_16x16x32_bf16 v[32:35], v[176:179], v[192:195], v[32:35]
	v_mfma_f32_16x16x32_bf16 v[20:23], v[168:171], v[200:203], v[20:23]
	v_mfma_f32_16x16x32_bf16 v[16:19], v[176:179], v[200:203], v[16:19]
	v_mfma_f32_16x16x32_bf16 v[4:7], v[168:171], v[208:211], v[4:7]
	v_mfma_f32_16x16x32_bf16 v[0:3], v[176:179], v[208:211], v[0:3]
	v_mfma_f32_16x16x32_bf16 v[52:55], v[172:175], v[188:191], v[52:55]
	v_mfma_f32_16x16x32_bf16 v[48:51], v[180:183], v[188:191], v[48:51]
	v_mfma_f32_16x16x32_bf16 v[36:39], v[172:175], v[196:199], v[36:39]
	v_mfma_f32_16x16x32_bf16 v[32:35], v[180:183], v[196:199], v[32:35]
	v_mfma_f32_16x16x32_bf16 v[20:23], v[172:175], v[204:207], v[20:23]
	v_mfma_f32_16x16x32_bf16 v[16:19], v[180:183], v[204:207], v[16:19]
	v_mfma_f32_16x16x32_bf16 v[4:7], v[172:175], v[212:215], v[4:7]
	v_mfma_f32_16x16x32_bf16 v[0:3], v[180:183], v[212:215], v[0:3]
	s_barrier
	s_movk_i32 s26, 0x100
	s_andn2_b64 vcc, exec, s[22:23]
	s_mov_b64 s[34:35], -1
	s_mov_b64 s[22:23], 0
	s_cbranch_vccz .LBB0_1018
	s_and_b64 vcc, exec, s[36:37]
	s_cbranch_vccz .LBB0_1021
	s_barrier

; #define PG8_STAGE(bufoff, gbase, voff) do { _Pragma("unroll") for (int _i = 0; _i < 2; ++_i) \
;         __builtin_amdgcn_global_load_lds((const unsigned*)((const char*)(gbase) + (voff)[_i]), (PG8_LAS unsigned*)(lds + (bufoff) + ldsw + _i * 8192), 16, 0, PG8_LOAD_AUX); } while (0)
; #define PG8_WAIT_V(n) asm volatile("s_waitcnt vmcnt(" #n ")" ::: "memory")
; #define PG8_WAIT_L(n) asm volatile("s_waitcnt lgkmcnt(" #n ")" ::: "memory")
; #define PG8_BAR __builtin_amdgcn_s_barrier()
;     __host__ __device__ bool next(int i, Unit& u) const {
;         const long L = (long)i * G + c; if (L >= nwg) return false;
;         int wgid = (int)L; { const int q = nwg / NXCD, r = nwg % NXCD, xcd = wgid % NXCD, off = wgid / NXCD; wgid = (xcd < r ? xcd * (q + 1) : r * (q + 1) + (xcd - r) * q) + off; }
;         const int nig = WGM * nN, gid = wgid / nig, fm = gid * WGM, gsz = (nM - fm) < WGM ? (nM - fm) : WGM;
;         u.pm = fm + ((wgid % nig) % gsz); u.pn = (wgid % nig) / gsz; return true;
; template <class Epi, class Sched, bool ALIGN_EPI = false, bool SP2 = false>
; __device__ __forceinline__ void gemm_phase(PG8_LAS unsigned char* lds, const Gemm g, const Sched& S, const Epi& E) {
;     ...
;         const bool has_next = S.next(ui + 1, nxt);
;         const char* nA = has_next ? (const char*)g.A + (size_t)nxt.pm * tstepA + (size_t)nxt.pn * apn : cA; const char* nB = has_next ? (const char*)g.Bt + (size_t)nxt.pn * tstepB : cB;
;         for (int t = 0; t < nt; t += 2) {
;             const bool last = (t == nt - 2);
;             const char* a1 = cA + (size_t)(t + 1) * kstep;
;             const char* a2 = last ? nA : cA + (size_t)(t + 2) * kstep; const char* b2 = last ? nB : cB + (size_t)(t + 2) * kstep;
;             const char* a3 = a2 + kstep; const char* b3 = b2 + kstep;
;             if (last && has_next) S.a_ready(nxt);
;             if constexpr (SP2) {
;             PG8_LDB(B0, 0, 0); PG8_LDB(B1, 0, 1); PG8_SCHED; PG8_LDA(At, 0, 0); PG8_STAGE(PG8_SA(1, 1), a1 + hstepA, voffA);
;             PG8_WAIT_V(8); PG8_WAIT_L(0); PG8_BAR; PG8_MMA(0, 0, At, B0); PG8_MMA(0, 1, At, B1); PG8_BAR; PG8_SCHED;
;             PG8_LDA(At, 0, 1); PG8_STAGE(PG8_SB(0, 0), b2, voffB); PG8_STAGE(PG8_SB(0, 1), b2 + hstepB, voffB); PG8_STAGE(PG8_SA(0, 0), a2, voffA);
;             PG8_WAIT_V(8); PG8_WAIT_L(0); PG8_BAR; PG8_MMA(1, 0, At, B0); PG8_MMA(1, 1, At, B1); PG8_BAR; PG8_SCHED;
.LBB0_1108:
	s_add_u32 s20, s20, 0x40080
	s_addc_u32 s21, s21, 0
	s_add_u32 s26, s22, 0x100
	s_addc_u32 s27, s23, 0
	s_mov_b32 s28, -2
	ds_read_b128 v[146:149], v157
	ds_read_b128 v[162:165], v157 offset:1024
	ds_read_b128 v[166:169], v157 offset:2048
	ds_read_b128 v[170:173], v157 offset:3072
	ds_read_b128 v[174:177], v158
	ds_read_b128 v[178:181], v158 offset:1024
	ds_read_b128 v[182:185], v158 offset:2048
	ds_read_b128 v[186:189], v158 offset:3072
	s_add_u32 s22, s20, 0xfffc0080
	s_addc_u32 s23, s21, -1
	s_cmp_eq_u32 s28, 12
	s_cselect_b32 s35, s17, s23
	s_cselect_b32 s34, s24, s22
	s_cselect_b32 s23, s15, s27
	s_cselect_b32 s22, s25, s26
	v_lshl_add_u64 v[150:151], s[20:21], 0, v[138:139]
	s_add_i32 m0, s45, 0xc000
	ds_read_b128 v[190:193], v159
	ds_read_b128 v[194:197], v159 offset:1024
	ds_read_b128 v[198:201], v159 offset:2048
	ds_read_b128 v[202:205], v159 offset:3072
	ds_read_b128 v[206:209], v159 offset:4096
	ds_read_b128 v[210:213], v159 offset:5120
	ds_read_b128 v[214:217], v159 offset:6144
	ds_read_b128 v[218:221], v159 offset:7168
	global_load_lds_dwordx4 v[150:151], off
	s_add_i32 m0, s45, 0xe000
	v_lshl_add_u64 v[150:151], s[20:21], 0, v[140:141]
	global_load_lds_dwordx4 v[150:151], off
	s_waitcnt vmcnt(8)
	s_waitcnt lgkmcnt(0)
	s_barrier
	s_waitcnt lgkmcnt(0)
	v_mfma_f32_16x16x32_bf16 v[124:127], v[146:149], v[190:193], 0
	s_add_i32 s49, s49, 1
	s_mul_i32 s2, s49, s52
	v_mfma_f32_16x16x32_bf16 v[120:123], v[166:169], v[190:193], 0
	s_mul_hi_u32 s3, s49, s53
	s_add_i32 s3, s3, s2
	v_mfma_f32_16x16x32_bf16 v[108:111], v[146:149], v[198:201], 0
	s_mul_i32 s2, s49, s53
	v_readlane_b32 s15, v239, 0
	v_mfma_f32_16x16x32_bf16 v[104:107], v[166:169], v[198:201], 0
	s_add_u32 s18, s2, s15
	s_addc_u32 s19, s3, s43
	v_mfma_f32_16x16x32_bf16 v[92:95], v[146:149], v[206:209], 0
	s_cmp_lt_u32 s18, 0xb00
	s_cselect_b64 s[2:3], -1, 0
	v_mfma_f32_16x16x32_bf16 v[88:91], v[166:169], v[206:209], 0
	s_ashr_i32 s14, s18, 31
	s_lshr_b32 s14, s14, 29
	v_mfma_f32_16x16x32_bf16 v[76:79], v[146:149], v[214:217], 0
	s_add_i32 s14, s18, s14
	s_ashr_i32 s15, s14, 3
	v_mfma_f32_16x16x32_bf16 v[72:75], v[166:169], v[214:217], 0
	s_and_b32 s14, s14, -8
	s_sub_i32 s14, s18, s14
	v_mfma_f32_16x16x32_bf16 v[124:127], v[162:165], v[194:197], v[124:127]
	s_cmp_lt_i32 s14, 0
	s_cselect_b32 s16, s44, 0x160
	v_mfma_f32_16x16x32_bf16 v[120:123], v[170:173], v[194:197], v[120:123]
	s_mul_i32 s14, s14, s16
	s_add_i32 s14, s14, s15
	v_mfma_f32_16x16x32_bf16 v[108:111], v[162:165], v[202:205], v[108:111]
	s_mul_hi_i32 s15, s14, 0x2e8ba2e9
	s_lshr_b32 s16, s15, 31
	v_mfma_f32_16x16x32_bf16 v[104:107], v[170:173], v[202:205], v[104:107]
	s_ashr_i32 s15, s15, 4
	s_add_i32 s15, s15, s16
	v_mfma_f32_16x16x32_bf16 v[92:95], v[162:165], v[210:213], v[92:95]
	s_lshl_b32 s16, s15, 2
	s_sub_i32 s17, 0x80, s16
	v_mfma_f32_16x16x32_bf16 v[88:91], v[170:173], v[210:213], v[88:91]
	s_min_i32 s17, s17, 4
	s_mulk_i32 s15, 0x58
	v_mfma_f32_16x16x32_bf16 v[76:79], v[162:165], v[218:221], v[76:79]
	s_sub_i32 s15, s14, s15
	s_lshr_b32 s14, s15, 2
	v_mfma_f32_16x16x32_bf16 v[72:75], v[170:173], v[218:221], v[72:75]
	s_and_b32 s15, s15, 3
	s_add_i32 s16, s16, s15
	v_mfma_f32_16x16x32_bf16 v[116:119], v[174:177], v[190:193], 0
	s_ashr_i32 s17, s16, 31
	s_lshl_b64 s[18:19], s[16:17], 19
	v_mfma_f32_16x16x32_bf16 v[112:115], v[182:185], v[190:193], 0
	s_add_u32 s18, s30, s18
	s_addc_u32 s19, s31, s19
	v_mfma_f32_16x16x32_bf16 v[100:103], v[174:177], v[198:201], 0
	s_sub_u32 s98, s20, 0x40080
	s_subb_u32 s99, s21, 0
	v_mfma_f32_16x16x32_bf16 v[96:99], v[182:185], v[198:201], 0
	s_cmp_lg_u64 s[2:3], 0
	s_cselect_b32 s17, s19, s99
	v_mfma_f32_16x16x32_bf16 v[84:87], v[174:177], v[206:209], 0
	s_cselect_b32 s24, s18, s98
	s_ashr_i32 s15, s14, 31
	v_mfma_f32_16x16x32_bf16 v[80:83], v[182:185], v[206:209], 0
	s_lshl_b64 s[98:99], s[14:15], 19
	s_add_u32 s36, s40, s98
	v_mfma_f32_16x16x32_bf16 v[68:71], v[174:177], v[214:217], 0
	s_addc_u32 s37, s41, s99
	s_sub_u32 s98, s26, 0x100
	v_mfma_f32_16x16x32_bf16 v[64:67], v[182:185], v[214:217], 0
	s_subb_u32 s99, s27, 0
	s_cmp_lg_u64 s[2:3], 0
	v_mfma_f32_16x16x32_bf16 v[116:119], v[178:181], v[194:197], v[116:119]
	s_cselect_b32 s15, s37, s99
	s_cselect_b32 s25, s36, s98
	v_mfma_f32_16x16x32_bf16 v[112:115], v[186:189], v[194:197], v[112:115]
	v_mfma_f32_16x16x32_bf16 v[100:103], v[178:181], v[202:205], v[100:103]
	v_mfma_f32_16x16x32_bf16 v[96:99], v[186:189], v[202:205], v[96:99]
	v_mfma_f32_16x16x32_bf16 v[84:87], v[178:181], v[210:213], v[84:87]
	v_mfma_f32_16x16x32_bf16 v[80:83], v[186:189], v[210:213], v[80:83]
	v_mfma_f32_16x16x32_bf16 v[68:71], v[178:181], v[218:221], v[68:71]
	v_mfma_f32_16x16x32_bf16 v[64:67], v[186:189], v[218:221], v[64:67]
	s_barrier
	s_add_i32 s29, s54, s42
	v_lshl_add_u64 v[150:151], s[22:23], 0, v[132:133]
	s_mov_b32 m0, s29
	ds_read_b128 v[190:193], v159 offset:16384
	ds_read_b128 v[194:197], v159 offset:17408
	ds_read_b128 v[198:201], v159 offset:18432
	ds_read_b128 v[202:205], v159 offset:19456
	ds_read_b128 v[206:209], v159 offset:20480
	ds_read_b128 v[210:213], v159 offset:21504
	ds_read_b128 v[214:217], v159 offset:22528
	ds_read_b128 v[218:221], v159 offset:23552
	global_load_lds_dwordx4 v[150:151], off
	s_add_i32 m0, s29, 0x2000
	s_add_u32 s30, s22, 0x40000
	v_lshl_add_u64 v[222:223], s[22:23], 0, v[128:129]
	s_addc_u32 s31, s23, 0
	s_add_i32 s29, s55, s42
	global_load_lds_dwordx4 v[222:223], off
	v_lshl_add_u64 v[224:225], s[30:31], 0, v[132:133]
	s_mov_b32 m0, s29
	v_lshl_add_u64 v[226:227], s[34:35], 0, v[130:131]
	global_load_lds_dwordx4 v[224:225], off
	s_add_i32 m0, s29, 0x2000
	v_lshl_add_u64 v[224:225], s[30:31], 0, v[128:129]
	global_load_lds_dwordx4 v[224:225], off
	s_mov_b32 m0, s45
	v_lshl_add_u64 v[224:225], s[34:35], 0, v[134:135]
	global_load_lds_dwordx4 v[224:225], off
	s_mov_b32 m0, s46
	s_nop 0
	global_load_lds_dwordx4 v[226:227], off
	s_waitcnt vmcnt(8)
	s_waitcnt lgkmcnt(0)
	s_barrier
; #define PG8_STAGE(bufoff, gbase, voff) do { _Pragma("unroll") for (int _i = 0; _i < 2; ++_i) \
;         __builtin_amdgcn_global_load_lds((const unsigned*)((const char*)(gbase) + (voff)[_i]), (PG8_LAS unsigned*)(lds + (bufoff) + ldsw + _i * 8192), 16, 0, PG8_LOAD_AUX); } while (0)
; #define PG8_LDA(dst, b, h) do { _Pragma("unroll") for (int m = 0; m < 4; ++m) _Pragma("unroll") for (int k = 0; k < 2; ++k) dst[m][k] = *(const PG8_LAS bf16x8*)(lds + PG8_SA(b, h) + aoff + m * 2048 + k * 1024); } while (0)
; #define PG8_LDB(dst, b, h) do { _Pragma("unroll") for (int n = 0; n < 2; ++n) _Pragma("unroll") for (int k = 0; k < 2; ++k) dst[n][k] = *(const PG8_LAS bf16x8*)(lds + PG8_SB(b, h) + boff + n * 2048 + k * 1024); } while (0)
; #define PG8_MMA(ai, bj, At, Bt) do { __builtin_amdgcn_s_setprio(1); _Pragma("unroll") for (int m = 0; m < 4; ++m) _Pragma("unroll") for (int n = 0; n < 2; ++n) _Pragma("unroll") for (int k = 0; k < 2; ++k) \
;         acc[ai][bj][m][n] = __builtin_amdgcn_mfma_f32_16x16x32_bf16(Bt[n][k], At[m][k], acc[ai][bj][m][n], 0, 0, 0); __builtin_amdgcn_s_setprio(0); } while (0)
; #define PG8_WAIT_V(n) asm volatile("s_waitcnt vmcnt(" #n ")" ::: "memory")
; #define PG8_WAIT_L(n) asm volatile("s_waitcnt lgkmcnt(" #n ")" ::: "memory")
; #define PG8_BAR __builtin_amdgcn_s_barrier()
; #define PG8_SCHED __builtin_amdgcn_sched_barrier(0)
; template <class Epi, class Sched, bool ALIGN_EPI = false, bool SP2 = false>
; __device__ __forceinline__ void gemm_phase(PG8_LAS unsigned char* lds, const Gemm g, const Sched& S, const Epi& E) {
;     ...
;             PG8_LDB(B0, 0, 0); PG8_LDB(B1, 0, 1); PG8_SCHED; PG8_LDA(At, 0, 0); PG8_STAGE(PG8_SA(1, 1), a1 + hstepA, voffA);
;             PG8_WAIT_V(8); PG8_WAIT_L(0); PG8_BAR; PG8_MMA(0, 0, At, B0); PG8_MMA(0, 1, At, B1); PG8_BAR; PG8_SCHED;
;             PG8_LDA(At, 0, 1); PG8_STAGE(PG8_SB(0, 0), b2, voffB); PG8_STAGE(PG8_SB(0, 1), b2 + hstepB, voffB); PG8_STAGE(PG8_SA(0, 0), a2, voffA);
;             PG8_WAIT_V(8); PG8_WAIT_L(0); PG8_BAR; PG8_MMA(1, 0, At, B0); PG8_MMA(1, 1, At, B1); PG8_BAR; PG8_SCHED;
	s_waitcnt lgkmcnt(0)
	v_mfma_f32_16x16x32_bf16 v[60:63], v[146:149], v[190:193], 0
	v_mfma_f32_16x16x32_bf16 v[56:59], v[166:169], v[190:193], 0
	v_mfma_f32_16x16x32_bf16 v[44:47], v[146:149], v[198:201], 0
	v_mfma_f32_16x16x32_bf16 v[40:43], v[166:169], v[198:201], 0
	v_mfma_f32_16x16x32_bf16 v[28:31], v[146:149], v[206:209], 0
	v_mfma_f32_16x16x32_bf16 v[24:27], v[166:169], v[206:209], 0
	v_mfma_f32_16x16x32_bf16 v[12:15], v[146:149], v[214:217], 0
	v_mfma_f32_16x16x32_bf16 v[8:11], v[166:169], v[214:217], 0
	v_mfma_f32_16x16x32_bf16 v[60:63], v[162:165], v[194:197], v[60:63]
	v_mfma_f32_16x16x32_bf16 v[56:59], v[170:173], v[194:197], v[56:59]
	v_mfma_f32_16x16x32_bf16 v[44:47], v[162:165], v[202:205], v[44:47]
	v_mfma_f32_16x16x32_bf16 v[40:43], v[170:173], v[202:205], v[40:43]
	v_mfma_f32_16x16x32_bf16 v[28:31], v[162:165], v[210:213], v[28:31]
	v_mfma_f32_16x16x32_bf16 v[24:27], v[170:173], v[210:213], v[24:27]
	v_mfma_f32_16x16x32_bf16 v[12:15], v[162:165], v[218:221], v[12:15]
	v_mfma_f32_16x16x32_bf16 v[8:11], v[170:173], v[218:221], v[8:11]
	v_mfma_f32_16x16x32_bf16 v[52:55], v[174:177], v[190:193], 0
	v_mfma_f32_16x16x32_bf16 v[48:51], v[182:185], v[190:193], 0
	v_mfma_f32_16x16x32_bf16 v[36:39], v[174:177], v[198:201], 0
	v_mfma_f32_16x16x32_bf16 v[32:35], v[182:185], v[198:201], 0
	v_mfma_f32_16x16x32_bf16 v[20:23], v[174:177], v[206:209], 0
	v_mfma_f32_16x16x32_bf16 v[16:19], v[182:185], v[206:209], 0
	v_mfma_f32_16x16x32_bf16 v[4:7], v[174:177], v[214:217], 0
	v_mfma_f32_16x16x32_bf16 v[0:3], v[182:185], v[214:217], 0
	v_mfma_f32_16x16x32_bf16 v[52:55], v[178:181], v[194:197], v[52:55]
	v_mfma_f32_16x16x32_bf16 v[48:51], v[186:189], v[194:197], v[48:51]
	v_mfma_f32_16x16x32_bf16 v[36:39], v[178:181], v[202:205], v[36:39]
	v_mfma_f32_16x16x32_bf16 v[32:35], v[186:189], v[202:205], v[32:35]
	v_mfma_f32_16x16x32_bf16 v[20:23], v[178:181], v[210:213], v[20:23]
	v_mfma_f32_16x16x32_bf16 v[16:19], v[186:189], v[210:213], v[16:19]
	v_mfma_f32_16x16x32_bf16 v[4:7], v[178:181], v[218:221], v[4:7]
	v_mfma_f32_16x16x32_bf16 v[0:3], v[186:189], v[218:221], v[0:3]
	s_barrier
	s_branch .Lkmid_P12
.LBB0_1111:
	ds_read_b128 v[146:149], v157
	ds_read_b128 v[162:165], v157 offset:1024
	ds_read_b128 v[166:169], v157 offset:2048
	ds_read_b128 v[170:173], v157 offset:3072
	ds_read_b128 v[174:177], v158
	ds_read_b128 v[178:181], v158 offset:1024
	ds_read_b128 v[182:185], v158 offset:2048
	ds_read_b128 v[186:189], v158 offset:3072
	s_add_u32 s22, s20, 0xfffc0080
	s_addc_u32 s23, s21, -1
	s_cmp_eq_u32 s28, 12
	s_cselect_b32 s35, s17, s23
	s_cselect_b32 s34, s24, s22
	s_cselect_b32 s23, s15, s27
	s_cselect_b32 s22, s25, s26
	v_lshl_add_u64 v[150:151], s[20:21], 0, v[138:139]
	s_add_i32 m0, s45, 0xc000
	ds_read_b128 v[190:193], v159
	ds_read_b128 v[194:197], v159 offset:1024
	ds_read_b128 v[198:201], v159 offset:2048
	ds_read_b128 v[202:205], v159 offset:3072
	ds_read_b128 v[206:209], v159 offset:4096
	ds_read_b128 v[210:213], v159 offset:5120
	ds_read_b128 v[214:217], v159 offset:6144
	ds_read_b128 v[218:221], v159 offset:7168
	global_load_lds_dwordx4 v[150:151], off
	s_add_i32 m0, s45, 0xe000
	v_lshl_add_u64 v[150:151], s[20:21], 0, v[140:141]
	global_load_lds_dwordx4 v[150:151], off
	s_waitcnt vmcnt(8)
	s_waitcnt lgkmcnt(0)
	s_barrier
	s_waitcnt lgkmcnt(0)
	v_mfma_f32_16x16x32_bf16 v[124:127], v[146:149], v[190:193], v[124:127]
	v_mfma_f32_16x16x32_bf16 v[120:123], v[166:169], v[190:193], v[120:123]
	v_mfma_f32_16x16x32_bf16 v[108:111], v[146:149], v[198:201], v[108:111]
	v_mfma_f32_16x16x32_bf16 v[104:107], v[166:169], v[198:201], v[104:107]
	v_mfma_f32_16x16x32_bf16 v[92:95], v[146:149], v[206:209], v[92:95]
	v_mfma_f32_16x16x32_bf16 v[88:91], v[166:169], v[206:209], v[88:91]
	v_mfma_f32_16x16x32_bf16 v[76:79], v[146:149], v[214:217], v[76:79]
	v_mfma_f32_16x16x32_bf16 v[72:75], v[166:169], v[214:217], v[72:75]
	v_mfma_f32_16x16x32_bf16 v[124:127], v[162:165], v[194:197], v[124:127]
	v_mfma_f32_16x16x32_bf16 v[120:123], v[170:173], v[194:197], v[120:123]
	v_mfma_f32_16x16x32_bf16 v[108:111], v[162:165], v[202:205], v[108:111]
	v_mfma_f32_16x16x32_bf16 v[104:107], v[170:173], v[202:205], v[104:107]
	v_mfma_f32_16x16x32_bf16 v[92:95], v[162:165], v[210:213], v[92:95]
	v_mfma_f32_16x16x32_bf16 v[88:91], v[170:173], v[210:213], v[88:91]
	v_mfma_f32_16x16x32_bf16 v[76:79], v[162:165], v[218:221], v[76:79]
	v_mfma_f32_16x16x32_bf16 v[72:75], v[170:173], v[218:221], v[72:75]
	v_mfma_f32_16x16x32_bf16 v[116:119], v[174:177], v[190:193], v[116:119]
	v_mfma_f32_16x16x32_bf16 v[112:115], v[182:185], v[190:193], v[112:115]
	v_mfma_f32_16x16x32_bf16 v[100:103], v[174:177], v[198:201], v[100:103]
	v_mfma_f32_16x16x32_bf16 v[96:99], v[182:185], v[198:201], v[96:99]
	v_mfma_f32_16x16x32_bf16 v[84:87], v[174:177], v[206:209], v[84:87]
	v_mfma_f32_16x16x32_bf16 v[80:83], v[182:185], v[206:209], v[80:83]
	v_mfma_f32_16x16x32_bf16 v[68:71], v[174:177], v[214:217], v[68:71]
	v_mfma_f32_16x16x32_bf16 v[64:67], v[182:185], v[214:217], v[64:67]
	v_mfma_f32_16x16x32_bf16 v[116:119], v[178:181], v[194:197], v[116:119]
	v_mfma_f32_16x16x32_bf16 v[112:115], v[186:189], v[194:197], v[112:115]
	v_mfma_f32_16x16x32_bf16 v[100:103], v[178:181], v[202:205], v[100:103]
	v_mfma_f32_16x16x32_bf16 v[96:99], v[186:189], v[202:205], v[96:99]
	v_mfma_f32_16x16x32_bf16 v[84:87], v[178:181], v[210:213], v[84:87]
	v_mfma_f32_16x16x32_bf16 v[80:83], v[186:189], v[210:213], v[80:83]
	v_mfma_f32_16x16x32_bf16 v[68:71], v[178:181], v[218:221], v[68:71]
	v_mfma_f32_16x16x32_bf16 v[64:67], v[186:189], v[218:221], v[64:67]
	s_barrier
; #define PG8_STAGE(bufoff, gbase, voff) do { _Pragma("unroll") for (int _i = 0; _i < 2; ++_i) \
;         __builtin_amdgcn_global_load_lds((const unsigned*)((const char*)(gbase) + (voff)[_i]), (PG8_LAS unsigned*)(lds + (bufoff) + ldsw + _i * 8192), 16, 0, PG8_LOAD_AUX); } while (0)
; #define PG8_LDA(dst, b, h) do { _Pragma("unroll") for (int m = 0; m < 4; ++m) _Pragma("unroll") for (int k = 0; k < 2; ++k) dst[m][k] = *(const PG8_LAS bf16x8*)(lds + PG8_SA(b, h) + aoff + m * 2048 + k * 1024); } while (0)
; #define PG8_LDB(dst, b, h) do { _Pragma("unroll") for (int n = 0; n < 2; ++n) _Pragma("unroll") for (int k = 0; k < 2; ++k) dst[n][k] = *(const PG8_LAS bf16x8*)(lds + PG8_SB(b, h) + boff + n * 2048 + k * 1024); } while (0)
; #define PG8_MMA(ai, bj, At, Bt) do { __builtin_amdgcn_s_setprio(1); _Pragma("unroll") for (int m = 0; m < 4; ++m) _Pragma("unroll") for (int n = 0; n < 2; ++n) _Pragma("unroll") for (int k = 0; k < 2; ++k) \
;         acc[ai][bj][m][n] = __builtin_amdgcn_mfma_f32_16x16x32_bf16(Bt[n][k], At[m][k], acc[ai][bj][m][n], 0, 0, 0); __builtin_amdgcn_s_setprio(0); } while (0)
; #define PG8_WAIT_V(n) asm volatile("s_waitcnt vmcnt(" #n ")" ::: "memory")
; #define PG8_WAIT_L(n) asm volatile("s_waitcnt lgkmcnt(" #n ")" ::: "memory")
; #define PG8_BAR __builtin_amdgcn_s_barrier()
; #define PG8_SCHED __builtin_amdgcn_sched_barrier(0)
; template <class Epi, class Sched, bool ALIGN_EPI = false, bool SP2 = false>
; __device__ __forceinline__ void gemm_phase(PG8_LAS unsigned char* lds, const Gemm g, const Sched& S, const Epi& E) {
;     ...
;             PG8_LDA(At, 0, 1); PG8_STAGE(PG8_SB(0, 0), b2, voffB); PG8_STAGE(PG8_SB(0, 1), b2 + hstepB, voffB); PG8_STAGE(PG8_SA(0, 0), a2, voffA);
;             PG8_WAIT_V(8); PG8_WAIT_L(0); PG8_BAR; PG8_MMA(1, 0, At, B0); PG8_MMA(1, 1, At, B1); PG8_BAR; PG8_SCHED;
;             PG8_LDB(B0, 1, 0); PG8_LDB(B1, 1, 1); PG8_SCHED; PG8_LDA(At, 1, 0); PG8_STAGE(PG8_SA(0, 1), a2 + hstepA, voffA);
	s_add_i32 s29, s54, s42
	v_lshl_add_u64 v[150:151], s[22:23], 0, v[132:133]
	s_mov_b32 m0, s29
	ds_read_b128 v[190:193], v159 offset:16384
	ds_read_b128 v[194:197], v159 offset:17408
	ds_read_b128 v[198:201], v159 offset:18432
	ds_read_b128 v[202:205], v159 offset:19456
	ds_read_b128 v[206:209], v159 offset:20480
	ds_read_b128 v[210:213], v159 offset:21504
	ds_read_b128 v[214:217], v159 offset:22528
	ds_read_b128 v[218:221], v159 offset:23552
	global_load_lds_dwordx4 v[150:151], off
	s_add_i32 m0, s29, 0x2000
	s_add_u32 s30, s22, 0x40000
	v_lshl_add_u64 v[222:223], s[22:23], 0, v[128:129]
	s_addc_u32 s31, s23, 0
	s_add_i32 s29, s55, s42
	global_load_lds_dwordx4 v[222:223], off
	v_lshl_add_u64 v[224:225], s[30:31], 0, v[132:133]
	s_mov_b32 m0, s29
	v_lshl_add_u64 v[226:227], s[34:35], 0, v[130:131]
	global_load_lds_dwordx4 v[224:225], off
	s_add_i32 m0, s29, 0x2000
	v_lshl_add_u64 v[224:225], s[30:31], 0, v[128:129]
	global_load_lds_dwordx4 v[224:225], off
	s_mov_b32 m0, s45
	v_lshl_add_u64 v[224:225], s[34:35], 0, v[134:135]
	global_load_lds_dwordx4 v[224:225], off
	s_mov_b32 m0, s46
	s_nop 0
	global_load_lds_dwordx4 v[226:227], off
	s_waitcnt vmcnt(8)
	s_waitcnt lgkmcnt(0)
	s_barrier
	s_waitcnt lgkmcnt(0)
	v_mfma_f32_16x16x32_bf16 v[60:63], v[146:149], v[190:193], v[60:63]
	v_mfma_f32_16x16x32_bf16 v[56:59], v[166:169], v[190:193], v[56:59]
	v_mfma_f32_16x16x32_bf16 v[44:47], v[146:149], v[198:201], v[44:47]
	v_mfma_f32_16x16x32_bf16 v[40:43], v[166:169], v[198:201], v[40:43]
	v_mfma_f32_16x16x32_bf16 v[28:31], v[146:149], v[206:209], v[28:31]
	v_mfma_f32_16x16x32_bf16 v[24:27], v[166:169], v[206:209], v[24:27]
	v_mfma_f32_16x16x32_bf16 v[12:15], v[146:149], v[214:217], v[12:15]
	v_mfma_f32_16x16x32_bf16 v[8:11], v[166:169], v[214:217], v[8:11]
	v_mfma_f32_16x16x32_bf16 v[60:63], v[162:165], v[194:197], v[60:63]
	v_mfma_f32_16x16x32_bf16 v[56:59], v[170:173], v[194:197], v[56:59]
	v_mfma_f32_16x16x32_bf16 v[44:47], v[162:165], v[202:205], v[44:47]
	v_mfma_f32_16x16x32_bf16 v[40:43], v[170:173], v[202:205], v[40:43]
	v_mfma_f32_16x16x32_bf16 v[28:31], v[162:165], v[210:213], v[28:31]
	v_mfma_f32_16x16x32_bf16 v[24:27], v[170:173], v[210:213], v[24:27]
	v_mfma_f32_16x16x32_bf16 v[12:15], v[162:165], v[218:221], v[12:15]
	v_mfma_f32_16x16x32_bf16 v[8:11], v[170:173], v[218:221], v[8:11]
	v_mfma_f32_16x16x32_bf16 v[52:55], v[174:177], v[190:193], v[52:55]
	v_mfma_f32_16x16x32_bf16 v[48:51], v[182:185], v[190:193], v[48:51]
	v_mfma_f32_16x16x32_bf16 v[36:39], v[174:177], v[198:201], v[36:39]
	v_mfma_f32_16x16x32_bf16 v[32:35], v[182:185], v[198:201], v[32:35]
	v_mfma_f32_16x16x32_bf16 v[20:23], v[174:177], v[206:209], v[20:23]
	v_mfma_f32_16x16x32_bf16 v[16:19], v[182:185], v[206:209], v[16:19]
	v_mfma_f32_16x16x32_bf16 v[4:7], v[174:177], v[214:217], v[4:7]
	v_mfma_f32_16x16x32_bf16 v[0:3], v[182:185], v[214:217], v[0:3]
	v_mfma_f32_16x16x32_bf16 v[52:55], v[178:181], v[194:197], v[52:55]
	v_mfma_f32_16x16x32_bf16 v[48:51], v[186:189], v[194:197], v[48:51]
	v_mfma_f32_16x16x32_bf16 v[36:39], v[178:181], v[202:205], v[36:39]
	v_mfma_f32_16x16x32_bf16 v[32:35], v[186:189], v[202:205], v[32:35]
	v_mfma_f32_16x16x32_bf16 v[20:23], v[178:181], v[210:213], v[20:23]
	v_mfma_f32_16x16x32_bf16 v[16:19], v[186:189], v[210:213], v[16:19]
	v_mfma_f32_16x16x32_bf16 v[4:7], v[178:181], v[218:221], v[4:7]
	v_mfma_f32_16x16x32_bf16 v[0:3], v[186:189], v[218:221], v[0:3]
	s_barrier
.Lkmid_P12:
	s_add_i32 s29, 0, 0x18000
	s_add_i32 s33, 0, 0x1c000
	v_add_u32_e32 v170, s29, v155
	v_add_u32_e32 v186, s33, v155
	ds_read_b128 v[146:149], v170
	ds_read_b128 v[162:165], v170 offset:1024
	ds_read_b128 v[166:169], v170 offset:2048
	ds_read_b128 v[170:173], v170 offset:3072
	ds_read_b128 v[174:177], v186
	ds_read_b128 v[178:181], v186 offset:1024
	ds_read_b128 v[182:185], v186 offset:2048
	ds_read_b128 v[186:189], v186 offset:3072
	s_add_u32 s30, s34, 0x40000
	s_addc_u32 s31, s35, 0
	s_mov_b32 m0, s47
	v_lshl_add_u64 v[228:229], s[30:31], 0, v[134:135]
	ds_read_b128 v[190:193], v159 offset:32768
	ds_read_b128 v[194:197], v159 offset:33792
	ds_read_b128 v[198:201], v159 offset:34816
	ds_read_b128 v[202:205], v159 offset:35840
	ds_read_b128 v[206:209], v159 offset:36864
	ds_read_b128 v[210:213], v159 offset:37888
	ds_read_b128 v[214:217], v159 offset:38912
	ds_read_b128 v[218:221], v159 offset:39936
	global_load_lds_dwordx4 v[228:229], off
	s_mov_b32 m0, s48
	v_lshl_add_u64 v[228:229], s[30:31], 0, v[130:131]
	global_load_lds_dwordx4 v[228:229], off
	s_waitcnt vmcnt(8)
	s_waitcnt lgkmcnt(0)
	s_barrier
; #define PG8_STAGE(bufoff, gbase, voff) do { _Pragma("unroll") for (int _i = 0; _i < 2; ++_i) \
;         __builtin_amdgcn_global_load_lds((const unsigned*)((const char*)(gbase) + (voff)[_i]), (PG8_LAS unsigned*)(lds + (bufoff) + ldsw + _i * 8192), 16, 0, PG8_LOAD_AUX); } while (0)
; #define PG8_LDA(dst, b, h) do { _Pragma("unroll") for (int m = 0; m < 4; ++m) _Pragma("unroll") for (int k = 0; k < 2; ++k) dst[m][k] = *(const PG8_LAS bf16x8*)(lds + PG8_SA(b, h) + aoff + m * 2048 + k * 1024); } while (0)
; #define PG8_MMA(ai, bj, At, Bt) do { __builtin_amdgcn_s_setprio(1); _Pragma("unroll") for (int m = 0; m < 4; ++m) _Pragma("unroll") for (int n = 0; n < 2; ++n) _Pragma("unroll") for (int k = 0; k < 2; ++k) \
;         acc[ai][bj][m][n] = __builtin_amdgcn_mfma_f32_16x16x32_bf16(Bt[n][k], At[m][k], acc[ai][bj][m][n], 0, 0, 0); __builtin_amdgcn_s_setprio(0); } while (0)
; #define PG8_WAIT_V(n) asm volatile("s_waitcnt vmcnt(" #n ")" ::: "memory")
; #define PG8_WAIT_L(n) asm volatile("s_waitcnt lgkmcnt(" #n ")" ::: "memory")
; #define PG8_BAR __builtin_amdgcn_s_barrier()
; #define PG8_SCHED __builtin_amdgcn_sched_barrier(0)
; template <class Epi, class Sched, bool ALIGN_EPI = false, bool SP2 = false>
; __device__ __forceinline__ void gemm_phase(PG8_LAS unsigned char* lds, const Gemm g, const Sched& S, const Epi& E) {
;     ...
;             PG8_WAIT_V(8); PG8_WAIT_L(0); PG8_BAR; PG8_MMA(0, 0, At, B0); PG8_MMA(0, 1, At, B1); PG8_BAR; PG8_SCHED;
;             PG8_LDA(At, 1, 1); PG8_STAGE(PG8_SB(1, 0), b3, voffB); PG8_STAGE(PG8_SB(1, 1), b3 + hstepB, voffB); PG8_STAGE(PG8_SA(1, 0), a3, voffA);
;             PG8_WAIT_V(8); PG8_WAIT_L(0); PG8_BAR; PG8_MMA(1, 0, At, B0); PG8_MMA(1, 1, At, B1); PG8_BAR; PG8_SCHED;
;     ...
;         if constexpr (ALIGN_EPI) { if (wr == 0) PG8_BAR; }
;         if constexpr (!Epi::AFTER_DRAIN) { E(acc, cur, wr, wc, fr, fq); S.done(cur); }
	s_waitcnt lgkmcnt(0)
	v_mfma_f32_16x16x32_bf16 v[124:127], v[146:149], v[190:193], v[124:127]
	v_mfma_f32_16x16x32_bf16 v[120:123], v[166:169], v[190:193], v[120:123]
	v_mfma_f32_16x16x32_bf16 v[108:111], v[146:149], v[198:201], v[108:111]
	v_mfma_f32_16x16x32_bf16 v[104:107], v[166:169], v[198:201], v[104:107]
	v_mfma_f32_16x16x32_bf16 v[92:95], v[146:149], v[206:209], v[92:95]
	v_mfma_f32_16x16x32_bf16 v[88:91], v[166:169], v[206:209], v[88:91]
	v_mfma_f32_16x16x32_bf16 v[76:79], v[146:149], v[214:217], v[76:79]
	v_mfma_f32_16x16x32_bf16 v[72:75], v[166:169], v[214:217], v[72:75]
	v_mfma_f32_16x16x32_bf16 v[124:127], v[162:165], v[194:197], v[124:127]
	v_mfma_f32_16x16x32_bf16 v[120:123], v[170:173], v[194:197], v[120:123]
	v_mfma_f32_16x16x32_bf16 v[108:111], v[162:165], v[202:205], v[108:111]
	v_mfma_f32_16x16x32_bf16 v[104:107], v[170:173], v[202:205], v[104:107]
	v_mfma_f32_16x16x32_bf16 v[92:95], v[162:165], v[210:213], v[92:95]
	v_mfma_f32_16x16x32_bf16 v[88:91], v[170:173], v[210:213], v[88:91]
	v_mfma_f32_16x16x32_bf16 v[76:79], v[162:165], v[218:221], v[76:79]
	v_mfma_f32_16x16x32_bf16 v[72:75], v[170:173], v[218:221], v[72:75]
	v_mfma_f32_16x16x32_bf16 v[116:119], v[174:177], v[190:193], v[116:119]
	v_mfma_f32_16x16x32_bf16 v[112:115], v[182:185], v[190:193], v[112:115]
	v_mfma_f32_16x16x32_bf16 v[100:103], v[174:177], v[198:201], v[100:103]
	v_mfma_f32_16x16x32_bf16 v[96:99], v[182:185], v[198:201], v[96:99]
	v_mfma_f32_16x16x32_bf16 v[84:87], v[174:177], v[206:209], v[84:87]
	v_mfma_f32_16x16x32_bf16 v[80:83], v[182:185], v[206:209], v[80:83]
	v_mfma_f32_16x16x32_bf16 v[68:71], v[174:177], v[214:217], v[68:71]
	v_mfma_f32_16x16x32_bf16 v[64:67], v[182:185], v[214:217], v[64:67]
	v_mfma_f32_16x16x32_bf16 v[116:119], v[178:181], v[194:197], v[116:119]
	v_mfma_f32_16x16x32_bf16 v[112:115], v[186:189], v[194:197], v[112:115]
	v_mfma_f32_16x16x32_bf16 v[100:103], v[178:181], v[202:205], v[100:103]
	v_mfma_f32_16x16x32_bf16 v[96:99], v[186:189], v[202:205], v[96:99]
	v_mfma_f32_16x16x32_bf16 v[84:87], v[178:181], v[210:213], v[84:87]
	v_mfma_f32_16x16x32_bf16 v[80:83], v[186:189], v[210:213], v[80:83]
	v_mfma_f32_16x16x32_bf16 v[68:71], v[178:181], v[218:221], v[68:71]
	v_mfma_f32_16x16x32_bf16 v[64:67], v[186:189], v[218:221], v[64:67]
	s_barrier
	s_add_i32 s29, s29, s42
	v_lshl_add_u64 v[150:151], v[150:151], 0, s[8:9]
	s_mov_b32 m0, s29
	ds_read_b128 v[190:193], v159 offset:49152
	ds_read_b128 v[194:197], v159 offset:50176
	ds_read_b128 v[198:201], v159 offset:51200
	ds_read_b128 v[202:205], v159 offset:52224
	ds_read_b128 v[206:209], v159 offset:53248
	ds_read_b128 v[210:213], v159 offset:54272
	ds_read_b128 v[214:217], v159 offset:55296
	ds_read_b128 v[218:221], v159 offset:56320
	global_load_lds_dwordx4 v[150:151], off
	s_add_i32 m0, s29, 0x2000
	s_add_u32 s22, s22, 0x40080
	v_lshl_add_u64 v[150:151], v[222:223], 0, s[8:9]
	s_addc_u32 s23, s23, 0
	s_add_i32 s29, s33, s42
	global_load_lds_dwordx4 v[150:151], off
	s_mov_b32 m0, s29
	v_lshl_add_u64 v[150:151], s[22:23], 0, v[132:133]
	global_load_lds_dwordx4 v[150:151], off
	s_add_i32 m0, s29, 0x2000
	v_lshl_add_u64 v[150:151], s[22:23], 0, v[128:129]
	global_load_lds_dwordx4 v[150:151], off
	s_mov_b32 m0, s50
	v_lshl_add_u64 v[150:151], v[224:225], 0, s[8:9]
	global_load_lds_dwordx4 v[150:151], off
	s_mov_b32 m0, s51
	v_lshl_add_u64 v[150:151], v[226:227], 0, s[8:9]
	global_load_lds_dwordx4 v[150:151], off
	s_waitcnt vmcnt(8)
	s_waitcnt lgkmcnt(0)
	s_barrier
	s_waitcnt lgkmcnt(0)
	v_mfma_f32_16x16x32_bf16 v[60:63], v[146:149], v[190:193], v[60:63]
	v_mfma_f32_16x16x32_bf16 v[56:59], v[166:169], v[190:193], v[56:59]
	v_mfma_f32_16x16x32_bf16 v[44:47], v[146:149], v[198:201], v[44:47]
	v_mfma_f32_16x16x32_bf16 v[40:43], v[166:169], v[198:201], v[40:43]
	v_mfma_f32_16x16x32_bf16 v[28:31], v[146:149], v[206:209], v[28:31]
	v_mfma_f32_16x16x32_bf16 v[24:27], v[166:169], v[206:209], v[24:27]
	v_mfma_f32_16x16x32_bf16 v[12:15], v[146:149], v[214:217], v[12:15]
	v_mfma_f32_16x16x32_bf16 v[8:11], v[166:169], v[214:217], v[8:11]
	v_mfma_f32_16x16x32_bf16 v[60:63], v[162:165], v[194:197], v[60:63]
	v_mfma_f32_16x16x32_bf16 v[56:59], v[170:173], v[194:197], v[56:59]
	v_mfma_f32_16x16x32_bf16 v[44:47], v[162:165], v[202:205], v[44:47]
	v_mfma_f32_16x16x32_bf16 v[40:43], v[170:173], v[202:205], v[40:43]
	v_mfma_f32_16x16x32_bf16 v[28:31], v[162:165], v[210:213], v[28:31]
	v_mfma_f32_16x16x32_bf16 v[24:27], v[170:173], v[210:213], v[24:27]
	v_mfma_f32_16x16x32_bf16 v[12:15], v[162:165], v[218:221], v[12:15]
	v_mfma_f32_16x16x32_bf16 v[8:11], v[170:173], v[218:221], v[8:11]
	v_mfma_f32_16x16x32_bf16 v[52:55], v[174:177], v[190:193], v[52:55]
	v_mfma_f32_16x16x32_bf16 v[48:51], v[182:185], v[190:193], v[48:51]
	v_mfma_f32_16x16x32_bf16 v[36:39], v[174:177], v[198:201], v[36:39]
	v_mfma_f32_16x16x32_bf16 v[32:35], v[182:185], v[198:201], v[32:35]
	v_mfma_f32_16x16x32_bf16 v[20:23], v[174:177], v[206:209], v[20:23]
	v_mfma_f32_16x16x32_bf16 v[16:19], v[182:185], v[206:209], v[16:19]
	v_mfma_f32_16x16x32_bf16 v[4:7], v[174:177], v[214:217], v[4:7]
	v_mfma_f32_16x16x32_bf16 v[0:3], v[182:185], v[214:217], v[0:3]
	v_mfma_f32_16x16x32_bf16 v[52:55], v[178:181], v[194:197], v[52:55]
	v_mfma_f32_16x16x32_bf16 v[48:51], v[186:189], v[194:197], v[48:51]
	v_mfma_f32_16x16x32_bf16 v[36:39], v[178:181], v[202:205], v[36:39]
	v_mfma_f32_16x16x32_bf16 v[32:35], v[186:189], v[202:205], v[32:35]
	v_mfma_f32_16x16x32_bf16 v[20:23], v[178:181], v[210:213], v[20:23]
	v_mfma_f32_16x16x32_bf16 v[16:19], v[186:189], v[210:213], v[16:19]
	v_mfma_f32_16x16x32_bf16 v[4:7], v[178:181], v[218:221], v[4:7]
	v_mfma_f32_16x16x32_bf16 v[0:3], v[186:189], v[218:221], v[0:3]
	s_barrier
	s_add_i32 s28, s28, 2
	s_add_u32 s20, s20, 0x100
	s_addc_u32 s21, s21, 0
	s_add_u32 s26, s26, 0x100
	s_addc_u32 s27, s27, 0
	s_cmp_gt_u32 s28, 13
	s_cbranch_scc0 .LBB0_1111
	v_lshl_add_u32 v204, s0, 8, v152
	v_ashrrev_i32_e32 v205, 31, v204
	v_lshlrev_b64 v[204:205], 6, v[204:205]
	v_lshl_add_u64 v[204:205], v[136:137], 0, v[204:205]
	v_add_co_u32_e32 v206, vcc, 0x2000, v204
	s_nop 1
	v_addc_co_u32_e32 v207, vcc, 0, v205, vcc
	global_load_dwordx4 v[172:175], v[204:205], off
	global_load_dwordx4 v[176:179], v[204:205], off offset:1024
	global_load_dwordx4 v[180:183], v[204:205], off offset:2048
	global_load_dwordx4 v[184:187], v[204:205], off offset:3072
	global_load_dwordx4 v[188:191], v[206:207], off
	global_load_dwordx4 v[192:195], v[206:207], off offset:1024
	global_load_dwordx4 v[196:199], v[206:207], off offset:2048
	global_load_dwordx4 v[200:203], v[206:207], off offset:3072
	s_and_b64 vcc, exec, s[12:13]
	s_cbranch_vccz .LBB0_1114
	s_barrier

; #define PG8_STAGE(bufoff, gbase, voff) do { _Pragma("unroll") for (int _i = 0; _i < 2; ++_i) \
;         __builtin_amdgcn_global_load_lds((const unsigned*)((const char*)(gbase) + (voff)[_i]), (PG8_LAS unsigned*)(lds + (bufoff) + ldsw + _i * 8192), 16, 0, PG8_LOAD_AUX); } while (0)
; #define PG8_LDA(dst, b, h) do { _Pragma("unroll") for (int m = 0; m < 4; ++m) _Pragma("unroll") for (int k = 0; k < 2; ++k) dst[m][k] = *(const PG8_LAS bf16x8*)(lds + PG8_SA(b, h) + aoff + m * 2048 + k * 1024); } while (0)
; #define PG8_LDB(dst, b, h) do { _Pragma("unroll") for (int n = 0; n < 2; ++n) _Pragma("unroll") for (int k = 0; k < 2; ++k) dst[n][k] = *(const PG8_LAS bf16x8*)(lds + PG8_SB(b, h) + boff + n * 2048 + k * 1024); } while (0)
; #define PG8_WAIT_V(n) asm volatile("s_waitcnt vmcnt(" #n ")" ::: "memory")
; #define PG8_WAIT_L(n) asm volatile("s_waitcnt lgkmcnt(" #n ")" ::: "memory")
; #define PG8_BAR __builtin_amdgcn_s_barrier()
; #define PG8_SCHED __builtin_amdgcn_sched_barrier(0)
; template <class Epi, class Sched, bool ALIGN_EPI = false, bool SP2 = false>
; __device__ __forceinline__ void gemm_phase(PG8_LAS unsigned char* lds, const Gemm g, const Sched& S, const Epi& E) {
;     ...
;         const char* nA = has_next ? (const char*)g.A + (size_t)nxt.pm * tstepA + (size_t)nxt.pn * apn : cA; const char* nB = has_next ? (const char*)g.Bt + (size_t)nxt.pn * tstepB : cB;
;         for (int t = 0; t < nt; t += 2) {
;             const bool last = (t == nt - 2);
;             const char* a1 = cA + (size_t)(t + 1) * kstep;
;             const char* a2 = last ? nA : cA + (size_t)(t + 2) * kstep; const char* b2 = last ? nB : cB + (size_t)(t + 2) * kstep;
;             const char* a3 = a2 + kstep; const char* b3 = b2 + kstep;
;             if (last && has_next) S.a_ready(nxt);
;             if constexpr (SP2) {
;             PG8_LDB(B0, 0, 0); PG8_LDB(B1, 0, 1); PG8_SCHED; PG8_LDA(At, 0, 0); PG8_STAGE(PG8_SA(1, 1), a1 + hstepA, voffA);
;             PG8_WAIT_V(8); PG8_WAIT_L(0); PG8_BAR; PG8_MMA(0, 0, At, B0); PG8_MMA(0, 1, At, B1); PG8_BAR; PG8_SCHED;
;             PG8_LDA(At, 0, 1); PG8_STAGE(PG8_SB(0, 0), b2, voffB); PG8_STAGE(PG8_SB(0, 1), b2 + hstepB, voffB); PG8_STAGE(PG8_SA(0, 0), a2, voffA);
;             PG8_WAIT_V(8); PG8_WAIT_L(0); PG8_BAR; PG8_MMA(1, 0, At, B0); PG8_MMA(1, 1, At, B1); PG8_BAR; PG8_SCHED;
.LBB0_1195:
	s_add_u32 s0, s0, 0xb0080
	s_addc_u32 s1, s1, 0
	s_add_u32 s25, s20, 0x100
	s_addc_u32 s26, s21, 0
	s_mov_b32 s27, -2
	s_waitcnt lgkmcnt(0)
	ds_read_b128 v[146:149], v155
	ds_read_b128 v[160:163], v155 offset:1024
	ds_read_b128 v[164:167], v155 offset:2048
	ds_read_b128 v[168:171], v155 offset:3072
	ds_read_b128 v[172:175], v156
	ds_read_b128 v[176:179], v156 offset:1024
	ds_read_b128 v[180:183], v156 offset:2048
	ds_read_b128 v[184:187], v156 offset:3072
	s_add_u32 s20, s0, 0xfff50080
	s_addc_u32 s21, s1, -1
	s_cmp_eq_u32 s27, 40
	s_cselect_b32 s23, s9, s21
	s_cselect_b32 s22, s8, s20
	s_cselect_b32 s21, s41, s26
	s_cselect_b32 s20, s40, s25
	v_lshl_add_u64 v[220:221], s[0:1], 0, v[138:139]
	s_add_i32 m0, s43, 0xc000
	ds_read_b128 v[188:191], v157
	ds_read_b128 v[192:195], v157 offset:1024
	ds_read_b128 v[196:199], v157 offset:2048
	ds_read_b128 v[200:203], v157 offset:3072
	ds_read_b128 v[204:207], v157 offset:4096
	ds_read_b128 v[208:211], v157 offset:5120
	ds_read_b128 v[212:215], v157 offset:6144
	ds_read_b128 v[216:219], v157 offset:7168
	global_load_lds_dwordx4 v[220:221], off
	s_add_i32 m0, s43, 0xe000
	v_lshl_add_u64 v[220:221], s[0:1], 0, v[140:141]
	global_load_lds_dwordx4 v[220:221], off
	s_waitcnt vmcnt(8)
	s_waitcnt lgkmcnt(0)
	s_barrier
	s_waitcnt lgkmcnt(0)
	v_mfma_f32_16x16x32_bf16 v[124:127], v[146:149], v[188:191], 0
	v_mfma_f32_16x16x32_bf16 v[120:123], v[164:167], v[188:191], 0
	v_mfma_f32_16x16x32_bf16 v[108:111], v[146:149], v[196:199], 0
	v_mfma_f32_16x16x32_bf16 v[104:107], v[164:167], v[196:199], 0
	v_mfma_f32_16x16x32_bf16 v[92:95], v[146:149], v[204:207], 0
	v_mfma_f32_16x16x32_bf16 v[88:91], v[164:167], v[204:207], 0
	v_mfma_f32_16x16x32_bf16 v[76:79], v[146:149], v[212:215], 0
	v_mfma_f32_16x16x32_bf16 v[72:75], v[164:167], v[212:215], 0
	v_mfma_f32_16x16x32_bf16 v[124:127], v[160:163], v[192:195], v[124:127]
	v_mfma_f32_16x16x32_bf16 v[120:123], v[168:171], v[192:195], v[120:123]
	v_mfma_f32_16x16x32_bf16 v[108:111], v[160:163], v[200:203], v[108:111]
	v_mfma_f32_16x16x32_bf16 v[104:107], v[168:171], v[200:203], v[104:107]
	v_mfma_f32_16x16x32_bf16 v[92:95], v[160:163], v[208:211], v[92:95]
	v_mfma_f32_16x16x32_bf16 v[88:91], v[168:171], v[208:211], v[88:91]
	v_mfma_f32_16x16x32_bf16 v[76:79], v[160:163], v[216:219], v[76:79]
	v_mfma_f32_16x16x32_bf16 v[72:75], v[168:171], v[216:219], v[72:75]
	v_mfma_f32_16x16x32_bf16 v[116:119], v[172:175], v[188:191], 0
	v_mfma_f32_16x16x32_bf16 v[112:115], v[180:183], v[188:191], 0
	v_mfma_f32_16x16x32_bf16 v[100:103], v[172:175], v[196:199], 0
	v_mfma_f32_16x16x32_bf16 v[96:99], v[180:183], v[196:199], 0
	v_mfma_f32_16x16x32_bf16 v[84:87], v[172:175], v[204:207], 0
	v_mfma_f32_16x16x32_bf16 v[80:83], v[180:183], v[204:207], 0
	v_mfma_f32_16x16x32_bf16 v[68:71], v[172:175], v[212:215], 0
	v_mfma_f32_16x16x32_bf16 v[64:67], v[180:183], v[212:215], 0
	v_mfma_f32_16x16x32_bf16 v[116:119], v[176:179], v[192:195], v[116:119]
	v_mfma_f32_16x16x32_bf16 v[112:115], v[184:187], v[192:195], v[112:115]
	v_mfma_f32_16x16x32_bf16 v[100:103], v[176:179], v[200:203], v[100:103]
	v_mfma_f32_16x16x32_bf16 v[96:99], v[184:187], v[200:203], v[96:99]
	v_mfma_f32_16x16x32_bf16 v[84:87], v[176:179], v[208:211], v[84:87]
	v_mfma_f32_16x16x32_bf16 v[80:83], v[184:187], v[208:211], v[80:83]
	v_mfma_f32_16x16x32_bf16 v[68:71], v[176:179], v[216:219], v[68:71]
	v_mfma_f32_16x16x32_bf16 v[64:67], v[184:187], v[216:219], v[64:67]
	s_barrier
	s_add_i32 s28, s55, s42
	v_lshl_add_u64 v[220:221], s[20:21], 0, v[130:131]
	s_mov_b32 m0, s28
	ds_read_b128 v[188:191], v157 offset:16384
	ds_read_b128 v[192:195], v157 offset:17408
	ds_read_b128 v[196:199], v157 offset:18432
	ds_read_b128 v[200:203], v157 offset:19456
	ds_read_b128 v[204:207], v157 offset:20480
	ds_read_b128 v[208:211], v157 offset:21504
	ds_read_b128 v[212:215], v157 offset:22528
	ds_read_b128 v[216:219], v157 offset:23552
	global_load_lds_dwordx4 v[220:221], off
	s_add_i32 m0, s28, 0x2000
	s_add_u32 s28, s20, 0x2c000
	v_lshl_add_u64 v[222:223], s[20:21], 0, v[134:135]
	s_addc_u32 s29, s21, 0
	s_add_i32 s30, s56, s42
	global_load_lds_dwordx4 v[222:223], off
	v_lshl_add_u64 v[224:225], s[28:29], 0, v[130:131]
	s_mov_b32 m0, s30
	v_lshl_add_u64 v[226:227], s[22:23], 0, v[132:133]
	global_load_lds_dwordx4 v[224:225], off
	s_add_i32 m0, s30, 0x2000
	v_lshl_add_u64 v[224:225], s[28:29], 0, v[134:135]
	global_load_lds_dwordx4 v[224:225], off
	s_mov_b32 m0, s43
	v_lshl_add_u64 v[224:225], s[22:23], 0, v[128:129]
	global_load_lds_dwordx4 v[224:225], off
	s_mov_b32 m0, s44
	s_nop 0
	global_load_lds_dwordx4 v[226:227], off
	s_waitcnt vmcnt(8)
	s_waitcnt lgkmcnt(0)
	s_barrier
	s_waitcnt lgkmcnt(0)
	v_mfma_f32_16x16x32_bf16 v[60:63], v[146:149], v[188:191], 0
	v_mfma_f32_16x16x32_bf16 v[56:59], v[164:167], v[188:191], 0
	v_mfma_f32_16x16x32_bf16 v[44:47], v[146:149], v[196:199], 0
	v_mfma_f32_16x16x32_bf16 v[40:43], v[164:167], v[196:199], 0
	v_mfma_f32_16x16x32_bf16 v[28:31], v[146:149], v[204:207], 0
	v_mfma_f32_16x16x32_bf16 v[24:27], v[164:167], v[204:207], 0
	v_mfma_f32_16x16x32_bf16 v[12:15], v[146:149], v[212:215], 0
	v_mfma_f32_16x16x32_bf16 v[8:11], v[164:167], v[212:215], 0
	v_mfma_f32_16x16x32_bf16 v[60:63], v[160:163], v[192:195], v[60:63]
	v_mfma_f32_16x16x32_bf16 v[56:59], v[168:171], v[192:195], v[56:59]
	v_mfma_f32_16x16x32_bf16 v[44:47], v[160:163], v[200:203], v[44:47]
	v_mfma_f32_16x16x32_bf16 v[40:43], v[168:171], v[200:203], v[40:43]
	v_mfma_f32_16x16x32_bf16 v[28:31], v[160:163], v[208:211], v[28:31]
	v_mfma_f32_16x16x32_bf16 v[24:27], v[168:171], v[208:211], v[24:27]
	v_mfma_f32_16x16x32_bf16 v[12:15], v[160:163], v[216:219], v[12:15]
	v_mfma_f32_16x16x32_bf16 v[8:11], v[168:171], v[216:219], v[8:11]
	v_mfma_f32_16x16x32_bf16 v[52:55], v[172:175], v[188:191], 0
	v_mfma_f32_16x16x32_bf16 v[48:51], v[180:183], v[188:191], 0
	v_mfma_f32_16x16x32_bf16 v[36:39], v[172:175], v[196:199], 0
	v_mfma_f32_16x16x32_bf16 v[32:35], v[180:183], v[196:199], 0
	v_mfma_f32_16x16x32_bf16 v[20:23], v[172:175], v[204:207], 0
	v_mfma_f32_16x16x32_bf16 v[16:19], v[180:183], v[204:207], 0
	v_mfma_f32_16x16x32_bf16 v[4:7], v[172:175], v[212:215], 0
	v_mfma_f32_16x16x32_bf16 v[0:3], v[180:183], v[212:215], 0
	v_mfma_f32_16x16x32_bf16 v[52:55], v[176:179], v[192:195], v[52:55]
	v_mfma_f32_16x16x32_bf16 v[48:51], v[184:187], v[192:195], v[48:51]
	v_mfma_f32_16x16x32_bf16 v[36:39], v[176:179], v[200:203], v[36:39]
	v_mfma_f32_16x16x32_bf16 v[32:35], v[184:187], v[200:203], v[32:35]
	v_mfma_f32_16x16x32_bf16 v[20:23], v[176:179], v[208:211], v[20:23]
	v_mfma_f32_16x16x32_bf16 v[16:19], v[184:187], v[208:211], v[16:19]
	v_mfma_f32_16x16x32_bf16 v[4:7], v[176:179], v[216:219], v[4:7]
	v_mfma_f32_16x16x32_bf16 v[0:3], v[184:187], v[216:219], v[0:3]
	s_barrier
	s_branch .Lkmid_P13
; #define PG8_STAGE(bufoff, gbase, voff) do { _Pragma("unroll") for (int _i = 0; _i < 2; ++_i) \
;         __builtin_amdgcn_global_load_lds((const unsigned*)((const char*)(gbase) + (voff)[_i]), (PG8_LAS unsigned*)(lds + (bufoff) + ldsw + _i * 8192), 16, 0, PG8_LOAD_AUX); } while (0)
; #define PG8_LDA(dst, b, h) do { _Pragma("unroll") for (int m = 0; m < 4; ++m) _Pragma("unroll") for (int k = 0; k < 2; ++k) dst[m][k] = *(const PG8_LAS bf16x8*)(lds + PG8_SA(b, h) + aoff + m * 2048 + k * 1024); } while (0)
; #define PG8_LDB(dst, b, h) do { _Pragma("unroll") for (int n = 0; n < 2; ++n) _Pragma("unroll") for (int k = 0; k < 2; ++k) dst[n][k] = *(const PG8_LAS bf16x8*)(lds + PG8_SB(b, h) + boff + n * 2048 + k * 1024); } while (0)
; #define PG8_MMA(ai, bj, At, Bt) do { __builtin_amdgcn_s_setprio(1); _Pragma("unroll") for (int m = 0; m < 4; ++m) _Pragma("unroll") for (int n = 0; n < 2; ++n) _Pragma("unroll") for (int k = 0; k < 2; ++k) \
;         acc[ai][bj][m][n] = __builtin_amdgcn_mfma_f32_16x16x32_bf16(Bt[n][k], At[m][k], acc[ai][bj][m][n], 0, 0, 0); __builtin_amdgcn_s_setprio(0); } while (0)
; #define PG8_WAIT_V(n) asm volatile("s_waitcnt vmcnt(" #n ")" ::: "memory")
; #define PG8_WAIT_L(n) asm volatile("s_waitcnt lgkmcnt(" #n ")" ::: "memory")
; template <class Epi, class Sched, bool ALIGN_EPI = false, bool SP2 = false>
; __device__ __forceinline__ void gemm_phase(PG8_LAS unsigned char* lds, const Gemm g, const Sched& S, const Epi& E) {
;     ...
;             const bool last = (t == nt - 2);
;             const char* a1 = cA + (size_t)(t + 1) * kstep;
;             const char* a2 = last ? nA : cA + (size_t)(t + 2) * kstep; const char* b2 = last ? nB : cB + (size_t)(t + 2) * kstep;
;             const char* a3 = a2 + kstep; const char* b3 = b2 + kstep;
;             if (last && has_next) S.a_ready(nxt);
;             if constexpr (SP2) {
;             PG8_LDB(B0, 0, 0); PG8_LDB(B1, 0, 1); PG8_SCHED; PG8_LDA(At, 0, 0); PG8_STAGE(PG8_SA(1, 1), a1 + hstepA, voffA);
;             PG8_WAIT_V(8); PG8_WAIT_L(0); PG8_BAR; PG8_MMA(0, 0, At, B0); PG8_MMA(0, 1, At, B1); PG8_BAR; PG8_SCHED;
;             PG8_LDA(At, 0, 1); PG8_STAGE(PG8_SB(0, 0), b2, voffB); PG8_STAGE(PG8_SB(0, 1), b2 + hstepB, voffB); PG8_STAGE(PG8_SA(0, 0), a2, voffA);
;             PG8_WAIT_V(8); PG8_WAIT_L(0); PG8_BAR; PG8_MMA(1, 0, At, B0); PG8_MMA(1, 1, At, B1); PG8_BAR; PG8_SCHED;
.LBB0_1196:
	ds_read_b128 v[146:149], v155
	ds_read_b128 v[160:163], v155 offset:1024
	ds_read_b128 v[164:167], v155 offset:2048
	ds_read_b128 v[168:171], v155 offset:3072
	ds_read_b128 v[172:175], v156
	ds_read_b128 v[176:179], v156 offset:1024
	ds_read_b128 v[180:183], v156 offset:2048
	ds_read_b128 v[184:187], v156 offset:3072
	s_add_u32 s20, s0, 0xfff50080
	s_addc_u32 s21, s1, -1
	s_cmp_eq_u32 s27, 40
	s_cselect_b32 s23, s9, s21
	s_cselect_b32 s22, s8, s20
	s_cselect_b32 s21, s41, s26
	s_cselect_b32 s20, s40, s25
	v_lshl_add_u64 v[220:221], s[0:1], 0, v[138:139]
	s_add_i32 m0, s43, 0xc000
	ds_read_b128 v[188:191], v157
	ds_read_b128 v[192:195], v157 offset:1024
	ds_read_b128 v[196:199], v157 offset:2048
	ds_read_b128 v[200:203], v157 offset:3072
	ds_read_b128 v[204:207], v157 offset:4096
	ds_read_b128 v[208:211], v157 offset:5120
	ds_read_b128 v[212:215], v157 offset:6144
	ds_read_b128 v[216:219], v157 offset:7168
	global_load_lds_dwordx4 v[220:221], off
	s_add_i32 m0, s43, 0xe000
	v_lshl_add_u64 v[220:221], s[0:1], 0, v[140:141]
	global_load_lds_dwordx4 v[220:221], off
	s_waitcnt vmcnt(8)
	s_waitcnt lgkmcnt(0)
	s_barrier
	s_waitcnt lgkmcnt(0)
	v_mfma_f32_16x16x32_bf16 v[124:127], v[146:149], v[188:191], v[124:127]
	v_mfma_f32_16x16x32_bf16 v[120:123], v[164:167], v[188:191], v[120:123]
	v_mfma_f32_16x16x32_bf16 v[108:111], v[146:149], v[196:199], v[108:111]
	v_mfma_f32_16x16x32_bf16 v[104:107], v[164:167], v[196:199], v[104:107]
	v_mfma_f32_16x16x32_bf16 v[92:95], v[146:149], v[204:207], v[92:95]
	v_mfma_f32_16x16x32_bf16 v[88:91], v[164:167], v[204:207], v[88:91]
	v_mfma_f32_16x16x32_bf16 v[76:79], v[146:149], v[212:215], v[76:79]
	v_mfma_f32_16x16x32_bf16 v[72:75], v[164:167], v[212:215], v[72:75]
	v_mfma_f32_16x16x32_bf16 v[124:127], v[160:163], v[192:195], v[124:127]
	v_mfma_f32_16x16x32_bf16 v[120:123], v[168:171], v[192:195], v[120:123]
	v_mfma_f32_16x16x32_bf16 v[108:111], v[160:163], v[200:203], v[108:111]
	v_mfma_f32_16x16x32_bf16 v[104:107], v[168:171], v[200:203], v[104:107]
	v_mfma_f32_16x16x32_bf16 v[92:95], v[160:163], v[208:211], v[92:95]
	v_mfma_f32_16x16x32_bf16 v[88:91], v[168:171], v[208:211], v[88:91]
	v_mfma_f32_16x16x32_bf16 v[76:79], v[160:163], v[216:219], v[76:79]
	v_mfma_f32_16x16x32_bf16 v[72:75], v[168:171], v[216:219], v[72:75]
	v_mfma_f32_16x16x32_bf16 v[116:119], v[172:175], v[188:191], v[116:119]
	v_mfma_f32_16x16x32_bf16 v[112:115], v[180:183], v[188:191], v[112:115]
	v_mfma_f32_16x16x32_bf16 v[100:103], v[172:175], v[196:199], v[100:103]
	v_mfma_f32_16x16x32_bf16 v[96:99], v[180:183], v[196:199], v[96:99]
	v_mfma_f32_16x16x32_bf16 v[84:87], v[172:175], v[204:207], v[84:87]
	v_mfma_f32_16x16x32_bf16 v[80:83], v[180:183], v[204:207], v[80:83]
	v_mfma_f32_16x16x32_bf16 v[68:71], v[172:175], v[212:215], v[68:71]
	v_mfma_f32_16x16x32_bf16 v[64:67], v[180:183], v[212:215], v[64:67]
	v_mfma_f32_16x16x32_bf16 v[116:119], v[176:179], v[192:195], v[116:119]
	v_mfma_f32_16x16x32_bf16 v[112:115], v[184:187], v[192:195], v[112:115]
	v_mfma_f32_16x16x32_bf16 v[100:103], v[176:179], v[200:203], v[100:103]
	v_mfma_f32_16x16x32_bf16 v[96:99], v[184:187], v[200:203], v[96:99]
	v_mfma_f32_16x16x32_bf16 v[84:87], v[176:179], v[208:211], v[84:87]
	v_mfma_f32_16x16x32_bf16 v[80:83], v[184:187], v[208:211], v[80:83]
	v_mfma_f32_16x16x32_bf16 v[68:71], v[176:179], v[216:219], v[68:71]
	v_mfma_f32_16x16x32_bf16 v[64:67], v[184:187], v[216:219], v[64:67]
	s_barrier
	s_add_i32 s28, s55, s42
	v_lshl_add_u64 v[220:221], s[20:21], 0, v[130:131]
	s_mov_b32 m0, s28
	ds_read_b128 v[188:191], v157 offset:16384
	ds_read_b128 v[192:195], v157 offset:17408
	ds_read_b128 v[196:199], v157 offset:18432
	ds_read_b128 v[200:203], v157 offset:19456
	ds_read_b128 v[204:207], v157 offset:20480
	ds_read_b128 v[208:211], v157 offset:21504
	ds_read_b128 v[212:215], v157 offset:22528
	ds_read_b128 v[216:219], v157 offset:23552
	global_load_lds_dwordx4 v[220:221], off
	s_add_i32 m0, s28, 0x2000
	s_add_u32 s28, s20, 0x2c000
	v_lshl_add_u64 v[222:223], s[20:21], 0, v[134:135]
	s_addc_u32 s29, s21, 0
	s_add_i32 s30, s56, s42
	global_load_lds_dwordx4 v[222:223], off
	v_lshl_add_u64 v[224:225], s[28:29], 0, v[130:131]
	s_mov_b32 m0, s30
	v_lshl_add_u64 v[226:227], s[22:23], 0, v[132:133]
	global_load_lds_dwordx4 v[224:225], off
	s_add_i32 m0, s30, 0x2000
	v_lshl_add_u64 v[224:225], s[28:29], 0, v[134:135]
	global_load_lds_dwordx4 v[224:225], off
	s_mov_b32 m0, s43
	v_lshl_add_u64 v[224:225], s[22:23], 0, v[128:129]
	global_load_lds_dwordx4 v[224:225], off
	s_mov_b32 m0, s44
	s_nop 0
	global_load_lds_dwordx4 v[226:227], off
	s_waitcnt vmcnt(8)
	s_waitcnt lgkmcnt(0)
	s_barrier
	s_waitcnt lgkmcnt(0)
	v_mfma_f32_16x16x32_bf16 v[60:63], v[146:149], v[188:191], v[60:63]
	v_mfma_f32_16x16x32_bf16 v[56:59], v[164:167], v[188:191], v[56:59]
	v_mfma_f32_16x16x32_bf16 v[44:47], v[146:149], v[196:199], v[44:47]
	v_mfma_f32_16x16x32_bf16 v[40:43], v[164:167], v[196:199], v[40:43]
	v_mfma_f32_16x16x32_bf16 v[28:31], v[146:149], v[204:207], v[28:31]
	v_mfma_f32_16x16x32_bf16 v[24:27], v[164:167], v[204:207], v[24:27]
	v_mfma_f32_16x16x32_bf16 v[12:15], v[146:149], v[212:215], v[12:15]
	v_mfma_f32_16x16x32_bf16 v[8:11], v[164:167], v[212:215], v[8:11]
	v_mfma_f32_16x16x32_bf16 v[60:63], v[160:163], v[192:195], v[60:63]
	v_mfma_f32_16x16x32_bf16 v[56:59], v[168:171], v[192:195], v[56:59]
	v_mfma_f32_16x16x32_bf16 v[44:47], v[160:163], v[200:203], v[44:47]
	v_mfma_f32_16x16x32_bf16 v[40:43], v[168:171], v[200:203], v[40:43]
	v_mfma_f32_16x16x32_bf16 v[28:31], v[160:163], v[208:211], v[28:31]
	v_mfma_f32_16x16x32_bf16 v[24:27], v[168:171], v[208:211], v[24:27]
	v_mfma_f32_16x16x32_bf16 v[12:15], v[160:163], v[216:219], v[12:15]
	v_mfma_f32_16x16x32_bf16 v[8:11], v[168:171], v[216:219], v[8:11]
	v_mfma_f32_16x16x32_bf16 v[52:55], v[172:175], v[188:191], v[52:55]
	v_mfma_f32_16x16x32_bf16 v[48:51], v[180:183], v[188:191], v[48:51]
	v_mfma_f32_16x16x32_bf16 v[36:39], v[172:175], v[196:199], v[36:39]
	v_mfma_f32_16x16x32_bf16 v[32:35], v[180:183], v[196:199], v[32:35]
	v_mfma_f32_16x16x32_bf16 v[20:23], v[172:175], v[204:207], v[20:23]
	v_mfma_f32_16x16x32_bf16 v[16:19], v[180:183], v[204:207], v[16:19]
	v_mfma_f32_16x16x32_bf16 v[4:7], v[172:175], v[212:215], v[4:7]
	v_mfma_f32_16x16x32_bf16 v[0:3], v[180:183], v[212:215], v[0:3]
	v_mfma_f32_16x16x32_bf16 v[52:55], v[176:179], v[192:195], v[52:55]
	v_mfma_f32_16x16x32_bf16 v[48:51], v[184:187], v[192:195], v[48:51]
	v_mfma_f32_16x16x32_bf16 v[36:39], v[176:179], v[200:203], v[36:39]
	v_mfma_f32_16x16x32_bf16 v[32:35], v[184:187], v[200:203], v[32:35]
	v_mfma_f32_16x16x32_bf16 v[20:23], v[176:179], v[208:211], v[20:23]
	v_mfma_f32_16x16x32_bf16 v[16:19], v[184:187], v[208:211], v[16:19]
	v_mfma_f32_16x16x32_bf16 v[4:7], v[176:179], v[216:219], v[4:7]
	v_mfma_f32_16x16x32_bf16 v[0:3], v[184:187], v[216:219], v[0:3]
	s_barrier
; #define PG8_STAGE(bufoff, gbase, voff) do { _Pragma("unroll") for (int _i = 0; _i < 2; ++_i) \
;         __builtin_amdgcn_global_load_lds((const unsigned*)((const char*)(gbase) + (voff)[_i]), (PG8_LAS unsigned*)(lds + (bufoff) + ldsw + _i * 8192), 16, 0, PG8_LOAD_AUX); } while (0)
; #define PG8_LDA(dst, b, h) do { _Pragma("unroll") for (int m = 0; m < 4; ++m) _Pragma("unroll") for (int k = 0; k < 2; ++k) dst[m][k] = *(const PG8_LAS bf16x8*)(lds + PG8_SA(b, h) + aoff + m * 2048 + k * 1024); } while (0)
; #define PG8_LDB(dst, b, h) do { _Pragma("unroll") for (int n = 0; n < 2; ++n) _Pragma("unroll") for (int k = 0; k < 2; ++k) dst[n][k] = *(const PG8_LAS bf16x8*)(lds + PG8_SB(b, h) + boff + n * 2048 + k * 1024); } while (0)
; #define PG8_MMA(ai, bj, At, Bt) do { __builtin_amdgcn_s_setprio(1); _Pragma("unroll") for (int m = 0; m < 4; ++m) _Pragma("unroll") for (int n = 0; n < 2; ++n) _Pragma("unroll") for (int k = 0; k < 2; ++k) \
;         acc[ai][bj][m][n] = __builtin_amdgcn_mfma_f32_16x16x32_bf16(Bt[n][k], At[m][k], acc[ai][bj][m][n], 0, 0, 0); __builtin_amdgcn_s_setprio(0); } while (0)
; #define PG8_WAIT_V(n) asm volatile("s_waitcnt vmcnt(" #n ")" ::: "memory")
; #define PG8_WAIT_L(n) asm volatile("s_waitcnt lgkmcnt(" #n ")" ::: "memory")
; #define PG8_BAR __builtin_amdgcn_s_barrier()
; #define PG8_SCHED __builtin_amdgcn_sched_barrier(0)
; template <class Epi, class Sched, bool ALIGN_EPI = false, bool SP2 = false>
; __device__ __forceinline__ void gemm_phase(PG8_LAS unsigned char* lds, const Gemm g, const Sched& S, const Epi& E) {
;     ...
;             PG8_LDB(B0, 1, 0); PG8_LDB(B1, 1, 1); PG8_SCHED; PG8_LDA(At, 1, 0); PG8_STAGE(PG8_SA(0, 1), a2 + hstepA, voffA);
;             PG8_WAIT_V(8); PG8_WAIT_L(0); PG8_BAR; PG8_MMA(0, 0, At, B0); PG8_MMA(0, 1, At, B1); PG8_BAR; PG8_SCHED;
.Lkmid_P13:
	s_add_i32 s28, 0, 0x18000
	v_add_u32_e32 v159, s28, v151
	s_add_i32 s29, 0, 0x1c000
	ds_read_b128 v[146:149], v159
	ds_read_b128 v[160:163], v159 offset:1024
	ds_read_b128 v[164:167], v159 offset:2048
	ds_read_b128 v[168:171], v159 offset:3072
	v_add_u32_e32 v159, s29, v151
	ds_read_b128 v[172:175], v159
	ds_read_b128 v[176:179], v159 offset:1024
	ds_read_b128 v[180:183], v159 offset:2048
	ds_read_b128 v[184:187], v159 offset:3072
	s_add_u32 s22, s22, 0xb0000
	s_addc_u32 s23, s23, 0
	s_mov_b32 m0, s45
	v_lshl_add_u64 v[228:229], s[22:23], 0, v[128:129]
	ds_read_b128 v[188:191], v157 offset:32768
	ds_read_b128 v[192:195], v157 offset:33792
	ds_read_b128 v[196:199], v157 offset:34816
	ds_read_b128 v[200:203], v157 offset:35840
	ds_read_b128 v[204:207], v157 offset:36864
	ds_read_b128 v[208:211], v157 offset:37888
	ds_read_b128 v[212:215], v157 offset:38912
	ds_read_b128 v[216:219], v157 offset:39936
	global_load_lds_dwordx4 v[228:229], off
	s_mov_b32 m0, s46
	v_lshl_add_u64 v[228:229], s[22:23], 0, v[132:133]
	global_load_lds_dwordx4 v[228:229], off
	s_waitcnt vmcnt(8)
	s_waitcnt lgkmcnt(0)
	s_barrier
	s_waitcnt lgkmcnt(0)
	v_mfma_f32_16x16x32_bf16 v[124:127], v[146:149], v[188:191], v[124:127]
	v_mfma_f32_16x16x32_bf16 v[120:123], v[164:167], v[188:191], v[120:123]
	v_mfma_f32_16x16x32_bf16 v[108:111], v[146:149], v[196:199], v[108:111]
	v_mfma_f32_16x16x32_bf16 v[104:107], v[164:167], v[196:199], v[104:107]
	v_mfma_f32_16x16x32_bf16 v[92:95], v[146:149], v[204:207], v[92:95]
	v_mfma_f32_16x16x32_bf16 v[88:91], v[164:167], v[204:207], v[88:91]
	v_mfma_f32_16x16x32_bf16 v[76:79], v[146:149], v[212:215], v[76:79]
	v_mfma_f32_16x16x32_bf16 v[72:75], v[164:167], v[212:215], v[72:75]
	v_mfma_f32_16x16x32_bf16 v[124:127], v[160:163], v[192:195], v[124:127]
	v_mfma_f32_16x16x32_bf16 v[120:123], v[168:171], v[192:195], v[120:123]
	v_mfma_f32_16x16x32_bf16 v[108:111], v[160:163], v[200:203], v[108:111]
	v_mfma_f32_16x16x32_bf16 v[104:107], v[168:171], v[200:203], v[104:107]
	v_mfma_f32_16x16x32_bf16 v[92:95], v[160:163], v[208:211], v[92:95]
	v_mfma_f32_16x16x32_bf16 v[88:91], v[168:171], v[208:211], v[88:91]
	v_mfma_f32_16x16x32_bf16 v[76:79], v[160:163], v[216:219], v[76:79]
	v_mfma_f32_16x16x32_bf16 v[72:75], v[168:171], v[216:219], v[72:75]
	v_mfma_f32_16x16x32_bf16 v[116:119], v[172:175], v[188:191], v[116:119]
	v_mfma_f32_16x16x32_bf16 v[112:115], v[180:183], v[188:191], v[112:115]
	v_mfma_f32_16x16x32_bf16 v[100:103], v[172:175], v[196:199], v[100:103]
	v_mfma_f32_16x16x32_bf16 v[96:99], v[180:183], v[196:199], v[96:99]
	v_mfma_f32_16x16x32_bf16 v[84:87], v[172:175], v[204:207], v[84:87]
	v_mfma_f32_16x16x32_bf16 v[80:83], v[180:183], v[204:207], v[80:83]
	v_mfma_f32_16x16x32_bf16 v[68:71], v[172:175], v[212:215], v[68:71]
	v_mfma_f32_16x16x32_bf16 v[64:67], v[180:183], v[212:215], v[64:67]
	v_mfma_f32_16x16x32_bf16 v[116:119], v[176:179], v[192:195], v[116:119]
	v_mfma_f32_16x16x32_bf16 v[112:115], v[184:187], v[192:195], v[112:115]
	v_mfma_f32_16x16x32_bf16 v[100:103], v[176:179], v[200:203], v[100:103]
	v_mfma_f32_16x16x32_bf16 v[96:99], v[184:187], v[200:203], v[96:99]
	v_mfma_f32_16x16x32_bf16 v[84:87], v[176:179], v[208:211], v[84:87]
	v_mfma_f32_16x16x32_bf16 v[80:83], v[184:187], v[208:211], v[80:83]
	v_mfma_f32_16x16x32_bf16 v[68:71], v[176:179], v[216:219], v[68:71]
	v_mfma_f32_16x16x32_bf16 v[64:67], v[184:187], v[216:219], v[64:67]
	s_barrier
; #define PG8_STAGE(bufoff, gbase, voff) do { _Pragma("unroll") for (int _i = 0; _i < 2; ++_i) \
;         __builtin_amdgcn_global_load_lds((const unsigned*)((const char*)(gbase) + (voff)[_i]), (PG8_LAS unsigned*)(lds + (bufoff) + ldsw + _i * 8192), 16, 0, PG8_LOAD_AUX); } while (0)
; #define PG8_LDA(dst, b, h) do { _Pragma("unroll") for (int m = 0; m < 4; ++m) _Pragma("unroll") for (int k = 0; k < 2; ++k) dst[m][k] = *(const PG8_LAS bf16x8*)(lds + PG8_SA(b, h) + aoff + m * 2048 + k * 1024); } while (0)
; #define PG8_MMA(ai, bj, At, Bt) do { __builtin_amdgcn_s_setprio(1); _Pragma("unroll") for (int m = 0; m < 4; ++m) _Pragma("unroll") for (int n = 0; n < 2; ++n) _Pragma("unroll") for (int k = 0; k < 2; ++k) \
;         acc[ai][bj][m][n] = __builtin_amdgcn_mfma_f32_16x16x32_bf16(Bt[n][k], At[m][k], acc[ai][bj][m][n], 0, 0, 0); __builtin_amdgcn_s_setprio(0); } while (0)
; #define PG8_WAIT_V(n) asm volatile("s_waitcnt vmcnt(" #n ")" ::: "memory")
; #define PG8_WAIT_L(n) asm volatile("s_waitcnt lgkmcnt(" #n ")" ::: "memory")
; #define PG8_BAR __builtin_amdgcn_s_barrier()
; #define PG8_SCHED __builtin_amdgcn_sched_barrier(0)
; template <class Epi, class Sched, bool ALIGN_EPI = false, bool SP2 = false>
; __device__ __forceinline__ void gemm_phase(PG8_LAS unsigned char* lds, const Gemm g, const Sched& S, const Epi& E) {
;     ...
;             PG8_LDA(At, 1, 1); PG8_STAGE(PG8_SB(1, 0), b3, voffB); PG8_STAGE(PG8_SB(1, 1), b3 + hstepB, voffB); PG8_STAGE(PG8_SA(1, 0), a3, voffA);
;             PG8_WAIT_V(8); PG8_WAIT_L(0); PG8_BAR; PG8_MMA(1, 0, At, B0); PG8_MMA(1, 1, At, B1); PG8_BAR; PG8_SCHED;
;     ...
;         if constexpr (ALIGN_EPI) { if (wr == 0) PG8_BAR; }
	s_add_i32 s22, s28, s42
	v_lshl_add_u64 v[220:221], v[220:221], 0, s[18:19]
	s_mov_b32 m0, s22
	ds_read_b128 v[188:191], v157 offset:49152
	ds_read_b128 v[192:195], v157 offset:50176
	ds_read_b128 v[196:199], v157 offset:51200
	ds_read_b128 v[200:203], v157 offset:52224
	ds_read_b128 v[204:207], v157 offset:53248
	ds_read_b128 v[208:211], v157 offset:54272
	ds_read_b128 v[212:215], v157 offset:55296
	ds_read_b128 v[216:219], v157 offset:56320
	global_load_lds_dwordx4 v[220:221], off
	s_add_i32 m0, s22, 0x2000
	s_add_u32 s20, s20, 0x2c080
	v_lshl_add_u64 v[220:221], v[222:223], 0, s[18:19]
	s_addc_u32 s21, s21, 0
	s_add_i32 s22, s29, s42
	global_load_lds_dwordx4 v[220:221], off
	s_mov_b32 m0, s22
	v_lshl_add_u64 v[220:221], s[20:21], 0, v[130:131]
	global_load_lds_dwordx4 v[220:221], off
	s_add_i32 m0, s22, 0x2000
	v_lshl_add_u64 v[220:221], s[20:21], 0, v[134:135]
	global_load_lds_dwordx4 v[220:221], off
	s_mov_b32 m0, s50
	v_lshl_add_u64 v[220:221], v[224:225], 0, s[18:19]
	global_load_lds_dwordx4 v[220:221], off
	s_mov_b32 m0, s51
	v_lshl_add_u64 v[220:221], v[226:227], 0, s[18:19]
	global_load_lds_dwordx4 v[220:221], off
	s_waitcnt vmcnt(8)
	s_waitcnt lgkmcnt(0)
	s_barrier
	s_waitcnt lgkmcnt(0)
	v_mfma_f32_16x16x32_bf16 v[60:63], v[146:149], v[188:191], v[60:63]
	v_mfma_f32_16x16x32_bf16 v[56:59], v[164:167], v[188:191], v[56:59]
	v_mfma_f32_16x16x32_bf16 v[44:47], v[146:149], v[196:199], v[44:47]
	v_mfma_f32_16x16x32_bf16 v[40:43], v[164:167], v[196:199], v[40:43]
	v_mfma_f32_16x16x32_bf16 v[28:31], v[146:149], v[204:207], v[28:31]
	v_mfma_f32_16x16x32_bf16 v[24:27], v[164:167], v[204:207], v[24:27]
	v_mfma_f32_16x16x32_bf16 v[12:15], v[146:149], v[212:215], v[12:15]
	v_mfma_f32_16x16x32_bf16 v[8:11], v[164:167], v[212:215], v[8:11]
	v_mfma_f32_16x16x32_bf16 v[60:63], v[160:163], v[192:195], v[60:63]
	v_mfma_f32_16x16x32_bf16 v[56:59], v[168:171], v[192:195], v[56:59]
	v_mfma_f32_16x16x32_bf16 v[44:47], v[160:163], v[200:203], v[44:47]
	v_mfma_f32_16x16x32_bf16 v[40:43], v[168:171], v[200:203], v[40:43]
	v_mfma_f32_16x16x32_bf16 v[28:31], v[160:163], v[208:211], v[28:31]
	v_mfma_f32_16x16x32_bf16 v[24:27], v[168:171], v[208:211], v[24:27]
	v_mfma_f32_16x16x32_bf16 v[12:15], v[160:163], v[216:219], v[12:15]
	v_mfma_f32_16x16x32_bf16 v[8:11], v[168:171], v[216:219], v[8:11]
	v_mfma_f32_16x16x32_bf16 v[52:55], v[172:175], v[188:191], v[52:55]
	v_mfma_f32_16x16x32_bf16 v[48:51], v[180:183], v[188:191], v[48:51]
	v_mfma_f32_16x16x32_bf16 v[36:39], v[172:175], v[196:199], v[36:39]
	v_mfma_f32_16x16x32_bf16 v[32:35], v[180:183], v[196:199], v[32:35]
	v_mfma_f32_16x16x32_bf16 v[20:23], v[172:175], v[204:207], v[20:23]
	v_mfma_f32_16x16x32_bf16 v[16:19], v[180:183], v[204:207], v[16:19]
	v_mfma_f32_16x16x32_bf16 v[4:7], v[172:175], v[212:215], v[4:7]
	v_mfma_f32_16x16x32_bf16 v[0:3], v[180:183], v[212:215], v[0:3]
	v_mfma_f32_16x16x32_bf16 v[52:55], v[176:179], v[192:195], v[52:55]
	v_mfma_f32_16x16x32_bf16 v[48:51], v[184:187], v[192:195], v[48:51]
	v_mfma_f32_16x16x32_bf16 v[36:39], v[176:179], v[200:203], v[36:39]
	v_mfma_f32_16x16x32_bf16 v[32:35], v[184:187], v[200:203], v[32:35]
	v_mfma_f32_16x16x32_bf16 v[20:23], v[176:179], v[208:211], v[20:23]
	v_mfma_f32_16x16x32_bf16 v[16:19], v[184:187], v[208:211], v[16:19]
	v_mfma_f32_16x16x32_bf16 v[4:7], v[176:179], v[216:219], v[4:7]
	v_mfma_f32_16x16x32_bf16 v[0:3], v[184:187], v[216:219], v[0:3]
	s_barrier
	s_add_i32 s27, s27, 2
	s_add_u32 s0, s0, 0x100
	s_addc_u32 s1, s1, 0
	s_add_u32 s25, s25, 0x100
	s_addc_u32 s26, s26, 0
	s_cmp_gt_u32 s27, 41
	s_cbranch_scc0 .LBB0_1196
	s_and_b64 vcc, exec, s[36:37]
	s_cbranch_vccz .LBB0_1199
	s_barrier
